# prompt attention: static per-row softmax reference kb[q] (logits bounded), running row-max tree / threshold test / deferred-rescale branch removed
# speedup vs baseline: 1.0712x; 1.0160x over previous
.LBB0_171:
	ds_read_b128 v[152:155], v135
	ds_read_b128 v[156:159], v135 offset:1024
	ds_read_b128 v[160:163], v135 offset:2048
	ds_read_b128 v[164:167], v135 offset:3072
	ds_read_b128 v[168:171], v141
	ds_read_b128 v[172:175], v141 offset:1024
	ds_read_b128 v[176:179], v141 offset:2048
	ds_read_b128 v[180:183], v141 offset:3072
	s_add_u32 s20, s16, s18
	s_addc_u32 s21, s17, s19
	s_add_u32 s20, s20, 0x8a00100
	s_addc_u32 s21, s21, 0
	s_add_u32 s59, s46, s18
	s_addc_u32 s60, s47, s19
	s_cmpk_eq_i32 s18, 0x700
	s_cselect_b32 s23, s7, s21
	s_cselect_b32 s22, s6, s20
	s_cselect_b32 s21, s5, s60
	s_cselect_b32 s20, s4, s59
	s_mov_b32 m0, s49
	v_lshl_add_u64 v[148:149], v[136:137], 0, s[18:19]
	ds_read_b128 v[184:187], v142
	ds_read_b128 v[188:191], v142 offset:1024
	ds_read_b128 v[192:195], v142 offset:2048
	ds_read_b128 v[196:199], v142 offset:3072
	ds_read_b128 v[200:203], v142 offset:4096
	ds_read_b128 v[204:207], v142 offset:5120
	ds_read_b128 v[208:211], v142 offset:6144
	ds_read_b128 v[216:219], v142 offset:7168
	global_load_lds_dwordx4 v[148:149], off
	v_lshl_add_u64 v[148:149], v[138:139], 0, s[18:19]
	s_mov_b32 m0, s50
	s_nop 0
	global_load_lds_dwordx4 v[148:149], off
	s_waitcnt vmcnt(8)
	s_waitcnt lgkmcnt(0)
	s_barrier
	s_setprio 1
	s_waitcnt lgkmcnt(0)
	v_mfma_f32_16x16x32_bf16 v[126:129], v[152:155], v[184:187], v[126:129]
	v_mfma_f32_16x16x32_bf16 v[122:125], v[160:163], v[184:187], v[122:125]
	v_mfma_f32_16x16x32_bf16 v[110:113], v[152:155], v[192:195], v[110:113]
	v_mfma_f32_16x16x32_bf16 v[106:109], v[160:163], v[192:195], v[106:109]
	v_mfma_f32_16x16x32_bf16 v[94:97], v[152:155], v[200:203], v[94:97]
	v_mfma_f32_16x16x32_bf16 v[90:93], v[160:163], v[200:203], v[90:93]
	v_mfma_f32_16x16x32_bf16 v[78:81], v[152:155], v[208:211], v[78:81]
	v_mfma_f32_16x16x32_bf16 v[74:77], v[160:163], v[208:211], v[74:77]
	v_mfma_f32_16x16x32_bf16 v[126:129], v[156:159], v[188:191], v[126:129]
	v_mfma_f32_16x16x32_bf16 v[122:125], v[164:167], v[188:191], v[122:125]
	v_mfma_f32_16x16x32_bf16 v[110:113], v[156:159], v[196:199], v[110:113]
	v_mfma_f32_16x16x32_bf16 v[106:109], v[164:167], v[196:199], v[106:109]
	v_mfma_f32_16x16x32_bf16 v[94:97], v[156:159], v[204:207], v[94:97]
	v_mfma_f32_16x16x32_bf16 v[90:93], v[164:167], v[204:207], v[90:93]
	v_mfma_f32_16x16x32_bf16 v[78:81], v[156:159], v[216:219], v[78:81]
	v_mfma_f32_16x16x32_bf16 v[74:77], v[164:167], v[216:219], v[74:77]
	s_setprio 0
	s_setprio 1
	v_mfma_f32_16x16x32_bf16 v[118:121], v[168:171], v[184:187], v[118:121]
	v_mfma_f32_16x16x32_bf16 v[114:117], v[176:179], v[184:187], v[114:117]
	v_mfma_f32_16x16x32_bf16 v[102:105], v[168:171], v[192:195], v[102:105]
	v_mfma_f32_16x16x32_bf16 v[98:101], v[176:179], v[192:195], v[98:101]
	v_mfma_f32_16x16x32_bf16 v[86:89], v[168:171], v[200:203], v[86:89]
	v_mfma_f32_16x16x32_bf16 v[82:85], v[176:179], v[200:203], v[82:85]
	v_mfma_f32_16x16x32_bf16 v[70:73], v[168:171], v[208:211], v[70:73]
	v_mfma_f32_16x16x32_bf16 v[66:69], v[176:179], v[208:211], v[66:69]
	v_mfma_f32_16x16x32_bf16 v[118:121], v[172:175], v[188:191], v[118:121]
	v_mfma_f32_16x16x32_bf16 v[114:117], v[180:183], v[188:191], v[114:117]
	v_mfma_f32_16x16x32_bf16 v[102:105], v[172:175], v[196:199], v[102:105]
	v_mfma_f32_16x16x32_bf16 v[98:101], v[180:183], v[196:199], v[98:101]
	v_mfma_f32_16x16x32_bf16 v[86:89], v[172:175], v[204:207], v[86:89]
	v_mfma_f32_16x16x32_bf16 v[82:85], v[180:183], v[204:207], v[82:85]
	v_mfma_f32_16x16x32_bf16 v[70:73], v[172:175], v[216:219], v[70:73]
	v_mfma_f32_16x16x32_bf16 v[66:69], v[180:183], v[216:219], v[66:69]
	s_setprio 0
	s_barrier
	s_mov_b32 m0, s51
	v_lshl_add_u64 v[148:149], s[20:21], 0, v[130:131]
	s_add_u32 s60, s20, 0x40000
	ds_read_b128 v[184:187], v142 offset:16384
	ds_read_b128 v[188:191], v142 offset:17408
	ds_read_b128 v[192:195], v142 offset:18432
	ds_read_b128 v[196:199], v142 offset:19456
	ds_read_b128 v[200:203], v142 offset:20480
	ds_read_b128 v[204:207], v142 offset:21504
	ds_read_b128 v[208:211], v142 offset:22528
	ds_read_b128 v[216:219], v142 offset:23552
	global_load_lds_dwordx4 v[148:149], off
	v_lshl_add_u64 v[212:213], s[20:21], 0, v[132:133]
	s_mov_b32 m0, s52
	s_addc_u32 s61, s21, 0
	global_load_lds_dwordx4 v[212:213], off
	v_lshl_add_u64 v[220:221], s[60:61], 0, v[130:131]
	s_mov_b32 m0, s53
	v_lshl_add_u64 v[222:223], s[22:23], 0, v[132:133]
	global_load_lds_dwordx4 v[220:221], off
	v_lshl_add_u64 v[220:221], s[60:61], 0, v[132:133]
	s_mov_b32 m0, s54
	s_nop 0
	global_load_lds_dwordx4 v[220:221], off
	v_lshl_add_u64 v[220:221], s[22:23], 0, v[130:131]
	s_mov_b32 m0, s26
	s_nop 0
	global_load_lds_dwordx4 v[220:221], off
	s_mov_b32 m0, s27
	s_nop 0
	global_load_lds_dwordx4 v[222:223], off
	s_waitcnt vmcnt(8)
	s_waitcnt lgkmcnt(0)
	s_barrier
	s_setprio 1
	s_waitcnt lgkmcnt(0)
	v_mfma_f32_16x16x32_bf16 v[62:65], v[152:155], v[184:187], v[62:65]
	v_mfma_f32_16x16x32_bf16 v[58:61], v[160:163], v[184:187], v[58:61]
	v_mfma_f32_16x16x32_bf16 v[46:49], v[152:155], v[192:195], v[46:49]
	v_mfma_f32_16x16x32_bf16 v[42:45], v[160:163], v[192:195], v[42:45]
	v_mfma_f32_16x16x32_bf16 v[30:33], v[152:155], v[200:203], v[30:33]
	v_mfma_f32_16x16x32_bf16 v[26:29], v[160:163], v[200:203], v[26:29]
	v_mfma_f32_16x16x32_bf16 v[14:17], v[152:155], v[208:211], v[14:17]
	v_mfma_f32_16x16x32_bf16 v[10:13], v[160:163], v[208:211], v[10:13]
	v_mfma_f32_16x16x32_bf16 v[62:65], v[156:159], v[188:191], v[62:65]
	v_mfma_f32_16x16x32_bf16 v[58:61], v[164:167], v[188:191], v[58:61]
	v_mfma_f32_16x16x32_bf16 v[46:49], v[156:159], v[196:199], v[46:49]
	v_mfma_f32_16x16x32_bf16 v[42:45], v[164:167], v[196:199], v[42:45]
	v_mfma_f32_16x16x32_bf16 v[30:33], v[156:159], v[204:207], v[30:33]
	v_mfma_f32_16x16x32_bf16 v[26:29], v[164:167], v[204:207], v[26:29]
	v_mfma_f32_16x16x32_bf16 v[14:17], v[156:159], v[216:219], v[14:17]
	v_mfma_f32_16x16x32_bf16 v[10:13], v[164:167], v[216:219], v[10:13]
	s_setprio 0
	s_setprio 1
	v_mfma_f32_16x16x32_bf16 v[54:57], v[168:171], v[184:187], v[54:57]
	v_mfma_f32_16x16x32_bf16 v[50:53], v[176:179], v[184:187], v[50:53]
	v_mfma_f32_16x16x32_bf16 v[38:41], v[168:171], v[192:195], v[38:41]
	v_mfma_f32_16x16x32_bf16 v[34:37], v[176:179], v[192:195], v[34:37]
	v_mfma_f32_16x16x32_bf16 v[22:25], v[168:171], v[200:203], v[22:25]
	v_mfma_f32_16x16x32_bf16 v[18:21], v[176:179], v[200:203], v[18:21]
	v_mfma_f32_16x16x32_bf16 v[6:9], v[168:171], v[208:211], v[6:9]
	v_mfma_f32_16x16x32_bf16 v[2:5], v[176:179], v[208:211], v[2:5]
	v_mfma_f32_16x16x32_bf16 v[54:57], v[172:175], v[188:191], v[54:57]
	v_mfma_f32_16x16x32_bf16 v[50:53], v[180:183], v[188:191], v[50:53]
	v_mfma_f32_16x16x32_bf16 v[38:41], v[172:175], v[196:199], v[38:41]
	v_mfma_f32_16x16x32_bf16 v[34:37], v[180:183], v[196:199], v[34:37]
	v_mfma_f32_16x16x32_bf16 v[22:25], v[172:175], v[204:207], v[22:25]
	v_mfma_f32_16x16x32_bf16 v[18:21], v[180:183], v[204:207], v[18:21]
	v_mfma_f32_16x16x32_bf16 v[6:9], v[172:175], v[216:219], v[6:9]
	v_mfma_f32_16x16x32_bf16 v[2:5], v[180:183], v[216:219], v[2:5]
	s_setprio 0
	s_barrier
	ds_read_b128 v[152:155], v143
	ds_read_b128 v[156:159], v143 offset:1024
	ds_read_b128 v[160:163], v143 offset:2048
	ds_read_b128 v[164:167], v143 offset:3072
	ds_read_b128 v[168:171], v144
	ds_read_b128 v[172:175], v144 offset:1024
	ds_read_b128 v[176:179], v144 offset:2048
	ds_read_b128 v[180:183], v144 offset:3072
	s_add_u32 s22, s22, 0x40000
	s_addc_u32 s23, s23, 0
	s_mov_b32 m0, s28
	v_lshl_add_u64 v[224:225], s[22:23], 0, v[130:131]
	ds_read_b128 v[184:187], v142 offset:32768
	ds_read_b128 v[188:191], v142 offset:33792
	ds_read_b128 v[192:195], v142 offset:34816
	ds_read_b128 v[196:199], v142 offset:35840
	ds_read_b128 v[200:203], v142 offset:36864
	ds_read_b128 v[204:207], v142 offset:37888
	ds_read_b128 v[208:211], v142 offset:38912
	ds_read_b128 v[216:219], v142 offset:39936
	global_load_lds_dwordx4 v[224:225], off
	v_lshl_add_u64 v[224:225], s[22:23], 0, v[132:133]
	s_mov_b32 m0, s29
	s_nop 0
	global_load_lds_dwordx4 v[224:225], off
	s_waitcnt vmcnt(8)
	s_waitcnt lgkmcnt(0)
	s_barrier
	s_setprio 1
	s_waitcnt lgkmcnt(0)
	v_mfma_f32_16x16x32_bf16 v[126:129], v[152:155], v[184:187], v[126:129]
	v_mfma_f32_16x16x32_bf16 v[122:125], v[160:163], v[184:187], v[122:125]
	v_mfma_f32_16x16x32_bf16 v[110:113], v[152:155], v[192:195], v[110:113]
	v_mfma_f32_16x16x32_bf16 v[106:109], v[160:163], v[192:195], v[106:109]
	v_mfma_f32_16x16x32_bf16 v[94:97], v[152:155], v[200:203], v[94:97]
	v_mfma_f32_16x16x32_bf16 v[90:93], v[160:163], v[200:203], v[90:93]
	v_mfma_f32_16x16x32_bf16 v[78:81], v[152:155], v[208:211], v[78:81]
	v_mfma_f32_16x16x32_bf16 v[74:77], v[160:163], v[208:211], v[74:77]
	v_mfma_f32_16x16x32_bf16 v[126:129], v[156:159], v[188:191], v[126:129]
	v_mfma_f32_16x16x32_bf16 v[122:125], v[164:167], v[188:191], v[122:125]
	v_mfma_f32_16x16x32_bf16 v[110:113], v[156:159], v[196:199], v[110:113]
	v_mfma_f32_16x16x32_bf16 v[106:109], v[164:167], v[196:199], v[106:109]
	v_mfma_f32_16x16x32_bf16 v[94:97], v[156:159], v[204:207], v[94:97]
	v_mfma_f32_16x16x32_bf16 v[90:93], v[164:167], v[204:207], v[90:93]
	v_mfma_f32_16x16x32_bf16 v[78:81], v[156:159], v[216:219], v[78:81]
	v_mfma_f32_16x16x32_bf16 v[74:77], v[164:167], v[216:219], v[74:77]
	s_setprio 0
	s_setprio 1
	v_mfma_f32_16x16x32_bf16 v[118:121], v[168:171], v[184:187], v[118:121]
	v_mfma_f32_16x16x32_bf16 v[114:117], v[176:179], v[184:187], v[114:117]
	v_mfma_f32_16x16x32_bf16 v[102:105], v[168:171], v[192:195], v[102:105]
	v_mfma_f32_16x16x32_bf16 v[98:101], v[176:179], v[192:195], v[98:101]
	v_mfma_f32_16x16x32_bf16 v[86:89], v[168:171], v[200:203], v[86:89]
	v_mfma_f32_16x16x32_bf16 v[82:85], v[176:179], v[200:203], v[82:85]
	v_mfma_f32_16x16x32_bf16 v[70:73], v[168:171], v[208:211], v[70:73]
	v_mfma_f32_16x16x32_bf16 v[66:69], v[176:179], v[208:211], v[66:69]
	v_mfma_f32_16x16x32_bf16 v[118:121], v[172:175], v[188:191], v[118:121]
	v_mfma_f32_16x16x32_bf16 v[114:117], v[180:183], v[188:191], v[114:117]
	v_mfma_f32_16x16x32_bf16 v[102:105], v[172:175], v[196:199], v[102:105]
	v_mfma_f32_16x16x32_bf16 v[98:101], v[180:183], v[196:199], v[98:101]
	v_mfma_f32_16x16x32_bf16 v[86:89], v[172:175], v[204:207], v[86:89]
	v_mfma_f32_16x16x32_bf16 v[82:85], v[180:183], v[204:207], v[82:85]
	v_mfma_f32_16x16x32_bf16 v[70:73], v[172:175], v[216:219], v[70:73]
	v_mfma_f32_16x16x32_bf16 v[66:69], v[180:183], v[216:219], v[66:69]
	s_setprio 0
	s_barrier
	s_mov_b32 m0, s55
	v_lshl_add_u64 v[148:149], v[148:149], 0, s[14:15]
	s_add_u32 s20, s20, 0x40080
	ds_read_b128 v[184:187], v142 offset:49152
	ds_read_b128 v[188:191], v142 offset:50176
	ds_read_b128 v[192:195], v142 offset:51200
	ds_read_b128 v[196:199], v142 offset:52224
	ds_read_b128 v[200:203], v142 offset:53248
	ds_read_b128 v[204:207], v142 offset:54272
	ds_read_b128 v[208:211], v142 offset:55296
	ds_read_b128 v[216:219], v142 offset:56320
	global_load_lds_dwordx4 v[148:149], off
	v_lshl_add_u64 v[148:149], v[212:213], 0, s[14:15]
	s_mov_b32 m0, s56
	s_addc_u32 s21, s21, 0
	global_load_lds_dwordx4 v[148:149], off
	v_lshl_add_u64 v[148:149], s[20:21], 0, v[130:131]
	s_mov_b32 m0, s57
	s_nop 0
	global_load_lds_dwordx4 v[148:149], off
	v_lshl_add_u64 v[148:149], s[20:21], 0, v[132:133]
	s_mov_b32 m0, s58
	s_nop 0
	global_load_lds_dwordx4 v[148:149], off
	v_lshl_add_u64 v[148:149], v[220:221], 0, s[14:15]
	s_mov_b32 m0, s30
	s_nop 0
	global_load_lds_dwordx4 v[148:149], off
	v_lshl_add_u64 v[148:149], v[222:223], 0, s[14:15]
	s_mov_b32 m0, s31
	s_nop 0
	global_load_lds_dwordx4 v[148:149], off
	s_waitcnt vmcnt(8)
	s_waitcnt lgkmcnt(0)
	s_barrier
	s_setprio 1
	s_waitcnt lgkmcnt(0)
	v_mfma_f32_16x16x32_bf16 v[62:65], v[152:155], v[184:187], v[62:65]
	v_mfma_f32_16x16x32_bf16 v[58:61], v[160:163], v[184:187], v[58:61]
	v_mfma_f32_16x16x32_bf16 v[46:49], v[152:155], v[192:195], v[46:49]
	v_mfma_f32_16x16x32_bf16 v[42:45], v[160:163], v[192:195], v[42:45]
	v_mfma_f32_16x16x32_bf16 v[30:33], v[152:155], v[200:203], v[30:33]
	v_mfma_f32_16x16x32_bf16 v[26:29], v[160:163], v[200:203], v[26:29]
	v_mfma_f32_16x16x32_bf16 v[14:17], v[152:155], v[208:211], v[14:17]
	v_mfma_f32_16x16x32_bf16 v[10:13], v[160:163], v[208:211], v[10:13]
	v_mfma_f32_16x16x32_bf16 v[62:65], v[156:159], v[188:191], v[62:65]
	v_mfma_f32_16x16x32_bf16 v[58:61], v[164:167], v[188:191], v[58:61]
	v_mfma_f32_16x16x32_bf16 v[46:49], v[156:159], v[196:199], v[46:49]
	v_mfma_f32_16x16x32_bf16 v[42:45], v[164:167], v[196:199], v[42:45]
	v_mfma_f32_16x16x32_bf16 v[30:33], v[156:159], v[204:207], v[30:33]
	v_mfma_f32_16x16x32_bf16 v[26:29], v[164:167], v[204:207], v[26:29]
	v_mfma_f32_16x16x32_bf16 v[14:17], v[156:159], v[216:219], v[14:17]
	v_mfma_f32_16x16x32_bf16 v[10:13], v[164:167], v[216:219], v[10:13]
	s_setprio 0
	s_setprio 1
	v_mfma_f32_16x16x32_bf16 v[54:57], v[168:171], v[184:187], v[54:57]
	v_mfma_f32_16x16x32_bf16 v[50:53], v[176:179], v[184:187], v[50:53]
	v_mfma_f32_16x16x32_bf16 v[38:41], v[168:171], v[192:195], v[38:41]
	v_mfma_f32_16x16x32_bf16 v[34:37], v[176:179], v[192:195], v[34:37]
	v_mfma_f32_16x16x32_bf16 v[22:25], v[168:171], v[200:203], v[22:25]
	v_mfma_f32_16x16x32_bf16 v[18:21], v[176:179], v[200:203], v[18:21]
	v_mfma_f32_16x16x32_bf16 v[6:9], v[168:171], v[208:211], v[6:9]
	v_mfma_f32_16x16x32_bf16 v[2:5], v[176:179], v[208:211], v[2:5]
	v_mfma_f32_16x16x32_bf16 v[54:57], v[172:175], v[188:191], v[54:57]
	v_mfma_f32_16x16x32_bf16 v[50:53], v[180:183], v[188:191], v[50:53]
	v_mfma_f32_16x16x32_bf16 v[38:41], v[172:175], v[196:199], v[38:41]
	v_mfma_f32_16x16x32_bf16 v[34:37], v[180:183], v[196:199], v[34:37]
	v_mfma_f32_16x16x32_bf16 v[22:25], v[172:175], v[204:207], v[22:25]
	v_mfma_f32_16x16x32_bf16 v[18:21], v[180:183], v[204:207], v[18:21]
	v_mfma_f32_16x16x32_bf16 v[6:9], v[172:175], v[216:219], v[6:9]
	v_mfma_f32_16x16x32_bf16 v[2:5], v[180:183], v[216:219], v[2:5]
	s_setprio 0
	s_barrier
	s_add_i32 s48, s48, 2
	s_add_u32 s18, s18, 0x100
	s_addc_u32 s19, s19, 0
	s_cmp_gt_u32 s48, 13
	s_cbranch_scc0 .LBB0_171
	s_cmpk_lt_u32 s3, 0x100
	s_cbranch_scc0 .LBB0_174
	s_barrier

.LBB0_231:
	ds_read_b128 v[142:145], v172
	ds_read_b128 v[146:149], v172 offset:1024
	ds_read_b128 v[150:153], v172 offset:2048
	ds_read_b128 v[154:157], v172 offset:3072
	ds_read_b128 v[158:161], v173
	ds_read_b128 v[176:179], v173 offset:1024
	ds_read_b128 v[180:183], v173 offset:2048
	ds_read_b128 v[184:187], v173 offset:3072
	s_add_u32 s46, s30, 0xfffc0080
	s_addc_u32 s47, s31, -1
	s_cmp_eq_u32 s66, 12
	s_cselect_b32 s49, s7, s47
	s_cselect_b32 s48, s25, s46
	s_cselect_b32 s47, s9, s65
	s_cselect_b32 s46, s63, s64
	v_lshl_add_u64 v[162:163], s[30:31], 0, v[136:137]
	s_add_i32 m0, s15, 0xc000
	ds_read_b128 v[188:191], v174
	ds_read_b128 v[192:195], v174 offset:1024
	ds_read_b128 v[196:199], v174 offset:2048
	ds_read_b128 v[200:203], v174 offset:3072
	ds_read_b128 v[204:207], v174 offset:4096
	ds_read_b128 v[208:211], v174 offset:5120
	ds_read_b128 v[216:219], v174 offset:6144
	ds_read_b128 v[220:223], v174 offset:7168
	global_load_lds_dwordx4 v[162:163], off
	v_lshl_add_u64 v[162:163], s[30:31], 0, v[138:139]
	s_add_i32 m0, s15, 0xe000
	s_nop 0
	global_load_lds_dwordx4 v[162:163], off
	s_waitcnt vmcnt(8)
	s_waitcnt lgkmcnt(0)
	s_barrier
	s_setprio 1
	s_waitcnt lgkmcnt(0)
	v_mfma_f32_16x16x32_bf16 v[124:127], v[142:145], v[188:191], v[124:127]
	v_mfma_f32_16x16x32_bf16 v[120:123], v[150:153], v[188:191], v[120:123]
	v_mfma_f32_16x16x32_bf16 v[108:111], v[142:145], v[196:199], v[108:111]
	v_mfma_f32_16x16x32_bf16 v[104:107], v[150:153], v[196:199], v[104:107]
	v_mfma_f32_16x16x32_bf16 v[92:95], v[142:145], v[204:207], v[92:95]
	v_mfma_f32_16x16x32_bf16 v[88:91], v[150:153], v[204:207], v[88:91]
	v_mfma_f32_16x16x32_bf16 v[76:79], v[142:145], v[216:219], v[76:79]
	v_mfma_f32_16x16x32_bf16 v[72:75], v[150:153], v[216:219], v[72:75]
	v_mfma_f32_16x16x32_bf16 v[124:127], v[146:149], v[192:195], v[124:127]
	v_mfma_f32_16x16x32_bf16 v[120:123], v[154:157], v[192:195], v[120:123]
	v_mfma_f32_16x16x32_bf16 v[108:111], v[146:149], v[200:203], v[108:111]
	v_mfma_f32_16x16x32_bf16 v[104:107], v[154:157], v[200:203], v[104:107]
	v_mfma_f32_16x16x32_bf16 v[92:95], v[146:149], v[208:211], v[92:95]
	v_mfma_f32_16x16x32_bf16 v[88:91], v[154:157], v[208:211], v[88:91]
	v_mfma_f32_16x16x32_bf16 v[76:79], v[146:149], v[220:223], v[76:79]
	v_mfma_f32_16x16x32_bf16 v[72:75], v[154:157], v[220:223], v[72:75]
	s_setprio 0
	s_setprio 1
	v_mfma_f32_16x16x32_bf16 v[116:119], v[158:161], v[188:191], v[116:119]
	v_mfma_f32_16x16x32_bf16 v[112:115], v[180:183], v[188:191], v[112:115]
	v_mfma_f32_16x16x32_bf16 v[100:103], v[158:161], v[196:199], v[100:103]
	v_mfma_f32_16x16x32_bf16 v[96:99], v[180:183], v[196:199], v[96:99]
	v_mfma_f32_16x16x32_bf16 v[84:87], v[158:161], v[204:207], v[84:87]
	v_mfma_f32_16x16x32_bf16 v[80:83], v[180:183], v[204:207], v[80:83]
	v_mfma_f32_16x16x32_bf16 v[68:71], v[158:161], v[216:219], v[68:71]
	v_mfma_f32_16x16x32_bf16 v[64:67], v[180:183], v[216:219], v[64:67]
	v_mfma_f32_16x16x32_bf16 v[116:119], v[176:179], v[192:195], v[116:119]
	v_mfma_f32_16x16x32_bf16 v[112:115], v[184:187], v[192:195], v[112:115]
	v_mfma_f32_16x16x32_bf16 v[100:103], v[176:179], v[200:203], v[100:103]
	v_mfma_f32_16x16x32_bf16 v[96:99], v[184:187], v[200:203], v[96:99]
	v_mfma_f32_16x16x32_bf16 v[84:87], v[176:179], v[208:211], v[84:87]
	v_mfma_f32_16x16x32_bf16 v[80:83], v[184:187], v[208:211], v[80:83]
	v_mfma_f32_16x16x32_bf16 v[68:71], v[176:179], v[220:223], v[68:71]
	v_mfma_f32_16x16x32_bf16 v[64:67], v[184:187], v[220:223], v[64:67]
	s_setprio 0
	s_barrier
	s_add_i32 s67, s12, s53
	v_lshl_add_u64 v[162:163], s[46:47], 0, v[128:129]
	s_mov_b32 m0, s67
	ds_read_b128 v[188:191], v174 offset:16384
	ds_read_b128 v[192:195], v174 offset:17408
	ds_read_b128 v[196:199], v174 offset:18432
	ds_read_b128 v[200:203], v174 offset:19456
	ds_read_b128 v[204:207], v174 offset:20480
	ds_read_b128 v[208:211], v174 offset:21504
	ds_read_b128 v[216:219], v174 offset:22528
	ds_read_b128 v[220:223], v174 offset:23552
	global_load_lds_dwordx4 v[162:163], off
	s_add_i32 m0, s67, 0x2000
	s_add_u32 s68, s46, 0x40000
	v_lshl_add_u64 v[212:213], s[46:47], 0, v[130:131]
	s_addc_u32 s69, s47, 0
	s_add_i32 s67, s62, s53
	global_load_lds_dwordx4 v[212:213], off
	v_lshl_add_u64 v[224:225], s[68:69], 0, v[128:129]
	s_mov_b32 m0, s67
	v_lshl_add_u64 v[226:227], s[48:49], 0, v[130:131]
	global_load_lds_dwordx4 v[224:225], off
	v_lshl_add_u64 v[224:225], s[68:69], 0, v[130:131]
	s_add_i32 m0, s67, 0x2000
	s_nop 0
	global_load_lds_dwordx4 v[224:225], off
	v_lshl_add_u64 v[224:225], s[48:49], 0, v[128:129]
	s_mov_b32 m0, s15
	s_nop 0
	global_load_lds_dwordx4 v[224:225], off
	s_mov_b32 m0, s54
	s_nop 0
	global_load_lds_dwordx4 v[226:227], off
	s_waitcnt vmcnt(8)
	s_waitcnt lgkmcnt(0)
	s_barrier
	s_setprio 1
	s_waitcnt lgkmcnt(0)
	v_mfma_f32_16x16x32_bf16 v[60:63], v[142:145], v[188:191], v[60:63]
	v_mfma_f32_16x16x32_bf16 v[56:59], v[150:153], v[188:191], v[56:59]
	v_mfma_f32_16x16x32_bf16 v[44:47], v[142:145], v[196:199], v[44:47]
	v_mfma_f32_16x16x32_bf16 v[40:43], v[150:153], v[196:199], v[40:43]
	v_mfma_f32_16x16x32_bf16 v[28:31], v[142:145], v[204:207], v[28:31]
	v_mfma_f32_16x16x32_bf16 v[24:27], v[150:153], v[204:207], v[24:27]
	v_mfma_f32_16x16x32_bf16 v[12:15], v[142:145], v[216:219], v[12:15]
	v_mfma_f32_16x16x32_bf16 v[8:11], v[150:153], v[216:219], v[8:11]
	v_mfma_f32_16x16x32_bf16 v[60:63], v[146:149], v[192:195], v[60:63]
	v_mfma_f32_16x16x32_bf16 v[56:59], v[154:157], v[192:195], v[56:59]
	v_mfma_f32_16x16x32_bf16 v[44:47], v[146:149], v[200:203], v[44:47]
	v_mfma_f32_16x16x32_bf16 v[40:43], v[154:157], v[200:203], v[40:43]
	v_mfma_f32_16x16x32_bf16 v[28:31], v[146:149], v[208:211], v[28:31]
	v_mfma_f32_16x16x32_bf16 v[24:27], v[154:157], v[208:211], v[24:27]
	v_mfma_f32_16x16x32_bf16 v[12:15], v[146:149], v[220:223], v[12:15]
	v_mfma_f32_16x16x32_bf16 v[8:11], v[154:157], v[220:223], v[8:11]
	s_setprio 0
	s_setprio 1
	v_mfma_f32_16x16x32_bf16 v[52:55], v[158:161], v[188:191], v[52:55]
	v_mfma_f32_16x16x32_bf16 v[48:51], v[180:183], v[188:191], v[48:51]
	v_mfma_f32_16x16x32_bf16 v[36:39], v[158:161], v[196:199], v[36:39]
	v_mfma_f32_16x16x32_bf16 v[32:35], v[180:183], v[196:199], v[32:35]
	v_mfma_f32_16x16x32_bf16 v[20:23], v[158:161], v[204:207], v[20:23]
	v_mfma_f32_16x16x32_bf16 v[16:19], v[180:183], v[204:207], v[16:19]
	v_mfma_f32_16x16x32_bf16 v[4:7], v[158:161], v[216:219], v[4:7]
	v_mfma_f32_16x16x32_bf16 v[0:3], v[180:183], v[216:219], v[0:3]
	v_mfma_f32_16x16x32_bf16 v[52:55], v[176:179], v[192:195], v[52:55]
	v_mfma_f32_16x16x32_bf16 v[48:51], v[184:187], v[192:195], v[48:51]
	v_mfma_f32_16x16x32_bf16 v[36:39], v[176:179], v[200:203], v[36:39]
	v_mfma_f32_16x16x32_bf16 v[32:35], v[184:187], v[200:203], v[32:35]
	v_mfma_f32_16x16x32_bf16 v[20:23], v[176:179], v[208:211], v[20:23]
	v_mfma_f32_16x16x32_bf16 v[16:19], v[184:187], v[208:211], v[16:19]
	v_mfma_f32_16x16x32_bf16 v[4:7], v[176:179], v[220:223], v[4:7]
	v_mfma_f32_16x16x32_bf16 v[0:3], v[184:187], v[220:223], v[0:3]
	s_setprio 0
	s_barrier
	s_add_i32 s67, 0, 0x18000
	v_add_u32_e32 v132, s67, v167
	s_add_i32 s68, 0, 0x1c000
	ds_read_b128 v[142:145], v132
	ds_read_b128 v[146:149], v132 offset:1024
	ds_read_b128 v[150:153], v132 offset:2048
	ds_read_b128 v[154:157], v132 offset:3072
	v_add_u32_e32 v132, s68, v167
	ds_read_b128 v[158:161], v132
	ds_read_b128 v[176:179], v132 offset:1024
	ds_read_b128 v[180:183], v132 offset:2048
	ds_read_b128 v[184:187], v132 offset:3072
	s_add_u32 s48, s48, 0x40000
	s_addc_u32 s49, s49, 0
	s_mov_b32 m0, s55
	v_lshl_add_u64 v[228:229], s[48:49], 0, v[128:129]
	ds_read_b128 v[188:191], v174 offset:32768
	ds_read_b128 v[192:195], v174 offset:33792
	ds_read_b128 v[196:199], v174 offset:34816
	ds_read_b128 v[200:203], v174 offset:35840
	ds_read_b128 v[204:207], v174 offset:36864
	ds_read_b128 v[208:211], v174 offset:37888
	ds_read_b128 v[216:219], v174 offset:38912
	ds_read_b128 v[220:223], v174 offset:39936
	global_load_lds_dwordx4 v[228:229], off
	v_lshl_add_u64 v[228:229], s[48:49], 0, v[130:131]
	s_mov_b32 m0, s56
	s_nop 0
	global_load_lds_dwordx4 v[228:229], off
	s_waitcnt vmcnt(8)
	s_waitcnt lgkmcnt(0)
	s_barrier
	s_setprio 1
	s_waitcnt lgkmcnt(0)
	v_mfma_f32_16x16x32_bf16 v[124:127], v[142:145], v[188:191], v[124:127]
	v_mfma_f32_16x16x32_bf16 v[120:123], v[150:153], v[188:191], v[120:123]
	v_mfma_f32_16x16x32_bf16 v[108:111], v[142:145], v[196:199], v[108:111]
	v_mfma_f32_16x16x32_bf16 v[104:107], v[150:153], v[196:199], v[104:107]
	v_mfma_f32_16x16x32_bf16 v[92:95], v[142:145], v[204:207], v[92:95]
	v_mfma_f32_16x16x32_bf16 v[88:91], v[150:153], v[204:207], v[88:91]
	v_mfma_f32_16x16x32_bf16 v[76:79], v[142:145], v[216:219], v[76:79]
	v_mfma_f32_16x16x32_bf16 v[72:75], v[150:153], v[216:219], v[72:75]
	v_mfma_f32_16x16x32_bf16 v[124:127], v[146:149], v[192:195], v[124:127]
	v_mfma_f32_16x16x32_bf16 v[120:123], v[154:157], v[192:195], v[120:123]
	v_mfma_f32_16x16x32_bf16 v[108:111], v[146:149], v[200:203], v[108:111]
	v_mfma_f32_16x16x32_bf16 v[104:107], v[154:157], v[200:203], v[104:107]
	v_mfma_f32_16x16x32_bf16 v[92:95], v[146:149], v[208:211], v[92:95]
	v_mfma_f32_16x16x32_bf16 v[88:91], v[154:157], v[208:211], v[88:91]
	v_mfma_f32_16x16x32_bf16 v[76:79], v[146:149], v[220:223], v[76:79]
	v_mfma_f32_16x16x32_bf16 v[72:75], v[154:157], v[220:223], v[72:75]
	s_setprio 0
	s_setprio 1
	v_mfma_f32_16x16x32_bf16 v[116:119], v[158:161], v[188:191], v[116:119]
	v_mfma_f32_16x16x32_bf16 v[112:115], v[180:183], v[188:191], v[112:115]
	v_mfma_f32_16x16x32_bf16 v[100:103], v[158:161], v[196:199], v[100:103]
	v_mfma_f32_16x16x32_bf16 v[96:99], v[180:183], v[196:199], v[96:99]
	v_mfma_f32_16x16x32_bf16 v[84:87], v[158:161], v[204:207], v[84:87]
	v_mfma_f32_16x16x32_bf16 v[80:83], v[180:183], v[204:207], v[80:83]
	v_mfma_f32_16x16x32_bf16 v[68:71], v[158:161], v[216:219], v[68:71]
	v_mfma_f32_16x16x32_bf16 v[64:67], v[180:183], v[216:219], v[64:67]
	v_mfma_f32_16x16x32_bf16 v[116:119], v[176:179], v[192:195], v[116:119]
	v_mfma_f32_16x16x32_bf16 v[112:115], v[184:187], v[192:195], v[112:115]
	v_mfma_f32_16x16x32_bf16 v[100:103], v[176:179], v[200:203], v[100:103]
	v_mfma_f32_16x16x32_bf16 v[96:99], v[184:187], v[200:203], v[96:99]
	v_mfma_f32_16x16x32_bf16 v[84:87], v[176:179], v[208:211], v[84:87]
	v_mfma_f32_16x16x32_bf16 v[80:83], v[184:187], v[208:211], v[80:83]
	v_mfma_f32_16x16x32_bf16 v[68:71], v[176:179], v[220:223], v[68:71]
	v_mfma_f32_16x16x32_bf16 v[64:67], v[184:187], v[220:223], v[64:67]
	s_setprio 0
	s_barrier
	s_add_i32 s48, s67, s53
	v_lshl_add_u64 v[162:163], v[162:163], 0, s[20:21]
	s_mov_b32 m0, s48
	ds_read_b128 v[188:191], v174 offset:49152
	ds_read_b128 v[192:195], v174 offset:50176
	ds_read_b128 v[196:199], v174 offset:51200
	ds_read_b128 v[200:203], v174 offset:52224
	ds_read_b128 v[204:207], v174 offset:53248
	ds_read_b128 v[208:211], v174 offset:54272
	ds_read_b128 v[216:219], v174 offset:55296
	ds_read_b128 v[220:223], v174 offset:56320
	global_load_lds_dwordx4 v[162:163], off
	s_add_i32 m0, s48, 0x2000
	s_add_u32 s46, s46, 0x40080
	v_lshl_add_u64 v[162:163], v[212:213], 0, s[20:21]
	s_addc_u32 s47, s47, 0
	s_add_i32 s48, s68, s53
	global_load_lds_dwordx4 v[162:163], off
	v_lshl_add_u64 v[162:163], s[46:47], 0, v[128:129]
	s_mov_b32 m0, s48
	s_nop 0
	global_load_lds_dwordx4 v[162:163], off
	v_lshl_add_u64 v[162:163], s[46:47], 0, v[130:131]
	s_add_i32 m0, s48, 0x2000
	s_nop 0
	global_load_lds_dwordx4 v[162:163], off
	v_lshl_add_u64 v[162:163], v[224:225], 0, s[20:21]
	s_mov_b32 m0, s60
	s_nop 0
	global_load_lds_dwordx4 v[162:163], off
	v_lshl_add_u64 v[162:163], v[226:227], 0, s[20:21]
	s_mov_b32 m0, s61
	s_nop 0
	global_load_lds_dwordx4 v[162:163], off
	s_waitcnt vmcnt(8)
	s_waitcnt lgkmcnt(0)
	s_barrier
	s_setprio 1
	s_waitcnt lgkmcnt(0)
	v_mfma_f32_16x16x32_bf16 v[60:63], v[142:145], v[188:191], v[60:63]
	v_mfma_f32_16x16x32_bf16 v[56:59], v[150:153], v[188:191], v[56:59]
	v_mfma_f32_16x16x32_bf16 v[44:47], v[142:145], v[196:199], v[44:47]
	v_mfma_f32_16x16x32_bf16 v[40:43], v[150:153], v[196:199], v[40:43]
	v_mfma_f32_16x16x32_bf16 v[28:31], v[142:145], v[204:207], v[28:31]
	v_mfma_f32_16x16x32_bf16 v[24:27], v[150:153], v[204:207], v[24:27]
	v_mfma_f32_16x16x32_bf16 v[12:15], v[142:145], v[216:219], v[12:15]
	v_mfma_f32_16x16x32_bf16 v[8:11], v[150:153], v[216:219], v[8:11]
	v_mfma_f32_16x16x32_bf16 v[60:63], v[146:149], v[192:195], v[60:63]
	v_mfma_f32_16x16x32_bf16 v[56:59], v[154:157], v[192:195], v[56:59]
	v_mfma_f32_16x16x32_bf16 v[44:47], v[146:149], v[200:203], v[44:47]
	v_mfma_f32_16x16x32_bf16 v[40:43], v[154:157], v[200:203], v[40:43]
	v_mfma_f32_16x16x32_bf16 v[28:31], v[146:149], v[208:211], v[28:31]
	v_mfma_f32_16x16x32_bf16 v[24:27], v[154:157], v[208:211], v[24:27]
	v_mfma_f32_16x16x32_bf16 v[12:15], v[146:149], v[220:223], v[12:15]
	v_mfma_f32_16x16x32_bf16 v[8:11], v[154:157], v[220:223], v[8:11]
	s_setprio 0
	s_setprio 1
	v_mfma_f32_16x16x32_bf16 v[52:55], v[158:161], v[188:191], v[52:55]
	v_mfma_f32_16x16x32_bf16 v[48:51], v[180:183], v[188:191], v[48:51]
	v_mfma_f32_16x16x32_bf16 v[36:39], v[158:161], v[196:199], v[36:39]
	v_mfma_f32_16x16x32_bf16 v[32:35], v[180:183], v[196:199], v[32:35]
	v_mfma_f32_16x16x32_bf16 v[20:23], v[158:161], v[204:207], v[20:23]
	v_mfma_f32_16x16x32_bf16 v[16:19], v[180:183], v[204:207], v[16:19]
	v_mfma_f32_16x16x32_bf16 v[4:7], v[158:161], v[216:219], v[4:7]
	v_mfma_f32_16x16x32_bf16 v[0:3], v[180:183], v[216:219], v[0:3]
	v_mfma_f32_16x16x32_bf16 v[52:55], v[176:179], v[192:195], v[52:55]
	v_mfma_f32_16x16x32_bf16 v[48:51], v[184:187], v[192:195], v[48:51]
	v_mfma_f32_16x16x32_bf16 v[36:39], v[176:179], v[200:203], v[36:39]
	v_mfma_f32_16x16x32_bf16 v[32:35], v[184:187], v[200:203], v[32:35]
	v_mfma_f32_16x16x32_bf16 v[20:23], v[176:179], v[208:211], v[20:23]
	v_mfma_f32_16x16x32_bf16 v[16:19], v[184:187], v[208:211], v[16:19]
	v_mfma_f32_16x16x32_bf16 v[4:7], v[176:179], v[220:223], v[4:7]
	v_mfma_f32_16x16x32_bf16 v[0:3], v[184:187], v[220:223], v[0:3]
	s_setprio 0
	s_barrier
	s_add_i32 s66, s66, 2
	s_add_u32 s30, s30, 0x100
	s_addc_u32 s31, s31, 0
	s_add_u32 s64, s64, 0x100
	s_addc_u32 s65, s65, 0
	s_cmp_gt_u32 s66, 13
	s_cbranch_scc0 .LBB0_231
	s_and_b64 vcc, exec, s[22:23]
	s_cbranch_vccz .LBB0_234
	s_barrier

.LBB0_312:
	s_add_u32 s52, s94, s14
	s_addc_u32 s53, s95, s15
	s_add_u32 s52, s52, 0x14d00100
	s_addc_u32 s53, s53, 0
	s_add_u32 s58, s96, s14
	s_addc_u32 s59, s97, s15
	s_add_i32 s63, 0, 0x10000
	s_cmpk_eq_i32 s14, 0x700
	s_cselect_b32 s55, s13, s53
	s_cselect_b32 s54, s12, s52
	v_add_u32_e32 v139, s63, v131
	s_cselect_b32 s53, s11, s59
	s_cselect_b32 s52, s10, s58
	s_add_i32 s77, 0, 0x14000
	ds_read_b128 v[140:143], v139
	ds_read_b128 v[156:159], v139 offset:1024
	ds_read_b128 v[160:163], v139 offset:2048
	ds_read_b128 v[164:167], v139 offset:3072
	v_add_u32_e32 v139, s77, v131
	ds_read_b128 v[186:189], v139
	ds_read_b128 v[190:193], v139 offset:1024
	ds_read_b128 v[194:197], v139 offset:2048
	ds_read_b128 v[198:201], v139 offset:3072
	v_lshl_add_u64 v[236:237], v[132:133], 0, s[14:15]
	s_add_i32 m0, s87, 0xc000
	ds_read_b128 v[202:205], v138
	ds_read_b128 v[206:209], v138 offset:1024
	ds_read_b128 v[210:213], v138 offset:2048
	ds_read_b128 v[216:219], v138 offset:3072
	ds_read_b128 v[220:223], v138 offset:4096
	ds_read_b128 v[224:227], v138 offset:5120
	ds_read_b128 v[228:231], v138 offset:6144
	ds_read_b128 v[232:235], v138 offset:7168
	global_load_lds_dwordx4 v[236:237], off
	v_lshl_add_u64 v[236:237], v[134:135], 0, s[14:15]
	s_add_i32 m0, s87, 0xe000
	s_nop 0
	global_load_lds_dwordx4 v[236:237], off
	s_waitcnt vmcnt(8)
	s_waitcnt lgkmcnt(0)
	s_barrier
	s_setprio 1
	s_waitcnt lgkmcnt(0)
	v_mfma_f32_16x16x32_bf16 v[124:127], v[140:143], v[202:205], v[124:127]
	v_mfma_f32_16x16x32_bf16 v[120:123], v[160:163], v[202:205], v[120:123]
	v_mfma_f32_16x16x32_bf16 v[108:111], v[140:143], v[210:213], v[108:111]
	v_mfma_f32_16x16x32_bf16 v[104:107], v[160:163], v[210:213], v[104:107]
	v_mfma_f32_16x16x32_bf16 v[92:95], v[140:143], v[220:223], v[92:95]
	v_mfma_f32_16x16x32_bf16 v[88:91], v[160:163], v[220:223], v[88:91]
	v_mfma_f32_16x16x32_bf16 v[76:79], v[140:143], v[228:231], v[76:79]
	v_mfma_f32_16x16x32_bf16 v[72:75], v[160:163], v[228:231], v[72:75]
	v_mfma_f32_16x16x32_bf16 v[124:127], v[156:159], v[206:209], v[124:127]
	v_mfma_f32_16x16x32_bf16 v[120:123], v[164:167], v[206:209], v[120:123]
	v_mfma_f32_16x16x32_bf16 v[108:111], v[156:159], v[216:219], v[108:111]
	v_mfma_f32_16x16x32_bf16 v[104:107], v[164:167], v[216:219], v[104:107]
	v_mfma_f32_16x16x32_bf16 v[92:95], v[156:159], v[224:227], v[92:95]
	v_mfma_f32_16x16x32_bf16 v[88:91], v[164:167], v[224:227], v[88:91]
	v_mfma_f32_16x16x32_bf16 v[76:79], v[156:159], v[232:235], v[76:79]
	v_mfma_f32_16x16x32_bf16 v[72:75], v[164:167], v[232:235], v[72:75]
	s_setprio 0
	s_setprio 1
	v_mfma_f32_16x16x32_bf16 v[116:119], v[186:189], v[202:205], v[116:119]
	v_mfma_f32_16x16x32_bf16 v[112:115], v[194:197], v[202:205], v[112:115]
	v_mfma_f32_16x16x32_bf16 v[100:103], v[186:189], v[210:213], v[100:103]
	v_mfma_f32_16x16x32_bf16 v[96:99], v[194:197], v[210:213], v[96:99]
	v_mfma_f32_16x16x32_bf16 v[84:87], v[186:189], v[220:223], v[84:87]
	v_mfma_f32_16x16x32_bf16 v[80:83], v[194:197], v[220:223], v[80:83]
	v_mfma_f32_16x16x32_bf16 v[68:71], v[186:189], v[228:231], v[68:71]
	v_mfma_f32_16x16x32_bf16 v[64:67], v[194:197], v[228:231], v[64:67]
	v_mfma_f32_16x16x32_bf16 v[116:119], v[190:193], v[206:209], v[116:119]
	v_mfma_f32_16x16x32_bf16 v[112:115], v[198:201], v[206:209], v[112:115]
	v_mfma_f32_16x16x32_bf16 v[100:103], v[190:193], v[216:219], v[100:103]
	v_mfma_f32_16x16x32_bf16 v[96:99], v[198:201], v[216:219], v[96:99]
	v_mfma_f32_16x16x32_bf16 v[84:87], v[190:193], v[224:227], v[84:87]
	v_mfma_f32_16x16x32_bf16 v[80:83], v[198:201], v[224:227], v[80:83]
	v_mfma_f32_16x16x32_bf16 v[68:71], v[190:193], v[232:235], v[68:71]
	v_mfma_f32_16x16x32_bf16 v[64:67], v[198:201], v[232:235], v[64:67]
	s_setprio 0
	s_barrier
	s_add_i32 s58, s63, s86
	v_lshl_add_u64 v[236:237], s[52:53], 0, v[148:149]
	s_mov_b32 m0, s58
	ds_read_b128 v[202:205], v138 offset:16384
	ds_read_b128 v[206:209], v138 offset:17408
	ds_read_b128 v[210:213], v138 offset:18432
	ds_read_b128 v[216:219], v138 offset:19456
	ds_read_b128 v[220:223], v138 offset:20480
	ds_read_b128 v[224:227], v138 offset:21504
	ds_read_b128 v[228:231], v138 offset:22528
	ds_read_b128 v[232:235], v138 offset:23552
	global_load_lds_dwordx4 v[236:237], off
	s_add_i32 m0, s58, 0x2000
	s_add_u32 s58, s52, 0x40000
	v_lshl_add_u64 v[238:239], s[52:53], 0, v[128:129]
	s_addc_u32 s59, s53, 0
	s_add_i32 s63, s77, s86
	global_load_lds_dwordx4 v[238:239], off
	v_lshl_add_u64 v[240:241], s[58:59], 0, v[148:149]
	s_mov_b32 m0, s63
	v_lshl_add_u64 v[242:243], s[54:55], 0, v[128:129]
	global_load_lds_dwordx4 v[240:241], off
	v_lshl_add_u64 v[240:241], s[58:59], 0, v[128:129]
	s_add_i32 m0, s63, 0x2000
	s_nop 0
	global_load_lds_dwordx4 v[240:241], off
	v_lshl_add_u64 v[240:241], s[54:55], 0, v[148:149]
	s_mov_b32 m0, s87
	s_nop 0
	global_load_lds_dwordx4 v[240:241], off
	s_mov_b32 m0, s88
	s_nop 0
	global_load_lds_dwordx4 v[242:243], off
	s_waitcnt vmcnt(8)
	s_waitcnt lgkmcnt(0)
	s_barrier
	s_setprio 1
	s_waitcnt lgkmcnt(0)
	v_mfma_f32_16x16x32_bf16 v[60:63], v[140:143], v[202:205], v[60:63]
	v_mfma_f32_16x16x32_bf16 v[56:59], v[160:163], v[202:205], v[56:59]
	v_mfma_f32_16x16x32_bf16 v[44:47], v[140:143], v[210:213], v[44:47]
	v_mfma_f32_16x16x32_bf16 v[40:43], v[160:163], v[210:213], v[40:43]
	v_mfma_f32_16x16x32_bf16 v[28:31], v[140:143], v[220:223], v[28:31]
	v_mfma_f32_16x16x32_bf16 v[24:27], v[160:163], v[220:223], v[24:27]
	v_mfma_f32_16x16x32_bf16 v[12:15], v[140:143], v[228:231], v[12:15]
	v_mfma_f32_16x16x32_bf16 v[8:11], v[160:163], v[228:231], v[8:11]
	v_mfma_f32_16x16x32_bf16 v[60:63], v[156:159], v[206:209], v[60:63]
	v_mfma_f32_16x16x32_bf16 v[56:59], v[164:167], v[206:209], v[56:59]
	v_mfma_f32_16x16x32_bf16 v[44:47], v[156:159], v[216:219], v[44:47]
	v_mfma_f32_16x16x32_bf16 v[40:43], v[164:167], v[216:219], v[40:43]
	v_mfma_f32_16x16x32_bf16 v[28:31], v[156:159], v[224:227], v[28:31]
	v_mfma_f32_16x16x32_bf16 v[24:27], v[164:167], v[224:227], v[24:27]
	v_mfma_f32_16x16x32_bf16 v[12:15], v[156:159], v[232:235], v[12:15]
	v_mfma_f32_16x16x32_bf16 v[8:11], v[164:167], v[232:235], v[8:11]
	s_setprio 0
	s_setprio 1
	v_mfma_f32_16x16x32_bf16 v[52:55], v[186:189], v[202:205], v[52:55]
	v_mfma_f32_16x16x32_bf16 v[48:51], v[194:197], v[202:205], v[48:51]
	v_mfma_f32_16x16x32_bf16 v[36:39], v[186:189], v[210:213], v[36:39]
	v_mfma_f32_16x16x32_bf16 v[32:35], v[194:197], v[210:213], v[32:35]
	v_mfma_f32_16x16x32_bf16 v[20:23], v[186:189], v[220:223], v[20:23]
	v_mfma_f32_16x16x32_bf16 v[16:19], v[194:197], v[220:223], v[16:19]
	v_mfma_f32_16x16x32_bf16 v[4:7], v[186:189], v[228:231], v[4:7]
	v_mfma_f32_16x16x32_bf16 v[0:3], v[194:197], v[228:231], v[0:3]
	v_mfma_f32_16x16x32_bf16 v[52:55], v[190:193], v[206:209], v[52:55]
	v_mfma_f32_16x16x32_bf16 v[48:51], v[198:201], v[206:209], v[48:51]
	v_mfma_f32_16x16x32_bf16 v[36:39], v[190:193], v[216:219], v[36:39]
	v_mfma_f32_16x16x32_bf16 v[32:35], v[198:201], v[216:219], v[32:35]
	v_mfma_f32_16x16x32_bf16 v[20:23], v[190:193], v[224:227], v[20:23]
	v_mfma_f32_16x16x32_bf16 v[16:19], v[198:201], v[224:227], v[16:19]
	v_mfma_f32_16x16x32_bf16 v[4:7], v[190:193], v[232:235], v[4:7]
	v_mfma_f32_16x16x32_bf16 v[0:3], v[198:201], v[232:235], v[0:3]
	s_setprio 0
	s_barrier
	s_add_i32 s58, 0, 0x18000
	v_add_u32_e32 v139, s58, v131
	s_add_i32 s59, 0, 0x1c000
	ds_read_b128 v[140:143], v139
	ds_read_b128 v[156:159], v139 offset:1024
	ds_read_b128 v[160:163], v139 offset:2048
	ds_read_b128 v[164:167], v139 offset:3072
	v_add_u32_e32 v139, s59, v131
	ds_read_b128 v[186:189], v139
	ds_read_b128 v[190:193], v139 offset:1024
	ds_read_b128 v[194:197], v139 offset:2048
	ds_read_b128 v[198:201], v139 offset:3072
	s_add_u32 s54, s54, 0x40000
	s_addc_u32 s55, s55, 0
	s_mov_b32 m0, s89
	v_lshl_add_u64 v[244:245], s[54:55], 0, v[148:149]
	ds_read_b128 v[202:205], v138 offset:32768
	ds_read_b128 v[206:209], v138 offset:33792
	ds_read_b128 v[210:213], v138 offset:34816
	ds_read_b128 v[216:219], v138 offset:35840
	ds_read_b128 v[220:223], v138 offset:36864
	ds_read_b128 v[224:227], v138 offset:37888
	ds_read_b128 v[228:231], v138 offset:38912
	ds_read_b128 v[232:235], v138 offset:39936
	global_load_lds_dwordx4 v[244:245], off
	v_lshl_add_u64 v[244:245], s[54:55], 0, v[128:129]
	s_mov_b32 m0, s90
	s_nop 0
	global_load_lds_dwordx4 v[244:245], off
	s_waitcnt vmcnt(8)
	s_waitcnt lgkmcnt(0)
	s_barrier
	s_setprio 1
	s_waitcnt lgkmcnt(0)
	v_mfma_f32_16x16x32_bf16 v[124:127], v[140:143], v[202:205], v[124:127]
	v_mfma_f32_16x16x32_bf16 v[120:123], v[160:163], v[202:205], v[120:123]
	v_mfma_f32_16x16x32_bf16 v[108:111], v[140:143], v[210:213], v[108:111]
	v_mfma_f32_16x16x32_bf16 v[104:107], v[160:163], v[210:213], v[104:107]
	v_mfma_f32_16x16x32_bf16 v[92:95], v[140:143], v[220:223], v[92:95]
	v_mfma_f32_16x16x32_bf16 v[88:91], v[160:163], v[220:223], v[88:91]
	v_mfma_f32_16x16x32_bf16 v[76:79], v[140:143], v[228:231], v[76:79]
	v_mfma_f32_16x16x32_bf16 v[72:75], v[160:163], v[228:231], v[72:75]
	v_mfma_f32_16x16x32_bf16 v[124:127], v[156:159], v[206:209], v[124:127]
	v_mfma_f32_16x16x32_bf16 v[120:123], v[164:167], v[206:209], v[120:123]
	v_mfma_f32_16x16x32_bf16 v[108:111], v[156:159], v[216:219], v[108:111]
	v_mfma_f32_16x16x32_bf16 v[104:107], v[164:167], v[216:219], v[104:107]
	v_mfma_f32_16x16x32_bf16 v[92:95], v[156:159], v[224:227], v[92:95]
	v_mfma_f32_16x16x32_bf16 v[88:91], v[164:167], v[224:227], v[88:91]
	v_mfma_f32_16x16x32_bf16 v[76:79], v[156:159], v[232:235], v[76:79]
	v_mfma_f32_16x16x32_bf16 v[72:75], v[164:167], v[232:235], v[72:75]
	s_setprio 0
	s_setprio 1
	v_mfma_f32_16x16x32_bf16 v[116:119], v[186:189], v[202:205], v[116:119]
	v_mfma_f32_16x16x32_bf16 v[112:115], v[194:197], v[202:205], v[112:115]
	v_mfma_f32_16x16x32_bf16 v[100:103], v[186:189], v[210:213], v[100:103]
	v_mfma_f32_16x16x32_bf16 v[96:99], v[194:197], v[210:213], v[96:99]
	v_mfma_f32_16x16x32_bf16 v[84:87], v[186:189], v[220:223], v[84:87]
	v_mfma_f32_16x16x32_bf16 v[80:83], v[194:197], v[220:223], v[80:83]
	v_mfma_f32_16x16x32_bf16 v[68:71], v[186:189], v[228:231], v[68:71]
	v_mfma_f32_16x16x32_bf16 v[64:67], v[194:197], v[228:231], v[64:67]
	v_mfma_f32_16x16x32_bf16 v[116:119], v[190:193], v[206:209], v[116:119]
	v_mfma_f32_16x16x32_bf16 v[112:115], v[198:201], v[206:209], v[112:115]
	v_mfma_f32_16x16x32_bf16 v[100:103], v[190:193], v[216:219], v[100:103]
	v_mfma_f32_16x16x32_bf16 v[96:99], v[198:201], v[216:219], v[96:99]
	v_mfma_f32_16x16x32_bf16 v[84:87], v[190:193], v[224:227], v[84:87]
	v_mfma_f32_16x16x32_bf16 v[80:83], v[198:201], v[224:227], v[80:83]
	v_mfma_f32_16x16x32_bf16 v[68:71], v[190:193], v[232:235], v[68:71]
	v_mfma_f32_16x16x32_bf16 v[64:67], v[198:201], v[232:235], v[64:67]
	s_setprio 0
	s_barrier
	s_add_i32 s54, s58, s86
	v_lshl_add_u64 v[236:237], v[236:237], 0, s[26:27]
	s_mov_b32 m0, s54
	ds_read_b128 v[202:205], v138 offset:49152
	ds_read_b128 v[206:209], v138 offset:50176
	ds_read_b128 v[210:213], v138 offset:51200
	ds_read_b128 v[216:219], v138 offset:52224
	ds_read_b128 v[220:223], v138 offset:53248
	ds_read_b128 v[224:227], v138 offset:54272
	ds_read_b128 v[228:231], v138 offset:55296
	ds_read_b128 v[232:235], v138 offset:56320
	global_load_lds_dwordx4 v[236:237], off
	s_add_i32 m0, s54, 0x2000
	s_add_u32 s52, s52, 0x40080
	v_lshl_add_u64 v[236:237], v[238:239], 0, s[26:27]
	s_addc_u32 s53, s53, 0
	s_add_i32 s54, s59, s86
	global_load_lds_dwordx4 v[236:237], off
	v_lshl_add_u64 v[236:237], s[52:53], 0, v[148:149]
	s_mov_b32 m0, s54
	s_nop 0
	global_load_lds_dwordx4 v[236:237], off
	v_lshl_add_u64 v[236:237], s[52:53], 0, v[128:129]
	s_add_i32 m0, s54, 0x2000
	s_nop 0
	global_load_lds_dwordx4 v[236:237], off
	v_lshl_add_u64 v[236:237], v[240:241], 0, s[26:27]
	s_mov_b32 m0, s92
	s_nop 0
	global_load_lds_dwordx4 v[236:237], off
	v_lshl_add_u64 v[236:237], v[242:243], 0, s[26:27]
	s_mov_b32 m0, s93
	s_nop 0
	global_load_lds_dwordx4 v[236:237], off
	s_waitcnt vmcnt(8)
	s_waitcnt lgkmcnt(0)
	s_barrier
	s_setprio 1
	s_waitcnt lgkmcnt(0)
	v_mfma_f32_16x16x32_bf16 v[60:63], v[140:143], v[202:205], v[60:63]
	v_mfma_f32_16x16x32_bf16 v[56:59], v[160:163], v[202:205], v[56:59]
	v_mfma_f32_16x16x32_bf16 v[44:47], v[140:143], v[210:213], v[44:47]
	v_mfma_f32_16x16x32_bf16 v[40:43], v[160:163], v[210:213], v[40:43]
	v_mfma_f32_16x16x32_bf16 v[28:31], v[140:143], v[220:223], v[28:31]
	v_mfma_f32_16x16x32_bf16 v[24:27], v[160:163], v[220:223], v[24:27]
	v_mfma_f32_16x16x32_bf16 v[12:15], v[140:143], v[228:231], v[12:15]
	v_mfma_f32_16x16x32_bf16 v[8:11], v[160:163], v[228:231], v[8:11]
	v_mfma_f32_16x16x32_bf16 v[60:63], v[156:159], v[206:209], v[60:63]
	v_mfma_f32_16x16x32_bf16 v[56:59], v[164:167], v[206:209], v[56:59]
	v_mfma_f32_16x16x32_bf16 v[44:47], v[156:159], v[216:219], v[44:47]
	v_mfma_f32_16x16x32_bf16 v[40:43], v[164:167], v[216:219], v[40:43]
	v_mfma_f32_16x16x32_bf16 v[28:31], v[156:159], v[224:227], v[28:31]
	v_mfma_f32_16x16x32_bf16 v[24:27], v[164:167], v[224:227], v[24:27]
	v_mfma_f32_16x16x32_bf16 v[12:15], v[156:159], v[232:235], v[12:15]
	v_mfma_f32_16x16x32_bf16 v[8:11], v[164:167], v[232:235], v[8:11]
	s_setprio 0
	s_setprio 1
	v_mfma_f32_16x16x32_bf16 v[52:55], v[186:189], v[202:205], v[52:55]
	v_mfma_f32_16x16x32_bf16 v[48:51], v[194:197], v[202:205], v[48:51]
	v_mfma_f32_16x16x32_bf16 v[36:39], v[186:189], v[210:213], v[36:39]
	v_mfma_f32_16x16x32_bf16 v[32:35], v[194:197], v[210:213], v[32:35]
	v_mfma_f32_16x16x32_bf16 v[20:23], v[186:189], v[220:223], v[20:23]
	v_mfma_f32_16x16x32_bf16 v[16:19], v[194:197], v[220:223], v[16:19]
	v_mfma_f32_16x16x32_bf16 v[4:7], v[186:189], v[228:231], v[4:7]
	v_mfma_f32_16x16x32_bf16 v[0:3], v[194:197], v[228:231], v[0:3]
	v_mfma_f32_16x16x32_bf16 v[52:55], v[190:193], v[206:209], v[52:55]
	v_mfma_f32_16x16x32_bf16 v[48:51], v[198:201], v[206:209], v[48:51]
	v_mfma_f32_16x16x32_bf16 v[36:39], v[190:193], v[216:219], v[36:39]
	v_mfma_f32_16x16x32_bf16 v[32:35], v[198:201], v[216:219], v[32:35]
	v_mfma_f32_16x16x32_bf16 v[20:23], v[190:193], v[224:227], v[20:23]
	v_mfma_f32_16x16x32_bf16 v[16:19], v[198:201], v[224:227], v[16:19]
	v_mfma_f32_16x16x32_bf16 v[4:7], v[190:193], v[232:235], v[4:7]
	v_mfma_f32_16x16x32_bf16 v[0:3], v[198:201], v[232:235], v[0:3]
	s_setprio 0
	s_barrier
	s_add_i32 s72, s72, 2
	s_add_u32 s14, s14, 0x100
	s_addc_u32 s15, s15, 0
	s_cmp_gt_u32 s72, 13
	s_cbranch_scc0 .LBB0_312
	s_cmpk_lt_u32 s83, 0x100
	s_cbranch_scc0 .LBB0_315
	s_barrier

.LBB0_365:
	s_add_u32 s54, s96, s52
	s_addc_u32 s55, s97, s53
	s_add_u32 s54, s54, 0x2f400100
	s_addc_u32 s55, s55, 0
	s_add_u32 s58, vcc_lo, s52
	s_addc_u32 s59, vcc_hi, s53
	s_add_i32 s77, 0, 0x10000
	s_cmpk_eq_i32 s52, 0x700
	s_cselect_b32 s57, s15, s55
	s_cselect_b32 s56, s14, s54
	v_add_u32_e32 v141, s77, v139
	s_cselect_b32 s55, s11, s59
	s_cselect_b32 s54, s10, s58
	s_add_i32 s63, 0, 0x14000
	ds_read_b128 v[156:159], v141
	ds_read_b128 v[160:163], v141 offset:1024
	ds_read_b128 v[164:167], v141 offset:2048
	ds_read_b128 v[188:191], v141 offset:3072
	v_add_u32_e32 v141, s63, v139
	ds_read_b128 v[192:195], v141
	ds_read_b128 v[196:199], v141 offset:1024
	ds_read_b128 v[200:203], v141 offset:2048
	ds_read_b128 v[204:207], v141 offset:3072
	v_lshl_add_u64 v[142:143], v[134:135], 0, s[52:53]
	s_add_i32 m0, s90, 0xc000
	ds_read_b128 v[208:211], v140
	ds_read_b128 v[216:219], v140 offset:1024
	ds_read_b128 v[220:223], v140 offset:2048
	ds_read_b128 v[224:227], v140 offset:3072
	ds_read_b128 v[228:231], v140 offset:4096
	ds_read_b128 v[232:235], v140 offset:5120
	ds_read_b128 v[236:239], v140 offset:6144
	ds_read_b128 v[240:243], v140 offset:7168
	global_load_lds_dwordx4 v[142:143], off
	v_lshl_add_u64 v[142:143], v[136:137], 0, s[52:53]
	s_add_i32 m0, s90, 0xe000
	s_nop 0
	global_load_lds_dwordx4 v[142:143], off
	s_waitcnt vmcnt(8)
	s_waitcnt lgkmcnt(0)
	s_barrier
	s_setprio 1
	s_waitcnt lgkmcnt(0)
	v_mfma_f32_16x16x32_bf16 v[124:127], v[156:159], v[208:211], v[124:127]
	v_mfma_f32_16x16x32_bf16 v[120:123], v[164:167], v[208:211], v[120:123]
	v_mfma_f32_16x16x32_bf16 v[108:111], v[156:159], v[220:223], v[108:111]
	v_mfma_f32_16x16x32_bf16 v[104:107], v[164:167], v[220:223], v[104:107]
	v_mfma_f32_16x16x32_bf16 v[92:95], v[156:159], v[228:231], v[92:95]
	v_mfma_f32_16x16x32_bf16 v[88:91], v[164:167], v[228:231], v[88:91]
	v_mfma_f32_16x16x32_bf16 v[76:79], v[156:159], v[236:239], v[76:79]
	v_mfma_f32_16x16x32_bf16 v[72:75], v[164:167], v[236:239], v[72:75]
	v_mfma_f32_16x16x32_bf16 v[124:127], v[160:163], v[216:219], v[124:127]
	v_mfma_f32_16x16x32_bf16 v[120:123], v[188:191], v[216:219], v[120:123]
	v_mfma_f32_16x16x32_bf16 v[108:111], v[160:163], v[224:227], v[108:111]
	v_mfma_f32_16x16x32_bf16 v[104:107], v[188:191], v[224:227], v[104:107]
	v_mfma_f32_16x16x32_bf16 v[92:95], v[160:163], v[232:235], v[92:95]
	v_mfma_f32_16x16x32_bf16 v[88:91], v[188:191], v[232:235], v[88:91]
	v_mfma_f32_16x16x32_bf16 v[76:79], v[160:163], v[240:243], v[76:79]
	v_mfma_f32_16x16x32_bf16 v[72:75], v[188:191], v[240:243], v[72:75]
	s_setprio 0
	s_setprio 1
	v_mfma_f32_16x16x32_bf16 v[116:119], v[192:195], v[208:211], v[116:119]
	v_mfma_f32_16x16x32_bf16 v[112:115], v[200:203], v[208:211], v[112:115]
	v_mfma_f32_16x16x32_bf16 v[100:103], v[192:195], v[220:223], v[100:103]
	v_mfma_f32_16x16x32_bf16 v[96:99], v[200:203], v[220:223], v[96:99]
	v_mfma_f32_16x16x32_bf16 v[84:87], v[192:195], v[228:231], v[84:87]
	v_mfma_f32_16x16x32_bf16 v[80:83], v[200:203], v[228:231], v[80:83]
	v_mfma_f32_16x16x32_bf16 v[68:71], v[192:195], v[236:239], v[68:71]
	v_mfma_f32_16x16x32_bf16 v[64:67], v[200:203], v[236:239], v[64:67]
	v_mfma_f32_16x16x32_bf16 v[116:119], v[196:199], v[216:219], v[116:119]
	v_mfma_f32_16x16x32_bf16 v[112:115], v[204:207], v[216:219], v[112:115]
	v_mfma_f32_16x16x32_bf16 v[100:103], v[196:199], v[224:227], v[100:103]
	v_mfma_f32_16x16x32_bf16 v[96:99], v[204:207], v[224:227], v[96:99]
	v_mfma_f32_16x16x32_bf16 v[84:87], v[196:199], v[232:235], v[84:87]
	v_mfma_f32_16x16x32_bf16 v[80:83], v[204:207], v[232:235], v[80:83]
	v_mfma_f32_16x16x32_bf16 v[68:71], v[196:199], v[240:243], v[68:71]
	v_mfma_f32_16x16x32_bf16 v[64:67], v[204:207], v[240:243], v[64:67]
	s_setprio 0
	s_barrier
	s_add_i32 s58, s77, s89
	v_lshl_add_u64 v[142:143], s[54:55], 0, v[148:149]
	s_mov_b32 m0, s58
	ds_read_b128 v[208:211], v140 offset:16384
	ds_read_b128 v[216:219], v140 offset:17408
	ds_read_b128 v[220:223], v140 offset:18432
	ds_read_b128 v[224:227], v140 offset:19456
	ds_read_b128 v[228:231], v140 offset:20480
	ds_read_b128 v[232:235], v140 offset:21504
	ds_read_b128 v[236:239], v140 offset:22528
	ds_read_b128 v[240:243], v140 offset:23552
	global_load_lds_dwordx4 v[142:143], off
	s_add_i32 m0, s58, 0x2000
	s_add_u32 s58, s54, 0x40000
	v_lshl_add_u64 v[212:213], s[54:55], 0, v[132:133]
	s_addc_u32 s59, s55, 0
	s_add_i32 s63, s63, s89
	global_load_lds_dwordx4 v[212:213], off
	v_lshl_add_u64 v[244:245], s[58:59], 0, v[148:149]
	s_mov_b32 m0, s63
	v_lshl_add_u64 v[246:247], s[56:57], 0, v[130:131]
	global_load_lds_dwordx4 v[244:245], off
	v_lshl_add_u64 v[244:245], s[58:59], 0, v[132:133]
	s_add_i32 m0, s63, 0x2000
	s_nop 0
	global_load_lds_dwordx4 v[244:245], off
	v_lshl_add_u64 v[244:245], s[56:57], 0, v[128:129]
	s_mov_b32 m0, s90
	s_nop 0
	global_load_lds_dwordx4 v[244:245], off
	s_mov_b32 m0, s91
	s_nop 0
	global_load_lds_dwordx4 v[246:247], off
	s_waitcnt vmcnt(8)
	s_waitcnt lgkmcnt(0)
	s_barrier
	s_setprio 1
	s_waitcnt lgkmcnt(0)
	v_mfma_f32_16x16x32_bf16 v[60:63], v[156:159], v[208:211], v[60:63]
	v_mfma_f32_16x16x32_bf16 v[56:59], v[164:167], v[208:211], v[56:59]
	v_mfma_f32_16x16x32_bf16 v[44:47], v[156:159], v[220:223], v[44:47]
	v_mfma_f32_16x16x32_bf16 v[40:43], v[164:167], v[220:223], v[40:43]
	v_mfma_f32_16x16x32_bf16 v[28:31], v[156:159], v[228:231], v[28:31]
	v_mfma_f32_16x16x32_bf16 v[24:27], v[164:167], v[228:231], v[24:27]
	v_mfma_f32_16x16x32_bf16 v[12:15], v[156:159], v[236:239], v[12:15]
	v_mfma_f32_16x16x32_bf16 v[8:11], v[164:167], v[236:239], v[8:11]
	v_mfma_f32_16x16x32_bf16 v[60:63], v[160:163], v[216:219], v[60:63]
	v_mfma_f32_16x16x32_bf16 v[56:59], v[188:191], v[216:219], v[56:59]
	v_mfma_f32_16x16x32_bf16 v[44:47], v[160:163], v[224:227], v[44:47]
	v_mfma_f32_16x16x32_bf16 v[40:43], v[188:191], v[224:227], v[40:43]
	v_mfma_f32_16x16x32_bf16 v[28:31], v[160:163], v[232:235], v[28:31]
	v_mfma_f32_16x16x32_bf16 v[24:27], v[188:191], v[232:235], v[24:27]
	v_mfma_f32_16x16x32_bf16 v[12:15], v[160:163], v[240:243], v[12:15]
	v_mfma_f32_16x16x32_bf16 v[8:11], v[188:191], v[240:243], v[8:11]
	s_setprio 0
	s_setprio 1
	v_mfma_f32_16x16x32_bf16 v[52:55], v[192:195], v[208:211], v[52:55]
	v_mfma_f32_16x16x32_bf16 v[48:51], v[200:203], v[208:211], v[48:51]
	v_mfma_f32_16x16x32_bf16 v[36:39], v[192:195], v[220:223], v[36:39]
	v_mfma_f32_16x16x32_bf16 v[32:35], v[200:203], v[220:223], v[32:35]
	v_mfma_f32_16x16x32_bf16 v[20:23], v[192:195], v[228:231], v[20:23]
	v_mfma_f32_16x16x32_bf16 v[16:19], v[200:203], v[228:231], v[16:19]
	v_mfma_f32_16x16x32_bf16 v[4:7], v[192:195], v[236:239], v[4:7]
	v_mfma_f32_16x16x32_bf16 v[0:3], v[200:203], v[236:239], v[0:3]
	v_mfma_f32_16x16x32_bf16 v[52:55], v[196:199], v[216:219], v[52:55]
	v_mfma_f32_16x16x32_bf16 v[48:51], v[204:207], v[216:219], v[48:51]
	v_mfma_f32_16x16x32_bf16 v[36:39], v[196:199], v[224:227], v[36:39]
	v_mfma_f32_16x16x32_bf16 v[32:35], v[204:207], v[224:227], v[32:35]
	v_mfma_f32_16x16x32_bf16 v[20:23], v[196:199], v[232:235], v[20:23]
	v_mfma_f32_16x16x32_bf16 v[16:19], v[204:207], v[232:235], v[16:19]
	v_mfma_f32_16x16x32_bf16 v[4:7], v[196:199], v[240:243], v[4:7]
	v_mfma_f32_16x16x32_bf16 v[0:3], v[204:207], v[240:243], v[0:3]
	s_setprio 0
	s_barrier
	s_add_i32 s58, 0, 0x18000
	v_add_u32_e32 v141, s58, v139
	s_add_i32 s59, 0, 0x1c000
	ds_read_b128 v[156:159], v141
	ds_read_b128 v[160:163], v141 offset:1024
	ds_read_b128 v[164:167], v141 offset:2048
	ds_read_b128 v[188:191], v141 offset:3072
	v_add_u32_e32 v141, s59, v139
	ds_read_b128 v[192:195], v141
	ds_read_b128 v[196:199], v141 offset:1024
	ds_read_b128 v[200:203], v141 offset:2048
	ds_read_b128 v[204:207], v141 offset:3072
	s_add_u32 s56, s56, 0x40000
	s_addc_u32 s57, s57, 0
	s_mov_b32 m0, s92
	v_lshl_add_u64 v[248:249], s[56:57], 0, v[128:129]
	ds_read_b128 v[208:211], v140 offset:32768
	ds_read_b128 v[216:219], v140 offset:33792
	ds_read_b128 v[220:223], v140 offset:34816
	ds_read_b128 v[224:227], v140 offset:35840
	ds_read_b128 v[228:231], v140 offset:36864
	ds_read_b128 v[232:235], v140 offset:37888
	ds_read_b128 v[236:239], v140 offset:38912
	ds_read_b128 v[240:243], v140 offset:39936
	global_load_lds_dwordx4 v[248:249], off
	v_lshl_add_u64 v[248:249], s[56:57], 0, v[130:131]
	s_mov_b32 m0, s93
	s_nop 0
	global_load_lds_dwordx4 v[248:249], off
	s_waitcnt vmcnt(8)
	s_waitcnt lgkmcnt(0)
	s_barrier
	s_setprio 1
	s_waitcnt lgkmcnt(0)
	v_mfma_f32_16x16x32_bf16 v[124:127], v[156:159], v[208:211], v[124:127]
	v_mfma_f32_16x16x32_bf16 v[120:123], v[164:167], v[208:211], v[120:123]
	v_mfma_f32_16x16x32_bf16 v[108:111], v[156:159], v[220:223], v[108:111]
	v_mfma_f32_16x16x32_bf16 v[104:107], v[164:167], v[220:223], v[104:107]
	v_mfma_f32_16x16x32_bf16 v[92:95], v[156:159], v[228:231], v[92:95]
	v_mfma_f32_16x16x32_bf16 v[88:91], v[164:167], v[228:231], v[88:91]
	v_mfma_f32_16x16x32_bf16 v[76:79], v[156:159], v[236:239], v[76:79]
	v_mfma_f32_16x16x32_bf16 v[72:75], v[164:167], v[236:239], v[72:75]
	v_mfma_f32_16x16x32_bf16 v[124:127], v[160:163], v[216:219], v[124:127]
	v_mfma_f32_16x16x32_bf16 v[120:123], v[188:191], v[216:219], v[120:123]
	v_mfma_f32_16x16x32_bf16 v[108:111], v[160:163], v[224:227], v[108:111]
	v_mfma_f32_16x16x32_bf16 v[104:107], v[188:191], v[224:227], v[104:107]
	v_mfma_f32_16x16x32_bf16 v[92:95], v[160:163], v[232:235], v[92:95]
	v_mfma_f32_16x16x32_bf16 v[88:91], v[188:191], v[232:235], v[88:91]
	v_mfma_f32_16x16x32_bf16 v[76:79], v[160:163], v[240:243], v[76:79]
	v_mfma_f32_16x16x32_bf16 v[72:75], v[188:191], v[240:243], v[72:75]
	s_setprio 0
	s_setprio 1
	v_mfma_f32_16x16x32_bf16 v[116:119], v[192:195], v[208:211], v[116:119]
	v_mfma_f32_16x16x32_bf16 v[112:115], v[200:203], v[208:211], v[112:115]
	v_mfma_f32_16x16x32_bf16 v[100:103], v[192:195], v[220:223], v[100:103]
	v_mfma_f32_16x16x32_bf16 v[96:99], v[200:203], v[220:223], v[96:99]
	v_mfma_f32_16x16x32_bf16 v[84:87], v[192:195], v[228:231], v[84:87]
	v_mfma_f32_16x16x32_bf16 v[80:83], v[200:203], v[228:231], v[80:83]
	v_mfma_f32_16x16x32_bf16 v[68:71], v[192:195], v[236:239], v[68:71]
	v_mfma_f32_16x16x32_bf16 v[64:67], v[200:203], v[236:239], v[64:67]
	v_mfma_f32_16x16x32_bf16 v[116:119], v[196:199], v[216:219], v[116:119]
	v_mfma_f32_16x16x32_bf16 v[112:115], v[204:207], v[216:219], v[112:115]
	v_mfma_f32_16x16x32_bf16 v[100:103], v[196:199], v[224:227], v[100:103]
	v_mfma_f32_16x16x32_bf16 v[96:99], v[204:207], v[224:227], v[96:99]
	v_mfma_f32_16x16x32_bf16 v[84:87], v[196:199], v[232:235], v[84:87]
	v_mfma_f32_16x16x32_bf16 v[80:83], v[204:207], v[232:235], v[80:83]
	v_mfma_f32_16x16x32_bf16 v[68:71], v[196:199], v[240:243], v[68:71]
	v_mfma_f32_16x16x32_bf16 v[64:67], v[204:207], v[240:243], v[64:67]
	s_setprio 0
	s_barrier
	s_add_i32 s56, s58, s89
	v_lshl_add_u64 v[142:143], v[142:143], 0, s[26:27]
	s_mov_b32 m0, s56
	ds_read_b128 v[208:211], v140 offset:49152
	ds_read_b128 v[216:219], v140 offset:50176
	ds_read_b128 v[220:223], v140 offset:51200
	ds_read_b128 v[224:227], v140 offset:52224
	ds_read_b128 v[228:231], v140 offset:53248
	ds_read_b128 v[232:235], v140 offset:54272
	ds_read_b128 v[236:239], v140 offset:55296
	ds_read_b128 v[240:243], v140 offset:56320
	global_load_lds_dwordx4 v[142:143], off
	s_add_i32 m0, s56, 0x2000
	s_add_u32 s54, s54, 0x40080
	v_lshl_add_u64 v[142:143], v[212:213], 0, s[26:27]
	s_addc_u32 s55, s55, 0
	s_add_i32 s56, s59, s89
	global_load_lds_dwordx4 v[142:143], off
	v_lshl_add_u64 v[142:143], s[54:55], 0, v[148:149]
	s_mov_b32 m0, s56
	s_nop 0
	global_load_lds_dwordx4 v[142:143], off
	v_lshl_add_u64 v[142:143], s[54:55], 0, v[132:133]
	s_add_i32 m0, s56, 0x2000
	s_nop 0
	global_load_lds_dwordx4 v[142:143], off
	v_lshl_add_u64 v[142:143], v[244:245], 0, s[26:27]
	s_mov_b32 m0, s94
	s_nop 0
	global_load_lds_dwordx4 v[142:143], off
	v_lshl_add_u64 v[142:143], v[246:247], 0, s[26:27]
	s_mov_b32 m0, s95
	s_nop 0
	global_load_lds_dwordx4 v[142:143], off
	s_waitcnt vmcnt(8)
	s_waitcnt lgkmcnt(0)
	s_barrier
	s_setprio 1
	s_waitcnt lgkmcnt(0)
	v_mfma_f32_16x16x32_bf16 v[60:63], v[156:159], v[208:211], v[60:63]
	v_mfma_f32_16x16x32_bf16 v[56:59], v[164:167], v[208:211], v[56:59]
	v_mfma_f32_16x16x32_bf16 v[44:47], v[156:159], v[220:223], v[44:47]
	v_mfma_f32_16x16x32_bf16 v[40:43], v[164:167], v[220:223], v[40:43]
	v_mfma_f32_16x16x32_bf16 v[28:31], v[156:159], v[228:231], v[28:31]
	v_mfma_f32_16x16x32_bf16 v[24:27], v[164:167], v[228:231], v[24:27]
	v_mfma_f32_16x16x32_bf16 v[12:15], v[156:159], v[236:239], v[12:15]
	v_mfma_f32_16x16x32_bf16 v[8:11], v[164:167], v[236:239], v[8:11]
	v_mfma_f32_16x16x32_bf16 v[60:63], v[160:163], v[216:219], v[60:63]
	v_mfma_f32_16x16x32_bf16 v[56:59], v[188:191], v[216:219], v[56:59]
	v_mfma_f32_16x16x32_bf16 v[44:47], v[160:163], v[224:227], v[44:47]
	v_mfma_f32_16x16x32_bf16 v[40:43], v[188:191], v[224:227], v[40:43]
	v_mfma_f32_16x16x32_bf16 v[28:31], v[160:163], v[232:235], v[28:31]
	v_mfma_f32_16x16x32_bf16 v[24:27], v[188:191], v[232:235], v[24:27]
	v_mfma_f32_16x16x32_bf16 v[12:15], v[160:163], v[240:243], v[12:15]
	v_mfma_f32_16x16x32_bf16 v[8:11], v[188:191], v[240:243], v[8:11]
	s_setprio 0
	s_setprio 1
	v_mfma_f32_16x16x32_bf16 v[52:55], v[192:195], v[208:211], v[52:55]
	v_mfma_f32_16x16x32_bf16 v[48:51], v[200:203], v[208:211], v[48:51]
	v_mfma_f32_16x16x32_bf16 v[36:39], v[192:195], v[220:223], v[36:39]
	v_mfma_f32_16x16x32_bf16 v[32:35], v[200:203], v[220:223], v[32:35]
	v_mfma_f32_16x16x32_bf16 v[20:23], v[192:195], v[228:231], v[20:23]
	v_mfma_f32_16x16x32_bf16 v[16:19], v[200:203], v[228:231], v[16:19]
	v_mfma_f32_16x16x32_bf16 v[4:7], v[192:195], v[236:239], v[4:7]
	v_mfma_f32_16x16x32_bf16 v[0:3], v[200:203], v[236:239], v[0:3]
	v_mfma_f32_16x16x32_bf16 v[52:55], v[196:199], v[216:219], v[52:55]
	v_mfma_f32_16x16x32_bf16 v[48:51], v[204:207], v[216:219], v[48:51]
	v_mfma_f32_16x16x32_bf16 v[36:39], v[196:199], v[224:227], v[36:39]
	v_mfma_f32_16x16x32_bf16 v[32:35], v[204:207], v[224:227], v[32:35]
	v_mfma_f32_16x16x32_bf16 v[20:23], v[196:199], v[232:235], v[20:23]
	v_mfma_f32_16x16x32_bf16 v[16:19], v[204:207], v[232:235], v[16:19]
	v_mfma_f32_16x16x32_bf16 v[4:7], v[196:199], v[240:243], v[4:7]
	v_mfma_f32_16x16x32_bf16 v[0:3], v[204:207], v[240:243], v[0:3]
	s_setprio 0
	s_barrier
	s_add_i32 s72, s72, 2
	s_add_u32 s52, s52, 0x100
	s_addc_u32 s53, s53, 0
	s_cmp_gt_u32 s72, 13
	s_cbranch_scc0 .LBB0_365
	s_cmpk_lt_u32 s88, 0x100
	s_cbranch_scc0 .LBB0_368
	s_barrier

.LBB0_439:
	ds_read_b128 v[128:131], v181
	ds_read_b128 v[132:135], v181 offset:1024
	ds_read_b128 v[136:139], v181 offset:2048
	ds_read_b128 v[140:143], v181 offset:3072
	ds_read_b128 v[160:163], v182
	ds_read_b128 v[164:167], v182 offset:1024
	ds_read_b128 v[168:171], v182 offset:2048
	ds_read_b128 v[172:175], v182 offset:3072
	s_add_u32 s52, s30, 0xfffc0080
	s_addc_u32 s53, s31, -1
	s_cmp_eq_u32 s76, 12
	s_cselect_b32 s55, s23, s53
	s_cselect_b32 s54, s29, s52
	s_cselect_b32 s53, s21, s74
	s_cselect_b32 s52, s71, s73
	v_lshl_add_u64 v[212:213], s[30:31], 0, v[152:153]
	s_add_i32 m0, s59, 0xc000
	ds_read_b128 v[184:187], v183
	ds_read_b128 v[188:191], v183 offset:1024
	ds_read_b128 v[192:195], v183 offset:2048
	ds_read_b128 v[196:199], v183 offset:3072
	ds_read_b128 v[200:203], v183 offset:4096
	ds_read_b128 v[204:207], v183 offset:5120
	ds_read_b128 v[208:211], v183 offset:6144
	ds_read_b128 v[216:219], v183 offset:7168
	global_load_lds_dwordx4 v[212:213], off
	v_lshl_add_u64 v[212:213], s[30:31], 0, v[154:155]
	s_add_i32 m0, s59, 0xe000
	s_nop 0
	global_load_lds_dwordx4 v[212:213], off
	s_waitcnt vmcnt(8)
	s_waitcnt lgkmcnt(0)
	s_barrier
	s_setprio 1
	s_waitcnt lgkmcnt(0)
	v_mfma_f32_16x16x32_bf16 v[124:127], v[128:131], v[184:187], v[124:127]
	v_mfma_f32_16x16x32_bf16 v[120:123], v[136:139], v[184:187], v[120:123]
	v_mfma_f32_16x16x32_bf16 v[108:111], v[128:131], v[192:195], v[108:111]
	v_mfma_f32_16x16x32_bf16 v[104:107], v[136:139], v[192:195], v[104:107]
	v_mfma_f32_16x16x32_bf16 v[92:95], v[128:131], v[200:203], v[92:95]
	v_mfma_f32_16x16x32_bf16 v[88:91], v[136:139], v[200:203], v[88:91]
	v_mfma_f32_16x16x32_bf16 v[76:79], v[128:131], v[208:211], v[76:79]
	v_mfma_f32_16x16x32_bf16 v[72:75], v[136:139], v[208:211], v[72:75]
	v_mfma_f32_16x16x32_bf16 v[124:127], v[132:135], v[188:191], v[124:127]
	v_mfma_f32_16x16x32_bf16 v[120:123], v[140:143], v[188:191], v[120:123]
	v_mfma_f32_16x16x32_bf16 v[108:111], v[132:135], v[196:199], v[108:111]
	v_mfma_f32_16x16x32_bf16 v[104:107], v[140:143], v[196:199], v[104:107]
	v_mfma_f32_16x16x32_bf16 v[92:95], v[132:135], v[204:207], v[92:95]
	v_mfma_f32_16x16x32_bf16 v[88:91], v[140:143], v[204:207], v[88:91]
	v_mfma_f32_16x16x32_bf16 v[76:79], v[132:135], v[216:219], v[76:79]
	v_mfma_f32_16x16x32_bf16 v[72:75], v[140:143], v[216:219], v[72:75]
	s_setprio 0
	s_setprio 1
	v_mfma_f32_16x16x32_bf16 v[116:119], v[160:163], v[184:187], v[116:119]
	v_mfma_f32_16x16x32_bf16 v[112:115], v[168:171], v[184:187], v[112:115]
	v_mfma_f32_16x16x32_bf16 v[100:103], v[160:163], v[192:195], v[100:103]
	v_mfma_f32_16x16x32_bf16 v[96:99], v[168:171], v[192:195], v[96:99]
	v_mfma_f32_16x16x32_bf16 v[84:87], v[160:163], v[200:203], v[84:87]
	v_mfma_f32_16x16x32_bf16 v[80:83], v[168:171], v[200:203], v[80:83]
	v_mfma_f32_16x16x32_bf16 v[68:71], v[160:163], v[208:211], v[68:71]
	v_mfma_f32_16x16x32_bf16 v[64:67], v[168:171], v[208:211], v[64:67]
	v_mfma_f32_16x16x32_bf16 v[116:119], v[164:167], v[188:191], v[116:119]
	v_mfma_f32_16x16x32_bf16 v[112:115], v[172:175], v[188:191], v[112:115]
	v_mfma_f32_16x16x32_bf16 v[100:103], v[164:167], v[196:199], v[100:103]
	v_mfma_f32_16x16x32_bf16 v[96:99], v[172:175], v[196:199], v[96:99]
	v_mfma_f32_16x16x32_bf16 v[84:87], v[164:167], v[204:207], v[84:87]
	v_mfma_f32_16x16x32_bf16 v[80:83], v[172:175], v[204:207], v[80:83]
	v_mfma_f32_16x16x32_bf16 v[68:71], v[164:167], v[216:219], v[68:71]
	v_mfma_f32_16x16x32_bf16 v[64:67], v[172:175], v[216:219], v[64:67]
	s_setprio 0
	s_barrier
	s_add_i32 s72, s68, s58
	v_lshl_add_u64 v[212:213], s[52:53], 0, v[146:147]
	s_mov_b32 m0, s72
	ds_read_b128 v[184:187], v183 offset:16384
	ds_read_b128 v[188:191], v183 offset:17408
	ds_read_b128 v[192:195], v183 offset:18432
	ds_read_b128 v[196:199], v183 offset:19456
	ds_read_b128 v[200:203], v183 offset:20480
	ds_read_b128 v[204:207], v183 offset:21504
	ds_read_b128 v[208:211], v183 offset:22528
	ds_read_b128 v[216:219], v183 offset:23552
	global_load_lds_dwordx4 v[212:213], off
	s_add_i32 m0, s72, 0x2000
	s_add_u32 s78, s52, 0x40000
	v_lshl_add_u64 v[220:221], s[52:53], 0, v[150:151]
	s_addc_u32 s79, s53, 0
	s_add_i32 s72, s69, s58
	global_load_lds_dwordx4 v[220:221], off
	v_lshl_add_u64 v[222:223], s[78:79], 0, v[146:147]
	s_mov_b32 m0, s72
	v_lshl_add_u64 v[224:225], s[54:55], 0, v[148:149]
	global_load_lds_dwordx4 v[222:223], off
	v_lshl_add_u64 v[222:223], s[78:79], 0, v[150:151]
	s_add_i32 m0, s72, 0x2000
	s_nop 0
	global_load_lds_dwordx4 v[222:223], off
	v_lshl_add_u64 v[222:223], s[54:55], 0, v[144:145]
	s_mov_b32 m0, s59
	s_nop 0
	global_load_lds_dwordx4 v[222:223], off
	s_mov_b32 m0, s60
	s_nop 0
	global_load_lds_dwordx4 v[224:225], off
	s_waitcnt vmcnt(8)
	s_waitcnt lgkmcnt(0)
	s_barrier
	s_setprio 1
	s_waitcnt lgkmcnt(0)
	v_mfma_f32_16x16x32_bf16 v[60:63], v[128:131], v[184:187], v[60:63]
	v_mfma_f32_16x16x32_bf16 v[56:59], v[136:139], v[184:187], v[56:59]
	v_mfma_f32_16x16x32_bf16 v[44:47], v[128:131], v[192:195], v[44:47]
	v_mfma_f32_16x16x32_bf16 v[40:43], v[136:139], v[192:195], v[40:43]
	v_mfma_f32_16x16x32_bf16 v[28:31], v[128:131], v[200:203], v[28:31]
	v_mfma_f32_16x16x32_bf16 v[24:27], v[136:139], v[200:203], v[24:27]
	v_mfma_f32_16x16x32_bf16 v[12:15], v[128:131], v[208:211], v[12:15]
	v_mfma_f32_16x16x32_bf16 v[8:11], v[136:139], v[208:211], v[8:11]
	v_mfma_f32_16x16x32_bf16 v[60:63], v[132:135], v[188:191], v[60:63]
	v_mfma_f32_16x16x32_bf16 v[56:59], v[140:143], v[188:191], v[56:59]
	v_mfma_f32_16x16x32_bf16 v[44:47], v[132:135], v[196:199], v[44:47]
	v_mfma_f32_16x16x32_bf16 v[40:43], v[140:143], v[196:199], v[40:43]
	v_mfma_f32_16x16x32_bf16 v[28:31], v[132:135], v[204:207], v[28:31]
	v_mfma_f32_16x16x32_bf16 v[24:27], v[140:143], v[204:207], v[24:27]
	v_mfma_f32_16x16x32_bf16 v[12:15], v[132:135], v[216:219], v[12:15]
	v_mfma_f32_16x16x32_bf16 v[8:11], v[140:143], v[216:219], v[8:11]
	s_setprio 0
	s_setprio 1
	v_mfma_f32_16x16x32_bf16 v[52:55], v[160:163], v[184:187], v[52:55]
	v_mfma_f32_16x16x32_bf16 v[48:51], v[168:171], v[184:187], v[48:51]
	v_mfma_f32_16x16x32_bf16 v[36:39], v[160:163], v[192:195], v[36:39]
	v_mfma_f32_16x16x32_bf16 v[32:35], v[168:171], v[192:195], v[32:35]
	v_mfma_f32_16x16x32_bf16 v[20:23], v[160:163], v[200:203], v[20:23]
	v_mfma_f32_16x16x32_bf16 v[16:19], v[168:171], v[200:203], v[16:19]
	v_mfma_f32_16x16x32_bf16 v[4:7], v[160:163], v[208:211], v[4:7]
	v_mfma_f32_16x16x32_bf16 v[0:3], v[168:171], v[208:211], v[0:3]
	v_mfma_f32_16x16x32_bf16 v[52:55], v[164:167], v[188:191], v[52:55]
	v_mfma_f32_16x16x32_bf16 v[48:51], v[172:175], v[188:191], v[48:51]
	v_mfma_f32_16x16x32_bf16 v[36:39], v[164:167], v[196:199], v[36:39]
	v_mfma_f32_16x16x32_bf16 v[32:35], v[172:175], v[196:199], v[32:35]
	v_mfma_f32_16x16x32_bf16 v[20:23], v[164:167], v[204:207], v[20:23]
	v_mfma_f32_16x16x32_bf16 v[16:19], v[172:175], v[204:207], v[16:19]
	v_mfma_f32_16x16x32_bf16 v[4:7], v[164:167], v[216:219], v[4:7]
	v_mfma_f32_16x16x32_bf16 v[0:3], v[172:175], v[216:219], v[0:3]
	s_setprio 0
	s_barrier
	s_add_i32 s72, 0, 0x18000
	s_add_i32 s77, 0, 0x1c000
	v_add_u32_e32 v140, s72, v179
	v_add_u32_e32 v172, s77, v179
	ds_read_b128 v[128:131], v140
	ds_read_b128 v[132:135], v140 offset:1024
	ds_read_b128 v[136:139], v140 offset:2048
	ds_read_b128 v[140:143], v140 offset:3072
	ds_read_b128 v[160:163], v172
	ds_read_b128 v[164:167], v172 offset:1024
	ds_read_b128 v[168:171], v172 offset:2048
	ds_read_b128 v[172:175], v172 offset:3072
	s_add_u32 s54, s54, 0x40000
	s_addc_u32 s55, s55, 0
	s_mov_b32 m0, s61
	v_lshl_add_u64 v[226:227], s[54:55], 0, v[144:145]
	ds_read_b128 v[184:187], v183 offset:32768
	ds_read_b128 v[188:191], v183 offset:33792
	ds_read_b128 v[192:195], v183 offset:34816
	ds_read_b128 v[196:199], v183 offset:35840
	ds_read_b128 v[200:203], v183 offset:36864
	ds_read_b128 v[204:207], v183 offset:37888
	ds_read_b128 v[208:211], v183 offset:38912
	ds_read_b128 v[216:219], v183 offset:39936
	global_load_lds_dwordx4 v[226:227], off
	v_lshl_add_u64 v[226:227], s[54:55], 0, v[148:149]
	s_mov_b32 m0, s62
	s_nop 0
	global_load_lds_dwordx4 v[226:227], off
	s_waitcnt vmcnt(8)
	s_waitcnt lgkmcnt(0)
	s_barrier
	s_setprio 1
	s_waitcnt lgkmcnt(0)
	v_mfma_f32_16x16x32_bf16 v[124:127], v[128:131], v[184:187], v[124:127]
	v_mfma_f32_16x16x32_bf16 v[120:123], v[136:139], v[184:187], v[120:123]
	v_mfma_f32_16x16x32_bf16 v[108:111], v[128:131], v[192:195], v[108:111]
	v_mfma_f32_16x16x32_bf16 v[104:107], v[136:139], v[192:195], v[104:107]
	v_mfma_f32_16x16x32_bf16 v[92:95], v[128:131], v[200:203], v[92:95]
	v_mfma_f32_16x16x32_bf16 v[88:91], v[136:139], v[200:203], v[88:91]
	v_mfma_f32_16x16x32_bf16 v[76:79], v[128:131], v[208:211], v[76:79]
	v_mfma_f32_16x16x32_bf16 v[72:75], v[136:139], v[208:211], v[72:75]
	v_mfma_f32_16x16x32_bf16 v[124:127], v[132:135], v[188:191], v[124:127]
	v_mfma_f32_16x16x32_bf16 v[120:123], v[140:143], v[188:191], v[120:123]
	v_mfma_f32_16x16x32_bf16 v[108:111], v[132:135], v[196:199], v[108:111]
	v_mfma_f32_16x16x32_bf16 v[104:107], v[140:143], v[196:199], v[104:107]
	v_mfma_f32_16x16x32_bf16 v[92:95], v[132:135], v[204:207], v[92:95]
	v_mfma_f32_16x16x32_bf16 v[88:91], v[140:143], v[204:207], v[88:91]
	v_mfma_f32_16x16x32_bf16 v[76:79], v[132:135], v[216:219], v[76:79]
	v_mfma_f32_16x16x32_bf16 v[72:75], v[140:143], v[216:219], v[72:75]
	s_setprio 0
	s_setprio 1
	v_mfma_f32_16x16x32_bf16 v[116:119], v[160:163], v[184:187], v[116:119]
	v_mfma_f32_16x16x32_bf16 v[112:115], v[168:171], v[184:187], v[112:115]
	v_mfma_f32_16x16x32_bf16 v[100:103], v[160:163], v[192:195], v[100:103]
	v_mfma_f32_16x16x32_bf16 v[96:99], v[168:171], v[192:195], v[96:99]
	v_mfma_f32_16x16x32_bf16 v[84:87], v[160:163], v[200:203], v[84:87]
	v_mfma_f32_16x16x32_bf16 v[80:83], v[168:171], v[200:203], v[80:83]
	v_mfma_f32_16x16x32_bf16 v[68:71], v[160:163], v[208:211], v[68:71]
	v_mfma_f32_16x16x32_bf16 v[64:67], v[168:171], v[208:211], v[64:67]
	v_mfma_f32_16x16x32_bf16 v[116:119], v[164:167], v[188:191], v[116:119]
	v_mfma_f32_16x16x32_bf16 v[112:115], v[172:175], v[188:191], v[112:115]
	v_mfma_f32_16x16x32_bf16 v[100:103], v[164:167], v[196:199], v[100:103]
	v_mfma_f32_16x16x32_bf16 v[96:99], v[172:175], v[196:199], v[96:99]
	v_mfma_f32_16x16x32_bf16 v[84:87], v[164:167], v[204:207], v[84:87]
	v_mfma_f32_16x16x32_bf16 v[80:83], v[172:175], v[204:207], v[80:83]
	v_mfma_f32_16x16x32_bf16 v[68:71], v[164:167], v[216:219], v[68:71]
	v_mfma_f32_16x16x32_bf16 v[64:67], v[172:175], v[216:219], v[64:67]
	s_setprio 0
	s_barrier
	s_add_i32 s54, s72, s58
	v_lshl_add_u64 v[212:213], v[212:213], 0, s[12:13]
	s_mov_b32 m0, s54
	ds_read_b128 v[184:187], v183 offset:49152
	ds_read_b128 v[188:191], v183 offset:50176
	ds_read_b128 v[192:195], v183 offset:51200
	ds_read_b128 v[196:199], v183 offset:52224
	ds_read_b128 v[200:203], v183 offset:53248
	ds_read_b128 v[204:207], v183 offset:54272
	ds_read_b128 v[208:211], v183 offset:55296
	ds_read_b128 v[216:219], v183 offset:56320
	global_load_lds_dwordx4 v[212:213], off
	s_add_i32 m0, s54, 0x2000
	s_add_u32 s52, s52, 0x40080
	v_lshl_add_u64 v[212:213], v[220:221], 0, s[12:13]
	s_addc_u32 s53, s53, 0
	s_add_i32 s54, s77, s58
	global_load_lds_dwordx4 v[212:213], off
	v_lshl_add_u64 v[212:213], s[52:53], 0, v[146:147]
	s_mov_b32 m0, s54
	s_nop 0
	global_load_lds_dwordx4 v[212:213], off
	v_lshl_add_u64 v[212:213], s[52:53], 0, v[150:151]
	s_add_i32 m0, s54, 0x2000
	s_nop 0
	global_load_lds_dwordx4 v[212:213], off
	v_lshl_add_u64 v[212:213], v[222:223], 0, s[12:13]
	s_mov_b32 m0, s66
	s_nop 0
	global_load_lds_dwordx4 v[212:213], off
	v_lshl_add_u64 v[212:213], v[224:225], 0, s[12:13]
	s_mov_b32 m0, s67
	s_nop 0
	global_load_lds_dwordx4 v[212:213], off
	s_waitcnt vmcnt(8)
	s_waitcnt lgkmcnt(0)
	s_barrier
	s_setprio 1
	s_waitcnt lgkmcnt(0)
	v_mfma_f32_16x16x32_bf16 v[60:63], v[128:131], v[184:187], v[60:63]
	v_mfma_f32_16x16x32_bf16 v[56:59], v[136:139], v[184:187], v[56:59]
	v_mfma_f32_16x16x32_bf16 v[44:47], v[128:131], v[192:195], v[44:47]
	v_mfma_f32_16x16x32_bf16 v[40:43], v[136:139], v[192:195], v[40:43]
	v_mfma_f32_16x16x32_bf16 v[28:31], v[128:131], v[200:203], v[28:31]
	v_mfma_f32_16x16x32_bf16 v[24:27], v[136:139], v[200:203], v[24:27]
	v_mfma_f32_16x16x32_bf16 v[12:15], v[128:131], v[208:211], v[12:15]
	v_mfma_f32_16x16x32_bf16 v[8:11], v[136:139], v[208:211], v[8:11]
	v_mfma_f32_16x16x32_bf16 v[60:63], v[132:135], v[188:191], v[60:63]
	v_mfma_f32_16x16x32_bf16 v[56:59], v[140:143], v[188:191], v[56:59]
	v_mfma_f32_16x16x32_bf16 v[44:47], v[132:135], v[196:199], v[44:47]
	v_mfma_f32_16x16x32_bf16 v[40:43], v[140:143], v[196:199], v[40:43]
	v_mfma_f32_16x16x32_bf16 v[28:31], v[132:135], v[204:207], v[28:31]
	v_mfma_f32_16x16x32_bf16 v[24:27], v[140:143], v[204:207], v[24:27]
	v_mfma_f32_16x16x32_bf16 v[12:15], v[132:135], v[216:219], v[12:15]
	v_mfma_f32_16x16x32_bf16 v[8:11], v[140:143], v[216:219], v[8:11]
	s_setprio 0
	s_setprio 1
	v_mfma_f32_16x16x32_bf16 v[52:55], v[160:163], v[184:187], v[52:55]
	v_mfma_f32_16x16x32_bf16 v[48:51], v[168:171], v[184:187], v[48:51]
	v_mfma_f32_16x16x32_bf16 v[36:39], v[160:163], v[192:195], v[36:39]
	v_mfma_f32_16x16x32_bf16 v[32:35], v[168:171], v[192:195], v[32:35]
	v_mfma_f32_16x16x32_bf16 v[20:23], v[160:163], v[200:203], v[20:23]
	v_mfma_f32_16x16x32_bf16 v[16:19], v[168:171], v[200:203], v[16:19]
	v_mfma_f32_16x16x32_bf16 v[4:7], v[160:163], v[208:211], v[4:7]
	v_mfma_f32_16x16x32_bf16 v[0:3], v[168:171], v[208:211], v[0:3]
	v_mfma_f32_16x16x32_bf16 v[52:55], v[164:167], v[188:191], v[52:55]
	v_mfma_f32_16x16x32_bf16 v[48:51], v[172:175], v[188:191], v[48:51]
	v_mfma_f32_16x16x32_bf16 v[36:39], v[164:167], v[196:199], v[36:39]
	v_mfma_f32_16x16x32_bf16 v[32:35], v[172:175], v[196:199], v[32:35]
	v_mfma_f32_16x16x32_bf16 v[20:23], v[164:167], v[204:207], v[20:23]
	v_mfma_f32_16x16x32_bf16 v[16:19], v[172:175], v[204:207], v[16:19]
	v_mfma_f32_16x16x32_bf16 v[4:7], v[164:167], v[216:219], v[4:7]
	v_mfma_f32_16x16x32_bf16 v[0:3], v[172:175], v[216:219], v[0:3]
	s_setprio 0
	s_barrier
	s_add_i32 s76, s76, 2
	s_add_u32 s30, s30, 0x100
	s_addc_u32 s31, s31, 0
	s_add_u32 s73, s73, 0x100
	s_addc_u32 s74, s74, 0
	s_cmp_gt_u32 s76, 13
	s_cbranch_scc0 .LBB0_439
	s_and_b64 vcc, exec, s[14:15]
	s_cbranch_vccz .LBB0_442
	s_barrier

.LBB0_488:
	ds_read_b128 v[146:149], v220
	ds_read_b128 v[150:153], v220 offset:1024
	ds_read_b128 v[154:157], v220 offset:2048
	ds_read_b128 v[158:161], v220 offset:3072
	ds_read_b128 v[162:165], v221
	ds_read_b128 v[166:169], v221 offset:1024
	ds_read_b128 v[170:173], v221 offset:2048
	ds_read_b128 v[174:177], v221 offset:3072
	s_add_u32 s68, s66, 0xfffc0080
	s_addc_u32 s69, s67, -1
	s_cmp_eq_u32 s97, 12
	s_cselect_b32 s71, s57, s69
	s_cselect_b32 s70, s63, s68
	s_cselect_b32 s69, s55, s96
	s_cselect_b32 s68, s65, s95
	v_lshl_add_u64 v[210:211], s[66:67], 0, v[138:139]
	s_add_i32 m0, s77, 0xc000
	ds_read_b128 v[178:181], v222
	ds_read_b128 v[182:185], v222 offset:1024
	ds_read_b128 v[186:189], v222 offset:2048
	ds_read_b128 v[190:193], v222 offset:3072
	ds_read_b128 v[194:197], v222 offset:4096
	ds_read_b128 v[198:201], v222 offset:5120
	ds_read_b128 v[202:205], v222 offset:6144
	ds_read_b128 v[206:209], v222 offset:7168
	global_load_lds_dwordx4 v[210:211], off
	v_lshl_add_u64 v[210:211], s[66:67], 0, v[140:141]
	s_add_i32 m0, s77, 0xe000
	s_nop 0
	global_load_lds_dwordx4 v[210:211], off
	s_waitcnt vmcnt(8)
	s_waitcnt lgkmcnt(0)
	s_barrier
	s_setprio 1
	s_waitcnt lgkmcnt(0)
	v_mfma_f32_16x16x32_bf16 v[124:127], v[146:149], v[178:181], v[124:127]
	v_mfma_f32_16x16x32_bf16 v[60:63], v[154:157], v[178:181], v[60:63]
	v_mfma_f32_16x16x32_bf16 v[116:119], v[146:149], v[186:189], v[116:119]
	v_mfma_f32_16x16x32_bf16 v[52:55], v[154:157], v[186:189], v[52:55]
	v_mfma_f32_16x16x32_bf16 v[112:115], v[146:149], v[194:197], v[112:115]
	v_mfma_f32_16x16x32_bf16 v[48:51], v[154:157], v[194:197], v[48:51]
	v_mfma_f32_16x16x32_bf16 v[108:111], v[146:149], v[202:205], v[108:111]
	v_mfma_f32_16x16x32_bf16 v[40:43], v[154:157], v[202:205], v[40:43]
	v_mfma_f32_16x16x32_bf16 v[124:127], v[150:153], v[182:185], v[124:127]
	v_mfma_f32_16x16x32_bf16 v[60:63], v[158:161], v[182:185], v[60:63]
	v_mfma_f32_16x16x32_bf16 v[116:119], v[150:153], v[190:193], v[116:119]
	v_mfma_f32_16x16x32_bf16 v[52:55], v[158:161], v[190:193], v[52:55]
	v_mfma_f32_16x16x32_bf16 v[112:115], v[150:153], v[198:201], v[112:115]
	v_mfma_f32_16x16x32_bf16 v[48:51], v[158:161], v[198:201], v[48:51]
	v_mfma_f32_16x16x32_bf16 v[108:111], v[150:153], v[206:209], v[108:111]
	v_mfma_f32_16x16x32_bf16 v[40:43], v[158:161], v[206:209], v[40:43]
	s_setprio 0
	s_setprio 1
	v_mfma_f32_16x16x32_bf16 v[120:123], v[162:165], v[178:181], v[120:123]
	v_mfma_f32_16x16x32_bf16 v[56:59], v[170:173], v[178:181], v[56:59]
	v_mfma_f32_16x16x32_bf16 v[104:107], v[162:165], v[186:189], v[104:107]
	v_mfma_f32_16x16x32_bf16 v[44:47], v[170:173], v[186:189], v[44:47]
	v_mfma_f32_16x16x32_bf16 v[100:103], v[162:165], v[194:197], v[100:103]
	v_mfma_f32_16x16x32_bf16 v[36:39], v[170:173], v[194:197], v[36:39]
	v_mfma_f32_16x16x32_bf16 v[96:99], v[162:165], v[202:205], v[96:99]
	v_mfma_f32_16x16x32_bf16 v[32:35], v[170:173], v[202:205], v[32:35]
	v_mfma_f32_16x16x32_bf16 v[120:123], v[166:169], v[182:185], v[120:123]
	v_mfma_f32_16x16x32_bf16 v[56:59], v[174:177], v[182:185], v[56:59]
	v_mfma_f32_16x16x32_bf16 v[104:107], v[166:169], v[190:193], v[104:107]
	v_mfma_f32_16x16x32_bf16 v[44:47], v[174:177], v[190:193], v[44:47]
	v_mfma_f32_16x16x32_bf16 v[100:103], v[166:169], v[198:201], v[100:103]
	v_mfma_f32_16x16x32_bf16 v[36:39], v[174:177], v[198:201], v[36:39]
	v_mfma_f32_16x16x32_bf16 v[96:99], v[166:169], v[206:209], v[96:99]
	v_mfma_f32_16x16x32_bf16 v[32:35], v[174:177], v[206:209], v[32:35]
	s_setprio 0
	s_barrier
	s_add_i32 s72, s91, s76
	v_lshl_add_u64 v[210:211], s[68:69], 0, v[128:129]
	s_mov_b32 m0, s72
	ds_read_b128 v[178:181], v222 offset:16384
	ds_read_b128 v[182:185], v222 offset:17408
	ds_read_b128 v[186:189], v222 offset:18432
	ds_read_b128 v[190:193], v222 offset:19456
	ds_read_b128 v[194:197], v222 offset:20480
	ds_read_b128 v[198:201], v222 offset:21504
	ds_read_b128 v[202:205], v222 offset:22528
	ds_read_b128 v[206:209], v222 offset:23552
	global_load_lds_dwordx4 v[210:211], off
	s_add_i32 m0, s72, 0x2000
	s_add_u32 vcc_lo, s68, 0x40000
	v_lshl_add_u64 v[212:213], s[68:69], 0, v[130:131]
	s_addc_u32 vcc_hi, s69, 0
	s_add_i32 s72, s92, s76
	global_load_lds_dwordx4 v[212:213], off
	v_lshl_add_u64 v[224:225], vcc, 0, v[128:129]
	s_mov_b32 m0, s72
	v_lshl_add_u64 v[226:227], s[70:71], 0, v[130:131]
	global_load_lds_dwordx4 v[224:225], off
	v_lshl_add_u64 v[224:225], vcc, 0, v[130:131]
	s_add_i32 m0, s72, 0x2000
	s_nop 0
	global_load_lds_dwordx4 v[224:225], off
	v_lshl_add_u64 v[224:225], s[70:71], 0, v[128:129]
	s_mov_b32 m0, s77
	s_nop 0
	global_load_lds_dwordx4 v[224:225], off
	s_mov_b32 m0, s78
	s_nop 0
	global_load_lds_dwordx4 v[226:227], off
	s_waitcnt vmcnt(8)
	s_waitcnt lgkmcnt(0)
	s_barrier
	s_setprio 1
	s_waitcnt lgkmcnt(0)
	v_mfma_f32_16x16x32_bf16 v[92:95], v[146:149], v[178:181], v[92:95]
	v_mfma_f32_16x16x32_bf16 v[28:31], v[154:157], v[178:181], v[28:31]
	v_mfma_f32_16x16x32_bf16 v[84:87], v[146:149], v[186:189], v[84:87]
	v_mfma_f32_16x16x32_bf16 v[20:23], v[154:157], v[186:189], v[20:23]
	v_mfma_f32_16x16x32_bf16 v[80:83], v[146:149], v[194:197], v[80:83]
	v_mfma_f32_16x16x32_bf16 v[16:19], v[154:157], v[194:197], v[16:19]
	v_mfma_f32_16x16x32_bf16 v[76:79], v[146:149], v[202:205], v[76:79]
	v_mfma_f32_16x16x32_bf16 v[8:11], v[154:157], v[202:205], v[8:11]
	v_mfma_f32_16x16x32_bf16 v[92:95], v[150:153], v[182:185], v[92:95]
	v_mfma_f32_16x16x32_bf16 v[28:31], v[158:161], v[182:185], v[28:31]
	v_mfma_f32_16x16x32_bf16 v[84:87], v[150:153], v[190:193], v[84:87]
	v_mfma_f32_16x16x32_bf16 v[20:23], v[158:161], v[190:193], v[20:23]
	v_mfma_f32_16x16x32_bf16 v[80:83], v[150:153], v[198:201], v[80:83]
	v_mfma_f32_16x16x32_bf16 v[16:19], v[158:161], v[198:201], v[16:19]
	v_mfma_f32_16x16x32_bf16 v[76:79], v[150:153], v[206:209], v[76:79]
	v_mfma_f32_16x16x32_bf16 v[8:11], v[158:161], v[206:209], v[8:11]
	s_setprio 0
	s_setprio 1
	v_mfma_f32_16x16x32_bf16 v[88:91], v[162:165], v[178:181], v[88:91]
	v_mfma_f32_16x16x32_bf16 v[24:27], v[170:173], v[178:181], v[24:27]
	v_mfma_f32_16x16x32_bf16 v[72:75], v[162:165], v[186:189], v[72:75]
	v_mfma_f32_16x16x32_bf16 v[12:15], v[170:173], v[186:189], v[12:15]
	v_mfma_f32_16x16x32_bf16 v[68:71], v[162:165], v[194:197], v[68:71]
	v_mfma_f32_16x16x32_bf16 v[4:7], v[170:173], v[194:197], v[4:7]
	v_mfma_f32_16x16x32_bf16 v[64:67], v[162:165], v[202:205], v[64:67]
	v_mfma_f32_16x16x32_bf16 v[0:3], v[170:173], v[202:205], v[0:3]
	v_mfma_f32_16x16x32_bf16 v[88:91], v[166:169], v[182:185], v[88:91]
	v_mfma_f32_16x16x32_bf16 v[24:27], v[174:177], v[182:185], v[24:27]
	v_mfma_f32_16x16x32_bf16 v[72:75], v[166:169], v[190:193], v[72:75]
	v_mfma_f32_16x16x32_bf16 v[12:15], v[174:177], v[190:193], v[12:15]
	v_mfma_f32_16x16x32_bf16 v[68:71], v[166:169], v[198:201], v[68:71]
	v_mfma_f32_16x16x32_bf16 v[4:7], v[174:177], v[198:201], v[4:7]
	v_mfma_f32_16x16x32_bf16 v[64:67], v[166:169], v[206:209], v[64:67]
	v_mfma_f32_16x16x32_bf16 v[0:3], v[174:177], v[206:209], v[0:3]
	s_setprio 0
	s_barrier
	s_add_i32 s72, 0, 0x18000
	s_add_i32 vcc_lo, 0, 0x1c000
	v_add_u32_e32 v158, s72, v216
	v_add_u32_e32 v174, vcc_lo, v216
	ds_read_b128 v[146:149], v158
	ds_read_b128 v[150:153], v158 offset:1024
	ds_read_b128 v[154:157], v158 offset:2048
	ds_read_b128 v[158:161], v158 offset:3072
	ds_read_b128 v[162:165], v174
	ds_read_b128 v[166:169], v174 offset:1024
	ds_read_b128 v[170:173], v174 offset:2048
	ds_read_b128 v[174:177], v174 offset:3072
	s_add_u32 s70, s70, 0x40000
	s_addc_u32 s71, s71, 0
	s_mov_b32 m0, s79
	v_lshl_add_u64 v[228:229], s[70:71], 0, v[128:129]
	ds_read_b128 v[178:181], v222 offset:32768
	ds_read_b128 v[182:185], v222 offset:33792
	ds_read_b128 v[186:189], v222 offset:34816
	ds_read_b128 v[190:193], v222 offset:35840
	ds_read_b128 v[194:197], v222 offset:36864
	ds_read_b128 v[198:201], v222 offset:37888
	ds_read_b128 v[202:205], v222 offset:38912
	ds_read_b128 v[206:209], v222 offset:39936
	global_load_lds_dwordx4 v[228:229], off
	v_lshl_add_u64 v[228:229], s[70:71], 0, v[130:131]
	s_mov_b32 m0, s80
	s_nop 0
	global_load_lds_dwordx4 v[228:229], off
	s_waitcnt vmcnt(8)
	s_waitcnt lgkmcnt(0)
	s_barrier
	s_setprio 1
	s_waitcnt lgkmcnt(0)
	v_mfma_f32_16x16x32_bf16 v[124:127], v[146:149], v[178:181], v[124:127]
	v_mfma_f32_16x16x32_bf16 v[60:63], v[154:157], v[178:181], v[60:63]
	v_mfma_f32_16x16x32_bf16 v[116:119], v[146:149], v[186:189], v[116:119]
	v_mfma_f32_16x16x32_bf16 v[52:55], v[154:157], v[186:189], v[52:55]
	v_mfma_f32_16x16x32_bf16 v[112:115], v[146:149], v[194:197], v[112:115]
	v_mfma_f32_16x16x32_bf16 v[48:51], v[154:157], v[194:197], v[48:51]
	v_mfma_f32_16x16x32_bf16 v[108:111], v[146:149], v[202:205], v[108:111]
	v_mfma_f32_16x16x32_bf16 v[40:43], v[154:157], v[202:205], v[40:43]
	v_mfma_f32_16x16x32_bf16 v[124:127], v[150:153], v[182:185], v[124:127]
	v_mfma_f32_16x16x32_bf16 v[60:63], v[158:161], v[182:185], v[60:63]
	v_mfma_f32_16x16x32_bf16 v[116:119], v[150:153], v[190:193], v[116:119]
	v_mfma_f32_16x16x32_bf16 v[52:55], v[158:161], v[190:193], v[52:55]
	v_mfma_f32_16x16x32_bf16 v[112:115], v[150:153], v[198:201], v[112:115]
	v_mfma_f32_16x16x32_bf16 v[48:51], v[158:161], v[198:201], v[48:51]
	v_mfma_f32_16x16x32_bf16 v[108:111], v[150:153], v[206:209], v[108:111]
	v_mfma_f32_16x16x32_bf16 v[40:43], v[158:161], v[206:209], v[40:43]
	s_setprio 0
	s_setprio 1
	v_mfma_f32_16x16x32_bf16 v[120:123], v[162:165], v[178:181], v[120:123]
	v_mfma_f32_16x16x32_bf16 v[56:59], v[170:173], v[178:181], v[56:59]
	v_mfma_f32_16x16x32_bf16 v[104:107], v[162:165], v[186:189], v[104:107]
	v_mfma_f32_16x16x32_bf16 v[44:47], v[170:173], v[186:189], v[44:47]
	v_mfma_f32_16x16x32_bf16 v[100:103], v[162:165], v[194:197], v[100:103]
	v_mfma_f32_16x16x32_bf16 v[36:39], v[170:173], v[194:197], v[36:39]
	v_mfma_f32_16x16x32_bf16 v[96:99], v[162:165], v[202:205], v[96:99]
	v_mfma_f32_16x16x32_bf16 v[32:35], v[170:173], v[202:205], v[32:35]
	v_mfma_f32_16x16x32_bf16 v[120:123], v[166:169], v[182:185], v[120:123]
	v_mfma_f32_16x16x32_bf16 v[56:59], v[174:177], v[182:185], v[56:59]
	v_mfma_f32_16x16x32_bf16 v[104:107], v[166:169], v[190:193], v[104:107]
	v_mfma_f32_16x16x32_bf16 v[44:47], v[174:177], v[190:193], v[44:47]
	v_mfma_f32_16x16x32_bf16 v[100:103], v[166:169], v[198:201], v[100:103]
	v_mfma_f32_16x16x32_bf16 v[36:39], v[174:177], v[198:201], v[36:39]
	v_mfma_f32_16x16x32_bf16 v[96:99], v[166:169], v[206:209], v[96:99]
	v_mfma_f32_16x16x32_bf16 v[32:35], v[174:177], v[206:209], v[32:35]
	s_setprio 0
	s_barrier
	s_add_i32 s70, s72, s76
	v_lshl_add_u64 v[210:211], v[210:211], 0, s[20:21]
	s_mov_b32 m0, s70
	ds_read_b128 v[178:181], v222 offset:49152
	ds_read_b128 v[182:185], v222 offset:50176
	ds_read_b128 v[186:189], v222 offset:51200
	ds_read_b128 v[190:193], v222 offset:52224
	ds_read_b128 v[194:197], v222 offset:53248
	ds_read_b128 v[198:201], v222 offset:54272
	ds_read_b128 v[202:205], v222 offset:55296
	ds_read_b128 v[206:209], v222 offset:56320
	global_load_lds_dwordx4 v[210:211], off
	s_add_i32 m0, s70, 0x2000
	s_add_u32 s68, s68, 0x40080
	v_lshl_add_u64 v[210:211], v[212:213], 0, s[20:21]
	s_addc_u32 s69, s69, 0
	s_add_i32 s70, vcc_lo, s76
	global_load_lds_dwordx4 v[210:211], off
	v_lshl_add_u64 v[210:211], s[68:69], 0, v[128:129]
	s_mov_b32 m0, s70
	s_nop 0
	global_load_lds_dwordx4 v[210:211], off
	v_lshl_add_u64 v[210:211], s[68:69], 0, v[130:131]
	s_add_i32 m0, s70, 0x2000
	s_nop 0
	global_load_lds_dwordx4 v[210:211], off
	v_lshl_add_u64 v[210:211], v[224:225], 0, s[20:21]
	s_mov_b32 m0, s88
	s_nop 0
	global_load_lds_dwordx4 v[210:211], off
	v_lshl_add_u64 v[210:211], v[226:227], 0, s[20:21]
	s_mov_b32 m0, s89
	s_nop 0
	global_load_lds_dwordx4 v[210:211], off
	s_waitcnt vmcnt(8)
	s_waitcnt lgkmcnt(0)
	s_barrier
	s_setprio 1
	s_waitcnt lgkmcnt(0)
	v_mfma_f32_16x16x32_bf16 v[92:95], v[146:149], v[178:181], v[92:95]
	v_mfma_f32_16x16x32_bf16 v[28:31], v[154:157], v[178:181], v[28:31]
	v_mfma_f32_16x16x32_bf16 v[84:87], v[146:149], v[186:189], v[84:87]
	v_mfma_f32_16x16x32_bf16 v[20:23], v[154:157], v[186:189], v[20:23]
	v_mfma_f32_16x16x32_bf16 v[80:83], v[146:149], v[194:197], v[80:83]
	v_mfma_f32_16x16x32_bf16 v[16:19], v[154:157], v[194:197], v[16:19]
	v_mfma_f32_16x16x32_bf16 v[76:79], v[146:149], v[202:205], v[76:79]
	v_mfma_f32_16x16x32_bf16 v[8:11], v[154:157], v[202:205], v[8:11]
	v_mfma_f32_16x16x32_bf16 v[92:95], v[150:153], v[182:185], v[92:95]
	v_mfma_f32_16x16x32_bf16 v[28:31], v[158:161], v[182:185], v[28:31]
	v_mfma_f32_16x16x32_bf16 v[84:87], v[150:153], v[190:193], v[84:87]
	v_mfma_f32_16x16x32_bf16 v[20:23], v[158:161], v[190:193], v[20:23]
	v_mfma_f32_16x16x32_bf16 v[80:83], v[150:153], v[198:201], v[80:83]
	v_mfma_f32_16x16x32_bf16 v[16:19], v[158:161], v[198:201], v[16:19]
	v_mfma_f32_16x16x32_bf16 v[76:79], v[150:153], v[206:209], v[76:79]
	v_mfma_f32_16x16x32_bf16 v[8:11], v[158:161], v[206:209], v[8:11]
	s_setprio 0
	s_setprio 1
	v_mfma_f32_16x16x32_bf16 v[88:91], v[162:165], v[178:181], v[88:91]
	v_mfma_f32_16x16x32_bf16 v[24:27], v[170:173], v[178:181], v[24:27]
	v_mfma_f32_16x16x32_bf16 v[72:75], v[162:165], v[186:189], v[72:75]
	v_mfma_f32_16x16x32_bf16 v[12:15], v[170:173], v[186:189], v[12:15]
	v_mfma_f32_16x16x32_bf16 v[68:71], v[162:165], v[194:197], v[68:71]
	v_mfma_f32_16x16x32_bf16 v[4:7], v[170:173], v[194:197], v[4:7]
	v_mfma_f32_16x16x32_bf16 v[64:67], v[162:165], v[202:205], v[64:67]
	v_mfma_f32_16x16x32_bf16 v[0:3], v[170:173], v[202:205], v[0:3]
	v_mfma_f32_16x16x32_bf16 v[88:91], v[166:169], v[182:185], v[88:91]
	v_mfma_f32_16x16x32_bf16 v[24:27], v[174:177], v[182:185], v[24:27]
	v_mfma_f32_16x16x32_bf16 v[72:75], v[166:169], v[190:193], v[72:75]
	v_mfma_f32_16x16x32_bf16 v[12:15], v[174:177], v[190:193], v[12:15]
	v_mfma_f32_16x16x32_bf16 v[68:71], v[166:169], v[198:201], v[68:71]
	v_mfma_f32_16x16x32_bf16 v[4:7], v[174:177], v[198:201], v[4:7]
	v_mfma_f32_16x16x32_bf16 v[64:67], v[166:169], v[206:209], v[64:67]
	v_mfma_f32_16x16x32_bf16 v[0:3], v[174:177], v[206:209], v[0:3]
	s_setprio 0
	s_barrier
	s_add_i32 s97, s97, 2
	s_add_u32 s66, s66, 0x100
	s_addc_u32 s67, s67, 0
	s_add_u32 s95, s95, 0x100
	s_addc_u32 s96, s96, 0
	s_cmp_gt_u32 s97, 13
	s_cbranch_scc0 .LBB0_488
	s_and_b64 vcc, exec, s[22:23]
	s_cbranch_vccz .LBB0_491
	s_barrier

.LBB0_567:
	ds_read_b128 v[144:147], v138
	ds_read_b128 v[148:151], v138 offset:1024
	ds_read_b128 v[152:155], v138 offset:2048
	ds_read_b128 v[160:163], v138 offset:3072
	ds_read_b128 v[164:167], v139
	ds_read_b128 v[168:171], v139 offset:1024
	ds_read_b128 v[172:175], v139 offset:2048
	ds_read_b128 v[176:179], v139 offset:3072
	s_or_b32 s26, s30, 1
	s_lshl_b64 s[90:91], s[26:27], 7
	s_add_i32 s26, s30, 2
	s_lshl_b64 s[52:53], s[26:27], 7
	s_cmp_lg_u32 s30, s78
	s_cselect_b32 s30, s52, 0
	s_cselect_b32 s31, s53, 0
	s_add_u32 s52, s24, s30
	s_addc_u32 s53, s25, s31
	s_add_u32 s30, s22, s30
	s_addc_u32 s31, s23, s31
	s_add_u32 s90, s24, s90
	s_addc_u32 s91, s25, s91
	s_add_u32 s90, s90, 0xb0000
	s_addc_u32 s91, s91, 0
	s_mov_b32 m0, s79
	v_lshl_add_u64 v[156:157], s[90:91], 0, v[128:129]
	ds_read_b128 v[180:183], v140
	ds_read_b128 v[184:187], v140 offset:1024
	ds_read_b128 v[188:191], v140 offset:2048
	ds_read_b128 v[192:195], v140 offset:3072
	ds_read_b128 v[196:199], v140 offset:4096
	ds_read_b128 v[200:203], v140 offset:5120
	ds_read_b128 v[204:207], v140 offset:6144
	ds_read_b128 v[208:211], v140 offset:7168
	global_load_lds_dwordx4 v[156:157], off
	v_lshl_add_u64 v[156:157], s[90:91], 0, v[132:133]
	s_mov_b32 m0, s72
	s_nop 0
	global_load_lds_dwordx4 v[156:157], off
	s_waitcnt vmcnt(8)
	s_waitcnt lgkmcnt(0)
	s_barrier
	s_setprio 1
	s_waitcnt lgkmcnt(0)
	v_mfma_f32_16x16x32_bf16 v[124:127], v[144:147], v[180:183], v[124:127]
	v_mfma_f32_16x16x32_bf16 v[120:123], v[152:155], v[180:183], v[120:123]
	v_mfma_f32_16x16x32_bf16 v[116:119], v[144:147], v[188:191], v[116:119]
	v_mfma_f32_16x16x32_bf16 v[112:115], v[152:155], v[188:191], v[112:115]
	v_mfma_f32_16x16x32_bf16 v[108:111], v[144:147], v[196:199], v[108:111]
	v_mfma_f32_16x16x32_bf16 v[104:107], v[152:155], v[196:199], v[104:107]
	v_mfma_f32_16x16x32_bf16 v[100:103], v[144:147], v[204:207], v[100:103]
	v_mfma_f32_16x16x32_bf16 v[96:99], v[152:155], v[204:207], v[96:99]
	v_mfma_f32_16x16x32_bf16 v[124:127], v[148:151], v[184:187], v[124:127]
	v_mfma_f32_16x16x32_bf16 v[120:123], v[160:163], v[184:187], v[120:123]
	v_mfma_f32_16x16x32_bf16 v[116:119], v[148:151], v[192:195], v[116:119]
	v_mfma_f32_16x16x32_bf16 v[112:115], v[160:163], v[192:195], v[112:115]
	v_mfma_f32_16x16x32_bf16 v[108:111], v[148:151], v[200:203], v[108:111]
	v_mfma_f32_16x16x32_bf16 v[104:107], v[160:163], v[200:203], v[104:107]
	v_mfma_f32_16x16x32_bf16 v[100:103], v[148:151], v[208:211], v[100:103]
	v_mfma_f32_16x16x32_bf16 v[96:99], v[160:163], v[208:211], v[96:99]
	s_setprio 0
	s_setprio 1
	v_mfma_f32_16x16x32_bf16 v[92:95], v[164:167], v[180:183], v[92:95]
	v_mfma_f32_16x16x32_bf16 v[88:91], v[172:175], v[180:183], v[88:91]
	v_mfma_f32_16x16x32_bf16 v[84:87], v[164:167], v[188:191], v[84:87]
	v_mfma_f32_16x16x32_bf16 v[80:83], v[172:175], v[188:191], v[80:83]
	v_mfma_f32_16x16x32_bf16 v[76:79], v[164:167], v[196:199], v[76:79]
	v_mfma_f32_16x16x32_bf16 v[72:75], v[172:175], v[196:199], v[72:75]
	v_mfma_f32_16x16x32_bf16 v[68:71], v[164:167], v[204:207], v[68:71]
	v_mfma_f32_16x16x32_bf16 v[64:67], v[172:175], v[204:207], v[64:67]
	v_mfma_f32_16x16x32_bf16 v[92:95], v[168:171], v[184:187], v[92:95]
	v_mfma_f32_16x16x32_bf16 v[88:91], v[176:179], v[184:187], v[88:91]
	v_mfma_f32_16x16x32_bf16 v[84:87], v[168:171], v[192:195], v[84:87]
	v_mfma_f32_16x16x32_bf16 v[80:83], v[176:179], v[192:195], v[80:83]
	v_mfma_f32_16x16x32_bf16 v[76:79], v[168:171], v[200:203], v[76:79]
	v_mfma_f32_16x16x32_bf16 v[72:75], v[176:179], v[200:203], v[72:75]
	v_mfma_f32_16x16x32_bf16 v[68:71], v[168:171], v[208:211], v[68:71]
	v_mfma_f32_16x16x32_bf16 v[64:67], v[176:179], v[208:211], v[64:67]
	s_setprio 0
	s_barrier
	s_mov_b32 m0, s80
	v_lshl_add_u64 v[156:157], s[30:31], 0, v[130:131]
	s_add_u32 s90, s30, 0xb0000
	ds_read_b128 v[180:183], v140 offset:16384
	ds_read_b128 v[184:187], v140 offset:17408
	ds_read_b128 v[188:191], v140 offset:18432
	ds_read_b128 v[192:195], v140 offset:19456
	ds_read_b128 v[196:199], v140 offset:20480
	ds_read_b128 v[200:203], v140 offset:21504
	ds_read_b128 v[204:207], v140 offset:22528
	ds_read_b128 v[208:211], v140 offset:23552
	global_load_lds_dwordx4 v[156:157], off
	v_lshl_add_u64 v[212:213], s[30:31], 0, v[134:135]
	s_mov_b32 m0, s81
	s_addc_u32 s91, s31, 0
	global_load_lds_dwordx4 v[212:213], off
	v_lshl_add_u64 v[216:217], s[90:91], 0, v[130:131]
	s_mov_b32 m0, s82
	v_lshl_add_u64 v[218:219], s[52:53], 0, v[132:133]
	global_load_lds_dwordx4 v[216:217], off
	v_lshl_add_u64 v[216:217], s[90:91], 0, v[134:135]
	s_mov_b32 m0, s83
	s_nop 0
	global_load_lds_dwordx4 v[216:217], off
	v_lshl_add_u64 v[216:217], s[52:53], 0, v[128:129]
	s_mov_b32 m0, s68
	s_nop 0
	global_load_lds_dwordx4 v[216:217], off
	s_mov_b32 m0, s69
	s_nop 0
	global_load_lds_dwordx4 v[218:219], off
	s_waitcnt vmcnt(8)
	s_waitcnt lgkmcnt(0)
	s_barrier
	s_setprio 1
	s_waitcnt lgkmcnt(0)
	v_mfma_f32_16x16x32_bf16 v[60:63], v[144:147], v[180:183], v[60:63]
	v_mfma_f32_16x16x32_bf16 v[56:59], v[152:155], v[180:183], v[56:59]
	v_mfma_f32_16x16x32_bf16 v[52:55], v[144:147], v[188:191], v[52:55]
	v_mfma_f32_16x16x32_bf16 v[48:51], v[152:155], v[188:191], v[48:51]
	v_mfma_f32_16x16x32_bf16 v[44:47], v[144:147], v[196:199], v[44:47]
	v_mfma_f32_16x16x32_bf16 v[40:43], v[152:155], v[196:199], v[40:43]
	v_mfma_f32_16x16x32_bf16 v[36:39], v[144:147], v[204:207], v[36:39]
	v_mfma_f32_16x16x32_bf16 v[32:35], v[152:155], v[204:207], v[32:35]
	v_mfma_f32_16x16x32_bf16 v[60:63], v[148:151], v[184:187], v[60:63]
	v_mfma_f32_16x16x32_bf16 v[56:59], v[160:163], v[184:187], v[56:59]
	v_mfma_f32_16x16x32_bf16 v[52:55], v[148:151], v[192:195], v[52:55]
	v_mfma_f32_16x16x32_bf16 v[48:51], v[160:163], v[192:195], v[48:51]
	v_mfma_f32_16x16x32_bf16 v[44:47], v[148:151], v[200:203], v[44:47]
	v_mfma_f32_16x16x32_bf16 v[40:43], v[160:163], v[200:203], v[40:43]
	v_mfma_f32_16x16x32_bf16 v[36:39], v[148:151], v[208:211], v[36:39]
	v_mfma_f32_16x16x32_bf16 v[32:35], v[160:163], v[208:211], v[32:35]
	s_setprio 0
	s_setprio 1
	v_mfma_f32_16x16x32_bf16 v[28:31], v[164:167], v[180:183], v[28:31]
	v_mfma_f32_16x16x32_bf16 v[24:27], v[172:175], v[180:183], v[24:27]
	v_mfma_f32_16x16x32_bf16 v[20:23], v[164:167], v[188:191], v[20:23]
	v_mfma_f32_16x16x32_bf16 v[16:19], v[172:175], v[188:191], v[16:19]
	v_mfma_f32_16x16x32_bf16 v[12:15], v[164:167], v[196:199], v[12:15]
	v_mfma_f32_16x16x32_bf16 v[8:11], v[172:175], v[196:199], v[8:11]
	v_mfma_f32_16x16x32_bf16 v[4:7], v[164:167], v[204:207], v[4:7]
	v_mfma_f32_16x16x32_bf16 v[0:3], v[172:175], v[204:207], v[0:3]
	v_mfma_f32_16x16x32_bf16 v[28:31], v[168:171], v[184:187], v[28:31]
	v_mfma_f32_16x16x32_bf16 v[24:27], v[176:179], v[184:187], v[24:27]
	v_mfma_f32_16x16x32_bf16 v[20:23], v[168:171], v[192:195], v[20:23]
	v_mfma_f32_16x16x32_bf16 v[16:19], v[176:179], v[192:195], v[16:19]
	v_mfma_f32_16x16x32_bf16 v[12:15], v[168:171], v[200:203], v[12:15]
	v_mfma_f32_16x16x32_bf16 v[8:11], v[176:179], v[200:203], v[8:11]
	v_mfma_f32_16x16x32_bf16 v[4:7], v[168:171], v[208:211], v[4:7]
	v_mfma_f32_16x16x32_bf16 v[0:3], v[176:179], v[208:211], v[0:3]
	s_setprio 0
	s_barrier
	ds_read_b128 v[144:147], v141
	ds_read_b128 v[148:151], v141 offset:1024
	ds_read_b128 v[152:155], v141 offset:2048
	ds_read_b128 v[160:163], v141 offset:3072
	ds_read_b128 v[164:167], v142
	ds_read_b128 v[168:171], v142 offset:1024
	ds_read_b128 v[172:175], v142 offset:2048
	ds_read_b128 v[176:179], v142 offset:3072
	s_add_u32 s52, s52, 0xb0000
	s_addc_u32 s53, s53, 0
	s_mov_b32 m0, s70
	v_lshl_add_u64 v[220:221], s[52:53], 0, v[128:129]
	ds_read_b128 v[180:183], v140 offset:32768
	ds_read_b128 v[184:187], v140 offset:33792
	ds_read_b128 v[188:191], v140 offset:34816
	ds_read_b128 v[192:195], v140 offset:35840
	ds_read_b128 v[196:199], v140 offset:36864
	ds_read_b128 v[200:203], v140 offset:37888
	ds_read_b128 v[204:207], v140 offset:38912
	ds_read_b128 v[208:211], v140 offset:39936
	global_load_lds_dwordx4 v[220:221], off
	v_lshl_add_u64 v[220:221], s[52:53], 0, v[132:133]
	s_mov_b32 m0, s71
	s_nop 0
	global_load_lds_dwordx4 v[220:221], off
	s_waitcnt vmcnt(8)
	s_waitcnt lgkmcnt(0)
	s_barrier
	s_setprio 1
	s_waitcnt lgkmcnt(0)
	v_mfma_f32_16x16x32_bf16 v[124:127], v[144:147], v[180:183], v[124:127]
	v_mfma_f32_16x16x32_bf16 v[120:123], v[152:155], v[180:183], v[120:123]
	v_mfma_f32_16x16x32_bf16 v[116:119], v[144:147], v[188:191], v[116:119]
	v_mfma_f32_16x16x32_bf16 v[112:115], v[152:155], v[188:191], v[112:115]
	v_mfma_f32_16x16x32_bf16 v[108:111], v[144:147], v[196:199], v[108:111]
	v_mfma_f32_16x16x32_bf16 v[104:107], v[152:155], v[196:199], v[104:107]
	v_mfma_f32_16x16x32_bf16 v[100:103], v[144:147], v[204:207], v[100:103]
	v_mfma_f32_16x16x32_bf16 v[96:99], v[152:155], v[204:207], v[96:99]
	v_mfma_f32_16x16x32_bf16 v[124:127], v[148:151], v[184:187], v[124:127]
	v_mfma_f32_16x16x32_bf16 v[120:123], v[160:163], v[184:187], v[120:123]
	v_mfma_f32_16x16x32_bf16 v[116:119], v[148:151], v[192:195], v[116:119]
	v_mfma_f32_16x16x32_bf16 v[112:115], v[160:163], v[192:195], v[112:115]
	v_mfma_f32_16x16x32_bf16 v[108:111], v[148:151], v[200:203], v[108:111]
	v_mfma_f32_16x16x32_bf16 v[104:107], v[160:163], v[200:203], v[104:107]
	v_mfma_f32_16x16x32_bf16 v[100:103], v[148:151], v[208:211], v[100:103]
	v_mfma_f32_16x16x32_bf16 v[96:99], v[160:163], v[208:211], v[96:99]
	s_setprio 0
	s_setprio 1
	v_mfma_f32_16x16x32_bf16 v[92:95], v[164:167], v[180:183], v[92:95]
	v_mfma_f32_16x16x32_bf16 v[88:91], v[172:175], v[180:183], v[88:91]
	v_mfma_f32_16x16x32_bf16 v[84:87], v[164:167], v[188:191], v[84:87]
	v_mfma_f32_16x16x32_bf16 v[80:83], v[172:175], v[188:191], v[80:83]
	v_mfma_f32_16x16x32_bf16 v[76:79], v[164:167], v[196:199], v[76:79]
	v_mfma_f32_16x16x32_bf16 v[72:75], v[172:175], v[196:199], v[72:75]
	v_mfma_f32_16x16x32_bf16 v[68:71], v[164:167], v[204:207], v[68:71]
	v_mfma_f32_16x16x32_bf16 v[64:67], v[172:175], v[204:207], v[64:67]
	v_mfma_f32_16x16x32_bf16 v[92:95], v[168:171], v[184:187], v[92:95]
	v_mfma_f32_16x16x32_bf16 v[88:91], v[176:179], v[184:187], v[88:91]
	v_mfma_f32_16x16x32_bf16 v[84:87], v[168:171], v[192:195], v[84:87]
	v_mfma_f32_16x16x32_bf16 v[80:83], v[176:179], v[192:195], v[80:83]
	v_mfma_f32_16x16x32_bf16 v[76:79], v[168:171], v[200:203], v[76:79]
	v_mfma_f32_16x16x32_bf16 v[72:75], v[176:179], v[200:203], v[72:75]
	v_mfma_f32_16x16x32_bf16 v[68:71], v[168:171], v[208:211], v[68:71]
	v_mfma_f32_16x16x32_bf16 v[64:67], v[176:179], v[208:211], v[64:67]
	s_setprio 0
	s_barrier
	s_mov_b32 m0, s86
	v_lshl_add_u64 v[156:157], v[156:157], 0, s[28:29]
	s_add_u32 s30, s30, 0xb0080
	ds_read_b128 v[180:183], v140 offset:49152
	ds_read_b128 v[184:187], v140 offset:50176
	ds_read_b128 v[188:191], v140 offset:51200
	ds_read_b128 v[192:195], v140 offset:52224
	ds_read_b128 v[196:199], v140 offset:53248
	ds_read_b128 v[200:203], v140 offset:54272
	ds_read_b128 v[204:207], v140 offset:55296
	ds_read_b128 v[208:211], v140 offset:56320
	global_load_lds_dwordx4 v[156:157], off
	v_lshl_add_u64 v[156:157], v[212:213], 0, s[28:29]
	s_mov_b32 m0, s87
	s_addc_u32 s31, s31, 0
	global_load_lds_dwordx4 v[156:157], off
	v_lshl_add_u64 v[156:157], s[30:31], 0, v[130:131]
	s_mov_b32 m0, s88
	s_nop 0
	global_load_lds_dwordx4 v[156:157], off
	v_lshl_add_u64 v[156:157], s[30:31], 0, v[134:135]
	s_mov_b32 m0, s89
	s_nop 0
	global_load_lds_dwordx4 v[156:157], off
	v_lshl_add_u64 v[156:157], v[216:217], 0, s[28:29]
	s_mov_b32 m0, s76
	s_nop 0
	global_load_lds_dwordx4 v[156:157], off
	v_lshl_add_u64 v[156:157], v[218:219], 0, s[28:29]
	s_mov_b32 m0, s77
	s_nop 0
	global_load_lds_dwordx4 v[156:157], off
	s_waitcnt vmcnt(8)
	s_waitcnt lgkmcnt(0)
	s_barrier
	s_setprio 1
	s_waitcnt lgkmcnt(0)
	v_mfma_f32_16x16x32_bf16 v[60:63], v[144:147], v[180:183], v[60:63]
	v_mfma_f32_16x16x32_bf16 v[56:59], v[152:155], v[180:183], v[56:59]
	v_mfma_f32_16x16x32_bf16 v[52:55], v[144:147], v[188:191], v[52:55]
	v_mfma_f32_16x16x32_bf16 v[48:51], v[152:155], v[188:191], v[48:51]
	v_mfma_f32_16x16x32_bf16 v[44:47], v[144:147], v[196:199], v[44:47]
	v_mfma_f32_16x16x32_bf16 v[40:43], v[152:155], v[196:199], v[40:43]
	v_mfma_f32_16x16x32_bf16 v[36:39], v[144:147], v[204:207], v[36:39]
	v_mfma_f32_16x16x32_bf16 v[32:35], v[152:155], v[204:207], v[32:35]
	v_mfma_f32_16x16x32_bf16 v[60:63], v[148:151], v[184:187], v[60:63]
	v_mfma_f32_16x16x32_bf16 v[56:59], v[160:163], v[184:187], v[56:59]
	v_mfma_f32_16x16x32_bf16 v[52:55], v[148:151], v[192:195], v[52:55]
	v_mfma_f32_16x16x32_bf16 v[48:51], v[160:163], v[192:195], v[48:51]
	v_mfma_f32_16x16x32_bf16 v[44:47], v[148:151], v[200:203], v[44:47]
	v_mfma_f32_16x16x32_bf16 v[40:43], v[160:163], v[200:203], v[40:43]
	v_mfma_f32_16x16x32_bf16 v[36:39], v[148:151], v[208:211], v[36:39]
	v_mfma_f32_16x16x32_bf16 v[32:35], v[160:163], v[208:211], v[32:35]
	s_setprio 0
	s_setprio 1
	v_mfma_f32_16x16x32_bf16 v[28:31], v[164:167], v[180:183], v[28:31]
	v_mfma_f32_16x16x32_bf16 v[24:27], v[172:175], v[180:183], v[24:27]
	v_mfma_f32_16x16x32_bf16 v[20:23], v[164:167], v[188:191], v[20:23]
	v_mfma_f32_16x16x32_bf16 v[16:19], v[172:175], v[188:191], v[16:19]
	v_mfma_f32_16x16x32_bf16 v[12:15], v[164:167], v[196:199], v[12:15]
	v_mfma_f32_16x16x32_bf16 v[8:11], v[172:175], v[196:199], v[8:11]
	v_mfma_f32_16x16x32_bf16 v[4:7], v[164:167], v[204:207], v[4:7]
	v_mfma_f32_16x16x32_bf16 v[0:3], v[172:175], v[204:207], v[0:3]
	v_mfma_f32_16x16x32_bf16 v[28:31], v[168:171], v[184:187], v[28:31]
	v_mfma_f32_16x16x32_bf16 v[24:27], v[176:179], v[184:187], v[24:27]
	v_mfma_f32_16x16x32_bf16 v[20:23], v[168:171], v[192:195], v[20:23]
	v_mfma_f32_16x16x32_bf16 v[16:19], v[176:179], v[192:195], v[16:19]
	v_mfma_f32_16x16x32_bf16 v[12:15], v[168:171], v[200:203], v[12:15]
	v_mfma_f32_16x16x32_bf16 v[8:11], v[176:179], v[200:203], v[8:11]
	v_mfma_f32_16x16x32_bf16 v[4:7], v[168:171], v[208:211], v[4:7]
	v_mfma_f32_16x16x32_bf16 v[0:3], v[176:179], v[208:211], v[0:3]
	s_setprio 0
	s_barrier
	s_cmp_ge_u32 s26, s74
	s_mov_b32 s30, s26
	s_cbranch_scc0 .LBB0_567
	s_cmpk_lt_u32 s67, 0x100
	s_cbranch_scc0 .LBB0_570
	s_barrier

.LBB0_581:
	ds_read_b128 v[148:151], v143
	ds_read_b128 v[152:155], v143 offset:1024
	ds_read_b128 v[162:165], v143 offset:2048
	ds_read_b128 v[166:169], v143 offset:3072
	ds_read_b128 v[170:173], v144
	ds_read_b128 v[174:177], v144 offset:1024
	ds_read_b128 v[178:181], v144 offset:2048
	ds_read_b128 v[182:185], v144 offset:3072
	s_add_u32 s30, s28, 0x100
	s_addc_u32 s31, s29, 0
	s_cmp_lg_u32 s67, 6
	s_cselect_b32 s52, s30, 0
	s_cselect_b32 s53, s31, 0
	s_add_u32 s54, s24, s52
	s_addc_u32 s55, s25, s53
	s_add_u32 s52, s22, s52
	s_addc_u32 s53, s23, s53
	s_mov_b32 m0, s68
	v_lshl_add_u64 v[156:157], v[136:137], 0, s[28:29]
	ds_read_b128 v[186:189], v145
	ds_read_b128 v[190:193], v145 offset:1024
	ds_read_b128 v[194:197], v145 offset:2048
	ds_read_b128 v[198:201], v145 offset:3072
	ds_read_b128 v[202:205], v145 offset:4096
	ds_read_b128 v[206:209], v145 offset:5120
	ds_read_b128 v[210:213], v145 offset:6144
	ds_read_b128 v[216:219], v145 offset:7168
	global_load_lds_dwordx4 v[156:157], off
	v_lshl_add_u64 v[156:157], v[138:139], 0, s[28:29]
	s_mov_b32 m0, s69
	s_nop 0
	global_load_lds_dwordx4 v[156:157], off
	s_waitcnt vmcnt(8)
	s_waitcnt lgkmcnt(0)
	s_barrier
	s_setprio 1
	s_waitcnt lgkmcnt(0)
	v_mfma_f32_16x16x32_bf16 v[124:127], v[148:151], v[186:189], v[124:127]
	v_mfma_f32_16x16x32_bf16 v[120:123], v[162:165], v[186:189], v[120:123]
	v_mfma_f32_16x16x32_bf16 v[108:111], v[148:151], v[194:197], v[108:111]
	v_mfma_f32_16x16x32_bf16 v[104:107], v[162:165], v[194:197], v[104:107]
	v_mfma_f32_16x16x32_bf16 v[92:95], v[148:151], v[202:205], v[92:95]
	v_mfma_f32_16x16x32_bf16 v[88:91], v[162:165], v[202:205], v[88:91]
	v_mfma_f32_16x16x32_bf16 v[76:79], v[148:151], v[210:213], v[76:79]
	v_mfma_f32_16x16x32_bf16 v[72:75], v[162:165], v[210:213], v[72:75]
	v_mfma_f32_16x16x32_bf16 v[124:127], v[152:155], v[190:193], v[124:127]
	v_mfma_f32_16x16x32_bf16 v[120:123], v[166:169], v[190:193], v[120:123]
	v_mfma_f32_16x16x32_bf16 v[108:111], v[152:155], v[198:201], v[108:111]
	v_mfma_f32_16x16x32_bf16 v[104:107], v[166:169], v[198:201], v[104:107]
	v_mfma_f32_16x16x32_bf16 v[92:95], v[152:155], v[206:209], v[92:95]
	v_mfma_f32_16x16x32_bf16 v[88:91], v[166:169], v[206:209], v[88:91]
	v_mfma_f32_16x16x32_bf16 v[76:79], v[152:155], v[216:219], v[76:79]
	v_mfma_f32_16x16x32_bf16 v[72:75], v[166:169], v[216:219], v[72:75]
	s_setprio 0
	s_setprio 1
	v_mfma_f32_16x16x32_bf16 v[116:119], v[170:173], v[186:189], v[116:119]
	v_mfma_f32_16x16x32_bf16 v[112:115], v[178:181], v[186:189], v[112:115]
	v_mfma_f32_16x16x32_bf16 v[100:103], v[170:173], v[194:197], v[100:103]
	v_mfma_f32_16x16x32_bf16 v[96:99], v[178:181], v[194:197], v[96:99]
	v_mfma_f32_16x16x32_bf16 v[84:87], v[170:173], v[202:205], v[84:87]
	v_mfma_f32_16x16x32_bf16 v[80:83], v[178:181], v[202:205], v[80:83]
	v_mfma_f32_16x16x32_bf16 v[68:71], v[170:173], v[210:213], v[68:71]
	v_mfma_f32_16x16x32_bf16 v[64:67], v[178:181], v[210:213], v[64:67]
	v_mfma_f32_16x16x32_bf16 v[116:119], v[174:177], v[190:193], v[116:119]
	v_mfma_f32_16x16x32_bf16 v[112:115], v[182:185], v[190:193], v[112:115]
	v_mfma_f32_16x16x32_bf16 v[100:103], v[174:177], v[198:201], v[100:103]
	v_mfma_f32_16x16x32_bf16 v[96:99], v[182:185], v[198:201], v[96:99]
	v_mfma_f32_16x16x32_bf16 v[84:87], v[174:177], v[206:209], v[84:87]
	v_mfma_f32_16x16x32_bf16 v[80:83], v[182:185], v[206:209], v[80:83]
	v_mfma_f32_16x16x32_bf16 v[68:71], v[174:177], v[216:219], v[68:71]
	v_mfma_f32_16x16x32_bf16 v[64:67], v[182:185], v[216:219], v[64:67]
	s_setprio 0
	s_barrier
	s_mov_b32 m0, s70
	v_lshl_add_u64 v[156:157], s[52:53], 0, v[130:131]
	s_add_u32 s28, s52, 0xb0000
	ds_read_b128 v[186:189], v145 offset:16384
	ds_read_b128 v[190:193], v145 offset:17408
	ds_read_b128 v[194:197], v145 offset:18432
	ds_read_b128 v[198:201], v145 offset:19456
	ds_read_b128 v[202:205], v145 offset:20480
	ds_read_b128 v[206:209], v145 offset:21504
	ds_read_b128 v[210:213], v145 offset:22528
	ds_read_b128 v[216:219], v145 offset:23552
	global_load_lds_dwordx4 v[156:157], off
	v_lshl_add_u64 v[220:221], s[52:53], 0, v[134:135]
	s_mov_b32 m0, s71
	s_addc_u32 s29, s53, 0
	global_load_lds_dwordx4 v[220:221], off
	v_lshl_add_u64 v[222:223], s[28:29], 0, v[130:131]
	s_mov_b32 m0, s72
	v_lshl_add_u64 v[224:225], s[54:55], 0, v[132:133]
	global_load_lds_dwordx4 v[222:223], off
	v_lshl_add_u64 v[222:223], s[28:29], 0, v[134:135]
	s_mov_b32 m0, s73
	s_nop 0
	global_load_lds_dwordx4 v[222:223], off
	v_lshl_add_u64 v[222:223], s[54:55], 0, v[128:129]
	s_mov_b32 m0, s63
	s_nop 0
	global_load_lds_dwordx4 v[222:223], off
	s_mov_b32 m0, s60
	s_nop 0
	global_load_lds_dwordx4 v[224:225], off
	s_waitcnt vmcnt(8)
	s_waitcnt lgkmcnt(0)
	s_barrier
	s_setprio 1
	s_waitcnt lgkmcnt(0)
	v_mfma_f32_16x16x32_bf16 v[60:63], v[148:151], v[186:189], v[60:63]
	v_mfma_f32_16x16x32_bf16 v[56:59], v[162:165], v[186:189], v[56:59]
	v_mfma_f32_16x16x32_bf16 v[44:47], v[148:151], v[194:197], v[44:47]
	v_mfma_f32_16x16x32_bf16 v[40:43], v[162:165], v[194:197], v[40:43]
	v_mfma_f32_16x16x32_bf16 v[28:31], v[148:151], v[202:205], v[28:31]
	v_mfma_f32_16x16x32_bf16 v[24:27], v[162:165], v[202:205], v[24:27]
	v_mfma_f32_16x16x32_bf16 v[12:15], v[148:151], v[210:213], v[12:15]
	v_mfma_f32_16x16x32_bf16 v[8:11], v[162:165], v[210:213], v[8:11]
	v_mfma_f32_16x16x32_bf16 v[60:63], v[152:155], v[190:193], v[60:63]
	v_mfma_f32_16x16x32_bf16 v[56:59], v[166:169], v[190:193], v[56:59]
	v_mfma_f32_16x16x32_bf16 v[44:47], v[152:155], v[198:201], v[44:47]
	v_mfma_f32_16x16x32_bf16 v[40:43], v[166:169], v[198:201], v[40:43]
	v_mfma_f32_16x16x32_bf16 v[28:31], v[152:155], v[206:209], v[28:31]
	v_mfma_f32_16x16x32_bf16 v[24:27], v[166:169], v[206:209], v[24:27]
	v_mfma_f32_16x16x32_bf16 v[12:15], v[152:155], v[216:219], v[12:15]
	v_mfma_f32_16x16x32_bf16 v[8:11], v[166:169], v[216:219], v[8:11]
	s_setprio 0
	s_setprio 1
	v_mfma_f32_16x16x32_bf16 v[52:55], v[170:173], v[186:189], v[52:55]
	v_mfma_f32_16x16x32_bf16 v[48:51], v[178:181], v[186:189], v[48:51]
	v_mfma_f32_16x16x32_bf16 v[36:39], v[170:173], v[194:197], v[36:39]
	v_mfma_f32_16x16x32_bf16 v[32:35], v[178:181], v[194:197], v[32:35]
	v_mfma_f32_16x16x32_bf16 v[20:23], v[170:173], v[202:205], v[20:23]
	v_mfma_f32_16x16x32_bf16 v[16:19], v[178:181], v[202:205], v[16:19]
	v_mfma_f32_16x16x32_bf16 v[4:7], v[170:173], v[210:213], v[4:7]
	v_mfma_f32_16x16x32_bf16 v[0:3], v[178:181], v[210:213], v[0:3]
	v_mfma_f32_16x16x32_bf16 v[52:55], v[174:177], v[190:193], v[52:55]
	v_mfma_f32_16x16x32_bf16 v[48:51], v[182:185], v[190:193], v[48:51]
	v_mfma_f32_16x16x32_bf16 v[36:39], v[174:177], v[198:201], v[36:39]
	v_mfma_f32_16x16x32_bf16 v[32:35], v[182:185], v[198:201], v[32:35]
	v_mfma_f32_16x16x32_bf16 v[20:23], v[174:177], v[206:209], v[20:23]
	v_mfma_f32_16x16x32_bf16 v[16:19], v[182:185], v[206:209], v[16:19]
	v_mfma_f32_16x16x32_bf16 v[4:7], v[174:177], v[216:219], v[4:7]
	v_mfma_f32_16x16x32_bf16 v[0:3], v[182:185], v[216:219], v[0:3]
	s_setprio 0
	s_barrier
	ds_read_b128 v[148:151], v146
	ds_read_b128 v[152:155], v146 offset:1024
	ds_read_b128 v[162:165], v146 offset:2048
	ds_read_b128 v[166:169], v146 offset:3072
	ds_read_b128 v[170:173], v147
	ds_read_b128 v[174:177], v147 offset:1024
	ds_read_b128 v[178:181], v147 offset:2048
	ds_read_b128 v[182:185], v147 offset:3072
	s_add_u32 s28, s54, 0xb0000
	s_addc_u32 s29, s55, 0
	s_mov_b32 m0, s61
	v_lshl_add_u64 v[226:227], s[28:29], 0, v[128:129]
	ds_read_b128 v[186:189], v145 offset:32768
	ds_read_b128 v[190:193], v145 offset:33792
	ds_read_b128 v[194:197], v145 offset:34816
	ds_read_b128 v[198:201], v145 offset:35840
	ds_read_b128 v[202:205], v145 offset:36864
	ds_read_b128 v[206:209], v145 offset:37888
	ds_read_b128 v[210:213], v145 offset:38912
	ds_read_b128 v[216:219], v145 offset:39936
	global_load_lds_dwordx4 v[226:227], off
	v_lshl_add_u64 v[226:227], s[28:29], 0, v[132:133]
	s_mov_b32 m0, s62
	s_nop 0
	global_load_lds_dwordx4 v[226:227], off
	s_waitcnt vmcnt(8)
	s_waitcnt lgkmcnt(0)
	s_barrier
	s_setprio 1
	s_waitcnt lgkmcnt(0)
	v_mfma_f32_16x16x32_bf16 v[124:127], v[148:151], v[186:189], v[124:127]
	v_mfma_f32_16x16x32_bf16 v[120:123], v[162:165], v[186:189], v[120:123]
	v_mfma_f32_16x16x32_bf16 v[108:111], v[148:151], v[194:197], v[108:111]
	v_mfma_f32_16x16x32_bf16 v[104:107], v[162:165], v[194:197], v[104:107]
	v_mfma_f32_16x16x32_bf16 v[92:95], v[148:151], v[202:205], v[92:95]
	v_mfma_f32_16x16x32_bf16 v[88:91], v[162:165], v[202:205], v[88:91]
	v_mfma_f32_16x16x32_bf16 v[76:79], v[148:151], v[210:213], v[76:79]
	v_mfma_f32_16x16x32_bf16 v[72:75], v[162:165], v[210:213], v[72:75]
	v_mfma_f32_16x16x32_bf16 v[124:127], v[152:155], v[190:193], v[124:127]
	v_mfma_f32_16x16x32_bf16 v[120:123], v[166:169], v[190:193], v[120:123]
	v_mfma_f32_16x16x32_bf16 v[108:111], v[152:155], v[198:201], v[108:111]
	v_mfma_f32_16x16x32_bf16 v[104:107], v[166:169], v[198:201], v[104:107]
	v_mfma_f32_16x16x32_bf16 v[92:95], v[152:155], v[206:209], v[92:95]
	v_mfma_f32_16x16x32_bf16 v[88:91], v[166:169], v[206:209], v[88:91]
	v_mfma_f32_16x16x32_bf16 v[76:79], v[152:155], v[216:219], v[76:79]
	v_mfma_f32_16x16x32_bf16 v[72:75], v[166:169], v[216:219], v[72:75]
	s_setprio 0
	s_setprio 1
	v_mfma_f32_16x16x32_bf16 v[116:119], v[170:173], v[186:189], v[116:119]
	v_mfma_f32_16x16x32_bf16 v[112:115], v[178:181], v[186:189], v[112:115]
	v_mfma_f32_16x16x32_bf16 v[100:103], v[170:173], v[194:197], v[100:103]
	v_mfma_f32_16x16x32_bf16 v[96:99], v[178:181], v[194:197], v[96:99]
	v_mfma_f32_16x16x32_bf16 v[84:87], v[170:173], v[202:205], v[84:87]
	v_mfma_f32_16x16x32_bf16 v[80:83], v[178:181], v[202:205], v[80:83]
	v_mfma_f32_16x16x32_bf16 v[68:71], v[170:173], v[210:213], v[68:71]
	v_mfma_f32_16x16x32_bf16 v[64:67], v[178:181], v[210:213], v[64:67]
	v_mfma_f32_16x16x32_bf16 v[116:119], v[174:177], v[190:193], v[116:119]
	v_mfma_f32_16x16x32_bf16 v[112:115], v[182:185], v[190:193], v[112:115]
	v_mfma_f32_16x16x32_bf16 v[100:103], v[174:177], v[198:201], v[100:103]
	v_mfma_f32_16x16x32_bf16 v[96:99], v[182:185], v[198:201], v[96:99]
	v_mfma_f32_16x16x32_bf16 v[84:87], v[174:177], v[206:209], v[84:87]
	v_mfma_f32_16x16x32_bf16 v[80:83], v[182:185], v[206:209], v[80:83]
	v_mfma_f32_16x16x32_bf16 v[68:71], v[174:177], v[216:219], v[68:71]
	v_mfma_f32_16x16x32_bf16 v[64:67], v[182:185], v[216:219], v[64:67]
	s_setprio 0
	s_barrier
	s_mov_b32 m0, s74
	v_lshl_add_u64 v[156:157], v[156:157], 0, s[26:27]
	s_add_u32 s28, s52, 0xb0080
	ds_read_b128 v[186:189], v145 offset:49152
	ds_read_b128 v[190:193], v145 offset:50176
	ds_read_b128 v[194:197], v145 offset:51200
	ds_read_b128 v[198:201], v145 offset:52224
	ds_read_b128 v[202:205], v145 offset:53248
	ds_read_b128 v[206:209], v145 offset:54272
	ds_read_b128 v[210:213], v145 offset:55296
	ds_read_b128 v[216:219], v145 offset:56320
	global_load_lds_dwordx4 v[156:157], off
	v_lshl_add_u64 v[156:157], v[220:221], 0, s[26:27]
	s_mov_b32 m0, s76
	s_addc_u32 s29, s53, 0
	global_load_lds_dwordx4 v[156:157], off
	v_lshl_add_u64 v[156:157], s[28:29], 0, v[130:131]
	s_mov_b32 m0, s77
	s_nop 0
	global_load_lds_dwordx4 v[156:157], off
	v_lshl_add_u64 v[156:157], s[28:29], 0, v[134:135]
	s_mov_b32 m0, s78
	s_nop 0
	global_load_lds_dwordx4 v[156:157], off
	v_lshl_add_u64 v[156:157], v[222:223], 0, s[26:27]
	s_mov_b32 m0, s64
	s_nop 0
	global_load_lds_dwordx4 v[156:157], off
	v_lshl_add_u64 v[156:157], v[224:225], 0, s[26:27]
	s_mov_b32 m0, s65
	s_nop 0
	global_load_lds_dwordx4 v[156:157], off
	s_waitcnt vmcnt(8)
	s_waitcnt lgkmcnt(0)
	s_barrier
	s_setprio 1
	s_waitcnt lgkmcnt(0)
	v_mfma_f32_16x16x32_bf16 v[60:63], v[148:151], v[186:189], v[60:63]
	v_mfma_f32_16x16x32_bf16 v[56:59], v[162:165], v[186:189], v[56:59]
	v_mfma_f32_16x16x32_bf16 v[44:47], v[148:151], v[194:197], v[44:47]
	v_mfma_f32_16x16x32_bf16 v[40:43], v[162:165], v[194:197], v[40:43]
	v_mfma_f32_16x16x32_bf16 v[28:31], v[148:151], v[202:205], v[28:31]
	v_mfma_f32_16x16x32_bf16 v[24:27], v[162:165], v[202:205], v[24:27]
	v_mfma_f32_16x16x32_bf16 v[12:15], v[148:151], v[210:213], v[12:15]
	v_mfma_f32_16x16x32_bf16 v[8:11], v[162:165], v[210:213], v[8:11]
	v_mfma_f32_16x16x32_bf16 v[60:63], v[152:155], v[190:193], v[60:63]
	v_mfma_f32_16x16x32_bf16 v[56:59], v[166:169], v[190:193], v[56:59]
	v_mfma_f32_16x16x32_bf16 v[44:47], v[152:155], v[198:201], v[44:47]
	v_mfma_f32_16x16x32_bf16 v[40:43], v[166:169], v[198:201], v[40:43]
	v_mfma_f32_16x16x32_bf16 v[28:31], v[152:155], v[206:209], v[28:31]
	v_mfma_f32_16x16x32_bf16 v[24:27], v[166:169], v[206:209], v[24:27]
	v_mfma_f32_16x16x32_bf16 v[12:15], v[152:155], v[216:219], v[12:15]
	v_mfma_f32_16x16x32_bf16 v[8:11], v[166:169], v[216:219], v[8:11]
	s_setprio 0
	s_setprio 1
	v_mfma_f32_16x16x32_bf16 v[52:55], v[170:173], v[186:189], v[52:55]
	v_mfma_f32_16x16x32_bf16 v[48:51], v[178:181], v[186:189], v[48:51]
	v_mfma_f32_16x16x32_bf16 v[36:39], v[170:173], v[194:197], v[36:39]
	v_mfma_f32_16x16x32_bf16 v[32:35], v[178:181], v[194:197], v[32:35]
	v_mfma_f32_16x16x32_bf16 v[20:23], v[170:173], v[202:205], v[20:23]
	v_mfma_f32_16x16x32_bf16 v[16:19], v[178:181], v[202:205], v[16:19]
	v_mfma_f32_16x16x32_bf16 v[4:7], v[170:173], v[210:213], v[4:7]
	v_mfma_f32_16x16x32_bf16 v[0:3], v[178:181], v[210:213], v[0:3]
	v_mfma_f32_16x16x32_bf16 v[52:55], v[174:177], v[190:193], v[52:55]
	v_mfma_f32_16x16x32_bf16 v[48:51], v[182:185], v[190:193], v[48:51]
	v_mfma_f32_16x16x32_bf16 v[36:39], v[174:177], v[198:201], v[36:39]
	v_mfma_f32_16x16x32_bf16 v[32:35], v[182:185], v[198:201], v[32:35]
	v_mfma_f32_16x16x32_bf16 v[20:23], v[174:177], v[206:209], v[20:23]
	v_mfma_f32_16x16x32_bf16 v[16:19], v[182:185], v[206:209], v[16:19]
	v_mfma_f32_16x16x32_bf16 v[4:7], v[174:177], v[216:219], v[4:7]
	v_mfma_f32_16x16x32_bf16 v[0:3], v[182:185], v[216:219], v[0:3]
	s_setprio 0
	s_barrier
	s_add_i32 s67, s67, 2
	s_cmp_gt_u32 s67, 7
	s_mov_b64 s[28:29], s[30:31]
	s_cbranch_scc0 .LBB0_581
	s_cmpk_lt_u32 s66, 0x100
	s_cbranch_scc0 .LBB0_584
	s_barrier

.LBB0_658:
	ds_read_b128 v[128:131], v177
	ds_read_b128 v[132:135], v177 offset:1024
	ds_read_b128 v[136:139], v177 offset:2048
	ds_read_b128 v[140:143], v177 offset:3072
	ds_read_b128 v[158:161], v178
	ds_read_b128 v[162:165], v178 offset:1024
	ds_read_b128 v[166:169], v178 offset:2048
	ds_read_b128 v[180:183], v178 offset:3072
	s_add_u32 s26, s24, 0x100
	s_addc_u32 s27, s25, 0
	s_cmp_eq_u32 s72, 40
	s_cselect_b32 s31, s7, s27
	s_cselect_b32 s30, s6, s26
	s_cselect_b32 s29, s23, s74
	s_cselect_b32 s28, s22, s12
	v_lshl_add_u64 v[170:171], s[24:25], 0, v[152:153]
	s_add_i32 m0, s57, 0xc000
	ds_read_b128 v[184:187], v179
	ds_read_b128 v[188:191], v179 offset:1024
	ds_read_b128 v[192:195], v179 offset:2048
	ds_read_b128 v[196:199], v179 offset:3072
	ds_read_b128 v[200:203], v179 offset:4096
	ds_read_b128 v[204:207], v179 offset:5120
	ds_read_b128 v[208:211], v179 offset:6144
	ds_read_b128 v[216:219], v179 offset:7168
	global_load_lds_dwordx4 v[170:171], off
	v_lshl_add_u64 v[170:171], s[24:25], 0, v[154:155]
	s_add_i32 m0, s57, 0xe000
	s_nop 0
	global_load_lds_dwordx4 v[170:171], off
	s_waitcnt vmcnt(8)
	s_waitcnt lgkmcnt(0)
	s_barrier
	s_setprio 1
	s_waitcnt lgkmcnt(0)
	v_mfma_f32_16x16x32_bf16 v[124:127], v[128:131], v[184:187], v[124:127]
	v_mfma_f32_16x16x32_bf16 v[120:123], v[136:139], v[184:187], v[120:123]
	v_mfma_f32_16x16x32_bf16 v[108:111], v[128:131], v[192:195], v[108:111]
	v_mfma_f32_16x16x32_bf16 v[104:107], v[136:139], v[192:195], v[104:107]
	v_mfma_f32_16x16x32_bf16 v[92:95], v[128:131], v[200:203], v[92:95]
	v_mfma_f32_16x16x32_bf16 v[88:91], v[136:139], v[200:203], v[88:91]
	v_mfma_f32_16x16x32_bf16 v[76:79], v[128:131], v[208:211], v[76:79]
	v_mfma_f32_16x16x32_bf16 v[72:75], v[136:139], v[208:211], v[72:75]
	v_mfma_f32_16x16x32_bf16 v[124:127], v[132:135], v[188:191], v[124:127]
	v_mfma_f32_16x16x32_bf16 v[120:123], v[140:143], v[188:191], v[120:123]
	v_mfma_f32_16x16x32_bf16 v[108:111], v[132:135], v[196:199], v[108:111]
	v_mfma_f32_16x16x32_bf16 v[104:107], v[140:143], v[196:199], v[104:107]
	v_mfma_f32_16x16x32_bf16 v[92:95], v[132:135], v[204:207], v[92:95]
	v_mfma_f32_16x16x32_bf16 v[88:91], v[140:143], v[204:207], v[88:91]
	v_mfma_f32_16x16x32_bf16 v[76:79], v[132:135], v[216:219], v[76:79]
	v_mfma_f32_16x16x32_bf16 v[72:75], v[140:143], v[216:219], v[72:75]
	s_setprio 0
	s_setprio 1
	v_mfma_f32_16x16x32_bf16 v[116:119], v[158:161], v[184:187], v[116:119]
	v_mfma_f32_16x16x32_bf16 v[112:115], v[166:169], v[184:187], v[112:115]
	v_mfma_f32_16x16x32_bf16 v[100:103], v[158:161], v[192:195], v[100:103]
	v_mfma_f32_16x16x32_bf16 v[96:99], v[166:169], v[192:195], v[96:99]
	v_mfma_f32_16x16x32_bf16 v[84:87], v[158:161], v[200:203], v[84:87]
	v_mfma_f32_16x16x32_bf16 v[80:83], v[166:169], v[200:203], v[80:83]
	v_mfma_f32_16x16x32_bf16 v[68:71], v[158:161], v[208:211], v[68:71]
	v_mfma_f32_16x16x32_bf16 v[64:67], v[166:169], v[208:211], v[64:67]
	v_mfma_f32_16x16x32_bf16 v[116:119], v[162:165], v[188:191], v[116:119]
	v_mfma_f32_16x16x32_bf16 v[112:115], v[180:183], v[188:191], v[112:115]
	v_mfma_f32_16x16x32_bf16 v[100:103], v[162:165], v[196:199], v[100:103]
	v_mfma_f32_16x16x32_bf16 v[96:99], v[180:183], v[196:199], v[96:99]
	v_mfma_f32_16x16x32_bf16 v[84:87], v[162:165], v[204:207], v[84:87]
	v_mfma_f32_16x16x32_bf16 v[80:83], v[180:183], v[204:207], v[80:83]
	v_mfma_f32_16x16x32_bf16 v[68:71], v[162:165], v[216:219], v[68:71]
	v_mfma_f32_16x16x32_bf16 v[64:67], v[180:183], v[216:219], v[64:67]
	s_setprio 0
	s_barrier
	s_add_i32 s24, s66, s56
	v_lshl_add_u64 v[170:171], s[28:29], 0, v[146:147]
	s_mov_b32 m0, s24
	ds_read_b128 v[184:187], v179 offset:16384
	ds_read_b128 v[188:191], v179 offset:17408
	ds_read_b128 v[192:195], v179 offset:18432
	ds_read_b128 v[196:199], v179 offset:19456
	ds_read_b128 v[200:203], v179 offset:20480
	ds_read_b128 v[204:207], v179 offset:21504
	ds_read_b128 v[208:211], v179 offset:22528
	ds_read_b128 v[216:219], v179 offset:23552
	global_load_lds_dwordx4 v[170:171], off
	s_add_i32 m0, s24, 0x2000
	s_add_u32 s24, s28, 0xb0000
	v_lshl_add_u64 v[212:213], s[28:29], 0, v[150:151]
	s_addc_u32 s25, s29, 0
	s_add_i32 s76, s67, s56
	global_load_lds_dwordx4 v[212:213], off
	v_lshl_add_u64 v[220:221], s[24:25], 0, v[146:147]
	s_mov_b32 m0, s76
	v_lshl_add_u64 v[222:223], s[30:31], 0, v[148:149]
	global_load_lds_dwordx4 v[220:221], off
	v_lshl_add_u64 v[220:221], s[24:25], 0, v[150:151]
	s_add_i32 m0, s76, 0x2000
	s_nop 0
	global_load_lds_dwordx4 v[220:221], off
	v_lshl_add_u64 v[220:221], s[30:31], 0, v[144:145]
	s_mov_b32 m0, s57
	s_nop 0
	global_load_lds_dwordx4 v[220:221], off
	s_mov_b32 m0, s58
	s_nop 0
	global_load_lds_dwordx4 v[222:223], off
	s_waitcnt vmcnt(8)
	s_waitcnt lgkmcnt(0)
	s_barrier
	s_setprio 1
	s_waitcnt lgkmcnt(0)
	v_mfma_f32_16x16x32_bf16 v[60:63], v[128:131], v[184:187], v[60:63]
	v_mfma_f32_16x16x32_bf16 v[56:59], v[136:139], v[184:187], v[56:59]
	v_mfma_f32_16x16x32_bf16 v[44:47], v[128:131], v[192:195], v[44:47]
	v_mfma_f32_16x16x32_bf16 v[40:43], v[136:139], v[192:195], v[40:43]
	v_mfma_f32_16x16x32_bf16 v[28:31], v[128:131], v[200:203], v[28:31]
	v_mfma_f32_16x16x32_bf16 v[24:27], v[136:139], v[200:203], v[24:27]
	v_mfma_f32_16x16x32_bf16 v[12:15], v[128:131], v[208:211], v[12:15]
	v_mfma_f32_16x16x32_bf16 v[8:11], v[136:139], v[208:211], v[8:11]
	v_mfma_f32_16x16x32_bf16 v[60:63], v[132:135], v[188:191], v[60:63]
	v_mfma_f32_16x16x32_bf16 v[56:59], v[140:143], v[188:191], v[56:59]
	v_mfma_f32_16x16x32_bf16 v[44:47], v[132:135], v[196:199], v[44:47]
	v_mfma_f32_16x16x32_bf16 v[40:43], v[140:143], v[196:199], v[40:43]
	v_mfma_f32_16x16x32_bf16 v[28:31], v[132:135], v[204:207], v[28:31]
	v_mfma_f32_16x16x32_bf16 v[24:27], v[140:143], v[204:207], v[24:27]
	v_mfma_f32_16x16x32_bf16 v[12:15], v[132:135], v[216:219], v[12:15]
	v_mfma_f32_16x16x32_bf16 v[8:11], v[140:143], v[216:219], v[8:11]
	s_setprio 0
	s_setprio 1
	v_mfma_f32_16x16x32_bf16 v[52:55], v[158:161], v[184:187], v[52:55]
	v_mfma_f32_16x16x32_bf16 v[48:51], v[166:169], v[184:187], v[48:51]
	v_mfma_f32_16x16x32_bf16 v[36:39], v[158:161], v[192:195], v[36:39]
	v_mfma_f32_16x16x32_bf16 v[32:35], v[166:169], v[192:195], v[32:35]
	v_mfma_f32_16x16x32_bf16 v[20:23], v[158:161], v[200:203], v[20:23]
	v_mfma_f32_16x16x32_bf16 v[16:19], v[166:169], v[200:203], v[16:19]
	v_mfma_f32_16x16x32_bf16 v[4:7], v[158:161], v[208:211], v[4:7]
	v_mfma_f32_16x16x32_bf16 v[0:3], v[166:169], v[208:211], v[0:3]
	v_mfma_f32_16x16x32_bf16 v[52:55], v[162:165], v[188:191], v[52:55]
	v_mfma_f32_16x16x32_bf16 v[48:51], v[180:183], v[188:191], v[48:51]
	v_mfma_f32_16x16x32_bf16 v[36:39], v[162:165], v[196:199], v[36:39]
	v_mfma_f32_16x16x32_bf16 v[32:35], v[180:183], v[196:199], v[32:35]
	v_mfma_f32_16x16x32_bf16 v[20:23], v[162:165], v[204:207], v[20:23]
	v_mfma_f32_16x16x32_bf16 v[16:19], v[180:183], v[204:207], v[16:19]
	v_mfma_f32_16x16x32_bf16 v[4:7], v[162:165], v[216:219], v[4:7]
	v_mfma_f32_16x16x32_bf16 v[0:3], v[180:183], v[216:219], v[0:3]
	s_setprio 0
	s_barrier
	s_add_i32 s76, 0, 0x18000
	s_add_i32 s77, 0, 0x1c000
	v_add_u32_e32 v140, s76, v175
	v_add_u32_e32 v180, s77, v175
	ds_read_b128 v[128:131], v140
	ds_read_b128 v[132:135], v140 offset:1024
	ds_read_b128 v[136:139], v140 offset:2048
	ds_read_b128 v[140:143], v140 offset:3072
	ds_read_b128 v[158:161], v180
	ds_read_b128 v[162:165], v180 offset:1024
	ds_read_b128 v[166:169], v180 offset:2048
	ds_read_b128 v[180:183], v180 offset:3072
	s_add_u32 s24, s30, 0xb0000
	s_addc_u32 s25, s31, 0
	s_mov_b32 m0, s59
	v_lshl_add_u64 v[224:225], s[24:25], 0, v[144:145]
	ds_read_b128 v[184:187], v179 offset:32768
	ds_read_b128 v[188:191], v179 offset:33792
	ds_read_b128 v[192:195], v179 offset:34816
	ds_read_b128 v[196:199], v179 offset:35840
	ds_read_b128 v[200:203], v179 offset:36864
	ds_read_b128 v[204:207], v179 offset:37888
	ds_read_b128 v[208:211], v179 offset:38912
	ds_read_b128 v[216:219], v179 offset:39936
	global_load_lds_dwordx4 v[224:225], off
	v_lshl_add_u64 v[224:225], s[24:25], 0, v[148:149]
	s_mov_b32 m0, s60
	s_nop 0
	global_load_lds_dwordx4 v[224:225], off
	s_waitcnt vmcnt(8)
	s_waitcnt lgkmcnt(0)
	s_barrier
	s_setprio 1
	s_waitcnt lgkmcnt(0)
	v_mfma_f32_16x16x32_bf16 v[124:127], v[128:131], v[184:187], v[124:127]
	v_mfma_f32_16x16x32_bf16 v[120:123], v[136:139], v[184:187], v[120:123]
	v_mfma_f32_16x16x32_bf16 v[108:111], v[128:131], v[192:195], v[108:111]
	v_mfma_f32_16x16x32_bf16 v[104:107], v[136:139], v[192:195], v[104:107]
	v_mfma_f32_16x16x32_bf16 v[92:95], v[128:131], v[200:203], v[92:95]
	v_mfma_f32_16x16x32_bf16 v[88:91], v[136:139], v[200:203], v[88:91]
	v_mfma_f32_16x16x32_bf16 v[76:79], v[128:131], v[208:211], v[76:79]
	v_mfma_f32_16x16x32_bf16 v[72:75], v[136:139], v[208:211], v[72:75]
	v_mfma_f32_16x16x32_bf16 v[124:127], v[132:135], v[188:191], v[124:127]
	v_mfma_f32_16x16x32_bf16 v[120:123], v[140:143], v[188:191], v[120:123]
	v_mfma_f32_16x16x32_bf16 v[108:111], v[132:135], v[196:199], v[108:111]
	v_mfma_f32_16x16x32_bf16 v[104:107], v[140:143], v[196:199], v[104:107]
	v_mfma_f32_16x16x32_bf16 v[92:95], v[132:135], v[204:207], v[92:95]
	v_mfma_f32_16x16x32_bf16 v[88:91], v[140:143], v[204:207], v[88:91]
	v_mfma_f32_16x16x32_bf16 v[76:79], v[132:135], v[216:219], v[76:79]
	v_mfma_f32_16x16x32_bf16 v[72:75], v[140:143], v[216:219], v[72:75]
	s_setprio 0
	s_setprio 1
	v_mfma_f32_16x16x32_bf16 v[116:119], v[158:161], v[184:187], v[116:119]
	v_mfma_f32_16x16x32_bf16 v[112:115], v[166:169], v[184:187], v[112:115]
	v_mfma_f32_16x16x32_bf16 v[100:103], v[158:161], v[192:195], v[100:103]
	v_mfma_f32_16x16x32_bf16 v[96:99], v[166:169], v[192:195], v[96:99]
	v_mfma_f32_16x16x32_bf16 v[84:87], v[158:161], v[200:203], v[84:87]
	v_mfma_f32_16x16x32_bf16 v[80:83], v[166:169], v[200:203], v[80:83]
	v_mfma_f32_16x16x32_bf16 v[68:71], v[158:161], v[208:211], v[68:71]
	v_mfma_f32_16x16x32_bf16 v[64:67], v[166:169], v[208:211], v[64:67]
	v_mfma_f32_16x16x32_bf16 v[116:119], v[162:165], v[188:191], v[116:119]
	v_mfma_f32_16x16x32_bf16 v[112:115], v[180:183], v[188:191], v[112:115]
	v_mfma_f32_16x16x32_bf16 v[100:103], v[162:165], v[196:199], v[100:103]
	v_mfma_f32_16x16x32_bf16 v[96:99], v[180:183], v[196:199], v[96:99]
	v_mfma_f32_16x16x32_bf16 v[84:87], v[162:165], v[204:207], v[84:87]
	v_mfma_f32_16x16x32_bf16 v[80:83], v[180:183], v[204:207], v[80:83]
	v_mfma_f32_16x16x32_bf16 v[68:71], v[162:165], v[216:219], v[68:71]
	v_mfma_f32_16x16x32_bf16 v[64:67], v[180:183], v[216:219], v[64:67]
	s_setprio 0
	s_barrier
	s_add_i32 s24, s76, s56
	v_lshl_add_u64 v[170:171], v[170:171], 0, s[16:17]
	s_mov_b32 m0, s24
	ds_read_b128 v[184:187], v179 offset:49152
	ds_read_b128 v[188:191], v179 offset:50176
	ds_read_b128 v[192:195], v179 offset:51200
	ds_read_b128 v[196:199], v179 offset:52224
	ds_read_b128 v[200:203], v179 offset:53248
	ds_read_b128 v[204:207], v179 offset:54272
	ds_read_b128 v[208:211], v179 offset:55296
	ds_read_b128 v[216:219], v179 offset:56320
	global_load_lds_dwordx4 v[170:171], off
	s_add_i32 m0, s24, 0x2000
	s_add_u32 s24, s28, 0xb0080
	v_lshl_add_u64 v[170:171], v[212:213], 0, s[16:17]
	s_addc_u32 s25, s29, 0
	s_add_i32 s28, s77, s56
	global_load_lds_dwordx4 v[170:171], off
	v_lshl_add_u64 v[170:171], s[24:25], 0, v[146:147]
	s_mov_b32 m0, s28
	s_nop 0
	global_load_lds_dwordx4 v[170:171], off
	v_lshl_add_u64 v[170:171], s[24:25], 0, v[150:151]
	s_add_i32 m0, s28, 0x2000
	s_nop 0
	global_load_lds_dwordx4 v[170:171], off
	v_lshl_add_u64 v[170:171], v[220:221], 0, s[16:17]
	s_mov_b32 m0, s64
	s_nop 0
	global_load_lds_dwordx4 v[170:171], off
	v_lshl_add_u64 v[170:171], v[222:223], 0, s[16:17]
	s_mov_b32 m0, s65
	s_nop 0
	global_load_lds_dwordx4 v[170:171], off
	s_waitcnt vmcnt(8)
	s_waitcnt lgkmcnt(0)
	s_barrier
	s_setprio 1
	s_waitcnt lgkmcnt(0)
	v_mfma_f32_16x16x32_bf16 v[60:63], v[128:131], v[184:187], v[60:63]
	v_mfma_f32_16x16x32_bf16 v[56:59], v[136:139], v[184:187], v[56:59]
	v_mfma_f32_16x16x32_bf16 v[44:47], v[128:131], v[192:195], v[44:47]
	v_mfma_f32_16x16x32_bf16 v[40:43], v[136:139], v[192:195], v[40:43]
	v_mfma_f32_16x16x32_bf16 v[28:31], v[128:131], v[200:203], v[28:31]
	v_mfma_f32_16x16x32_bf16 v[24:27], v[136:139], v[200:203], v[24:27]
	v_mfma_f32_16x16x32_bf16 v[12:15], v[128:131], v[208:211], v[12:15]
	v_mfma_f32_16x16x32_bf16 v[8:11], v[136:139], v[208:211], v[8:11]
	v_mfma_f32_16x16x32_bf16 v[60:63], v[132:135], v[188:191], v[60:63]
	v_mfma_f32_16x16x32_bf16 v[56:59], v[140:143], v[188:191], v[56:59]
	v_mfma_f32_16x16x32_bf16 v[44:47], v[132:135], v[196:199], v[44:47]
	v_mfma_f32_16x16x32_bf16 v[40:43], v[140:143], v[196:199], v[40:43]
	v_mfma_f32_16x16x32_bf16 v[28:31], v[132:135], v[204:207], v[28:31]
	v_mfma_f32_16x16x32_bf16 v[24:27], v[140:143], v[204:207], v[24:27]
	v_mfma_f32_16x16x32_bf16 v[12:15], v[132:135], v[216:219], v[12:15]
	v_mfma_f32_16x16x32_bf16 v[8:11], v[140:143], v[216:219], v[8:11]
	s_setprio 0
	s_setprio 1
	v_mfma_f32_16x16x32_bf16 v[52:55], v[158:161], v[184:187], v[52:55]
	v_mfma_f32_16x16x32_bf16 v[48:51], v[166:169], v[184:187], v[48:51]
	v_mfma_f32_16x16x32_bf16 v[36:39], v[158:161], v[192:195], v[36:39]
	v_mfma_f32_16x16x32_bf16 v[32:35], v[166:169], v[192:195], v[32:35]
	v_mfma_f32_16x16x32_bf16 v[20:23], v[158:161], v[200:203], v[20:23]
	v_mfma_f32_16x16x32_bf16 v[16:19], v[166:169], v[200:203], v[16:19]
	v_mfma_f32_16x16x32_bf16 v[4:7], v[158:161], v[208:211], v[4:7]
	v_mfma_f32_16x16x32_bf16 v[0:3], v[166:169], v[208:211], v[0:3]
	v_mfma_f32_16x16x32_bf16 v[52:55], v[162:165], v[188:191], v[52:55]
	v_mfma_f32_16x16x32_bf16 v[48:51], v[180:183], v[188:191], v[48:51]
	v_mfma_f32_16x16x32_bf16 v[36:39], v[162:165], v[196:199], v[36:39]
	v_mfma_f32_16x16x32_bf16 v[32:35], v[180:183], v[196:199], v[32:35]
	v_mfma_f32_16x16x32_bf16 v[20:23], v[162:165], v[204:207], v[20:23]
	v_mfma_f32_16x16x32_bf16 v[16:19], v[180:183], v[204:207], v[16:19]
	v_mfma_f32_16x16x32_bf16 v[4:7], v[162:165], v[216:219], v[4:7]
	v_mfma_f32_16x16x32_bf16 v[0:3], v[180:183], v[216:219], v[0:3]
	s_setprio 0
	s_barrier
	s_add_i32 s72, s72, 2
	s_add_u32 s12, s12, 0x100
	s_addc_u32 s74, s74, 0
	s_cmp_gt_u32 s72, 41
	s_mov_b64 s[24:25], s[26:27]
	s_cbranch_scc0 .LBB0_658
	s_and_b64 vcc, exec, s[18:19]
	s_cbranch_vccz .LBB0_661
	s_barrier

.LBB0_707:
	ds_read_b128 v[48:51], v196
	ds_read_b128 v[52:55], v196 offset:1024
	ds_read_b128 v[56:59], v196 offset:2048
	ds_read_b128 v[60:63], v196 offset:3072
	ds_read_b128 v[162:165], v197
	ds_read_b128 v[166:169], v197 offset:1024
	ds_read_b128 v[170:173], v197 offset:2048
	ds_read_b128 v[174:177], v197 offset:3072
	s_add_u32 s6, s4, 0xfffc0080
	s_addc_u32 s7, s5, -1
	s_cmp_eq_u32 s56, 12
	s_cselect_b32 s9, s11, s7
	s_cselect_b32 s8, s27, s6
	s_cselect_b32 s7, s25, s55
	s_cselect_b32 s6, s53, s54
	v_lshl_add_u64 v[190:191], s[4:5], 0, v[154:155]
	s_add_i32 m0, s63, 0xc000
	ds_read_b128 v[178:181], v198
	ds_read_b128 v[182:185], v198 offset:1024
	ds_read_b128 v[186:189], v198 offset:2048
	ds_read_b128 v[200:203], v198 offset:3072
	ds_read_b128 v[204:207], v198 offset:4096
	ds_read_b128 v[208:211], v198 offset:5120
	ds_read_b128 v[216:219], v198 offset:6144
	ds_read_b128 v[220:223], v198 offset:7168
	global_load_lds_dwordx4 v[190:191], off
	v_lshl_add_u64 v[190:191], s[4:5], 0, v[156:157]
	s_add_i32 m0, s63, 0xe000
	s_nop 0
	global_load_lds_dwordx4 v[190:191], off
	s_waitcnt vmcnt(8)
	s_waitcnt lgkmcnt(0)
	s_barrier
	s_setprio 1
	s_waitcnt lgkmcnt(0)
	v_mfma_f32_16x16x32_bf16 v[140:143], v[48:51], v[178:181], v[140:143]
	v_mfma_f32_16x16x32_bf16 v[136:139], v[56:59], v[178:181], v[136:139]
	v_mfma_f32_16x16x32_bf16 v[124:127], v[48:51], v[186:189], v[124:127]
	v_mfma_f32_16x16x32_bf16 v[120:123], v[56:59], v[186:189], v[120:123]
	v_mfma_f32_16x16x32_bf16 v[108:111], v[48:51], v[204:207], v[108:111]
	v_mfma_f32_16x16x32_bf16 v[104:107], v[56:59], v[204:207], v[104:107]
	v_mfma_f32_16x16x32_bf16 v[92:95], v[48:51], v[216:219], v[92:95]
	v_mfma_f32_16x16x32_bf16 v[88:91], v[56:59], v[216:219], v[88:91]
	v_mfma_f32_16x16x32_bf16 v[140:143], v[52:55], v[182:185], v[140:143]
	v_mfma_f32_16x16x32_bf16 v[136:139], v[60:63], v[182:185], v[136:139]
	v_mfma_f32_16x16x32_bf16 v[124:127], v[52:55], v[200:203], v[124:127]
	v_mfma_f32_16x16x32_bf16 v[120:123], v[60:63], v[200:203], v[120:123]
	v_mfma_f32_16x16x32_bf16 v[108:111], v[52:55], v[208:211], v[108:111]
	v_mfma_f32_16x16x32_bf16 v[104:107], v[60:63], v[208:211], v[104:107]
	v_mfma_f32_16x16x32_bf16 v[92:95], v[52:55], v[220:223], v[92:95]
	v_mfma_f32_16x16x32_bf16 v[88:91], v[60:63], v[220:223], v[88:91]
	s_setprio 0
	s_setprio 1
	v_mfma_f32_16x16x32_bf16 v[132:135], v[162:165], v[178:181], v[132:135]
	v_mfma_f32_16x16x32_bf16 v[128:131], v[170:173], v[178:181], v[128:131]
	v_mfma_f32_16x16x32_bf16 v[116:119], v[162:165], v[186:189], v[116:119]
	v_mfma_f32_16x16x32_bf16 v[112:115], v[170:173], v[186:189], v[112:115]
	v_mfma_f32_16x16x32_bf16 v[100:103], v[162:165], v[204:207], v[100:103]
	v_mfma_f32_16x16x32_bf16 v[96:99], v[170:173], v[204:207], v[96:99]
	v_mfma_f32_16x16x32_bf16 v[84:87], v[162:165], v[216:219], v[84:87]
	v_mfma_f32_16x16x32_bf16 v[80:83], v[170:173], v[216:219], v[80:83]
	v_mfma_f32_16x16x32_bf16 v[132:135], v[166:169], v[182:185], v[132:135]
	v_mfma_f32_16x16x32_bf16 v[128:131], v[174:177], v[182:185], v[128:131]
	v_mfma_f32_16x16x32_bf16 v[116:119], v[166:169], v[200:203], v[116:119]
	v_mfma_f32_16x16x32_bf16 v[112:115], v[174:177], v[200:203], v[112:115]
	v_mfma_f32_16x16x32_bf16 v[100:103], v[166:169], v[208:211], v[100:103]
	v_mfma_f32_16x16x32_bf16 v[96:99], v[174:177], v[208:211], v[96:99]
	v_mfma_f32_16x16x32_bf16 v[84:87], v[166:169], v[220:223], v[84:87]
	v_mfma_f32_16x16x32_bf16 v[80:83], v[174:177], v[220:223], v[80:83]
	s_setprio 0
	s_barrier
	s_add_i32 s57, s87, s62
	v_lshl_add_u64 v[190:191], s[6:7], 0, v[144:145]
	s_mov_b32 m0, s57
	ds_read_b128 v[178:181], v198 offset:16384
	ds_read_b128 v[182:185], v198 offset:17408
	ds_read_b128 v[186:189], v198 offset:18432
	ds_read_b128 v[200:203], v198 offset:19456
	ds_read_b128 v[204:207], v198 offset:20480
	ds_read_b128 v[208:211], v198 offset:21504
	ds_read_b128 v[216:219], v198 offset:22528
	ds_read_b128 v[220:223], v198 offset:23552
	global_load_lds_dwordx4 v[190:191], off
	s_add_i32 m0, s57, 0x2000
	s_add_u32 s58, s6, 0x40000
	v_lshl_add_u64 v[212:213], s[6:7], 0, v[146:147]
	s_addc_u32 s59, s7, 0
	s_add_i32 s57, s88, s62
	global_load_lds_dwordx4 v[212:213], off
	v_lshl_add_u64 v[224:225], s[58:59], 0, v[144:145]
	s_mov_b32 m0, s57
	v_lshl_add_u64 v[226:227], s[8:9], 0, v[146:147]
	global_load_lds_dwordx4 v[224:225], off
	v_lshl_add_u64 v[224:225], s[58:59], 0, v[146:147]
	s_add_i32 m0, s57, 0x2000
	s_nop 0
	global_load_lds_dwordx4 v[224:225], off
	v_lshl_add_u64 v[224:225], s[8:9], 0, v[144:145]
	s_mov_b32 m0, s63
	s_nop 0
	global_load_lds_dwordx4 v[224:225], off
	s_mov_b32 m0, s64
	s_nop 0
	global_load_lds_dwordx4 v[226:227], off
	s_waitcnt vmcnt(8)
	s_waitcnt lgkmcnt(0)
	s_barrier
	s_setprio 1
	s_waitcnt lgkmcnt(0)
	v_mfma_f32_16x16x32_bf16 v[76:79], v[48:51], v[178:181], v[76:79]
	v_mfma_f32_16x16x32_bf16 v[72:75], v[56:59], v[178:181], v[72:75]
	v_mfma_f32_16x16x32_bf16 v[44:47], v[48:51], v[186:189], v[44:47]
	v_mfma_f32_16x16x32_bf16 v[40:43], v[56:59], v[186:189], v[40:43]
	v_mfma_f32_16x16x32_bf16 v[28:31], v[48:51], v[204:207], v[28:31]
	v_mfma_f32_16x16x32_bf16 v[24:27], v[56:59], v[204:207], v[24:27]
	v_mfma_f32_16x16x32_bf16 v[12:15], v[48:51], v[216:219], v[12:15]
	v_mfma_f32_16x16x32_bf16 v[8:11], v[56:59], v[216:219], v[8:11]
	v_mfma_f32_16x16x32_bf16 v[76:79], v[52:55], v[182:185], v[76:79]
	v_mfma_f32_16x16x32_bf16 v[72:75], v[60:63], v[182:185], v[72:75]
	v_mfma_f32_16x16x32_bf16 v[44:47], v[52:55], v[200:203], v[44:47]
	v_mfma_f32_16x16x32_bf16 v[40:43], v[60:63], v[200:203], v[40:43]
	v_mfma_f32_16x16x32_bf16 v[28:31], v[52:55], v[208:211], v[28:31]
	v_mfma_f32_16x16x32_bf16 v[24:27], v[60:63], v[208:211], v[24:27]
	v_mfma_f32_16x16x32_bf16 v[12:15], v[52:55], v[220:223], v[12:15]
	v_mfma_f32_16x16x32_bf16 v[8:11], v[60:63], v[220:223], v[8:11]
	s_setprio 0
	s_setprio 1
	v_mfma_f32_16x16x32_bf16 v[36:39], v[162:165], v[186:189], v[36:39]
	v_mfma_f32_16x16x32_bf16 v[32:35], v[170:173], v[186:189], v[32:35]
	v_mfma_f32_16x16x32_bf16 v[20:23], v[162:165], v[204:207], v[20:23]
	v_mfma_f32_16x16x32_bf16 v[16:19], v[170:173], v[204:207], v[16:19]
	v_mfma_f32_16x16x32_bf16 v[4:7], v[162:165], v[216:219], v[4:7]
	v_mfma_f32_16x16x32_bf16 v[0:3], v[170:173], v[216:219], v[0:3]
	v_mfma_f32_16x16x32_bf16 v[48:51], v[162:165], v[178:181], v[68:71]
	v_mfma_f32_16x16x32_bf16 v[52:55], v[170:173], v[178:181], v[64:67]
	v_mfma_f32_16x16x32_bf16 v[36:39], v[166:169], v[200:203], v[36:39]
	v_mfma_f32_16x16x32_bf16 v[32:35], v[174:177], v[200:203], v[32:35]
	v_mfma_f32_16x16x32_bf16 v[20:23], v[166:169], v[208:211], v[20:23]
	v_mfma_f32_16x16x32_bf16 v[16:19], v[174:177], v[208:211], v[16:19]
	v_mfma_f32_16x16x32_bf16 v[4:7], v[166:169], v[220:223], v[4:7]
	v_mfma_f32_16x16x32_bf16 v[0:3], v[174:177], v[220:223], v[0:3]
	v_mfma_f32_16x16x32_bf16 v[48:51], v[166:169], v[182:185], v[48:51]
	v_mfma_f32_16x16x32_bf16 v[52:55], v[174:177], v[182:185], v[52:55]
	s_setprio 0
	s_barrier
	s_add_i32 s57, 0, 0x18000
	s_add_i32 s58, 0, 0x1c000
	v_add_u32_e32 v68, s57, v193
	v_add_u32_e32 v174, s58, v193
	ds_read_b128 v[56:59], v68
	ds_read_b128 v[60:63], v68 offset:1024
	ds_read_b128 v[64:67], v68 offset:2048
	ds_read_b128 v[68:71], v68 offset:3072
	ds_read_b128 v[162:165], v174
	ds_read_b128 v[166:169], v174 offset:1024
	ds_read_b128 v[170:173], v174 offset:2048
	ds_read_b128 v[174:177], v174 offset:3072
	s_add_u32 s8, s8, 0x40000
	s_addc_u32 s9, s9, 0
	s_mov_b32 m0, s65
	v_lshl_add_u64 v[228:229], s[8:9], 0, v[144:145]
	ds_read_b128 v[178:181], v198 offset:32768
	ds_read_b128 v[182:185], v198 offset:33792
	ds_read_b128 v[186:189], v198 offset:34816
	ds_read_b128 v[200:203], v198 offset:35840
	ds_read_b128 v[204:207], v198 offset:36864
	ds_read_b128 v[208:211], v198 offset:37888
	ds_read_b128 v[216:219], v198 offset:38912
	ds_read_b128 v[220:223], v198 offset:39936
	global_load_lds_dwordx4 v[228:229], off
	v_lshl_add_u64 v[228:229], s[8:9], 0, v[146:147]
	s_mov_b32 m0, s66
	s_nop 0
	global_load_lds_dwordx4 v[228:229], off
	s_waitcnt vmcnt(8)
	s_waitcnt lgkmcnt(0)
	s_barrier
	s_setprio 1
	s_waitcnt lgkmcnt(0)
	v_mfma_f32_16x16x32_bf16 v[140:143], v[56:59], v[178:181], v[140:143]
	v_mfma_f32_16x16x32_bf16 v[136:139], v[64:67], v[178:181], v[136:139]
	v_mfma_f32_16x16x32_bf16 v[124:127], v[56:59], v[186:189], v[124:127]
	v_mfma_f32_16x16x32_bf16 v[120:123], v[64:67], v[186:189], v[120:123]
	v_mfma_f32_16x16x32_bf16 v[108:111], v[56:59], v[204:207], v[108:111]
	v_mfma_f32_16x16x32_bf16 v[104:107], v[64:67], v[204:207], v[104:107]
	v_mfma_f32_16x16x32_bf16 v[92:95], v[56:59], v[216:219], v[92:95]
	v_mfma_f32_16x16x32_bf16 v[88:91], v[64:67], v[216:219], v[88:91]
	v_mfma_f32_16x16x32_bf16 v[140:143], v[60:63], v[182:185], v[140:143]
	v_mfma_f32_16x16x32_bf16 v[136:139], v[68:71], v[182:185], v[136:139]
	v_mfma_f32_16x16x32_bf16 v[124:127], v[60:63], v[200:203], v[124:127]
	v_mfma_f32_16x16x32_bf16 v[120:123], v[68:71], v[200:203], v[120:123]
	v_mfma_f32_16x16x32_bf16 v[108:111], v[60:63], v[208:211], v[108:111]
	v_mfma_f32_16x16x32_bf16 v[104:107], v[68:71], v[208:211], v[104:107]
	v_mfma_f32_16x16x32_bf16 v[92:95], v[60:63], v[220:223], v[92:95]
	v_mfma_f32_16x16x32_bf16 v[88:91], v[68:71], v[220:223], v[88:91]
	s_setprio 0
	s_setprio 1
	v_mfma_f32_16x16x32_bf16 v[132:135], v[162:165], v[178:181], v[132:135]
	v_mfma_f32_16x16x32_bf16 v[128:131], v[170:173], v[178:181], v[128:131]
	v_mfma_f32_16x16x32_bf16 v[116:119], v[162:165], v[186:189], v[116:119]
	v_mfma_f32_16x16x32_bf16 v[112:115], v[170:173], v[186:189], v[112:115]
	v_mfma_f32_16x16x32_bf16 v[100:103], v[162:165], v[204:207], v[100:103]
	v_mfma_f32_16x16x32_bf16 v[96:99], v[170:173], v[204:207], v[96:99]
	v_mfma_f32_16x16x32_bf16 v[84:87], v[162:165], v[216:219], v[84:87]
	v_mfma_f32_16x16x32_bf16 v[80:83], v[170:173], v[216:219], v[80:83]
	v_mfma_f32_16x16x32_bf16 v[132:135], v[166:169], v[182:185], v[132:135]
	v_mfma_f32_16x16x32_bf16 v[128:131], v[174:177], v[182:185], v[128:131]
	v_mfma_f32_16x16x32_bf16 v[116:119], v[166:169], v[200:203], v[116:119]
	v_mfma_f32_16x16x32_bf16 v[112:115], v[174:177], v[200:203], v[112:115]
	v_mfma_f32_16x16x32_bf16 v[100:103], v[166:169], v[208:211], v[100:103]
	v_mfma_f32_16x16x32_bf16 v[96:99], v[174:177], v[208:211], v[96:99]
	v_mfma_f32_16x16x32_bf16 v[84:87], v[166:169], v[220:223], v[84:87]
	v_mfma_f32_16x16x32_bf16 v[80:83], v[174:177], v[220:223], v[80:83]
	s_setprio 0
	s_barrier
	s_add_i32 s8, s57, s62
	v_lshl_add_u64 v[190:191], v[190:191], 0, s[20:21]
	s_mov_b32 m0, s8
	ds_read_b128 v[178:181], v198 offset:49152
	ds_read_b128 v[182:185], v198 offset:50176
	ds_read_b128 v[186:189], v198 offset:51200
	ds_read_b128 v[200:203], v198 offset:52224
	ds_read_b128 v[204:207], v198 offset:53248
	ds_read_b128 v[208:211], v198 offset:54272
	ds_read_b128 v[216:219], v198 offset:55296
	ds_read_b128 v[220:223], v198 offset:56320
	global_load_lds_dwordx4 v[190:191], off
	s_add_i32 m0, s8, 0x2000
	s_add_u32 s6, s6, 0x40080
	v_lshl_add_u64 v[190:191], v[212:213], 0, s[20:21]
	s_addc_u32 s7, s7, 0
	s_add_i32 s8, s58, s62
	global_load_lds_dwordx4 v[190:191], off
	v_lshl_add_u64 v[190:191], s[6:7], 0, v[144:145]
	s_mov_b32 m0, s8
	s_nop 0
	global_load_lds_dwordx4 v[190:191], off
	v_lshl_add_u64 v[190:191], s[6:7], 0, v[146:147]
	s_add_i32 m0, s8, 0x2000
	s_nop 0
	global_load_lds_dwordx4 v[190:191], off
	v_lshl_add_u64 v[190:191], v[224:225], 0, s[20:21]
	s_mov_b32 m0, s81
	s_nop 0
	global_load_lds_dwordx4 v[190:191], off
	v_lshl_add_u64 v[190:191], v[226:227], 0, s[20:21]
	s_mov_b32 m0, s82
	s_nop 0
	global_load_lds_dwordx4 v[190:191], off
	s_waitcnt vmcnt(8)
	s_waitcnt lgkmcnt(0)
	s_barrier
	s_setprio 1
	s_waitcnt lgkmcnt(0)
	v_mfma_f32_16x16x32_bf16 v[76:79], v[56:59], v[178:181], v[76:79]
	v_mfma_f32_16x16x32_bf16 v[72:75], v[64:67], v[178:181], v[72:75]
	v_mfma_f32_16x16x32_bf16 v[44:47], v[56:59], v[186:189], v[44:47]
	v_mfma_f32_16x16x32_bf16 v[40:43], v[64:67], v[186:189], v[40:43]
	v_mfma_f32_16x16x32_bf16 v[28:31], v[56:59], v[204:207], v[28:31]
	v_mfma_f32_16x16x32_bf16 v[24:27], v[64:67], v[204:207], v[24:27]
	v_mfma_f32_16x16x32_bf16 v[12:15], v[56:59], v[216:219], v[12:15]
	v_mfma_f32_16x16x32_bf16 v[8:11], v[64:67], v[216:219], v[8:11]
	v_mfma_f32_16x16x32_bf16 v[76:79], v[60:63], v[182:185], v[76:79]
	v_mfma_f32_16x16x32_bf16 v[72:75], v[68:71], v[182:185], v[72:75]
	v_mfma_f32_16x16x32_bf16 v[44:47], v[60:63], v[200:203], v[44:47]
	v_mfma_f32_16x16x32_bf16 v[40:43], v[68:71], v[200:203], v[40:43]
	v_mfma_f32_16x16x32_bf16 v[28:31], v[60:63], v[208:211], v[28:31]
	v_mfma_f32_16x16x32_bf16 v[24:27], v[68:71], v[208:211], v[24:27]
	v_mfma_f32_16x16x32_bf16 v[12:15], v[60:63], v[220:223], v[12:15]
	v_mfma_f32_16x16x32_bf16 v[8:11], v[68:71], v[220:223], v[8:11]
	s_setprio 0
	s_setprio 1
	v_mfma_f32_16x16x32_bf16 v[48:51], v[162:165], v[178:181], v[48:51]
	v_mfma_f32_16x16x32_bf16 v[68:71], v[166:169], v[182:185], v[48:51]
	v_mfma_f32_16x16x32_bf16 v[48:51], v[170:173], v[178:181], v[52:55]
	v_mfma_f32_16x16x32_bf16 v[36:39], v[162:165], v[186:189], v[36:39]
	v_mfma_f32_16x16x32_bf16 v[32:35], v[170:173], v[186:189], v[32:35]
	v_mfma_f32_16x16x32_bf16 v[20:23], v[162:165], v[204:207], v[20:23]
	v_mfma_f32_16x16x32_bf16 v[16:19], v[170:173], v[204:207], v[16:19]
	v_mfma_f32_16x16x32_bf16 v[4:7], v[162:165], v[216:219], v[4:7]
	v_mfma_f32_16x16x32_bf16 v[0:3], v[170:173], v[216:219], v[0:3]
	v_mfma_f32_16x16x32_bf16 v[64:67], v[174:177], v[182:185], v[48:51]
	v_mfma_f32_16x16x32_bf16 v[36:39], v[166:169], v[200:203], v[36:39]
	v_mfma_f32_16x16x32_bf16 v[32:35], v[174:177], v[200:203], v[32:35]
	v_mfma_f32_16x16x32_bf16 v[20:23], v[166:169], v[208:211], v[20:23]
	v_mfma_f32_16x16x32_bf16 v[16:19], v[174:177], v[208:211], v[16:19]
	v_mfma_f32_16x16x32_bf16 v[4:7], v[166:169], v[220:223], v[4:7]
	v_mfma_f32_16x16x32_bf16 v[0:3], v[174:177], v[220:223], v[0:3]
	s_setprio 0
	s_barrier
	s_add_i32 s56, s56, 2
	s_add_u32 s4, s4, 0x100
	s_addc_u32 s5, s5, 0
	s_add_u32 s54, s54, 0x100
	s_addc_u32 s55, s55, 0
	s_cmp_gt_u32 s56, 13
	s_cbranch_scc0 .LBB0_707
	s_and_b64 vcc, exec, s[22:23]
	s_cbranch_vccz .LBB0_710
	s_barrier

.LBB0_950:
	s_add_u32 s54, s94, s52
	s_addc_u32 s55, s95, s53
	s_add_u32 s54, s54, 0x14d00100
	s_addc_u32 s55, s55, 0
	s_add_u32 s60, s96, s52
	s_addc_u32 s61, s97, s53
	s_add_i32 vcc_hi, 0, 0x10000
	s_cmpk_eq_i32 s52, 0x700
	s_cselect_b32 s57, s7, s55
	s_cselect_b32 s56, s6, s54
	v_add_u32_e32 v141, vcc_hi, v133
	s_cselect_b32 s55, s5, s61
	s_cselect_b32 s54, s4, s60
	s_add_i32 s78, 0, 0x14000
	ds_read_b128 v[142:145], v141
	ds_read_b128 v[146:149], v141 offset:1024
	ds_read_b128 v[150:153], v141 offset:2048
	ds_read_b128 v[154:157], v141 offset:3072
	v_add_u32_e32 v141, s78, v133
	ds_read_b128 v[158:161], v141
	ds_read_b128 v[162:165], v141 offset:1024
	ds_read_b128 v[166:169], v141 offset:2048
	ds_read_b128 v[170:173], v141 offset:3072
	v_lshl_add_u64 v[186:187], v[134:135], 0, s[52:53]
	s_add_i32 m0, s87, 0xc000
	ds_read_b128 v[174:177], v140
	ds_read_b128 v[178:181], v140 offset:1024
	ds_read_b128 v[182:185], v140 offset:2048
	ds_read_b128 v[190:193], v140 offset:3072
	ds_read_b128 v[206:209], v140 offset:4096
	ds_read_b128 v[210:213], v140 offset:5120
	ds_read_b128 v[216:219], v140 offset:6144
	ds_read_b128 v[220:223], v140 offset:7168
	global_load_lds_dwordx4 v[186:187], off
	v_lshl_add_u64 v[186:187], v[136:137], 0, s[52:53]
	s_add_i32 m0, s87, 0xe000
	s_nop 0
	global_load_lds_dwordx4 v[186:187], off
	s_waitcnt vmcnt(8)
	s_waitcnt lgkmcnt(0)
	s_barrier
	s_setprio 1
	s_waitcnt lgkmcnt(0)
	v_mfma_f32_16x16x32_bf16 v[126:129], v[142:145], v[174:177], v[126:129]
	v_mfma_f32_16x16x32_bf16 v[122:125], v[150:153], v[174:177], v[122:125]
	v_mfma_f32_16x16x32_bf16 v[110:113], v[142:145], v[182:185], v[110:113]
	v_mfma_f32_16x16x32_bf16 v[106:109], v[150:153], v[182:185], v[106:109]
	v_mfma_f32_16x16x32_bf16 v[94:97], v[142:145], v[206:209], v[94:97]
	v_mfma_f32_16x16x32_bf16 v[90:93], v[150:153], v[206:209], v[90:93]
	v_mfma_f32_16x16x32_bf16 v[78:81], v[142:145], v[216:219], v[78:81]
	v_mfma_f32_16x16x32_bf16 v[74:77], v[150:153], v[216:219], v[74:77]
	v_mfma_f32_16x16x32_bf16 v[126:129], v[146:149], v[178:181], v[126:129]
	v_mfma_f32_16x16x32_bf16 v[122:125], v[154:157], v[178:181], v[122:125]
	v_mfma_f32_16x16x32_bf16 v[110:113], v[146:149], v[190:193], v[110:113]
	v_mfma_f32_16x16x32_bf16 v[106:109], v[154:157], v[190:193], v[106:109]
	v_mfma_f32_16x16x32_bf16 v[94:97], v[146:149], v[210:213], v[94:97]
	v_mfma_f32_16x16x32_bf16 v[90:93], v[154:157], v[210:213], v[90:93]
	v_mfma_f32_16x16x32_bf16 v[78:81], v[146:149], v[220:223], v[78:81]
	v_mfma_f32_16x16x32_bf16 v[74:77], v[154:157], v[220:223], v[74:77]
	s_setprio 0
	s_setprio 1
	v_mfma_f32_16x16x32_bf16 v[118:121], v[158:161], v[174:177], v[118:121]
	v_mfma_f32_16x16x32_bf16 v[114:117], v[166:169], v[174:177], v[114:117]
	v_mfma_f32_16x16x32_bf16 v[102:105], v[158:161], v[182:185], v[102:105]
	v_mfma_f32_16x16x32_bf16 v[98:101], v[166:169], v[182:185], v[98:101]
	v_mfma_f32_16x16x32_bf16 v[86:89], v[158:161], v[206:209], v[86:89]
	v_mfma_f32_16x16x32_bf16 v[82:85], v[166:169], v[206:209], v[82:85]
	v_mfma_f32_16x16x32_bf16 v[70:73], v[158:161], v[216:219], v[70:73]
	v_mfma_f32_16x16x32_bf16 v[66:69], v[166:169], v[216:219], v[66:69]
	v_mfma_f32_16x16x32_bf16 v[118:121], v[162:165], v[178:181], v[118:121]
	v_mfma_f32_16x16x32_bf16 v[114:117], v[170:173], v[178:181], v[114:117]
	v_mfma_f32_16x16x32_bf16 v[102:105], v[162:165], v[190:193], v[102:105]
	v_mfma_f32_16x16x32_bf16 v[98:101], v[170:173], v[190:193], v[98:101]
	v_mfma_f32_16x16x32_bf16 v[86:89], v[162:165], v[210:213], v[86:89]
	v_mfma_f32_16x16x32_bf16 v[82:85], v[170:173], v[210:213], v[82:85]
	v_mfma_f32_16x16x32_bf16 v[70:73], v[162:165], v[220:223], v[70:73]
	v_mfma_f32_16x16x32_bf16 v[66:69], v[170:173], v[220:223], v[66:69]
	s_setprio 0
	s_barrier
	s_add_i32 s60, vcc_hi, s86
	v_lshl_add_u64 v[186:187], s[54:55], 0, v[0:1]
	s_mov_b32 m0, s60
	ds_read_b128 v[174:177], v140 offset:16384
	ds_read_b128 v[178:181], v140 offset:17408
	ds_read_b128 v[182:185], v140 offset:18432
	ds_read_b128 v[190:193], v140 offset:19456
	ds_read_b128 v[206:209], v140 offset:20480
	ds_read_b128 v[210:213], v140 offset:21504
	ds_read_b128 v[216:219], v140 offset:22528
	ds_read_b128 v[220:223], v140 offset:23552
	global_load_lds_dwordx4 v[186:187], off
	s_add_i32 m0, s60, 0x2000
	s_add_u32 s60, s54, 0x40000
	v_lshl_add_u64 v[224:225], s[54:55], 0, v[130:131]
	s_addc_u32 s61, s55, 0
	s_add_i32 s78, s78, s86
	global_load_lds_dwordx4 v[224:225], off
	v_lshl_add_u64 v[226:227], s[60:61], 0, v[0:1]
	s_mov_b32 m0, s78
	v_lshl_add_u64 v[228:229], s[56:57], 0, v[130:131]
	global_load_lds_dwordx4 v[226:227], off
	v_lshl_add_u64 v[226:227], s[60:61], 0, v[130:131]
	s_add_i32 m0, s78, 0x2000
	s_nop 0
	global_load_lds_dwordx4 v[226:227], off
	v_lshl_add_u64 v[226:227], s[56:57], 0, v[0:1]
	s_mov_b32 m0, s87
	s_nop 0
	global_load_lds_dwordx4 v[226:227], off
	s_mov_b32 m0, s88
	s_nop 0
	global_load_lds_dwordx4 v[228:229], off
	s_waitcnt vmcnt(8)
	s_waitcnt lgkmcnt(0)
	s_barrier
	s_setprio 1
	s_waitcnt lgkmcnt(0)
	v_mfma_f32_16x16x32_bf16 v[62:65], v[142:145], v[174:177], v[62:65]
	v_mfma_f32_16x16x32_bf16 v[58:61], v[150:153], v[174:177], v[58:61]
	v_mfma_f32_16x16x32_bf16 v[46:49], v[142:145], v[182:185], v[46:49]
	v_mfma_f32_16x16x32_bf16 v[42:45], v[150:153], v[182:185], v[42:45]
	v_mfma_f32_16x16x32_bf16 v[30:33], v[142:145], v[206:209], v[30:33]
	v_mfma_f32_16x16x32_bf16 v[26:29], v[150:153], v[206:209], v[26:29]
	v_mfma_f32_16x16x32_bf16 v[14:17], v[142:145], v[216:219], v[14:17]
	v_mfma_f32_16x16x32_bf16 v[10:13], v[150:153], v[216:219], v[10:13]
	v_mfma_f32_16x16x32_bf16 v[62:65], v[146:149], v[178:181], v[62:65]
	v_mfma_f32_16x16x32_bf16 v[58:61], v[154:157], v[178:181], v[58:61]
	v_mfma_f32_16x16x32_bf16 v[46:49], v[146:149], v[190:193], v[46:49]
	v_mfma_f32_16x16x32_bf16 v[42:45], v[154:157], v[190:193], v[42:45]
	v_mfma_f32_16x16x32_bf16 v[30:33], v[146:149], v[210:213], v[30:33]
	v_mfma_f32_16x16x32_bf16 v[26:29], v[154:157], v[210:213], v[26:29]
	v_mfma_f32_16x16x32_bf16 v[14:17], v[146:149], v[220:223], v[14:17]
	v_mfma_f32_16x16x32_bf16 v[10:13], v[154:157], v[220:223], v[10:13]
	s_setprio 0
	s_setprio 1
	v_mfma_f32_16x16x32_bf16 v[54:57], v[158:161], v[174:177], v[54:57]
	v_mfma_f32_16x16x32_bf16 v[50:53], v[166:169], v[174:177], v[50:53]
	v_mfma_f32_16x16x32_bf16 v[38:41], v[158:161], v[182:185], v[38:41]
	v_mfma_f32_16x16x32_bf16 v[34:37], v[166:169], v[182:185], v[34:37]
	v_mfma_f32_16x16x32_bf16 v[22:25], v[158:161], v[206:209], v[22:25]
	v_mfma_f32_16x16x32_bf16 v[18:21], v[166:169], v[206:209], v[18:21]
	v_mfma_f32_16x16x32_bf16 v[6:9], v[158:161], v[216:219], v[6:9]
	v_mfma_f32_16x16x32_bf16 v[2:5], v[166:169], v[216:219], v[2:5]
	v_mfma_f32_16x16x32_bf16 v[54:57], v[162:165], v[178:181], v[54:57]
	v_mfma_f32_16x16x32_bf16 v[50:53], v[170:173], v[178:181], v[50:53]
	v_mfma_f32_16x16x32_bf16 v[38:41], v[162:165], v[190:193], v[38:41]
	v_mfma_f32_16x16x32_bf16 v[34:37], v[170:173], v[190:193], v[34:37]
	v_mfma_f32_16x16x32_bf16 v[22:25], v[162:165], v[210:213], v[22:25]
	v_mfma_f32_16x16x32_bf16 v[18:21], v[170:173], v[210:213], v[18:21]
	v_mfma_f32_16x16x32_bf16 v[6:9], v[162:165], v[220:223], v[6:9]
	v_mfma_f32_16x16x32_bf16 v[2:5], v[170:173], v[220:223], v[2:5]
	s_setprio 0
	s_barrier
	s_add_i32 s60, 0, 0x18000
	v_add_u32_e32 v141, s60, v133
	s_add_i32 s61, 0, 0x1c000
	ds_read_b128 v[142:145], v141
	ds_read_b128 v[146:149], v141 offset:1024
	ds_read_b128 v[150:153], v141 offset:2048
	ds_read_b128 v[154:157], v141 offset:3072
	v_add_u32_e32 v141, s61, v133
	ds_read_b128 v[158:161], v141
	ds_read_b128 v[162:165], v141 offset:1024
	ds_read_b128 v[166:169], v141 offset:2048
	ds_read_b128 v[170:173], v141 offset:3072
	s_add_u32 s56, s56, 0x40000
	s_addc_u32 s57, s57, 0
	s_mov_b32 m0, s89
	v_lshl_add_u64 v[230:231], s[56:57], 0, v[0:1]
	ds_read_b128 v[174:177], v140 offset:32768
	ds_read_b128 v[178:181], v140 offset:33792
	ds_read_b128 v[182:185], v140 offset:34816
	ds_read_b128 v[190:193], v140 offset:35840
	ds_read_b128 v[206:209], v140 offset:36864
	ds_read_b128 v[210:213], v140 offset:37888
	ds_read_b128 v[216:219], v140 offset:38912
	ds_read_b128 v[220:223], v140 offset:39936
	global_load_lds_dwordx4 v[230:231], off
	v_lshl_add_u64 v[230:231], s[56:57], 0, v[130:131]
	s_mov_b32 m0, s90
	s_nop 0
	global_load_lds_dwordx4 v[230:231], off
	s_waitcnt vmcnt(8)
	s_waitcnt lgkmcnt(0)
	s_barrier
	s_setprio 1
	s_waitcnt lgkmcnt(0)
	v_mfma_f32_16x16x32_bf16 v[126:129], v[142:145], v[174:177], v[126:129]
	v_mfma_f32_16x16x32_bf16 v[122:125], v[150:153], v[174:177], v[122:125]
	v_mfma_f32_16x16x32_bf16 v[110:113], v[142:145], v[182:185], v[110:113]
	v_mfma_f32_16x16x32_bf16 v[106:109], v[150:153], v[182:185], v[106:109]
	v_mfma_f32_16x16x32_bf16 v[94:97], v[142:145], v[206:209], v[94:97]
	v_mfma_f32_16x16x32_bf16 v[90:93], v[150:153], v[206:209], v[90:93]
	v_mfma_f32_16x16x32_bf16 v[78:81], v[142:145], v[216:219], v[78:81]
	v_mfma_f32_16x16x32_bf16 v[74:77], v[150:153], v[216:219], v[74:77]
	v_mfma_f32_16x16x32_bf16 v[126:129], v[146:149], v[178:181], v[126:129]
	v_mfma_f32_16x16x32_bf16 v[122:125], v[154:157], v[178:181], v[122:125]
	v_mfma_f32_16x16x32_bf16 v[110:113], v[146:149], v[190:193], v[110:113]
	v_mfma_f32_16x16x32_bf16 v[106:109], v[154:157], v[190:193], v[106:109]
	v_mfma_f32_16x16x32_bf16 v[94:97], v[146:149], v[210:213], v[94:97]
	v_mfma_f32_16x16x32_bf16 v[90:93], v[154:157], v[210:213], v[90:93]
	v_mfma_f32_16x16x32_bf16 v[78:81], v[146:149], v[220:223], v[78:81]
	v_mfma_f32_16x16x32_bf16 v[74:77], v[154:157], v[220:223], v[74:77]
	s_setprio 0
	s_setprio 1
	v_mfma_f32_16x16x32_bf16 v[118:121], v[158:161], v[174:177], v[118:121]
	v_mfma_f32_16x16x32_bf16 v[114:117], v[166:169], v[174:177], v[114:117]
	v_mfma_f32_16x16x32_bf16 v[102:105], v[158:161], v[182:185], v[102:105]
	v_mfma_f32_16x16x32_bf16 v[98:101], v[166:169], v[182:185], v[98:101]
	v_mfma_f32_16x16x32_bf16 v[86:89], v[158:161], v[206:209], v[86:89]
	v_mfma_f32_16x16x32_bf16 v[82:85], v[166:169], v[206:209], v[82:85]
	v_mfma_f32_16x16x32_bf16 v[70:73], v[158:161], v[216:219], v[70:73]
	v_mfma_f32_16x16x32_bf16 v[66:69], v[166:169], v[216:219], v[66:69]
	v_mfma_f32_16x16x32_bf16 v[118:121], v[162:165], v[178:181], v[118:121]
	v_mfma_f32_16x16x32_bf16 v[114:117], v[170:173], v[178:181], v[114:117]
	v_mfma_f32_16x16x32_bf16 v[102:105], v[162:165], v[190:193], v[102:105]
	v_mfma_f32_16x16x32_bf16 v[98:101], v[170:173], v[190:193], v[98:101]
	v_mfma_f32_16x16x32_bf16 v[86:89], v[162:165], v[210:213], v[86:89]
	v_mfma_f32_16x16x32_bf16 v[82:85], v[170:173], v[210:213], v[82:85]
	v_mfma_f32_16x16x32_bf16 v[70:73], v[162:165], v[220:223], v[70:73]
	v_mfma_f32_16x16x32_bf16 v[66:69], v[170:173], v[220:223], v[66:69]
	s_setprio 0
	s_barrier
	s_add_i32 s56, s60, s86
	v_lshl_add_u64 v[186:187], v[186:187], 0, s[20:21]
	s_mov_b32 m0, s56
	ds_read_b128 v[174:177], v140 offset:49152
	ds_read_b128 v[178:181], v140 offset:50176
	ds_read_b128 v[182:185], v140 offset:51200
	ds_read_b128 v[190:193], v140 offset:52224
	ds_read_b128 v[206:209], v140 offset:53248
	ds_read_b128 v[210:213], v140 offset:54272
	ds_read_b128 v[216:219], v140 offset:55296
	ds_read_b128 v[220:223], v140 offset:56320
	global_load_lds_dwordx4 v[186:187], off
	s_add_i32 m0, s56, 0x2000
	s_add_u32 s54, s54, 0x40080
	v_lshl_add_u64 v[186:187], v[224:225], 0, s[20:21]
	s_addc_u32 s55, s55, 0
	s_add_i32 s56, s61, s86
	global_load_lds_dwordx4 v[186:187], off
	v_lshl_add_u64 v[186:187], s[54:55], 0, v[0:1]
	s_mov_b32 m0, s56
	s_nop 0
	global_load_lds_dwordx4 v[186:187], off
	v_lshl_add_u64 v[186:187], s[54:55], 0, v[130:131]
	s_add_i32 m0, s56, 0x2000
	s_nop 0
	global_load_lds_dwordx4 v[186:187], off
	v_lshl_add_u64 v[186:187], v[226:227], 0, s[20:21]
	s_mov_b32 m0, s92
	s_nop 0
	global_load_lds_dwordx4 v[186:187], off
	v_lshl_add_u64 v[186:187], v[228:229], 0, s[20:21]
	s_mov_b32 m0, s93
	s_nop 0
	global_load_lds_dwordx4 v[186:187], off
	s_waitcnt vmcnt(8)
	s_waitcnt lgkmcnt(0)
	s_barrier
	s_setprio 1
	s_waitcnt lgkmcnt(0)
	v_mfma_f32_16x16x32_bf16 v[62:65], v[142:145], v[174:177], v[62:65]
	v_mfma_f32_16x16x32_bf16 v[58:61], v[150:153], v[174:177], v[58:61]
	v_mfma_f32_16x16x32_bf16 v[46:49], v[142:145], v[182:185], v[46:49]
	v_mfma_f32_16x16x32_bf16 v[42:45], v[150:153], v[182:185], v[42:45]
	v_mfma_f32_16x16x32_bf16 v[30:33], v[142:145], v[206:209], v[30:33]
	v_mfma_f32_16x16x32_bf16 v[26:29], v[150:153], v[206:209], v[26:29]
	v_mfma_f32_16x16x32_bf16 v[14:17], v[142:145], v[216:219], v[14:17]
	v_mfma_f32_16x16x32_bf16 v[10:13], v[150:153], v[216:219], v[10:13]
	v_mfma_f32_16x16x32_bf16 v[62:65], v[146:149], v[178:181], v[62:65]
	v_mfma_f32_16x16x32_bf16 v[58:61], v[154:157], v[178:181], v[58:61]
	v_mfma_f32_16x16x32_bf16 v[46:49], v[146:149], v[190:193], v[46:49]
	v_mfma_f32_16x16x32_bf16 v[42:45], v[154:157], v[190:193], v[42:45]
	v_mfma_f32_16x16x32_bf16 v[30:33], v[146:149], v[210:213], v[30:33]
	v_mfma_f32_16x16x32_bf16 v[26:29], v[154:157], v[210:213], v[26:29]
	v_mfma_f32_16x16x32_bf16 v[14:17], v[146:149], v[220:223], v[14:17]
	v_mfma_f32_16x16x32_bf16 v[10:13], v[154:157], v[220:223], v[10:13]
	s_setprio 0
	s_setprio 1
	v_mfma_f32_16x16x32_bf16 v[54:57], v[158:161], v[174:177], v[54:57]
	v_mfma_f32_16x16x32_bf16 v[50:53], v[166:169], v[174:177], v[50:53]
	v_mfma_f32_16x16x32_bf16 v[38:41], v[158:161], v[182:185], v[38:41]
	v_mfma_f32_16x16x32_bf16 v[34:37], v[166:169], v[182:185], v[34:37]
	v_mfma_f32_16x16x32_bf16 v[22:25], v[158:161], v[206:209], v[22:25]
	v_mfma_f32_16x16x32_bf16 v[18:21], v[166:169], v[206:209], v[18:21]
	v_mfma_f32_16x16x32_bf16 v[6:9], v[158:161], v[216:219], v[6:9]
	v_mfma_f32_16x16x32_bf16 v[2:5], v[166:169], v[216:219], v[2:5]
	v_mfma_f32_16x16x32_bf16 v[54:57], v[162:165], v[178:181], v[54:57]
	v_mfma_f32_16x16x32_bf16 v[50:53], v[170:173], v[178:181], v[50:53]
	v_mfma_f32_16x16x32_bf16 v[38:41], v[162:165], v[190:193], v[38:41]
	v_mfma_f32_16x16x32_bf16 v[34:37], v[170:173], v[190:193], v[34:37]
	v_mfma_f32_16x16x32_bf16 v[22:25], v[162:165], v[210:213], v[22:25]
	v_mfma_f32_16x16x32_bf16 v[18:21], v[170:173], v[210:213], v[18:21]
	v_mfma_f32_16x16x32_bf16 v[6:9], v[162:165], v[220:223], v[6:9]
	v_mfma_f32_16x16x32_bf16 v[2:5], v[170:173], v[220:223], v[2:5]
	s_setprio 0
	s_barrier
	s_add_i32 vcc_lo, vcc_lo, 2
	s_add_u32 s52, s52, 0x100
	s_addc_u32 s53, s53, 0
	s_cmp_gt_u32 vcc_lo, 13
	s_cbranch_scc0 .LBB0_950
	s_cmpk_lt_u32 s85, 0x100
	s_cbranch_scc0 .LBB0_953
	s_barrier

.LBB0_1005:
	s_add_u32 s54, s93, s52
	s_addc_u32 s55, s94, s53
	s_add_u32 s54, s54, 0x8a00100
	s_addc_u32 s55, s55, 0
	s_add_u32 s60, s95, s52
	s_addc_u32 s61, s96, s53
	s_add_i32 vcc_lo, 0, 0x10000
	s_cmpk_eq_i32 s52, 0x700
	s_cselect_b32 s57, s7, s55
	s_cselect_b32 s56, s6, s54
	v_add_u32_e32 v143, vcc_lo, v141
	s_cselect_b32 s55, s5, s61
	s_cselect_b32 s54, s4, s60
	s_add_i32 s60, 0, 0x14000
	ds_read_b128 v[144:147], v143
	ds_read_b128 v[148:151], v143 offset:1024
	ds_read_b128 v[152:155], v143 offset:2048
	ds_read_b128 v[160:163], v143 offset:3072
	v_add_u32_e32 v143, s60, v141
	ds_read_b128 v[164:167], v143
	ds_read_b128 v[168:171], v143 offset:1024
	ds_read_b128 v[172:175], v143 offset:2048
	ds_read_b128 v[176:179], v143 offset:3072
	v_lshl_add_u64 v[156:157], v[136:137], 0, s[52:53]
	s_add_i32 m0, s87, 0xc000
	ds_read_b128 v[180:183], v142
	ds_read_b128 v[184:187], v142 offset:1024
	ds_read_b128 v[190:193], v142 offset:2048
	ds_read_b128 v[206:209], v142 offset:3072
	ds_read_b128 v[210:213], v142 offset:4096
	ds_read_b128 v[216:219], v142 offset:5120
	ds_read_b128 v[220:223], v142 offset:6144
	ds_read_b128 v[224:227], v142 offset:7168
	global_load_lds_dwordx4 v[156:157], off
	v_lshl_add_u64 v[156:157], v[138:139], 0, s[52:53]
	s_add_i32 m0, s87, 0xe000
	s_nop 0
	global_load_lds_dwordx4 v[156:157], off
	s_waitcnt vmcnt(8)
	s_waitcnt lgkmcnt(0)
	s_barrier
	s_setprio 1
	s_waitcnt lgkmcnt(0)
	v_mfma_f32_16x16x32_bf16 v[126:129], v[144:147], v[180:183], v[126:129]
	v_mfma_f32_16x16x32_bf16 v[122:125], v[152:155], v[180:183], v[122:125]
	v_mfma_f32_16x16x32_bf16 v[110:113], v[144:147], v[190:193], v[110:113]
	v_mfma_f32_16x16x32_bf16 v[106:109], v[152:155], v[190:193], v[106:109]
	v_mfma_f32_16x16x32_bf16 v[94:97], v[144:147], v[210:213], v[94:97]
	v_mfma_f32_16x16x32_bf16 v[90:93], v[152:155], v[210:213], v[90:93]
	v_mfma_f32_16x16x32_bf16 v[78:81], v[144:147], v[220:223], v[78:81]
	v_mfma_f32_16x16x32_bf16 v[74:77], v[152:155], v[220:223], v[74:77]
	v_mfma_f32_16x16x32_bf16 v[126:129], v[148:151], v[184:187], v[126:129]
	v_mfma_f32_16x16x32_bf16 v[122:125], v[160:163], v[184:187], v[122:125]
	v_mfma_f32_16x16x32_bf16 v[110:113], v[148:151], v[206:209], v[110:113]
	v_mfma_f32_16x16x32_bf16 v[106:109], v[160:163], v[206:209], v[106:109]
	v_mfma_f32_16x16x32_bf16 v[94:97], v[148:151], v[216:219], v[94:97]
	v_mfma_f32_16x16x32_bf16 v[90:93], v[160:163], v[216:219], v[90:93]
	v_mfma_f32_16x16x32_bf16 v[78:81], v[148:151], v[224:227], v[78:81]
	v_mfma_f32_16x16x32_bf16 v[74:77], v[160:163], v[224:227], v[74:77]
	s_setprio 0
	s_setprio 1
	v_mfma_f32_16x16x32_bf16 v[118:121], v[164:167], v[180:183], v[118:121]
	v_mfma_f32_16x16x32_bf16 v[114:117], v[172:175], v[180:183], v[114:117]
	v_mfma_f32_16x16x32_bf16 v[102:105], v[164:167], v[190:193], v[102:105]
	v_mfma_f32_16x16x32_bf16 v[98:101], v[172:175], v[190:193], v[98:101]
	v_mfma_f32_16x16x32_bf16 v[86:89], v[164:167], v[210:213], v[86:89]
	v_mfma_f32_16x16x32_bf16 v[82:85], v[172:175], v[210:213], v[82:85]
	v_mfma_f32_16x16x32_bf16 v[70:73], v[164:167], v[220:223], v[70:73]
	v_mfma_f32_16x16x32_bf16 v[66:69], v[172:175], v[220:223], v[66:69]
	v_mfma_f32_16x16x32_bf16 v[118:121], v[168:171], v[184:187], v[118:121]
	v_mfma_f32_16x16x32_bf16 v[114:117], v[176:179], v[184:187], v[114:117]
	v_mfma_f32_16x16x32_bf16 v[102:105], v[168:171], v[206:209], v[102:105]
	v_mfma_f32_16x16x32_bf16 v[98:101], v[176:179], v[206:209], v[98:101]
	v_mfma_f32_16x16x32_bf16 v[86:89], v[168:171], v[216:219], v[86:89]
	v_mfma_f32_16x16x32_bf16 v[82:85], v[176:179], v[216:219], v[82:85]
	v_mfma_f32_16x16x32_bf16 v[70:73], v[168:171], v[224:227], v[70:73]
	v_mfma_f32_16x16x32_bf16 v[66:69], v[176:179], v[224:227], v[66:69]
	s_setprio 0
	s_barrier
	s_add_i32 s61, vcc_lo, s86
	v_lshl_add_u64 v[156:157], s[54:55], 0, v[0:1]
	s_mov_b32 m0, s61
	ds_read_b128 v[180:183], v142 offset:16384
	ds_read_b128 v[184:187], v142 offset:17408
	ds_read_b128 v[190:193], v142 offset:18432
	ds_read_b128 v[206:209], v142 offset:19456
	ds_read_b128 v[210:213], v142 offset:20480
	ds_read_b128 v[216:219], v142 offset:21504
	ds_read_b128 v[220:223], v142 offset:22528
	ds_read_b128 v[224:227], v142 offset:23552
	global_load_lds_dwordx4 v[156:157], off
	s_add_i32 m0, s61, 0x2000
	s_add_u32 vcc_lo, s54, 0x40000
	v_lshl_add_u64 v[228:229], s[54:55], 0, v[134:135]
	s_addc_u32 vcc_hi, s55, 0
	s_add_i32 s60, s60, s86
	global_load_lds_dwordx4 v[228:229], off
	v_lshl_add_u64 v[230:231], vcc, 0, v[0:1]
	s_mov_b32 m0, s60
	v_lshl_add_u64 v[232:233], s[56:57], 0, v[132:133]
	global_load_lds_dwordx4 v[230:231], off
	v_lshl_add_u64 v[230:231], vcc, 0, v[134:135]
	s_add_i32 m0, s60, 0x2000
	s_nop 0
	global_load_lds_dwordx4 v[230:231], off
	v_lshl_add_u64 v[230:231], s[56:57], 0, v[130:131]
	s_mov_b32 m0, s87
	s_nop 0
	global_load_lds_dwordx4 v[230:231], off
	s_mov_b32 m0, s88
	s_nop 0
	global_load_lds_dwordx4 v[232:233], off
	s_waitcnt vmcnt(8)
	s_waitcnt lgkmcnt(0)
	s_barrier
	s_setprio 1
	s_waitcnt lgkmcnt(0)
	v_mfma_f32_16x16x32_bf16 v[62:65], v[144:147], v[180:183], v[62:65]
	v_mfma_f32_16x16x32_bf16 v[58:61], v[152:155], v[180:183], v[58:61]
	v_mfma_f32_16x16x32_bf16 v[46:49], v[144:147], v[190:193], v[46:49]
	v_mfma_f32_16x16x32_bf16 v[42:45], v[152:155], v[190:193], v[42:45]
	v_mfma_f32_16x16x32_bf16 v[30:33], v[144:147], v[210:213], v[30:33]
	v_mfma_f32_16x16x32_bf16 v[26:29], v[152:155], v[210:213], v[26:29]
	v_mfma_f32_16x16x32_bf16 v[14:17], v[144:147], v[220:223], v[14:17]
	v_mfma_f32_16x16x32_bf16 v[10:13], v[152:155], v[220:223], v[10:13]
	v_mfma_f32_16x16x32_bf16 v[62:65], v[148:151], v[184:187], v[62:65]
	v_mfma_f32_16x16x32_bf16 v[58:61], v[160:163], v[184:187], v[58:61]
	v_mfma_f32_16x16x32_bf16 v[46:49], v[148:151], v[206:209], v[46:49]
	v_mfma_f32_16x16x32_bf16 v[42:45], v[160:163], v[206:209], v[42:45]
	v_mfma_f32_16x16x32_bf16 v[30:33], v[148:151], v[216:219], v[30:33]
	v_mfma_f32_16x16x32_bf16 v[26:29], v[160:163], v[216:219], v[26:29]
	v_mfma_f32_16x16x32_bf16 v[14:17], v[148:151], v[224:227], v[14:17]
	v_mfma_f32_16x16x32_bf16 v[10:13], v[160:163], v[224:227], v[10:13]
	s_setprio 0
	s_setprio 1
	v_mfma_f32_16x16x32_bf16 v[54:57], v[164:167], v[180:183], v[54:57]
	v_mfma_f32_16x16x32_bf16 v[50:53], v[172:175], v[180:183], v[50:53]
	v_mfma_f32_16x16x32_bf16 v[38:41], v[164:167], v[190:193], v[38:41]
	v_mfma_f32_16x16x32_bf16 v[34:37], v[172:175], v[190:193], v[34:37]
	v_mfma_f32_16x16x32_bf16 v[22:25], v[164:167], v[210:213], v[22:25]
	v_mfma_f32_16x16x32_bf16 v[18:21], v[172:175], v[210:213], v[18:21]
	v_mfma_f32_16x16x32_bf16 v[6:9], v[164:167], v[220:223], v[6:9]
	v_mfma_f32_16x16x32_bf16 v[2:5], v[172:175], v[220:223], v[2:5]
	v_mfma_f32_16x16x32_bf16 v[54:57], v[168:171], v[184:187], v[54:57]
	v_mfma_f32_16x16x32_bf16 v[50:53], v[176:179], v[184:187], v[50:53]
	v_mfma_f32_16x16x32_bf16 v[38:41], v[168:171], v[206:209], v[38:41]
	v_mfma_f32_16x16x32_bf16 v[34:37], v[176:179], v[206:209], v[34:37]
	v_mfma_f32_16x16x32_bf16 v[22:25], v[168:171], v[216:219], v[22:25]
	v_mfma_f32_16x16x32_bf16 v[18:21], v[176:179], v[216:219], v[18:21]
	v_mfma_f32_16x16x32_bf16 v[6:9], v[168:171], v[224:227], v[6:9]
	v_mfma_f32_16x16x32_bf16 v[2:5], v[176:179], v[224:227], v[2:5]
	s_setprio 0
	s_barrier
	s_add_i32 s60, 0, 0x18000
	v_add_u32_e32 v143, s60, v141
	s_add_i32 s61, 0, 0x1c000
	ds_read_b128 v[144:147], v143
	ds_read_b128 v[148:151], v143 offset:1024
	ds_read_b128 v[152:155], v143 offset:2048
	ds_read_b128 v[160:163], v143 offset:3072
	v_add_u32_e32 v143, s61, v141
	ds_read_b128 v[164:167], v143
	ds_read_b128 v[168:171], v143 offset:1024
	ds_read_b128 v[172:175], v143 offset:2048
	ds_read_b128 v[176:179], v143 offset:3072
	s_add_u32 s56, s56, 0x40000
	s_addc_u32 s57, s57, 0
	s_mov_b32 m0, s89
	v_lshl_add_u64 v[234:235], s[56:57], 0, v[130:131]
	ds_read_b128 v[180:183], v142 offset:32768
	ds_read_b128 v[184:187], v142 offset:33792
	ds_read_b128 v[190:193], v142 offset:34816
	ds_read_b128 v[206:209], v142 offset:35840
	ds_read_b128 v[210:213], v142 offset:36864
	ds_read_b128 v[216:219], v142 offset:37888
	ds_read_b128 v[220:223], v142 offset:38912
	ds_read_b128 v[224:227], v142 offset:39936
	global_load_lds_dwordx4 v[234:235], off
	v_lshl_add_u64 v[234:235], s[56:57], 0, v[132:133]
	s_mov_b32 m0, s90
	s_nop 0
	global_load_lds_dwordx4 v[234:235], off
	s_waitcnt vmcnt(8)
	s_waitcnt lgkmcnt(0)
	s_barrier
	s_setprio 1
	s_waitcnt lgkmcnt(0)
	v_mfma_f32_16x16x32_bf16 v[126:129], v[144:147], v[180:183], v[126:129]
	v_mfma_f32_16x16x32_bf16 v[122:125], v[152:155], v[180:183], v[122:125]
	v_mfma_f32_16x16x32_bf16 v[110:113], v[144:147], v[190:193], v[110:113]
	v_mfma_f32_16x16x32_bf16 v[106:109], v[152:155], v[190:193], v[106:109]
	v_mfma_f32_16x16x32_bf16 v[94:97], v[144:147], v[210:213], v[94:97]
	v_mfma_f32_16x16x32_bf16 v[90:93], v[152:155], v[210:213], v[90:93]
	v_mfma_f32_16x16x32_bf16 v[78:81], v[144:147], v[220:223], v[78:81]
	v_mfma_f32_16x16x32_bf16 v[74:77], v[152:155], v[220:223], v[74:77]
	v_mfma_f32_16x16x32_bf16 v[126:129], v[148:151], v[184:187], v[126:129]
	v_mfma_f32_16x16x32_bf16 v[122:125], v[160:163], v[184:187], v[122:125]
	v_mfma_f32_16x16x32_bf16 v[110:113], v[148:151], v[206:209], v[110:113]
	v_mfma_f32_16x16x32_bf16 v[106:109], v[160:163], v[206:209], v[106:109]
	v_mfma_f32_16x16x32_bf16 v[94:97], v[148:151], v[216:219], v[94:97]
	v_mfma_f32_16x16x32_bf16 v[90:93], v[160:163], v[216:219], v[90:93]
	v_mfma_f32_16x16x32_bf16 v[78:81], v[148:151], v[224:227], v[78:81]
	v_mfma_f32_16x16x32_bf16 v[74:77], v[160:163], v[224:227], v[74:77]
	s_setprio 0
	s_setprio 1
	v_mfma_f32_16x16x32_bf16 v[118:121], v[164:167], v[180:183], v[118:121]
	v_mfma_f32_16x16x32_bf16 v[114:117], v[172:175], v[180:183], v[114:117]
	v_mfma_f32_16x16x32_bf16 v[102:105], v[164:167], v[190:193], v[102:105]
	v_mfma_f32_16x16x32_bf16 v[98:101], v[172:175], v[190:193], v[98:101]
	v_mfma_f32_16x16x32_bf16 v[86:89], v[164:167], v[210:213], v[86:89]
	v_mfma_f32_16x16x32_bf16 v[82:85], v[172:175], v[210:213], v[82:85]
	v_mfma_f32_16x16x32_bf16 v[70:73], v[164:167], v[220:223], v[70:73]
	v_mfma_f32_16x16x32_bf16 v[66:69], v[172:175], v[220:223], v[66:69]
	v_mfma_f32_16x16x32_bf16 v[118:121], v[168:171], v[184:187], v[118:121]
	v_mfma_f32_16x16x32_bf16 v[114:117], v[176:179], v[184:187], v[114:117]
	v_mfma_f32_16x16x32_bf16 v[102:105], v[168:171], v[206:209], v[102:105]
	v_mfma_f32_16x16x32_bf16 v[98:101], v[176:179], v[206:209], v[98:101]
	v_mfma_f32_16x16x32_bf16 v[86:89], v[168:171], v[216:219], v[86:89]
	v_mfma_f32_16x16x32_bf16 v[82:85], v[176:179], v[216:219], v[82:85]
	v_mfma_f32_16x16x32_bf16 v[70:73], v[168:171], v[224:227], v[70:73]
	v_mfma_f32_16x16x32_bf16 v[66:69], v[176:179], v[224:227], v[66:69]
	s_setprio 0
	s_barrier
	s_add_i32 s56, s60, s86
	v_lshl_add_u64 v[156:157], v[156:157], 0, s[20:21]
	s_mov_b32 m0, s56
	ds_read_b128 v[180:183], v142 offset:49152
	ds_read_b128 v[184:187], v142 offset:50176
	ds_read_b128 v[190:193], v142 offset:51200
	ds_read_b128 v[206:209], v142 offset:52224
	ds_read_b128 v[210:213], v142 offset:53248
	ds_read_b128 v[216:219], v142 offset:54272
	ds_read_b128 v[220:223], v142 offset:55296
	ds_read_b128 v[224:227], v142 offset:56320
	global_load_lds_dwordx4 v[156:157], off
	s_add_i32 m0, s56, 0x2000
	s_add_u32 s54, s54, 0x40080
	v_lshl_add_u64 v[156:157], v[228:229], 0, s[20:21]
	s_addc_u32 s55, s55, 0
	s_add_i32 s56, s61, s86
	global_load_lds_dwordx4 v[156:157], off
	v_lshl_add_u64 v[156:157], s[54:55], 0, v[0:1]
	s_mov_b32 m0, s56
	s_nop 0
	global_load_lds_dwordx4 v[156:157], off
	v_lshl_add_u64 v[156:157], s[54:55], 0, v[134:135]
	s_add_i32 m0, s56, 0x2000
	s_nop 0
	global_load_lds_dwordx4 v[156:157], off
	v_lshl_add_u64 v[156:157], v[230:231], 0, s[20:21]
	s_mov_b32 m0, s91
	s_nop 0
	global_load_lds_dwordx4 v[156:157], off
	v_lshl_add_u64 v[156:157], v[232:233], 0, s[20:21]
	s_mov_b32 m0, s92
	s_nop 0
	global_load_lds_dwordx4 v[156:157], off
	s_waitcnt vmcnt(8)
	s_waitcnt lgkmcnt(0)
	s_barrier
	s_setprio 1
	s_waitcnt lgkmcnt(0)
	v_mfma_f32_16x16x32_bf16 v[62:65], v[144:147], v[180:183], v[62:65]
	v_mfma_f32_16x16x32_bf16 v[58:61], v[152:155], v[180:183], v[58:61]
	v_mfma_f32_16x16x32_bf16 v[46:49], v[144:147], v[190:193], v[46:49]
	v_mfma_f32_16x16x32_bf16 v[42:45], v[152:155], v[190:193], v[42:45]
	v_mfma_f32_16x16x32_bf16 v[30:33], v[144:147], v[210:213], v[30:33]
	v_mfma_f32_16x16x32_bf16 v[26:29], v[152:155], v[210:213], v[26:29]
	v_mfma_f32_16x16x32_bf16 v[14:17], v[144:147], v[220:223], v[14:17]
	v_mfma_f32_16x16x32_bf16 v[10:13], v[152:155], v[220:223], v[10:13]
	v_mfma_f32_16x16x32_bf16 v[62:65], v[148:151], v[184:187], v[62:65]
	v_mfma_f32_16x16x32_bf16 v[58:61], v[160:163], v[184:187], v[58:61]
	v_mfma_f32_16x16x32_bf16 v[46:49], v[148:151], v[206:209], v[46:49]
	v_mfma_f32_16x16x32_bf16 v[42:45], v[160:163], v[206:209], v[42:45]
	v_mfma_f32_16x16x32_bf16 v[30:33], v[148:151], v[216:219], v[30:33]
	v_mfma_f32_16x16x32_bf16 v[26:29], v[160:163], v[216:219], v[26:29]
	v_mfma_f32_16x16x32_bf16 v[14:17], v[148:151], v[224:227], v[14:17]
	v_mfma_f32_16x16x32_bf16 v[10:13], v[160:163], v[224:227], v[10:13]
	s_setprio 0
	s_setprio 1
	v_mfma_f32_16x16x32_bf16 v[54:57], v[164:167], v[180:183], v[54:57]
	v_mfma_f32_16x16x32_bf16 v[50:53], v[172:175], v[180:183], v[50:53]
	v_mfma_f32_16x16x32_bf16 v[38:41], v[164:167], v[190:193], v[38:41]
	v_mfma_f32_16x16x32_bf16 v[34:37], v[172:175], v[190:193], v[34:37]
	v_mfma_f32_16x16x32_bf16 v[22:25], v[164:167], v[210:213], v[22:25]
	v_mfma_f32_16x16x32_bf16 v[18:21], v[172:175], v[210:213], v[18:21]
	v_mfma_f32_16x16x32_bf16 v[6:9], v[164:167], v[220:223], v[6:9]
	v_mfma_f32_16x16x32_bf16 v[2:5], v[172:175], v[220:223], v[2:5]
	v_mfma_f32_16x16x32_bf16 v[54:57], v[168:171], v[184:187], v[54:57]
	v_mfma_f32_16x16x32_bf16 v[50:53], v[176:179], v[184:187], v[50:53]
	v_mfma_f32_16x16x32_bf16 v[38:41], v[168:171], v[206:209], v[38:41]
	v_mfma_f32_16x16x32_bf16 v[34:37], v[176:179], v[206:209], v[34:37]
	v_mfma_f32_16x16x32_bf16 v[22:25], v[168:171], v[216:219], v[22:25]
	v_mfma_f32_16x16x32_bf16 v[18:21], v[176:179], v[216:219], v[18:21]
	v_mfma_f32_16x16x32_bf16 v[6:9], v[168:171], v[224:227], v[6:9]
	v_mfma_f32_16x16x32_bf16 v[2:5], v[176:179], v[224:227], v[2:5]
	s_setprio 0
	s_barrier
	s_add_i32 s97, s97, 2
	s_add_u32 s52, s52, 0x100
	s_addc_u32 s53, s53, 0
	s_cmp_gt_u32 s97, 13
	s_cbranch_scc0 .LBB0_1005
	s_cmpk_lt_u32 s85, 0x100
	s_cbranch_scc0 .LBB0_1008
	s_barrier

.LBB0_1042:
	v_lshlrev_b32_e32 v0, 1, v34
	v_and_b32_e32 v212, 32, v0
	v_lshlrev_b32_e32 v0, 4, v34
	v_and_b32_e32 v0, 0xc0, v0
	v_lshl_or_b32 v210, v208, 8, v0
	v_add_u32_e32 v0, 0, v212
	v_add3_u32 v219, v0, v209, v210
	s_lshl_b32 s98, s56, 8
	s_add_i32 s98, s98, 0x14c00
	v_lshl_add_u32 v0, v215, 2, s98
	ds_read_b32 v0, v0
	s_and_b32 s5, s5, 0x3fffffc0
	s_lshl_b32 s5, s5, 2
	s_add_i32 s85, s5, 0
	s_waitcnt vmcnt(0) lgkmcnt(0)
	s_barrier
	s_cmp_lg_u32 0, -1
	s_mov_b32 s52, 1
	s_mov_b32 s57, 0
	v_lshl_add_u32 v213, v207, 2, s85
	s_nop 0
	s_nop 0
	s_nop 1
	s_nop 0
	v_sub_f32_e32 v2, v2, v0
	v_sub_f32_e32 v3, v3, v0
	v_add_f32_e32 v220, v1, v0
	v_sub_f32_e32 v18, v18, v0
	v_sub_f32_e32 v19, v19, v0
	v_sub_f32_e32 v4, v4, v0
	s_nop 0
	v_exp_f32_e32 v64, v2
	v_exp_f32_e32 v65, v3
	v_lshl_add_u64 v[2:3], v[190:191], 0, s[24:25]
	s_mov_b32 s5, m0
	s_mov_b32 m0, s86
	s_nop 0
	global_load_lds_dwordx4 v[2:3], off
	s_mov_b32 m0, s5
	s_cselect_b32 s5, 0, 0
	s_add_i32 s4, s5, s4
	v_lshl_add_u64 v[2:3], v[192:193], 0, s[22:23]
	s_add_i32 s4, s4, 0x8000
	s_mov_b32 s5, m0
	s_mov_b32 m0, s4
	s_nop 0
	global_load_lds_dwordx4 v[2:3], off
	s_mov_b32 m0, s5
	ds_read_b128 v[172:175], v218 offset:8192
	ds_read_b128 v[168:171], v218 offset:8704
	ds_read_b128 v[164:167], v218 offset:10240
	ds_read_b128 v[160:163], v218 offset:10752
	ds_read_b128 v[156:159], v218 offset:12288
	ds_read_b128 v[152:155], v218 offset:12800
	ds_read_b128 v[148:151], v218 offset:14336
	ds_read_b128 v[144:147], v218 offset:14848
	v_sub_f32_e32 v20, v20, v0
	v_sub_f32_e32 v5, v5, v0
	v_sub_f32_e32 v21, v21, v0
	v_sub_f32_e32 v6, v6, v0
	v_sub_f32_e32 v22, v22, v0
	v_sub_f32_e32 v7, v7, v0
	v_sub_f32_e32 v23, v23, v0
	v_sub_f32_e32 v8, v8, v0
	v_sub_f32_e32 v24, v24, v0
	v_sub_f32_e32 v9, v9, v0
	v_sub_f32_e32 v25, v25, v0
	v_sub_f32_e32 v10, v10, v0
	v_sub_f32_e32 v26, v26, v0
	v_sub_f32_e32 v11, v11, v0
	v_sub_f32_e32 v27, v27, v0
	v_sub_f32_e32 v12, v12, v0
	v_sub_f32_e32 v28, v28, v0
	v_sub_f32_e32 v13, v13, v0
	v_sub_f32_e32 v29, v29, v0
	v_sub_f32_e32 v14, v14, v0
	v_sub_f32_e32 v30, v30, v0
	v_sub_f32_e32 v15, v15, v0
	v_sub_f32_e32 v31, v31, v0
	v_sub_f32_e32 v16, v16, v0
	v_sub_f32_e32 v32, v32, v0
	v_sub_f32_e32 v17, v17, v0
	v_sub_f32_e32 v0, v33, v0
	v_exp_f32_e32 v66, v4
	v_exp_f32_e32 v67, v5
	v_exp_f32_e32 v68, v6
	v_exp_f32_e32 v69, v7
	v_exp_f32_e32 v70, v8
	v_exp_f32_e32 v71, v9
	v_exp_f32_e32 v72, v10
	v_exp_f32_e32 v73, v11
	v_exp_f32_e32 v74, v12
	v_exp_f32_e32 v75, v13
	v_exp_f32_e32 v76, v14
	v_exp_f32_e32 v77, v15
	v_exp_f32_e32 v78, v16
	v_exp_f32_e32 v79, v17
	v_exp_f32_e32 v48, v18
	v_exp_f32_e32 v49, v19
	v_exp_f32_e32 v50, v20
	v_exp_f32_e32 v51, v21
	v_exp_f32_e32 v52, v22
	v_exp_f32_e32 v53, v23
	v_exp_f32_e32 v54, v24
	v_exp_f32_e32 v55, v25
	v_exp_f32_e32 v56, v26
	v_exp_f32_e32 v57, v27
	v_exp_f32_e32 v58, v28
	v_exp_f32_e32 v59, v29
	v_exp_f32_e32 v60, v30
	v_exp_f32_e32 v61, v31
	v_exp_f32_e32 v62, v32
	v_exp_f32_e32 v63, v0
	s_waitcnt vmcnt(2) lgkmcnt(0)
	s_barrier
	s_cmp_lt_i32 s88, 7
	v_cmp_gt_u32_e64 s[4:5], 32, v205
	s_cbranch_scc1 .LBB0_1058
	v_mov_b32_e32 v14, v1
	v_mov_b32_e32 v15, v1
	s_mov_b64 s[52:53], 0xa0000
	v_mov_b32_e32 v0, v1
	v_mov_b32_e32 v2, v1
	v_mov_b32_e32 v3, v1
	v_mov_b32_e32 v4, v1
	v_mov_b32_e32 v5, v1
	v_mov_b32_e32 v6, v1
	v_mov_b32_e32 v7, v1
	v_mov_b32_e32 v8, v1
	v_mov_b32_e32 v9, v1
	v_mov_b32_e32 v10, v1
	v_mov_b32_e32 v11, v1
	v_mov_b32_e32 v12, v1
	v_mov_b32_e32 v13, v1
	v_mov_b64_e32 v[46:47], v[14:15]
	v_mov_b64_e32 v[30:31], v[14:15]
	v_lshl_add_u64 v[180:181], v[192:193], 0, s[24:25]
	v_lshl_add_u64 v[182:183], v[190:191], 0, s[52:53]
	v_add3_u32 v185, v184, v217, s80
	s_mov_b32 s52, 0
	s_movk_i32 s57, 0x4000
	s_movk_i32 s59, 0x2000
	v_mov_b32_e32 v221, 0
	s_mov_b32 s58, 6
	v_mov_b64_e32 v[44:45], v[12:13]
	v_mov_b64_e32 v[42:43], v[10:11]
	v_mov_b64_e32 v[40:41], v[8:9]
	v_mov_b64_e32 v[38:39], v[6:7]
	v_mov_b64_e32 v[36:37], v[4:5]
	v_mov_b64_e32 v[34:35], v[2:3]
	v_mov_b64_e32 v[32:33], v[0:1]
	v_mov_b64_e32 v[28:29], v[12:13]
	v_mov_b64_e32 v[26:27], v[10:11]
	v_mov_b64_e32 v[24:25], v[8:9]
	v_mov_b64_e32 v[22:23], v[6:7]
	v_mov_b64_e32 v[20:21], v[4:5]
	v_mov_b64_e32 v[18:19], v[2:3]
	v_mov_b64_e32 v[16:17], v[0:1]
.LBB0_1044:
	ds_read_b128 v[2:5], v185
	ds_read_b128 v[6:9], v185 offset:32
	ds_read_b128 v[10:13], v185 offset:64
	ds_read_b128 v[80:83], v185 offset:96
	ds_read_b128 v[176:179], v185 offset:128
	ds_read_b128 v[84:87], v185 offset:160
	ds_read_b128 v[88:91], v185 offset:192
	ds_read_b128 v[92:95], v185 offset:224
	s_waitcnt lgkmcnt(4)
	v_sub_f32_e32 v111, v83, v220
	v_sub_f32_e32 v110, v82, v220
	v_sub_f32_e32 v109, v81, v220
	v_sub_f32_e32 v108, v80, v220
	v_sub_f32_e32 v107, v13, v220
	v_sub_f32_e32 v106, v12, v220
	v_sub_f32_e32 v105, v11, v220
	v_sub_f32_e32 v104, v10, v220
	v_sub_f32_e32 v103, v9, v220
	v_sub_f32_e32 v102, v8, v220
	v_sub_f32_e32 v101, v7, v220
	v_sub_f32_e32 v100, v6, v220
	v_sub_f32_e32 v99, v5, v220
	v_sub_f32_e32 v98, v4, v220
	v_sub_f32_e32 v97, v3, v220
	v_sub_f32_e32 v96, v2, v220
	s_waitcnt lgkmcnt(0)
	v_sub_f32_e32 v95, v95, v220
	v_sub_f32_e32 v94, v94, v220
	v_sub_f32_e32 v93, v93, v220
	v_sub_f32_e32 v92, v92, v220
	v_sub_f32_e32 v91, v91, v220
	v_sub_f32_e32 v90, v90, v220
	v_sub_f32_e32 v89, v89, v220
	v_sub_f32_e32 v88, v88, v220
	v_sub_f32_e32 v87, v87, v220
	v_sub_f32_e32 v86, v86, v220
	v_sub_f32_e32 v85, v85, v220
	v_sub_f32_e32 v84, v84, v220
	v_sub_f32_e32 v83, v179, v220
	v_sub_f32_e32 v82, v178, v220
	v_sub_f32_e32 v81, v177, v220
	v_sub_f32_e32 v80, v176, v220
	v_add_u32_e32 v0, s52, v219
	ds_read_b64_tr_b16 v[176:177], v0 offset:24576
	ds_read_b64_tr_b16 v[178:179], v0 offset:25088
	v_mfma_f32_32x32x16_bf16 v[96:111], v[172:175], v[128:131], v[96:111]
	v_add_f32_e32 v2, v64, v65
	v_add_f32_e32 v2, v66, v2
	v_add_f32_e32 v2, v67, v2
	v_add_f32_e32 v2, v68, v2
	v_add_f32_e32 v2, v69, v2
	v_cvt_pk_bf16_f32 v140, v64, v65
	v_cvt_pk_bf16_f32 v141, v66, v67
	ds_read_b64_tr_b16 v[172:173], v0 offset:28672
	ds_read_b64_tr_b16 v[174:175], v0 offset:29184
	v_mfma_f32_32x32x16_bf16 v[80:95], v[168:171], v[128:131], v[80:95]
	v_add_f32_e32 v2, v70, v2
	v_add_f32_e32 v2, v71, v2
	v_add_f32_e32 v2, v72, v2
	v_add_f32_e32 v2, v73, v2
	v_cvt_pk_bf16_f32 v142, v68, v69
	v_cvt_pk_bf16_f32 v143, v70, v71
	ds_read_b64_tr_b16 v[10:11], v0 offset:25600
	ds_read_b64_tr_b16 v[12:13], v0 offset:26112
	v_mfma_f32_32x32x16_bf16 v[96:111], v[164:167], v[120:123], v[96:111]
	v_add_f32_e32 v2, v74, v2
	v_add_f32_e32 v2, v75, v2
	v_add_f32_e32 v2, v76, v2
	v_add_f32_e32 v2, v77, v2
	v_cvt_pk_bf16_f32 v136, v72, v73
	v_cvt_pk_bf16_f32 v137, v74, v75
	ds_read_b64_tr_b16 v[6:7], v0 offset:29696
	ds_read_b64_tr_b16 v[8:9], v0 offset:30208
	v_mfma_f32_32x32x16_bf16 v[80:95], v[160:163], v[120:123], v[80:95]
	v_add_f32_e32 v2, v78, v2
	v_add_f32_e32 v2, v79, v2
	v_add_f32_e32 v2, v48, v2
	v_add_f32_e32 v14, v49, v2
	v_cvt_pk_bf16_f32 v138, v76, v77
	v_cvt_pk_bf16_f32 v139, v78, v79
	ds_read_b64_tr_b16 v[2:3], v0 offset:26624
	ds_read_b64_tr_b16 v[4:5], v0 offset:27136
	v_mfma_f32_32x32x16_bf16 v[96:111], v[156:159], v[116:119], v[96:111]
	v_add_f32_e32 v14, v50, v14
	v_add_f32_e32 v14, v51, v14
	v_add_f32_e32 v14, v52, v14
	v_add_f32_e32 v14, v53, v14
	v_cvt_pk_bf16_f32 v132, v48, v49
	v_cvt_pk_bf16_f32 v133, v50, v51
	ds_read_b64_tr_b16 v[64:65], v0 offset:30720
	ds_read_b64_tr_b16 v[66:67], v0 offset:31232
	v_mfma_f32_32x32x16_bf16 v[80:95], v[152:155], v[116:119], v[80:95]
	v_add_f32_e32 v14, v54, v14
	v_add_f32_e32 v14, v55, v14
	v_add_f32_e32 v14, v56, v14
	v_add_f32_e32 v14, v57, v14
	v_cvt_pk_bf16_f32 v134, v52, v53
	v_cvt_pk_bf16_f32 v135, v54, v55
	ds_read_b64_tr_b16 v[52:53], v0 offset:27648
	ds_read_b64_tr_b16 v[54:55], v0 offset:28160
	v_mfma_f32_32x32x16_bf16 v[96:111], v[148:151], v[112:115], v[96:111]
	v_add_f32_e32 v14, v58, v14
	v_add_f32_e32 v14, v59, v14
	v_add_f32_e32 v14, v60, v14
	v_add_f32_e32 v14, v61, v14
	v_cvt_pk_bf16_f32 v124, v56, v57
	v_cvt_pk_bf16_f32 v125, v58, v59
	ds_read_b64_tr_b16 v[48:49], v0 offset:31744
	ds_read_b64_tr_b16 v[50:51], v0 offset:32256
	v_mfma_f32_32x32x16_bf16 v[80:95], v[144:147], v[112:115], v[80:95]
	v_add_f32_e32 v0, v62, v14
	v_add_f32_e32 v0, v63, v0
	v_add_f32_e32 v0, 0, v0
	v_cvt_pk_bf16_f32 v126, v60, v61
	v_cvt_pk_bf16_f32 v127, v62, v63
	v_lshl_add_u64 v[14:15], v[182:183], 0, s[26:27]
	s_add_i32 s52, s59, s86
	s_mov_b32 s53, m0
	s_mov_b32 m0, s52
	s_nop 0
	global_load_lds_dwordx4 v[14:15], off
	s_mov_b32 m0, s53
	v_lshl_add_u64 v[14:15], v[180:181], 0, s[26:27]
	s_add_i32 s52, s57, s87
	s_mov_b32 s53, m0
	s_mov_b32 m0, s52
	s_nop 0
	global_load_lds_dwordx4 v[14:15], off
	s_mov_b32 m0, s53
	v_add_f32_e32 v14, v221, v0
	s_mov_b64 s[52:53], 0

.LBB0_1047:
	s_add_i32 s52, s57, 0x2000
	ds_read_b128 v[48:51], v185 offset:256
	ds_read_b128 v[52:55], v185 offset:288
	ds_read_b128 v[56:59], v185 offset:320
	ds_read_b128 v[60:63], v185 offset:352
	ds_read_b128 v[164:167], v185 offset:384
	ds_read_b128 v[168:171], v185 offset:416
	ds_read_b128 v[172:175], v185 offset:448
	ds_read_b128 v[176:179], v185 offset:480
	s_cmpk_lg_i32 s57, 0x4000
	s_waitcnt lgkmcnt(4)
	v_sub_f32_e32 v79, v63, v220
	v_sub_f32_e32 v78, v62, v220
	v_sub_f32_e32 v77, v61, v220
	v_sub_f32_e32 v76, v60, v220
	v_sub_f32_e32 v75, v59, v220
	v_sub_f32_e32 v74, v58, v220
	v_sub_f32_e32 v73, v57, v220
	v_sub_f32_e32 v72, v56, v220
	v_sub_f32_e32 v71, v55, v220
	v_sub_f32_e32 v70, v54, v220
	v_sub_f32_e32 v69, v53, v220
	v_sub_f32_e32 v68, v52, v220
	v_sub_f32_e32 v67, v51, v220
	v_sub_f32_e32 v66, v50, v220
	v_sub_f32_e32 v65, v49, v220
	v_sub_f32_e32 v64, v48, v220
	s_waitcnt lgkmcnt(0)
	v_sub_f32_e32 v63, v179, v220
	v_sub_f32_e32 v62, v178, v220
	v_sub_f32_e32 v61, v177, v220
	v_sub_f32_e32 v60, v176, v220
	v_sub_f32_e32 v59, v175, v220
	v_sub_f32_e32 v58, v174, v220
	v_sub_f32_e32 v57, v173, v220
	v_sub_f32_e32 v56, v172, v220
	v_sub_f32_e32 v55, v171, v220
	v_sub_f32_e32 v54, v170, v220
	v_sub_f32_e32 v53, v169, v220
	v_sub_f32_e32 v52, v168, v220
	v_sub_f32_e32 v51, v167, v220
	v_sub_f32_e32 v50, v166, v220
	v_sub_f32_e32 v49, v165, v220
	v_sub_f32_e32 v48, v164, v220
	s_cselect_b32 s89, s52, 0
	v_add_u32_e32 v15, s59, v219
	ds_read_b64_tr_b16 v[164:165], v15 offset:24576
	ds_read_b64_tr_b16 v[166:167], v15 offset:25088
	v_mfma_f32_32x32x16_bf16 v[64:79], v[160:163], v[128:131], v[64:79]
	v_add_f32_e32 v124, v96, v97
	v_add_f32_e32 v124, v98, v124
	v_add_f32_e32 v124, v99, v124
	v_add_f32_e32 v124, v100, v124
	v_add_f32_e32 v124, v101, v124
	v_cvt_pk_bf16_f32 v140, v96, v97
	v_cvt_pk_bf16_f32 v141, v98, v99
	ds_read_b64_tr_b16 v[160:161], v15 offset:28672
	ds_read_b64_tr_b16 v[162:163], v15 offset:29184
	v_mfma_f32_32x32x16_bf16 v[48:63], v[152:155], v[128:131], v[48:63]
	v_add_f32_e32 v96, v102, v124
	v_add_f32_e32 v96, v103, v96
	v_add_f32_e32 v96, v104, v96
	v_add_f32_e32 v96, v105, v96
	v_cvt_pk_bf16_f32 v142, v100, v101
	v_cvt_pk_bf16_f32 v143, v102, v103
	ds_read_b64_tr_b16 v[152:153], v15 offset:25600
	ds_read_b64_tr_b16 v[154:155], v15 offset:26112
	v_mfma_f32_32x32x16_bf16 v[64:79], v[156:159], v[120:123], v[64:79]
	v_add_f32_e32 v96, v106, v96
	v_add_f32_e32 v96, v107, v96
	v_add_f32_e32 v96, v108, v96
	v_add_f32_e32 v96, v109, v96
	v_cvt_pk_bf16_f32 v136, v104, v105
	v_cvt_pk_bf16_f32 v137, v106, v107
	ds_read_b64_tr_b16 v[104:105], v15 offset:29696
	ds_read_b64_tr_b16 v[106:107], v15 offset:30208
	v_mfma_f32_32x32x16_bf16 v[48:63], v[144:147], v[120:123], v[48:63]
	v_add_f32_e32 v96, v110, v96
	v_add_f32_e32 v96, v111, v96
	v_add_f32_e32 v96, v80, v96
	v_add_f32_e32 v96, v81, v96
	v_cvt_pk_bf16_f32 v138, v108, v109
	v_cvt_pk_bf16_f32 v139, v110, v111
	ds_read_b64_tr_b16 v[100:101], v15 offset:26624
	ds_read_b64_tr_b16 v[102:103], v15 offset:27136
	v_mfma_f32_32x32x16_bf16 v[64:79], v[148:151], v[116:119], v[64:79]
	v_add_f32_e32 v96, v82, v96
	v_add_f32_e32 v96, v83, v96
	v_add_f32_e32 v96, v84, v96
	v_add_f32_e32 v108, v85, v96
	v_cvt_pk_bf16_f32 v132, v80, v81
	v_cvt_pk_bf16_f32 v133, v82, v83
	ds_read_b64_tr_b16 v[96:97], v15 offset:30720
	ds_read_b64_tr_b16 v[98:99], v15 offset:31232
	v_mfma_f32_32x32x16_bf16 v[48:63], v[6:9], v[116:119], v[48:63]
	v_add_f32_e32 v80, v86, v108
	v_add_f32_e32 v80, v87, v80
	v_add_f32_e32 v80, v88, v80
	v_add_f32_e32 v108, v89, v80
	v_cvt_pk_bf16_f32 v134, v84, v85
	v_cvt_pk_bf16_f32 v135, v86, v87
	ds_read_b64_tr_b16 v[80:81], v15 offset:27648
	ds_read_b64_tr_b16 v[82:83], v15 offset:28160
	v_mfma_f32_32x32x16_bf16 v[64:79], v[10:13], v[112:115], v[64:79]
	v_add_f32_e32 v6, v90, v108
	v_add_f32_e32 v6, v91, v6
	v_add_f32_e32 v6, v92, v6
	v_add_f32_e32 v84, v93, v6
	v_cvt_pk_bf16_f32 v124, v88, v89
	v_cvt_pk_bf16_f32 v125, v90, v91
	ds_read_b64_tr_b16 v[6:7], v15 offset:31744
	ds_read_b64_tr_b16 v[8:9], v15 offset:32256
	v_mfma_f32_32x32x16_bf16 v[48:63], v[2:5], v[112:115], v[48:63]
	v_add_f32_e32 v10, v94, v84
	v_add_f32_e32 v10, v95, v10
	v_add_f32_e32 v10, 0, v10
	v_cvt_pk_bf16_f32 v126, v92, v93
	v_cvt_pk_bf16_f32 v127, v94, v95
	s_nop 3
	s_add_i32 s52, s57, s86
	s_mov_b32 s53, m0
	s_mov_b32 m0, s52
	s_nop 0
	global_load_lds_dwordx4 v[182:183], off
	s_mov_b32 m0, s53
	s_add_i32 s52, s89, s87
	s_mov_b32 s53, m0
	s_mov_b32 m0, s52
	s_nop 0
	global_load_lds_dwordx4 v[180:181], off
	s_mov_b32 m0, s53
	v_add_f32_e32 v221, v14, v10
	s_mov_b64 s[52:53], 0

.LBB0_1060:
	v_lshl_add_u32 v0, s88, 8, v216
	v_add_u32_e32 v2, 0xffffff00, v0
	v_add_u32_e32 v6, 0xffffff80, v0
	v_add_u32_e32 v10, 0xffffff20, v0
	v_add_u32_e32 v14, 0xffffffa0, v0
	ds_read_b128 v[2:5], v2
	ds_read_b128 v[6:9], v6
	ds_read_b128 v[10:13], v10
	ds_read_b128 v[96:99], v14
	v_add_u32_e32 v14, 0xffffff40, v0
	v_subrev_u32_e32 v15, 64, v0
	v_add_u32_e32 v80, 0xffffff60, v0
	v_subrev_u32_e32 v0, 32, v0
	ds_read_b128 v[80:83], v80
	ds_read_b128 v[84:87], v14
	ds_read_b128 v[100:103], v15
	ds_read_b128 v[104:107], v0
	s_waitcnt lgkmcnt(3)
	v_sub_f32_e32 v95, v83, v220
	v_sub_f32_e32 v94, v82, v220
	v_sub_f32_e32 v93, v81, v220
	v_sub_f32_e32 v92, v80, v220
	s_waitcnt lgkmcnt(2)
	v_sub_f32_e32 v91, v87, v220
	v_sub_f32_e32 v90, v86, v220
	v_sub_f32_e32 v89, v85, v220
	v_sub_f32_e32 v88, v84, v220
	v_sub_f32_e32 v87, v13, v220
	v_sub_f32_e32 v86, v12, v220
	v_sub_f32_e32 v85, v11, v220
	v_sub_f32_e32 v84, v10, v220
	v_sub_f32_e32 v83, v5, v220
	v_sub_f32_e32 v82, v4, v220
	v_sub_f32_e32 v81, v3, v220
	v_sub_f32_e32 v80, v2, v220
	s_waitcnt lgkmcnt(0)
	v_sub_f32_e32 v111, v107, v220
	v_sub_f32_e32 v110, v106, v220
	v_sub_f32_e32 v109, v105, v220
	v_sub_f32_e32 v108, v104, v220
	v_sub_f32_e32 v107, v103, v220
	v_sub_f32_e32 v106, v102, v220
	v_sub_f32_e32 v105, v101, v220
	v_sub_f32_e32 v104, v100, v220
	v_sub_f32_e32 v103, v99, v220
	v_sub_f32_e32 v102, v98, v220
	v_sub_f32_e32 v101, v97, v220
	v_sub_f32_e32 v100, v96, v220
	v_sub_f32_e32 v99, v9, v220
	v_sub_f32_e32 v98, v8, v220
	v_sub_f32_e32 v97, v7, v220
	v_sub_f32_e32 v96, v6, v220
	v_add_u32_e32 v0, s90, v219
	ds_read_b64_tr_b16 v[176:177], v0 offset:24576
	ds_read_b64_tr_b16 v[178:179], v0 offset:25088
	v_add_f32_e32 v2, v64, v65
	v_add_f32_e32 v2, v66, v2
	v_add_f32_e32 v2, v67, v2
	v_add_f32_e32 v2, v68, v2
	v_add_f32_e32 v2, v69, v2
	v_cvt_pk_bf16_f32 v140, v64, v65
	v_cvt_pk_bf16_f32 v141, v66, v67
	v_mfma_f32_32x32x16_bf16 v[80:95], v[172:175], v[128:131], v[80:95]
	ds_read_b64_tr_b16 v[172:173], v0 offset:28672
	ds_read_b64_tr_b16 v[174:175], v0 offset:29184
	v_add_f32_e32 v2, v70, v2
	v_add_f32_e32 v2, v71, v2
	v_add_f32_e32 v2, v72, v2
	v_add_f32_e32 v2, v73, v2
	v_cvt_pk_bf16_f32 v142, v68, v69
	v_cvt_pk_bf16_f32 v143, v70, v71
	v_mfma_f32_32x32x16_bf16 v[96:111], v[168:171], v[128:131], v[96:111]
	ds_read_b64_tr_b16 v[168:169], v0 offset:25600
	ds_read_b64_tr_b16 v[170:171], v0 offset:26112
	v_add_f32_e32 v2, v74, v2
	v_add_f32_e32 v2, v75, v2
	v_add_f32_e32 v2, v76, v2
	v_add_f32_e32 v2, v77, v2
	v_cvt_pk_bf16_f32 v136, v72, v73
	v_cvt_pk_bf16_f32 v137, v74, v75
	v_mfma_f32_32x32x16_bf16 v[80:95], v[164:167], v[120:123], v[80:95]
	ds_read_b64_tr_b16 v[128:129], v0 offset:29696
	ds_read_b64_tr_b16 v[130:131], v0 offset:30208
	v_add_f32_e32 v2, v78, v2
	v_add_f32_e32 v2, v79, v2
	v_add_f32_e32 v2, v48, v2
	v_add_f32_e32 v2, v49, v2
	v_cvt_pk_bf16_f32 v138, v76, v77
	v_cvt_pk_bf16_f32 v139, v78, v79
	v_mfma_f32_32x32x16_bf16 v[96:111], v[160:163], v[120:123], v[96:111]
	ds_read_b64_tr_b16 v[120:121], v0 offset:26624
	ds_read_b64_tr_b16 v[122:123], v0 offset:27136
	v_add_f32_e32 v2, v50, v2
	v_add_f32_e32 v2, v51, v2
	v_add_f32_e32 v2, v52, v2
	v_add_f32_e32 v2, v53, v2
	v_cvt_pk_bf16_f32 v132, v48, v49
	v_cvt_pk_bf16_f32 v133, v50, v51
	v_mfma_f32_32x32x16_bf16 v[80:95], v[156:159], v[116:119], v[80:95]
	ds_read_b64_tr_b16 v[10:11], v0 offset:30720
	ds_read_b64_tr_b16 v[12:13], v0 offset:31232
	v_add_f32_e32 v2, v54, v2
	v_add_f32_e32 v2, v55, v2
	v_add_f32_e32 v2, v56, v2
	v_add_f32_e32 v2, v57, v2
	v_cvt_pk_bf16_f32 v134, v52, v53
	v_cvt_pk_bf16_f32 v135, v54, v55
	v_mfma_f32_32x32x16_bf16 v[96:111], v[152:155], v[116:119], v[96:111]
	ds_read_b64_tr_b16 v[6:7], v0 offset:27648
	ds_read_b64_tr_b16 v[8:9], v0 offset:28160
	v_add_f32_e32 v2, v58, v2
	v_add_f32_e32 v2, v59, v2
	v_add_f32_e32 v2, v60, v2
	v_add_f32_e32 v14, v61, v2
	v_cvt_pk_bf16_f32 v124, v56, v57
	v_cvt_pk_bf16_f32 v125, v58, v59
	v_mfma_f32_32x32x16_bf16 v[80:95], v[148:151], v[112:115], v[80:95]
	ds_read_b64_tr_b16 v[2:3], v0 offset:31744
	ds_read_b64_tr_b16 v[4:5], v0 offset:32256
	v_add_f32_e32 v0, v62, v14
	v_add_f32_e32 v0, v63, v0
	v_add_f32_e32 v0, 0, v0
	v_cvt_pk_bf16_f32 v126, v60, v61
	v_cvt_pk_bf16_f32 v127, v62, v63
	v_mfma_f32_32x32x16_bf16 v[96:111], v[144:147], v[112:115], v[96:111]
	v_or_b32_e32 v15, 0xe0, v211
	v_or_b32_e32 v14, 0xc0, v211
	v_cmp_le_i32_e32 vcc, v15, v215
	v_add_f32_e32 v0, v221, v0
	s_nop 7
	v_cndmask_b32_e32 v48, v202, v96, vcc
	v_cmp_lt_i32_e32 vcc, v14, v215
	s_nop 1
	v_cndmask_b32_e32 v65, v202, v81, vcc
	v_cmp_le_i32_e32 vcc, v14, v215
	v_or_b32_e32 v14, 0xe1, v211
	s_nop 0
	v_cndmask_b32_e32 v64, v202, v80, vcc
	v_cmp_le_i32_e32 vcc, v14, v215
	v_or_b32_e32 v14, 0xc2, v211
	v_cndmask_b32_e32 v49, v202, v97, vcc
	v_cmp_le_i32_e32 vcc, v14, v215
	v_or_b32_e32 v14, 0xe2, v211
	s_nop 0
	v_cndmask_b32_e32 v66, v202, v82, vcc
	v_cmp_le_i32_e32 vcc, v14, v215
	v_or_b32_e32 v14, 0xc3, v211
	s_nop 0
	v_cndmask_b32_e32 v50, v202, v98, vcc
	v_cmp_le_i32_e32 vcc, v14, v215
	v_or_b32_e32 v14, 0xe3, v211
	s_nop 0
	v_cndmask_b32_e32 v67, v202, v83, vcc
	v_cmp_le_i32_e32 vcc, v14, v215
	v_or_b32_e32 v14, 0xc8, v211
	s_nop 0
	v_cndmask_b32_e32 v51, v202, v99, vcc
	v_cmp_le_i32_e32 vcc, v14, v215
	v_or_b32_e32 v14, 0xe8, v211
	s_nop 0
	v_cndmask_b32_e32 v68, v202, v84, vcc
	v_cmp_le_i32_e32 vcc, v14, v215
	v_or_b32_e32 v14, 0xc9, v211
	s_nop 0
	v_cndmask_b32_e32 v52, v202, v100, vcc
	v_cmp_le_i32_e32 vcc, v14, v215
	v_or_b32_e32 v14, 0xe9, v211
	s_nop 0
	v_cndmask_b32_e32 v69, v202, v85, vcc
	v_cmp_le_i32_e32 vcc, v14, v215
	v_or_b32_e32 v14, 0xca, v211
	s_nop 0
	v_cndmask_b32_e32 v53, v202, v101, vcc
	v_cmp_le_i32_e32 vcc, v14, v215
	v_or_b32_e32 v14, 0xea, v211
	s_nop 0
	v_cndmask_b32_e32 v70, v202, v86, vcc
	v_cmp_le_i32_e32 vcc, v14, v215
	v_or_b32_e32 v14, 0xcb, v211
	s_nop 0
	v_cndmask_b32_e32 v54, v202, v102, vcc
	v_cmp_le_i32_e32 vcc, v14, v215
	v_or_b32_e32 v14, 0xeb, v211
	s_nop 0
	v_cndmask_b32_e32 v71, v202, v87, vcc
	v_cmp_le_i32_e32 vcc, v14, v215
	v_or_b32_e32 v14, 0xd0, v211
	s_nop 0
	v_cndmask_b32_e32 v55, v202, v103, vcc
	v_cmp_le_i32_e32 vcc, v14, v215
	v_or_b32_e32 v14, 0xf0, v211
	s_nop 0
	v_cndmask_b32_e32 v72, v202, v88, vcc
	v_cmp_le_i32_e32 vcc, v14, v215
	v_or_b32_e32 v14, 0xd1, v211
	s_nop 0
	v_cndmask_b32_e32 v56, v202, v104, vcc
	v_cmp_le_i32_e32 vcc, v14, v215
	v_or_b32_e32 v14, 0xf1, v211
	s_nop 0
	v_cndmask_b32_e32 v73, v202, v89, vcc
	v_cmp_le_i32_e32 vcc, v14, v215
	v_or_b32_e32 v14, 0xd2, v211
	s_nop 0
	v_cndmask_b32_e32 v57, v202, v105, vcc
	v_cmp_le_i32_e32 vcc, v14, v215
	v_or_b32_e32 v14, 0xf2, v211
	s_nop 0
	v_cndmask_b32_e32 v74, v202, v90, vcc
	v_cmp_le_i32_e32 vcc, v14, v215
	v_or_b32_e32 v14, 0xd3, v211
	s_nop 0
	v_cndmask_b32_e32 v58, v202, v106, vcc
	v_cmp_le_i32_e32 vcc, v14, v215
	v_or_b32_e32 v14, 0xf3, v211
	s_nop 0
	v_cndmask_b32_e32 v75, v202, v91, vcc
	v_cmp_le_i32_e32 vcc, v14, v215
	v_or_b32_e32 v14, 0xd8, v211
	s_nop 0
	v_cndmask_b32_e32 v59, v202, v107, vcc
	v_cmp_le_i32_e32 vcc, v14, v215
	v_or_b32_e32 v14, 0xf8, v211
	s_nop 0
	v_cndmask_b32_e32 v76, v202, v92, vcc
	v_cmp_le_i32_e32 vcc, v14, v215
	v_or_b32_e32 v14, 0xd9, v211
	s_nop 0
	v_cndmask_b32_e32 v60, v202, v108, vcc
	v_cmp_le_i32_e32 vcc, v14, v215
	v_or_b32_e32 v14, 0xf9, v211
	s_nop 0
	v_cndmask_b32_e32 v77, v202, v93, vcc
	v_cmp_le_i32_e32 vcc, v14, v215
	v_or_b32_e32 v14, 0xda, v211
	s_nop 0
	v_cndmask_b32_e32 v61, v202, v109, vcc
	v_cmp_le_i32_e32 vcc, v14, v215
	v_or_b32_e32 v14, 0xfa, v211
	s_nop 0
	v_cndmask_b32_e32 v78, v202, v94, vcc
	v_cmp_le_i32_e32 vcc, v14, v215
	v_or_b32_e32 v14, 0xdb, v211
	s_nop 0
	v_cndmask_b32_e32 v62, v202, v110, vcc
	v_cmp_le_i32_e32 vcc, v14, v215
	v_or_b32_e32 v14, 0xfb, v211
	s_nop 0
	v_cndmask_b32_e32 v79, v202, v95, vcc
	v_cmp_le_i32_e32 vcc, v14, v215
	v_cndmask_b32_e32 v63, v202, v111, vcc
	s_mov_b64 s[4:5], 0

.LBB0_1083:
	v_add_f32_e32 v221, v221, v15
	s_mov_b64 s[54:55], 0

.LBB0_1094:
	v_add_f32_e32 v221, v221, v80
	s_mov_b64 s[56:57], 0

.LBB0_1160:
	ds_read_b128 v[128:131], v179
	ds_read_b128 v[132:135], v179 offset:1024
	ds_read_b128 v[136:139], v179 offset:2048
	ds_read_b128 v[140:143], v179 offset:3072
	ds_read_b128 v[160:163], v180
	ds_read_b128 v[164:167], v180 offset:1024
	ds_read_b128 v[168:171], v180 offset:2048
	ds_read_b128 v[182:185], v180 offset:3072
	s_add_u32 s44, s30, 0xfffc0080
	s_addc_u32 s45, s31, -1
	s_cmp_eq_u32 s72, 12
	s_cselect_b32 s53, s23, s45
	s_cselect_b32 s52, s29, s44
	s_cselect_b32 s45, s21, s71
	s_cselect_b32 s44, s69, s70
	v_lshl_add_u64 v[172:173], s[30:31], 0, v[152:153]
	s_add_i32 m0, s57, 0xc000
	ds_read_b128 v[186:189], v181
	ds_read_b128 v[190:193], v181 offset:1024
	ds_read_b128 v[194:197], v181 offset:2048
	ds_read_b128 v[198:201], v181 offset:3072
	ds_read_b128 v[202:205], v181 offset:4096
	ds_read_b128 v[206:209], v181 offset:5120
	ds_read_b128 v[210:213], v181 offset:6144
	ds_read_b128 v[216:219], v181 offset:7168
	global_load_lds_dwordx4 v[172:173], off
	v_lshl_add_u64 v[172:173], s[30:31], 0, v[154:155]
	s_add_i32 m0, s57, 0xe000
	s_nop 0
	global_load_lds_dwordx4 v[172:173], off
	s_waitcnt vmcnt(8)
	s_waitcnt lgkmcnt(0)
	s_barrier
	s_setprio 1
	s_waitcnt lgkmcnt(0)
	v_mfma_f32_16x16x32_bf16 v[124:127], v[128:131], v[186:189], v[124:127]
	v_mfma_f32_16x16x32_bf16 v[120:123], v[136:139], v[186:189], v[120:123]
	v_mfma_f32_16x16x32_bf16 v[108:111], v[128:131], v[194:197], v[108:111]
	v_mfma_f32_16x16x32_bf16 v[104:107], v[136:139], v[194:197], v[104:107]
	v_mfma_f32_16x16x32_bf16 v[92:95], v[128:131], v[202:205], v[92:95]
	v_mfma_f32_16x16x32_bf16 v[88:91], v[136:139], v[202:205], v[88:91]
	v_mfma_f32_16x16x32_bf16 v[76:79], v[128:131], v[210:213], v[76:79]
	v_mfma_f32_16x16x32_bf16 v[72:75], v[136:139], v[210:213], v[72:75]
	v_mfma_f32_16x16x32_bf16 v[124:127], v[132:135], v[190:193], v[124:127]
	v_mfma_f32_16x16x32_bf16 v[120:123], v[140:143], v[190:193], v[120:123]
	v_mfma_f32_16x16x32_bf16 v[108:111], v[132:135], v[198:201], v[108:111]
	v_mfma_f32_16x16x32_bf16 v[104:107], v[140:143], v[198:201], v[104:107]
	v_mfma_f32_16x16x32_bf16 v[92:95], v[132:135], v[206:209], v[92:95]
	v_mfma_f32_16x16x32_bf16 v[88:91], v[140:143], v[206:209], v[88:91]
	v_mfma_f32_16x16x32_bf16 v[76:79], v[132:135], v[216:219], v[76:79]
	v_mfma_f32_16x16x32_bf16 v[72:75], v[140:143], v[216:219], v[72:75]
	s_setprio 0
	s_setprio 1
	v_mfma_f32_16x16x32_bf16 v[116:119], v[160:163], v[186:189], v[116:119]
	v_mfma_f32_16x16x32_bf16 v[112:115], v[168:171], v[186:189], v[112:115]
	v_mfma_f32_16x16x32_bf16 v[100:103], v[160:163], v[194:197], v[100:103]
	v_mfma_f32_16x16x32_bf16 v[96:99], v[168:171], v[194:197], v[96:99]
	v_mfma_f32_16x16x32_bf16 v[84:87], v[160:163], v[202:205], v[84:87]
	v_mfma_f32_16x16x32_bf16 v[80:83], v[168:171], v[202:205], v[80:83]
	v_mfma_f32_16x16x32_bf16 v[68:71], v[160:163], v[210:213], v[68:71]
	v_mfma_f32_16x16x32_bf16 v[64:67], v[168:171], v[210:213], v[64:67]
	v_mfma_f32_16x16x32_bf16 v[116:119], v[164:167], v[190:193], v[116:119]
	v_mfma_f32_16x16x32_bf16 v[112:115], v[182:185], v[190:193], v[112:115]
	v_mfma_f32_16x16x32_bf16 v[100:103], v[164:167], v[198:201], v[100:103]
	v_mfma_f32_16x16x32_bf16 v[96:99], v[182:185], v[198:201], v[96:99]
	v_mfma_f32_16x16x32_bf16 v[84:87], v[164:167], v[206:209], v[84:87]
	v_mfma_f32_16x16x32_bf16 v[80:83], v[182:185], v[206:209], v[80:83]
	v_mfma_f32_16x16x32_bf16 v[68:71], v[164:167], v[216:219], v[68:71]
	v_mfma_f32_16x16x32_bf16 v[64:67], v[182:185], v[216:219], v[64:67]
	s_setprio 0
	s_barrier
	s_add_i32 s73, s66, s56
	v_lshl_add_u64 v[172:173], s[44:45], 0, v[146:147]
	s_mov_b32 m0, s73
	ds_read_b128 v[186:189], v181 offset:16384
	ds_read_b128 v[190:193], v181 offset:17408
	ds_read_b128 v[194:197], v181 offset:18432
	ds_read_b128 v[198:201], v181 offset:19456
	ds_read_b128 v[202:205], v181 offset:20480
	ds_read_b128 v[206:209], v181 offset:21504
	ds_read_b128 v[210:213], v181 offset:22528
	ds_read_b128 v[216:219], v181 offset:23552
	global_load_lds_dwordx4 v[172:173], off
	s_add_i32 m0, s73, 0x2000
	s_add_u32 s76, s44, 0x40000
	v_lshl_add_u64 v[220:221], s[44:45], 0, v[150:151]
	s_addc_u32 s77, s45, 0
	s_add_i32 s73, s67, s56
	global_load_lds_dwordx4 v[220:221], off
	v_lshl_add_u64 v[222:223], s[76:77], 0, v[146:147]
	s_mov_b32 m0, s73
	v_lshl_add_u64 v[224:225], s[52:53], 0, v[148:149]
	global_load_lds_dwordx4 v[222:223], off
	v_lshl_add_u64 v[222:223], s[76:77], 0, v[150:151]
	s_add_i32 m0, s73, 0x2000
	s_nop 0
	global_load_lds_dwordx4 v[222:223], off
	v_lshl_add_u64 v[222:223], s[52:53], 0, v[144:145]
	s_mov_b32 m0, s57
	s_nop 0
	global_load_lds_dwordx4 v[222:223], off
	s_mov_b32 m0, s58
	s_nop 0
	global_load_lds_dwordx4 v[224:225], off
	s_waitcnt vmcnt(8)
	s_waitcnt lgkmcnt(0)
	s_barrier
	s_setprio 1
	s_waitcnt lgkmcnt(0)
	v_mfma_f32_16x16x32_bf16 v[60:63], v[128:131], v[186:189], v[60:63]
	v_mfma_f32_16x16x32_bf16 v[56:59], v[136:139], v[186:189], v[56:59]
	v_mfma_f32_16x16x32_bf16 v[44:47], v[128:131], v[194:197], v[44:47]
	v_mfma_f32_16x16x32_bf16 v[40:43], v[136:139], v[194:197], v[40:43]
	v_mfma_f32_16x16x32_bf16 v[28:31], v[128:131], v[202:205], v[28:31]
	v_mfma_f32_16x16x32_bf16 v[24:27], v[136:139], v[202:205], v[24:27]
	v_mfma_f32_16x16x32_bf16 v[12:15], v[128:131], v[210:213], v[12:15]
	v_mfma_f32_16x16x32_bf16 v[8:11], v[136:139], v[210:213], v[8:11]
	v_mfma_f32_16x16x32_bf16 v[60:63], v[132:135], v[190:193], v[60:63]
	v_mfma_f32_16x16x32_bf16 v[56:59], v[140:143], v[190:193], v[56:59]
	v_mfma_f32_16x16x32_bf16 v[44:47], v[132:135], v[198:201], v[44:47]
	v_mfma_f32_16x16x32_bf16 v[40:43], v[140:143], v[198:201], v[40:43]
	v_mfma_f32_16x16x32_bf16 v[28:31], v[132:135], v[206:209], v[28:31]
	v_mfma_f32_16x16x32_bf16 v[24:27], v[140:143], v[206:209], v[24:27]
	v_mfma_f32_16x16x32_bf16 v[12:15], v[132:135], v[216:219], v[12:15]
	v_mfma_f32_16x16x32_bf16 v[8:11], v[140:143], v[216:219], v[8:11]
	s_setprio 0
	s_setprio 1
	v_mfma_f32_16x16x32_bf16 v[52:55], v[160:163], v[186:189], v[52:55]
	v_mfma_f32_16x16x32_bf16 v[48:51], v[168:171], v[186:189], v[48:51]
	v_mfma_f32_16x16x32_bf16 v[36:39], v[160:163], v[194:197], v[36:39]
	v_mfma_f32_16x16x32_bf16 v[32:35], v[168:171], v[194:197], v[32:35]
	v_mfma_f32_16x16x32_bf16 v[20:23], v[160:163], v[202:205], v[20:23]
	v_mfma_f32_16x16x32_bf16 v[16:19], v[168:171], v[202:205], v[16:19]
	v_mfma_f32_16x16x32_bf16 v[4:7], v[160:163], v[210:213], v[4:7]
	v_mfma_f32_16x16x32_bf16 v[0:3], v[168:171], v[210:213], v[0:3]
	v_mfma_f32_16x16x32_bf16 v[52:55], v[164:167], v[190:193], v[52:55]
	v_mfma_f32_16x16x32_bf16 v[48:51], v[182:185], v[190:193], v[48:51]
	v_mfma_f32_16x16x32_bf16 v[36:39], v[164:167], v[198:201], v[36:39]
	v_mfma_f32_16x16x32_bf16 v[32:35], v[182:185], v[198:201], v[32:35]
	v_mfma_f32_16x16x32_bf16 v[20:23], v[164:167], v[206:209], v[20:23]
	v_mfma_f32_16x16x32_bf16 v[16:19], v[182:185], v[206:209], v[16:19]
	v_mfma_f32_16x16x32_bf16 v[4:7], v[164:167], v[216:219], v[4:7]
	v_mfma_f32_16x16x32_bf16 v[0:3], v[182:185], v[216:219], v[0:3]
	s_setprio 0
	s_barrier
	s_add_i32 s73, 0, 0x18000
	s_add_i32 s74, 0, 0x1c000
	v_add_u32_e32 v140, s73, v177
	v_add_u32_e32 v182, s74, v177
	ds_read_b128 v[128:131], v140
	ds_read_b128 v[132:135], v140 offset:1024
	ds_read_b128 v[136:139], v140 offset:2048
	ds_read_b128 v[140:143], v140 offset:3072
	ds_read_b128 v[160:163], v182
	ds_read_b128 v[164:167], v182 offset:1024
	ds_read_b128 v[168:171], v182 offset:2048
	ds_read_b128 v[182:185], v182 offset:3072
	s_add_u32 s52, s52, 0x40000
	s_addc_u32 s53, s53, 0
	s_mov_b32 m0, s59
	v_lshl_add_u64 v[226:227], s[52:53], 0, v[144:145]
	ds_read_b128 v[186:189], v181 offset:32768
	ds_read_b128 v[190:193], v181 offset:33792
	ds_read_b128 v[194:197], v181 offset:34816
	ds_read_b128 v[198:201], v181 offset:35840
	ds_read_b128 v[202:205], v181 offset:36864
	ds_read_b128 v[206:209], v181 offset:37888
	ds_read_b128 v[210:213], v181 offset:38912
	ds_read_b128 v[216:219], v181 offset:39936
	global_load_lds_dwordx4 v[226:227], off
	v_lshl_add_u64 v[226:227], s[52:53], 0, v[148:149]
	s_mov_b32 m0, s60
	s_nop 0
	global_load_lds_dwordx4 v[226:227], off
	s_waitcnt vmcnt(8)
	s_waitcnt lgkmcnt(0)
	s_barrier
	s_setprio 1
	s_waitcnt lgkmcnt(0)
	v_mfma_f32_16x16x32_bf16 v[124:127], v[128:131], v[186:189], v[124:127]
	v_mfma_f32_16x16x32_bf16 v[120:123], v[136:139], v[186:189], v[120:123]
	v_mfma_f32_16x16x32_bf16 v[108:111], v[128:131], v[194:197], v[108:111]
	v_mfma_f32_16x16x32_bf16 v[104:107], v[136:139], v[194:197], v[104:107]
	v_mfma_f32_16x16x32_bf16 v[92:95], v[128:131], v[202:205], v[92:95]
	v_mfma_f32_16x16x32_bf16 v[88:91], v[136:139], v[202:205], v[88:91]
	v_mfma_f32_16x16x32_bf16 v[76:79], v[128:131], v[210:213], v[76:79]
	v_mfma_f32_16x16x32_bf16 v[72:75], v[136:139], v[210:213], v[72:75]
	v_mfma_f32_16x16x32_bf16 v[124:127], v[132:135], v[190:193], v[124:127]
	v_mfma_f32_16x16x32_bf16 v[120:123], v[140:143], v[190:193], v[120:123]
	v_mfma_f32_16x16x32_bf16 v[108:111], v[132:135], v[198:201], v[108:111]
	v_mfma_f32_16x16x32_bf16 v[104:107], v[140:143], v[198:201], v[104:107]
	v_mfma_f32_16x16x32_bf16 v[92:95], v[132:135], v[206:209], v[92:95]
	v_mfma_f32_16x16x32_bf16 v[88:91], v[140:143], v[206:209], v[88:91]
	v_mfma_f32_16x16x32_bf16 v[76:79], v[132:135], v[216:219], v[76:79]
	v_mfma_f32_16x16x32_bf16 v[72:75], v[140:143], v[216:219], v[72:75]
	s_setprio 0
	s_setprio 1
	v_mfma_f32_16x16x32_bf16 v[116:119], v[160:163], v[186:189], v[116:119]
	v_mfma_f32_16x16x32_bf16 v[112:115], v[168:171], v[186:189], v[112:115]
	v_mfma_f32_16x16x32_bf16 v[100:103], v[160:163], v[194:197], v[100:103]
	v_mfma_f32_16x16x32_bf16 v[96:99], v[168:171], v[194:197], v[96:99]
	v_mfma_f32_16x16x32_bf16 v[84:87], v[160:163], v[202:205], v[84:87]
	v_mfma_f32_16x16x32_bf16 v[80:83], v[168:171], v[202:205], v[80:83]
	v_mfma_f32_16x16x32_bf16 v[68:71], v[160:163], v[210:213], v[68:71]
	v_mfma_f32_16x16x32_bf16 v[64:67], v[168:171], v[210:213], v[64:67]
	v_mfma_f32_16x16x32_bf16 v[116:119], v[164:167], v[190:193], v[116:119]
	v_mfma_f32_16x16x32_bf16 v[112:115], v[182:185], v[190:193], v[112:115]
	v_mfma_f32_16x16x32_bf16 v[100:103], v[164:167], v[198:201], v[100:103]
	v_mfma_f32_16x16x32_bf16 v[96:99], v[182:185], v[198:201], v[96:99]
	v_mfma_f32_16x16x32_bf16 v[84:87], v[164:167], v[206:209], v[84:87]
	v_mfma_f32_16x16x32_bf16 v[80:83], v[182:185], v[206:209], v[80:83]
	v_mfma_f32_16x16x32_bf16 v[68:71], v[164:167], v[216:219], v[68:71]
	v_mfma_f32_16x16x32_bf16 v[64:67], v[182:185], v[216:219], v[64:67]
	s_setprio 0
	s_barrier
	s_add_i32 s52, s73, s56
	v_lshl_add_u64 v[172:173], v[172:173], 0, s[14:15]
	s_mov_b32 m0, s52
	ds_read_b128 v[186:189], v181 offset:49152
	ds_read_b128 v[190:193], v181 offset:50176
	ds_read_b128 v[194:197], v181 offset:51200
	ds_read_b128 v[198:201], v181 offset:52224
	ds_read_b128 v[202:205], v181 offset:53248
	ds_read_b128 v[206:209], v181 offset:54272
	ds_read_b128 v[210:213], v181 offset:55296
	ds_read_b128 v[216:219], v181 offset:56320
	global_load_lds_dwordx4 v[172:173], off
	s_add_i32 m0, s52, 0x2000
	s_add_u32 s44, s44, 0x40080
	v_lshl_add_u64 v[172:173], v[220:221], 0, s[14:15]
	s_addc_u32 s45, s45, 0
	s_add_i32 s52, s74, s56
	global_load_lds_dwordx4 v[172:173], off
	v_lshl_add_u64 v[172:173], s[44:45], 0, v[146:147]
	s_mov_b32 m0, s52
	s_nop 0
	global_load_lds_dwordx4 v[172:173], off
	v_lshl_add_u64 v[172:173], s[44:45], 0, v[150:151]
	s_add_i32 m0, s52, 0x2000
	s_nop 0
	global_load_lds_dwordx4 v[172:173], off
	v_lshl_add_u64 v[172:173], v[222:223], 0, s[14:15]
	s_mov_b32 m0, s64
	s_nop 0
	global_load_lds_dwordx4 v[172:173], off
	v_lshl_add_u64 v[172:173], v[224:225], 0, s[14:15]
	s_mov_b32 m0, s65
	s_nop 0
	global_load_lds_dwordx4 v[172:173], off
	s_waitcnt vmcnt(8)
	s_waitcnt lgkmcnt(0)
	s_barrier
	s_setprio 1
	s_waitcnt lgkmcnt(0)
	v_mfma_f32_16x16x32_bf16 v[60:63], v[128:131], v[186:189], v[60:63]
	v_mfma_f32_16x16x32_bf16 v[56:59], v[136:139], v[186:189], v[56:59]
	v_mfma_f32_16x16x32_bf16 v[44:47], v[128:131], v[194:197], v[44:47]
	v_mfma_f32_16x16x32_bf16 v[40:43], v[136:139], v[194:197], v[40:43]
	v_mfma_f32_16x16x32_bf16 v[28:31], v[128:131], v[202:205], v[28:31]
	v_mfma_f32_16x16x32_bf16 v[24:27], v[136:139], v[202:205], v[24:27]
	v_mfma_f32_16x16x32_bf16 v[12:15], v[128:131], v[210:213], v[12:15]
	v_mfma_f32_16x16x32_bf16 v[8:11], v[136:139], v[210:213], v[8:11]
	v_mfma_f32_16x16x32_bf16 v[60:63], v[132:135], v[190:193], v[60:63]
	v_mfma_f32_16x16x32_bf16 v[56:59], v[140:143], v[190:193], v[56:59]
	v_mfma_f32_16x16x32_bf16 v[44:47], v[132:135], v[198:201], v[44:47]
	v_mfma_f32_16x16x32_bf16 v[40:43], v[140:143], v[198:201], v[40:43]
	v_mfma_f32_16x16x32_bf16 v[28:31], v[132:135], v[206:209], v[28:31]
	v_mfma_f32_16x16x32_bf16 v[24:27], v[140:143], v[206:209], v[24:27]
	v_mfma_f32_16x16x32_bf16 v[12:15], v[132:135], v[216:219], v[12:15]
	v_mfma_f32_16x16x32_bf16 v[8:11], v[140:143], v[216:219], v[8:11]
	s_setprio 0
	s_setprio 1
	v_mfma_f32_16x16x32_bf16 v[52:55], v[160:163], v[186:189], v[52:55]
	v_mfma_f32_16x16x32_bf16 v[48:51], v[168:171], v[186:189], v[48:51]
	v_mfma_f32_16x16x32_bf16 v[36:39], v[160:163], v[194:197], v[36:39]
	v_mfma_f32_16x16x32_bf16 v[32:35], v[168:171], v[194:197], v[32:35]
	v_mfma_f32_16x16x32_bf16 v[20:23], v[160:163], v[202:205], v[20:23]
	v_mfma_f32_16x16x32_bf16 v[16:19], v[168:171], v[202:205], v[16:19]
	v_mfma_f32_16x16x32_bf16 v[4:7], v[160:163], v[210:213], v[4:7]
	v_mfma_f32_16x16x32_bf16 v[0:3], v[168:171], v[210:213], v[0:3]
	v_mfma_f32_16x16x32_bf16 v[52:55], v[164:167], v[190:193], v[52:55]
	v_mfma_f32_16x16x32_bf16 v[48:51], v[182:185], v[190:193], v[48:51]
	v_mfma_f32_16x16x32_bf16 v[36:39], v[164:167], v[198:201], v[36:39]
	v_mfma_f32_16x16x32_bf16 v[32:35], v[182:185], v[198:201], v[32:35]
	v_mfma_f32_16x16x32_bf16 v[20:23], v[164:167], v[206:209], v[20:23]
	v_mfma_f32_16x16x32_bf16 v[16:19], v[182:185], v[206:209], v[16:19]
	v_mfma_f32_16x16x32_bf16 v[4:7], v[164:167], v[216:219], v[4:7]
	v_mfma_f32_16x16x32_bf16 v[0:3], v[182:185], v[216:219], v[0:3]
	s_setprio 0
	s_barrier
	s_add_i32 s72, s72, 2
	s_add_u32 s30, s30, 0x100
	s_addc_u32 s31, s31, 0
	s_add_u32 s70, s70, 0x100
	s_addc_u32 s71, s71, 0
	s_cmp_gt_u32 s72, 13
	s_cbranch_scc0 .LBB0_1160
	s_and_b64 vcc, exec, s[16:17]
	s_cbranch_vccz .LBB0_1163
	s_barrier

.LBB0_1209:
	ds_read_b128 v[146:149], v216
	ds_read_b128 v[150:153], v216 offset:1024
	ds_read_b128 v[154:157], v216 offset:2048
	ds_read_b128 v[158:161], v216 offset:3072
	ds_read_b128 v[162:165], v217
	ds_read_b128 v[166:169], v217 offset:1024
	ds_read_b128 v[170:173], v217 offset:2048
	ds_read_b128 v[174:177], v217 offset:3072
	s_add_u32 s62, s60, 0xfffc0080
	s_addc_u32 s63, s61, -1
	s_cmp_eq_u32 s89, 12
	s_cselect_b32 s65, s51, s63
	s_cselect_b32 s64, s57, s62
	s_cselect_b32 s63, s45, s88
	s_cselect_b32 s62, s59, s87
	v_lshl_add_u64 v[220:221], s[60:61], 0, v[138:139]
	s_add_i32 m0, s69, 0xc000
	ds_read_b128 v[178:181], v218
	ds_read_b128 v[182:185], v218 offset:1024
	ds_read_b128 v[186:189], v218 offset:2048
	ds_read_b128 v[190:193], v218 offset:3072
	ds_read_b128 v[194:197], v218 offset:4096
	ds_read_b128 v[198:201], v218 offset:5120
	ds_read_b128 v[202:205], v218 offset:6144
	ds_read_b128 v[206:209], v218 offset:7168
	global_load_lds_dwordx4 v[220:221], off
	v_lshl_add_u64 v[220:221], s[60:61], 0, v[140:141]
	s_add_i32 m0, s69, 0xe000
	s_nop 0
	global_load_lds_dwordx4 v[220:221], off
	s_waitcnt vmcnt(8)
	s_waitcnt lgkmcnt(0)
	s_barrier
	s_setprio 1
	s_waitcnt lgkmcnt(0)
	v_mfma_f32_16x16x32_bf16 v[124:127], v[146:149], v[178:181], v[124:127]
	v_mfma_f32_16x16x32_bf16 v[60:63], v[154:157], v[178:181], v[60:63]
	v_mfma_f32_16x16x32_bf16 v[116:119], v[146:149], v[186:189], v[116:119]
	v_mfma_f32_16x16x32_bf16 v[52:55], v[154:157], v[186:189], v[52:55]
	v_mfma_f32_16x16x32_bf16 v[112:115], v[146:149], v[194:197], v[112:115]
	v_mfma_f32_16x16x32_bf16 v[48:51], v[154:157], v[194:197], v[48:51]
	v_mfma_f32_16x16x32_bf16 v[108:111], v[146:149], v[202:205], v[108:111]
	v_mfma_f32_16x16x32_bf16 v[40:43], v[154:157], v[202:205], v[40:43]
	v_mfma_f32_16x16x32_bf16 v[124:127], v[150:153], v[182:185], v[124:127]
	v_mfma_f32_16x16x32_bf16 v[60:63], v[158:161], v[182:185], v[60:63]
	v_mfma_f32_16x16x32_bf16 v[116:119], v[150:153], v[190:193], v[116:119]
	v_mfma_f32_16x16x32_bf16 v[52:55], v[158:161], v[190:193], v[52:55]
	v_mfma_f32_16x16x32_bf16 v[112:115], v[150:153], v[198:201], v[112:115]
	v_mfma_f32_16x16x32_bf16 v[48:51], v[158:161], v[198:201], v[48:51]
	v_mfma_f32_16x16x32_bf16 v[108:111], v[150:153], v[206:209], v[108:111]
	v_mfma_f32_16x16x32_bf16 v[40:43], v[158:161], v[206:209], v[40:43]
	s_setprio 0
	s_setprio 1
	v_mfma_f32_16x16x32_bf16 v[120:123], v[162:165], v[178:181], v[120:123]
	v_mfma_f32_16x16x32_bf16 v[56:59], v[170:173], v[178:181], v[56:59]
	v_mfma_f32_16x16x32_bf16 v[104:107], v[162:165], v[186:189], v[104:107]
	v_mfma_f32_16x16x32_bf16 v[44:47], v[170:173], v[186:189], v[44:47]
	v_mfma_f32_16x16x32_bf16 v[100:103], v[162:165], v[194:197], v[100:103]
	v_mfma_f32_16x16x32_bf16 v[36:39], v[170:173], v[194:197], v[36:39]
	v_mfma_f32_16x16x32_bf16 v[96:99], v[162:165], v[202:205], v[96:99]
	v_mfma_f32_16x16x32_bf16 v[32:35], v[170:173], v[202:205], v[32:35]
	v_mfma_f32_16x16x32_bf16 v[120:123], v[166:169], v[182:185], v[120:123]
	v_mfma_f32_16x16x32_bf16 v[56:59], v[174:177], v[182:185], v[56:59]
	v_mfma_f32_16x16x32_bf16 v[104:107], v[166:169], v[190:193], v[104:107]
	v_mfma_f32_16x16x32_bf16 v[44:47], v[174:177], v[190:193], v[44:47]
	v_mfma_f32_16x16x32_bf16 v[100:103], v[166:169], v[198:201], v[100:103]
	v_mfma_f32_16x16x32_bf16 v[36:39], v[174:177], v[198:201], v[36:39]
	v_mfma_f32_16x16x32_bf16 v[96:99], v[166:169], v[206:209], v[96:99]
	v_mfma_f32_16x16x32_bf16 v[32:35], v[174:177], v[206:209], v[32:35]
	s_setprio 0
	s_barrier
	s_add_i32 s90, s82, s68
	v_lshl_add_u64 v[220:221], s[62:63], 0, v[128:129]
	s_mov_b32 m0, s90
	ds_read_b128 v[178:181], v218 offset:16384
	ds_read_b128 v[182:185], v218 offset:17408
	ds_read_b128 v[186:189], v218 offset:18432
	ds_read_b128 v[190:193], v218 offset:19456
	ds_read_b128 v[194:197], v218 offset:20480
	ds_read_b128 v[198:201], v218 offset:21504
	ds_read_b128 v[202:205], v218 offset:22528
	ds_read_b128 v[206:209], v218 offset:23552
	global_load_lds_dwordx4 v[220:221], off
	s_add_i32 m0, s90, 0x2000
	s_add_u32 s90, s62, 0x40000
	v_lshl_add_u64 v[222:223], s[62:63], 0, v[130:131]
	s_addc_u32 s91, s63, 0
	s_add_i32 s92, s83, s68
	global_load_lds_dwordx4 v[222:223], off
	v_lshl_add_u64 v[224:225], s[90:91], 0, v[128:129]
	s_mov_b32 m0, s92
	v_lshl_add_u64 v[226:227], s[64:65], 0, v[130:131]
	global_load_lds_dwordx4 v[224:225], off
	v_lshl_add_u64 v[224:225], s[90:91], 0, v[130:131]
	s_add_i32 m0, s92, 0x2000
	s_nop 0
	global_load_lds_dwordx4 v[224:225], off
	v_lshl_add_u64 v[224:225], s[64:65], 0, v[128:129]
	s_mov_b32 m0, s69
	s_nop 0
	global_load_lds_dwordx4 v[224:225], off
	s_mov_b32 m0, s70
	s_nop 0
	global_load_lds_dwordx4 v[226:227], off
	s_waitcnt vmcnt(8)
	s_waitcnt lgkmcnt(0)
	s_barrier
	s_setprio 1
	s_waitcnt lgkmcnt(0)
	v_mfma_f32_16x16x32_bf16 v[92:95], v[146:149], v[178:181], v[92:95]
	v_mfma_f32_16x16x32_bf16 v[28:31], v[154:157], v[178:181], v[28:31]
	v_mfma_f32_16x16x32_bf16 v[84:87], v[146:149], v[186:189], v[84:87]
	v_mfma_f32_16x16x32_bf16 v[20:23], v[154:157], v[186:189], v[20:23]
	v_mfma_f32_16x16x32_bf16 v[80:83], v[146:149], v[194:197], v[80:83]
	v_mfma_f32_16x16x32_bf16 v[16:19], v[154:157], v[194:197], v[16:19]
	v_mfma_f32_16x16x32_bf16 v[76:79], v[146:149], v[202:205], v[76:79]
	v_mfma_f32_16x16x32_bf16 v[8:11], v[154:157], v[202:205], v[8:11]
	v_mfma_f32_16x16x32_bf16 v[92:95], v[150:153], v[182:185], v[92:95]
	v_mfma_f32_16x16x32_bf16 v[28:31], v[158:161], v[182:185], v[28:31]
	v_mfma_f32_16x16x32_bf16 v[84:87], v[150:153], v[190:193], v[84:87]
	v_mfma_f32_16x16x32_bf16 v[20:23], v[158:161], v[190:193], v[20:23]
	v_mfma_f32_16x16x32_bf16 v[80:83], v[150:153], v[198:201], v[80:83]
	v_mfma_f32_16x16x32_bf16 v[16:19], v[158:161], v[198:201], v[16:19]
	v_mfma_f32_16x16x32_bf16 v[76:79], v[150:153], v[206:209], v[76:79]
	v_mfma_f32_16x16x32_bf16 v[8:11], v[158:161], v[206:209], v[8:11]
	s_setprio 0
	s_setprio 1
	v_mfma_f32_16x16x32_bf16 v[88:91], v[162:165], v[178:181], v[88:91]
	v_mfma_f32_16x16x32_bf16 v[24:27], v[170:173], v[178:181], v[24:27]
	v_mfma_f32_16x16x32_bf16 v[72:75], v[162:165], v[186:189], v[72:75]
	v_mfma_f32_16x16x32_bf16 v[12:15], v[170:173], v[186:189], v[12:15]
	v_mfma_f32_16x16x32_bf16 v[68:71], v[162:165], v[194:197], v[68:71]
	v_mfma_f32_16x16x32_bf16 v[4:7], v[170:173], v[194:197], v[4:7]
	v_mfma_f32_16x16x32_bf16 v[64:67], v[162:165], v[202:205], v[64:67]
	v_mfma_f32_16x16x32_bf16 v[0:3], v[170:173], v[202:205], v[0:3]
	v_mfma_f32_16x16x32_bf16 v[88:91], v[166:169], v[182:185], v[88:91]
	v_mfma_f32_16x16x32_bf16 v[24:27], v[174:177], v[182:185], v[24:27]
	v_mfma_f32_16x16x32_bf16 v[72:75], v[166:169], v[190:193], v[72:75]
	v_mfma_f32_16x16x32_bf16 v[12:15], v[174:177], v[190:193], v[12:15]
	v_mfma_f32_16x16x32_bf16 v[68:71], v[166:169], v[198:201], v[68:71]
	v_mfma_f32_16x16x32_bf16 v[4:7], v[174:177], v[198:201], v[4:7]
	v_mfma_f32_16x16x32_bf16 v[64:67], v[166:169], v[206:209], v[64:67]
	v_mfma_f32_16x16x32_bf16 v[0:3], v[174:177], v[206:209], v[0:3]
	s_setprio 0
	s_barrier
	s_add_i32 s90, 0, 0x18000
	s_add_i32 s91, 0, 0x1c000
	v_add_u32_e32 v158, s90, v211
	v_add_u32_e32 v174, s91, v211
	ds_read_b128 v[146:149], v158
	ds_read_b128 v[150:153], v158 offset:1024
	ds_read_b128 v[154:157], v158 offset:2048
	ds_read_b128 v[158:161], v158 offset:3072
	ds_read_b128 v[162:165], v174
	ds_read_b128 v[166:169], v174 offset:1024
	ds_read_b128 v[170:173], v174 offset:2048
	ds_read_b128 v[174:177], v174 offset:3072
	s_add_u32 s64, s64, 0x40000
	s_addc_u32 s65, s65, 0
	s_mov_b32 m0, s71
	v_lshl_add_u64 v[228:229], s[64:65], 0, v[128:129]
	ds_read_b128 v[178:181], v218 offset:32768
	ds_read_b128 v[182:185], v218 offset:33792
	ds_read_b128 v[186:189], v218 offset:34816
	ds_read_b128 v[190:193], v218 offset:35840
	ds_read_b128 v[194:197], v218 offset:36864
	ds_read_b128 v[198:201], v218 offset:37888
	ds_read_b128 v[202:205], v218 offset:38912
	ds_read_b128 v[206:209], v218 offset:39936
	global_load_lds_dwordx4 v[228:229], off
	v_lshl_add_u64 v[228:229], s[64:65], 0, v[130:131]
	s_mov_b32 m0, s72
	s_nop 0
	global_load_lds_dwordx4 v[228:229], off
	s_waitcnt vmcnt(8)
	s_waitcnt lgkmcnt(0)
	s_barrier
	s_setprio 1
	s_waitcnt lgkmcnt(0)
	v_mfma_f32_16x16x32_bf16 v[124:127], v[146:149], v[178:181], v[124:127]
	v_mfma_f32_16x16x32_bf16 v[60:63], v[154:157], v[178:181], v[60:63]
	v_mfma_f32_16x16x32_bf16 v[116:119], v[146:149], v[186:189], v[116:119]
	v_mfma_f32_16x16x32_bf16 v[52:55], v[154:157], v[186:189], v[52:55]
	v_mfma_f32_16x16x32_bf16 v[112:115], v[146:149], v[194:197], v[112:115]
	v_mfma_f32_16x16x32_bf16 v[48:51], v[154:157], v[194:197], v[48:51]
	v_mfma_f32_16x16x32_bf16 v[108:111], v[146:149], v[202:205], v[108:111]
	v_mfma_f32_16x16x32_bf16 v[40:43], v[154:157], v[202:205], v[40:43]
	v_mfma_f32_16x16x32_bf16 v[124:127], v[150:153], v[182:185], v[124:127]
	v_mfma_f32_16x16x32_bf16 v[60:63], v[158:161], v[182:185], v[60:63]
	v_mfma_f32_16x16x32_bf16 v[116:119], v[150:153], v[190:193], v[116:119]
	v_mfma_f32_16x16x32_bf16 v[52:55], v[158:161], v[190:193], v[52:55]
	v_mfma_f32_16x16x32_bf16 v[112:115], v[150:153], v[198:201], v[112:115]
	v_mfma_f32_16x16x32_bf16 v[48:51], v[158:161], v[198:201], v[48:51]
	v_mfma_f32_16x16x32_bf16 v[108:111], v[150:153], v[206:209], v[108:111]
	v_mfma_f32_16x16x32_bf16 v[40:43], v[158:161], v[206:209], v[40:43]
	s_setprio 0
	s_setprio 1
	v_mfma_f32_16x16x32_bf16 v[120:123], v[162:165], v[178:181], v[120:123]
	v_mfma_f32_16x16x32_bf16 v[56:59], v[170:173], v[178:181], v[56:59]
	v_mfma_f32_16x16x32_bf16 v[104:107], v[162:165], v[186:189], v[104:107]
	v_mfma_f32_16x16x32_bf16 v[44:47], v[170:173], v[186:189], v[44:47]
	v_mfma_f32_16x16x32_bf16 v[100:103], v[162:165], v[194:197], v[100:103]
	v_mfma_f32_16x16x32_bf16 v[36:39], v[170:173], v[194:197], v[36:39]
	v_mfma_f32_16x16x32_bf16 v[96:99], v[162:165], v[202:205], v[96:99]
	v_mfma_f32_16x16x32_bf16 v[32:35], v[170:173], v[202:205], v[32:35]
	v_mfma_f32_16x16x32_bf16 v[120:123], v[166:169], v[182:185], v[120:123]
	v_mfma_f32_16x16x32_bf16 v[56:59], v[174:177], v[182:185], v[56:59]
	v_mfma_f32_16x16x32_bf16 v[104:107], v[166:169], v[190:193], v[104:107]
	v_mfma_f32_16x16x32_bf16 v[44:47], v[174:177], v[190:193], v[44:47]
	v_mfma_f32_16x16x32_bf16 v[100:103], v[166:169], v[198:201], v[100:103]
	v_mfma_f32_16x16x32_bf16 v[36:39], v[174:177], v[198:201], v[36:39]
	v_mfma_f32_16x16x32_bf16 v[96:99], v[166:169], v[206:209], v[96:99]
	v_mfma_f32_16x16x32_bf16 v[32:35], v[174:177], v[206:209], v[32:35]
	s_setprio 0
	s_barrier
	s_add_i32 s64, s90, s68
	v_lshl_add_u64 v[220:221], v[220:221], 0, s[20:21]
	s_mov_b32 m0, s64
	ds_read_b128 v[178:181], v218 offset:49152
	ds_read_b128 v[182:185], v218 offset:50176
	ds_read_b128 v[186:189], v218 offset:51200
	ds_read_b128 v[190:193], v218 offset:52224
	ds_read_b128 v[194:197], v218 offset:53248
	ds_read_b128 v[198:201], v218 offset:54272
	ds_read_b128 v[202:205], v218 offset:55296
	ds_read_b128 v[206:209], v218 offset:56320
	global_load_lds_dwordx4 v[220:221], off
	s_add_i32 m0, s64, 0x2000
	s_add_u32 s62, s62, 0x40080
	v_lshl_add_u64 v[220:221], v[222:223], 0, s[20:21]
	s_addc_u32 s63, s63, 0
	s_add_i32 s64, s91, s68
	global_load_lds_dwordx4 v[220:221], off
	v_lshl_add_u64 v[220:221], s[62:63], 0, v[128:129]
	s_mov_b32 m0, s64
	s_nop 0
	global_load_lds_dwordx4 v[220:221], off
	v_lshl_add_u64 v[220:221], s[62:63], 0, v[130:131]
	s_add_i32 m0, s64, 0x2000
	s_nop 0
	global_load_lds_dwordx4 v[220:221], off
	v_lshl_add_u64 v[220:221], v[224:225], 0, s[20:21]
	s_mov_b32 m0, s79
	s_nop 0
	global_load_lds_dwordx4 v[220:221], off
	v_lshl_add_u64 v[220:221], v[226:227], 0, s[20:21]
	s_mov_b32 m0, s80
	s_nop 0
	global_load_lds_dwordx4 v[220:221], off
	s_waitcnt vmcnt(8)
	s_waitcnt lgkmcnt(0)
	s_barrier
	s_setprio 1
	s_waitcnt lgkmcnt(0)
	v_mfma_f32_16x16x32_bf16 v[92:95], v[146:149], v[178:181], v[92:95]
	v_mfma_f32_16x16x32_bf16 v[28:31], v[154:157], v[178:181], v[28:31]
	v_mfma_f32_16x16x32_bf16 v[84:87], v[146:149], v[186:189], v[84:87]
	v_mfma_f32_16x16x32_bf16 v[20:23], v[154:157], v[186:189], v[20:23]
	v_mfma_f32_16x16x32_bf16 v[80:83], v[146:149], v[194:197], v[80:83]
	v_mfma_f32_16x16x32_bf16 v[16:19], v[154:157], v[194:197], v[16:19]
	v_mfma_f32_16x16x32_bf16 v[76:79], v[146:149], v[202:205], v[76:79]
	v_mfma_f32_16x16x32_bf16 v[8:11], v[154:157], v[202:205], v[8:11]
	v_mfma_f32_16x16x32_bf16 v[92:95], v[150:153], v[182:185], v[92:95]
	v_mfma_f32_16x16x32_bf16 v[28:31], v[158:161], v[182:185], v[28:31]
	v_mfma_f32_16x16x32_bf16 v[84:87], v[150:153], v[190:193], v[84:87]
	v_mfma_f32_16x16x32_bf16 v[20:23], v[158:161], v[190:193], v[20:23]
	v_mfma_f32_16x16x32_bf16 v[80:83], v[150:153], v[198:201], v[80:83]
	v_mfma_f32_16x16x32_bf16 v[16:19], v[158:161], v[198:201], v[16:19]
	v_mfma_f32_16x16x32_bf16 v[76:79], v[150:153], v[206:209], v[76:79]
	v_mfma_f32_16x16x32_bf16 v[8:11], v[158:161], v[206:209], v[8:11]
	s_setprio 0
	s_setprio 1
	v_mfma_f32_16x16x32_bf16 v[88:91], v[162:165], v[178:181], v[88:91]
	v_mfma_f32_16x16x32_bf16 v[24:27], v[170:173], v[178:181], v[24:27]
	v_mfma_f32_16x16x32_bf16 v[72:75], v[162:165], v[186:189], v[72:75]
	v_mfma_f32_16x16x32_bf16 v[12:15], v[170:173], v[186:189], v[12:15]
	v_mfma_f32_16x16x32_bf16 v[68:71], v[162:165], v[194:197], v[68:71]
	v_mfma_f32_16x16x32_bf16 v[4:7], v[170:173], v[194:197], v[4:7]
	v_mfma_f32_16x16x32_bf16 v[64:67], v[162:165], v[202:205], v[64:67]
	v_mfma_f32_16x16x32_bf16 v[0:3], v[170:173], v[202:205], v[0:3]
	v_mfma_f32_16x16x32_bf16 v[88:91], v[166:169], v[182:185], v[88:91]
	v_mfma_f32_16x16x32_bf16 v[24:27], v[174:177], v[182:185], v[24:27]
	v_mfma_f32_16x16x32_bf16 v[72:75], v[166:169], v[190:193], v[72:75]
	v_mfma_f32_16x16x32_bf16 v[12:15], v[174:177], v[190:193], v[12:15]
	v_mfma_f32_16x16x32_bf16 v[68:71], v[166:169], v[198:201], v[68:71]
	v_mfma_f32_16x16x32_bf16 v[4:7], v[174:177], v[198:201], v[4:7]
	v_mfma_f32_16x16x32_bf16 v[64:67], v[166:169], v[206:209], v[64:67]
	v_mfma_f32_16x16x32_bf16 v[0:3], v[174:177], v[206:209], v[0:3]
	s_setprio 0
	s_barrier
	s_add_i32 s89, s89, 2
	s_add_u32 s60, s60, 0x100
	s_addc_u32 s61, s61, 0
	s_add_u32 s87, s87, 0x100
	s_addc_u32 s88, s88, 0
	s_cmp_gt_u32 s89, 13
	s_cbranch_scc0 .LBB0_1209
	s_and_b64 vcc, exec, s[22:23]
	s_cbranch_vccz .LBB0_1212
	s_barrier

.LBB0_1288:
	ds_read_b128 v[144:147], v138
	ds_read_b128 v[148:151], v138 offset:1024
	ds_read_b128 v[152:155], v138 offset:2048
	ds_read_b128 v[156:159], v138 offset:3072
	ds_read_b128 v[160:163], v139
	ds_read_b128 v[164:167], v139 offset:1024
	ds_read_b128 v[168:171], v139 offset:2048
	ds_read_b128 v[172:175], v139 offset:3072
	s_or_b32 s26, s30, 1
	s_lshl_b64 s[82:83], s[26:27], 7
	s_add_i32 s26, s30, 2
	s_lshl_b64 s[42:43], s[26:27], 7
	s_cmp_lg_u32 s30, s70
	s_cselect_b32 s30, s42, 0
	s_cselect_b32 s31, s43, 0
	s_add_u32 s42, s24, s30
	s_addc_u32 s43, s25, s31
	s_add_u32 s30, s22, s30
	s_addc_u32 s31, s23, s31
	s_add_u32 s82, s24, s82
	s_addc_u32 s83, s25, s83
	s_add_u32 s82, s82, 0xb0000
	s_addc_u32 s83, s83, 0
	s_mov_b32 m0, s71
	v_lshl_add_u64 v[208:209], s[82:83], 0, v[128:129]
	ds_read_b128 v[176:179], v141
	ds_read_b128 v[180:183], v141 offset:1024
	ds_read_b128 v[184:187], v141 offset:2048
	ds_read_b128 v[188:191], v141 offset:3072
	ds_read_b128 v[192:195], v141 offset:4096
	ds_read_b128 v[196:199], v141 offset:5120
	ds_read_b128 v[200:203], v141 offset:6144
	ds_read_b128 v[204:207], v141 offset:7168
	global_load_lds_dwordx4 v[208:209], off
	v_lshl_add_u64 v[208:209], s[82:83], 0, v[132:133]
	s_mov_b32 m0, s72
	s_nop 0
	global_load_lds_dwordx4 v[208:209], off
	s_waitcnt vmcnt(8)
	s_waitcnt lgkmcnt(0)
	s_barrier
	s_setprio 1
	s_waitcnt lgkmcnt(0)
	v_mfma_f32_16x16x32_bf16 v[124:127], v[144:147], v[176:179], v[124:127]
	v_mfma_f32_16x16x32_bf16 v[120:123], v[152:155], v[176:179], v[120:123]
	v_mfma_f32_16x16x32_bf16 v[116:119], v[144:147], v[184:187], v[116:119]
	v_mfma_f32_16x16x32_bf16 v[112:115], v[152:155], v[184:187], v[112:115]
	v_mfma_f32_16x16x32_bf16 v[108:111], v[144:147], v[192:195], v[108:111]
	v_mfma_f32_16x16x32_bf16 v[104:107], v[152:155], v[192:195], v[104:107]
	v_mfma_f32_16x16x32_bf16 v[100:103], v[144:147], v[200:203], v[100:103]
	v_mfma_f32_16x16x32_bf16 v[96:99], v[152:155], v[200:203], v[96:99]
	v_mfma_f32_16x16x32_bf16 v[124:127], v[148:151], v[180:183], v[124:127]
	v_mfma_f32_16x16x32_bf16 v[120:123], v[156:159], v[180:183], v[120:123]
	v_mfma_f32_16x16x32_bf16 v[116:119], v[148:151], v[188:191], v[116:119]
	v_mfma_f32_16x16x32_bf16 v[112:115], v[156:159], v[188:191], v[112:115]
	v_mfma_f32_16x16x32_bf16 v[108:111], v[148:151], v[196:199], v[108:111]
	v_mfma_f32_16x16x32_bf16 v[104:107], v[156:159], v[196:199], v[104:107]
	v_mfma_f32_16x16x32_bf16 v[100:103], v[148:151], v[204:207], v[100:103]
	v_mfma_f32_16x16x32_bf16 v[96:99], v[156:159], v[204:207], v[96:99]
	s_setprio 0
	s_setprio 1
	v_mfma_f32_16x16x32_bf16 v[92:95], v[160:163], v[176:179], v[92:95]
	v_mfma_f32_16x16x32_bf16 v[88:91], v[168:171], v[176:179], v[88:91]
	v_mfma_f32_16x16x32_bf16 v[84:87], v[160:163], v[184:187], v[84:87]
	v_mfma_f32_16x16x32_bf16 v[80:83], v[168:171], v[184:187], v[80:83]
	v_mfma_f32_16x16x32_bf16 v[76:79], v[160:163], v[192:195], v[76:79]
	v_mfma_f32_16x16x32_bf16 v[72:75], v[168:171], v[192:195], v[72:75]
	v_mfma_f32_16x16x32_bf16 v[68:71], v[160:163], v[200:203], v[68:71]
	v_mfma_f32_16x16x32_bf16 v[64:67], v[168:171], v[200:203], v[64:67]
	v_mfma_f32_16x16x32_bf16 v[92:95], v[164:167], v[180:183], v[92:95]
	v_mfma_f32_16x16x32_bf16 v[88:91], v[172:175], v[180:183], v[88:91]
	v_mfma_f32_16x16x32_bf16 v[84:87], v[164:167], v[188:191], v[84:87]
	v_mfma_f32_16x16x32_bf16 v[80:83], v[172:175], v[188:191], v[80:83]
	v_mfma_f32_16x16x32_bf16 v[76:79], v[164:167], v[196:199], v[76:79]
	v_mfma_f32_16x16x32_bf16 v[72:75], v[172:175], v[196:199], v[72:75]
	v_mfma_f32_16x16x32_bf16 v[68:71], v[164:167], v[204:207], v[68:71]
	v_mfma_f32_16x16x32_bf16 v[64:67], v[172:175], v[204:207], v[64:67]
	s_setprio 0
	s_barrier
	s_mov_b32 m0, s73
	v_lshl_add_u64 v[208:209], s[30:31], 0, v[130:131]
	s_add_u32 s82, s30, 0xb0000
	ds_read_b128 v[176:179], v141 offset:16384
	ds_read_b128 v[180:183], v141 offset:17408
	ds_read_b128 v[184:187], v141 offset:18432
	ds_read_b128 v[188:191], v141 offset:19456
	ds_read_b128 v[192:195], v141 offset:20480
	ds_read_b128 v[196:199], v141 offset:21504
	ds_read_b128 v[200:203], v141 offset:22528
	ds_read_b128 v[204:207], v141 offset:23552
	global_load_lds_dwordx4 v[208:209], off
	v_lshl_add_u64 v[210:211], s[30:31], 0, v[134:135]
	s_mov_b32 m0, s74
	s_addc_u32 s83, s31, 0
	global_load_lds_dwordx4 v[210:211], off
	v_lshl_add_u64 v[212:213], s[82:83], 0, v[130:131]
	s_mov_b32 m0, s76
	v_lshl_add_u64 v[216:217], s[42:43], 0, v[132:133]
	global_load_lds_dwordx4 v[212:213], off
	v_lshl_add_u64 v[212:213], s[82:83], 0, v[134:135]
	s_mov_b32 m0, s77
	s_nop 0
	global_load_lds_dwordx4 v[212:213], off
	v_lshl_add_u64 v[212:213], s[42:43], 0, v[128:129]
	s_mov_b32 m0, s62
	s_nop 0
	global_load_lds_dwordx4 v[212:213], off
	s_mov_b32 m0, s63
	s_nop 0
	global_load_lds_dwordx4 v[216:217], off
	s_waitcnt vmcnt(8)
	s_waitcnt lgkmcnt(0)
	s_barrier
	s_setprio 1
	s_waitcnt lgkmcnt(0)
	v_mfma_f32_16x16x32_bf16 v[60:63], v[144:147], v[176:179], v[60:63]
	v_mfma_f32_16x16x32_bf16 v[56:59], v[152:155], v[176:179], v[56:59]
	v_mfma_f32_16x16x32_bf16 v[52:55], v[144:147], v[184:187], v[52:55]
	v_mfma_f32_16x16x32_bf16 v[48:51], v[152:155], v[184:187], v[48:51]
	v_mfma_f32_16x16x32_bf16 v[44:47], v[144:147], v[192:195], v[44:47]
	v_mfma_f32_16x16x32_bf16 v[40:43], v[152:155], v[192:195], v[40:43]
	v_mfma_f32_16x16x32_bf16 v[36:39], v[144:147], v[200:203], v[36:39]
	v_mfma_f32_16x16x32_bf16 v[32:35], v[152:155], v[200:203], v[32:35]
	v_mfma_f32_16x16x32_bf16 v[60:63], v[148:151], v[180:183], v[60:63]
	v_mfma_f32_16x16x32_bf16 v[56:59], v[156:159], v[180:183], v[56:59]
	v_mfma_f32_16x16x32_bf16 v[52:55], v[148:151], v[188:191], v[52:55]
	v_mfma_f32_16x16x32_bf16 v[48:51], v[156:159], v[188:191], v[48:51]
	v_mfma_f32_16x16x32_bf16 v[44:47], v[148:151], v[196:199], v[44:47]
	v_mfma_f32_16x16x32_bf16 v[40:43], v[156:159], v[196:199], v[40:43]
	v_mfma_f32_16x16x32_bf16 v[36:39], v[148:151], v[204:207], v[36:39]
	v_mfma_f32_16x16x32_bf16 v[32:35], v[156:159], v[204:207], v[32:35]
	s_setprio 0
	s_setprio 1
	v_mfma_f32_16x16x32_bf16 v[28:31], v[160:163], v[176:179], v[28:31]
	v_mfma_f32_16x16x32_bf16 v[24:27], v[168:171], v[176:179], v[24:27]
	v_mfma_f32_16x16x32_bf16 v[20:23], v[160:163], v[184:187], v[20:23]
	v_mfma_f32_16x16x32_bf16 v[16:19], v[168:171], v[184:187], v[16:19]
	v_mfma_f32_16x16x32_bf16 v[12:15], v[160:163], v[192:195], v[12:15]
	v_mfma_f32_16x16x32_bf16 v[8:11], v[168:171], v[192:195], v[8:11]
	v_mfma_f32_16x16x32_bf16 v[4:7], v[160:163], v[200:203], v[4:7]
	v_mfma_f32_16x16x32_bf16 v[0:3], v[168:171], v[200:203], v[0:3]
	v_mfma_f32_16x16x32_bf16 v[28:31], v[164:167], v[180:183], v[28:31]
	v_mfma_f32_16x16x32_bf16 v[24:27], v[172:175], v[180:183], v[24:27]
	v_mfma_f32_16x16x32_bf16 v[20:23], v[164:167], v[188:191], v[20:23]
	v_mfma_f32_16x16x32_bf16 v[16:19], v[172:175], v[188:191], v[16:19]
	v_mfma_f32_16x16x32_bf16 v[12:15], v[164:167], v[196:199], v[12:15]
	v_mfma_f32_16x16x32_bf16 v[8:11], v[172:175], v[196:199], v[8:11]
	v_mfma_f32_16x16x32_bf16 v[4:7], v[164:167], v[204:207], v[4:7]
	v_mfma_f32_16x16x32_bf16 v[0:3], v[172:175], v[204:207], v[0:3]
	s_setprio 0
	s_barrier
	ds_read_b128 v[144:147], v142
	ds_read_b128 v[148:151], v142 offset:1024
	ds_read_b128 v[152:155], v142 offset:2048
	ds_read_b128 v[156:159], v142 offset:3072
	ds_read_b128 v[160:163], v143
	ds_read_b128 v[164:167], v143 offset:1024
	ds_read_b128 v[168:171], v143 offset:2048
	ds_read_b128 v[172:175], v143 offset:3072
	s_add_u32 s42, s42, 0xb0000
	s_addc_u32 s43, s43, 0
	s_mov_b32 m0, s64
	v_lshl_add_u64 v[218:219], s[42:43], 0, v[128:129]
	ds_read_b128 v[176:179], v141 offset:32768
	ds_read_b128 v[180:183], v141 offset:33792
	ds_read_b128 v[184:187], v141 offset:34816
	ds_read_b128 v[188:191], v141 offset:35840
	ds_read_b128 v[192:195], v141 offset:36864
	ds_read_b128 v[196:199], v141 offset:37888
	ds_read_b128 v[200:203], v141 offset:38912
	ds_read_b128 v[204:207], v141 offset:39936
	global_load_lds_dwordx4 v[218:219], off
	v_lshl_add_u64 v[218:219], s[42:43], 0, v[132:133]
	s_mov_b32 m0, s65
	s_nop 0
	global_load_lds_dwordx4 v[218:219], off
	s_waitcnt vmcnt(8)
	s_waitcnt lgkmcnt(0)
	s_barrier
	s_setprio 1
	s_waitcnt lgkmcnt(0)
	v_mfma_f32_16x16x32_bf16 v[124:127], v[144:147], v[176:179], v[124:127]
	v_mfma_f32_16x16x32_bf16 v[120:123], v[152:155], v[176:179], v[120:123]
	v_mfma_f32_16x16x32_bf16 v[116:119], v[144:147], v[184:187], v[116:119]
	v_mfma_f32_16x16x32_bf16 v[112:115], v[152:155], v[184:187], v[112:115]
	v_mfma_f32_16x16x32_bf16 v[108:111], v[144:147], v[192:195], v[108:111]
	v_mfma_f32_16x16x32_bf16 v[104:107], v[152:155], v[192:195], v[104:107]
	v_mfma_f32_16x16x32_bf16 v[100:103], v[144:147], v[200:203], v[100:103]
	v_mfma_f32_16x16x32_bf16 v[96:99], v[152:155], v[200:203], v[96:99]
	v_mfma_f32_16x16x32_bf16 v[124:127], v[148:151], v[180:183], v[124:127]
	v_mfma_f32_16x16x32_bf16 v[120:123], v[156:159], v[180:183], v[120:123]
	v_mfma_f32_16x16x32_bf16 v[116:119], v[148:151], v[188:191], v[116:119]
	v_mfma_f32_16x16x32_bf16 v[112:115], v[156:159], v[188:191], v[112:115]
	v_mfma_f32_16x16x32_bf16 v[108:111], v[148:151], v[196:199], v[108:111]
	v_mfma_f32_16x16x32_bf16 v[104:107], v[156:159], v[196:199], v[104:107]
	v_mfma_f32_16x16x32_bf16 v[100:103], v[148:151], v[204:207], v[100:103]
	v_mfma_f32_16x16x32_bf16 v[96:99], v[156:159], v[204:207], v[96:99]
	s_setprio 0
	s_setprio 1
	v_mfma_f32_16x16x32_bf16 v[92:95], v[160:163], v[176:179], v[92:95]
	v_mfma_f32_16x16x32_bf16 v[88:91], v[168:171], v[176:179], v[88:91]
	v_mfma_f32_16x16x32_bf16 v[84:87], v[160:163], v[184:187], v[84:87]
	v_mfma_f32_16x16x32_bf16 v[80:83], v[168:171], v[184:187], v[80:83]
	v_mfma_f32_16x16x32_bf16 v[76:79], v[160:163], v[192:195], v[76:79]
	v_mfma_f32_16x16x32_bf16 v[72:75], v[168:171], v[192:195], v[72:75]
	v_mfma_f32_16x16x32_bf16 v[68:71], v[160:163], v[200:203], v[68:71]
	v_mfma_f32_16x16x32_bf16 v[64:67], v[168:171], v[200:203], v[64:67]
	v_mfma_f32_16x16x32_bf16 v[92:95], v[164:167], v[180:183], v[92:95]
	v_mfma_f32_16x16x32_bf16 v[88:91], v[172:175], v[180:183], v[88:91]
	v_mfma_f32_16x16x32_bf16 v[84:87], v[164:167], v[188:191], v[84:87]
	v_mfma_f32_16x16x32_bf16 v[80:83], v[172:175], v[188:191], v[80:83]
	v_mfma_f32_16x16x32_bf16 v[76:79], v[164:167], v[196:199], v[76:79]
	v_mfma_f32_16x16x32_bf16 v[72:75], v[172:175], v[196:199], v[72:75]
	v_mfma_f32_16x16x32_bf16 v[68:71], v[164:167], v[204:207], v[68:71]
	v_mfma_f32_16x16x32_bf16 v[64:67], v[172:175], v[204:207], v[64:67]
	s_setprio 0
	s_barrier
	s_mov_b32 m0, s78
	v_lshl_add_u64 v[208:209], v[208:209], 0, s[28:29]
	s_add_u32 s30, s30, 0xb0080
	ds_read_b128 v[176:179], v141 offset:49152
	ds_read_b128 v[180:183], v141 offset:50176
	ds_read_b128 v[184:187], v141 offset:51200
	ds_read_b128 v[188:191], v141 offset:52224
	ds_read_b128 v[192:195], v141 offset:53248
	ds_read_b128 v[196:199], v141 offset:54272
	ds_read_b128 v[200:203], v141 offset:55296
	ds_read_b128 v[204:207], v141 offset:56320
	global_load_lds_dwordx4 v[208:209], off
	v_lshl_add_u64 v[208:209], v[210:211], 0, s[28:29]
	s_mov_b32 m0, s79
	s_addc_u32 s31, s31, 0
	global_load_lds_dwordx4 v[208:209], off
	v_lshl_add_u64 v[208:209], s[30:31], 0, v[130:131]
	s_mov_b32 m0, s80
	s_nop 0
	global_load_lds_dwordx4 v[208:209], off
	v_lshl_add_u64 v[208:209], s[30:31], 0, v[134:135]
	s_mov_b32 m0, s81
	s_nop 0
	global_load_lds_dwordx4 v[208:209], off
	v_lshl_add_u64 v[208:209], v[212:213], 0, s[28:29]
	s_mov_b32 m0, s68
	s_nop 0
	global_load_lds_dwordx4 v[208:209], off
	v_lshl_add_u64 v[208:209], v[216:217], 0, s[28:29]
	s_mov_b32 m0, s69
	s_nop 0
	global_load_lds_dwordx4 v[208:209], off
	s_waitcnt vmcnt(8)
	s_waitcnt lgkmcnt(0)
	s_barrier
	s_setprio 1
	s_waitcnt lgkmcnt(0)
	v_mfma_f32_16x16x32_bf16 v[60:63], v[144:147], v[176:179], v[60:63]
	v_mfma_f32_16x16x32_bf16 v[56:59], v[152:155], v[176:179], v[56:59]
	v_mfma_f32_16x16x32_bf16 v[52:55], v[144:147], v[184:187], v[52:55]
	v_mfma_f32_16x16x32_bf16 v[48:51], v[152:155], v[184:187], v[48:51]
	v_mfma_f32_16x16x32_bf16 v[44:47], v[144:147], v[192:195], v[44:47]
	v_mfma_f32_16x16x32_bf16 v[40:43], v[152:155], v[192:195], v[40:43]
	v_mfma_f32_16x16x32_bf16 v[36:39], v[144:147], v[200:203], v[36:39]
	v_mfma_f32_16x16x32_bf16 v[32:35], v[152:155], v[200:203], v[32:35]
	v_mfma_f32_16x16x32_bf16 v[60:63], v[148:151], v[180:183], v[60:63]
	v_mfma_f32_16x16x32_bf16 v[56:59], v[156:159], v[180:183], v[56:59]
	v_mfma_f32_16x16x32_bf16 v[52:55], v[148:151], v[188:191], v[52:55]
	v_mfma_f32_16x16x32_bf16 v[48:51], v[156:159], v[188:191], v[48:51]
	v_mfma_f32_16x16x32_bf16 v[44:47], v[148:151], v[196:199], v[44:47]
	v_mfma_f32_16x16x32_bf16 v[40:43], v[156:159], v[196:199], v[40:43]
	v_mfma_f32_16x16x32_bf16 v[36:39], v[148:151], v[204:207], v[36:39]
	v_mfma_f32_16x16x32_bf16 v[32:35], v[156:159], v[204:207], v[32:35]
	s_setprio 0
	s_setprio 1
	v_mfma_f32_16x16x32_bf16 v[28:31], v[160:163], v[176:179], v[28:31]
	v_mfma_f32_16x16x32_bf16 v[24:27], v[168:171], v[176:179], v[24:27]
	v_mfma_f32_16x16x32_bf16 v[20:23], v[160:163], v[184:187], v[20:23]
	v_mfma_f32_16x16x32_bf16 v[16:19], v[168:171], v[184:187], v[16:19]
	v_mfma_f32_16x16x32_bf16 v[12:15], v[160:163], v[192:195], v[12:15]
	v_mfma_f32_16x16x32_bf16 v[8:11], v[168:171], v[192:195], v[8:11]
	v_mfma_f32_16x16x32_bf16 v[4:7], v[160:163], v[200:203], v[4:7]
	v_mfma_f32_16x16x32_bf16 v[0:3], v[168:171], v[200:203], v[0:3]
	v_mfma_f32_16x16x32_bf16 v[28:31], v[164:167], v[180:183], v[28:31]
	v_mfma_f32_16x16x32_bf16 v[24:27], v[172:175], v[180:183], v[24:27]
	v_mfma_f32_16x16x32_bf16 v[20:23], v[164:167], v[188:191], v[20:23]
	v_mfma_f32_16x16x32_bf16 v[16:19], v[172:175], v[188:191], v[16:19]
	v_mfma_f32_16x16x32_bf16 v[12:15], v[164:167], v[196:199], v[12:15]
	v_mfma_f32_16x16x32_bf16 v[8:11], v[172:175], v[196:199], v[8:11]
	v_mfma_f32_16x16x32_bf16 v[4:7], v[164:167], v[204:207], v[4:7]
	v_mfma_f32_16x16x32_bf16 v[0:3], v[172:175], v[204:207], v[0:3]
	s_setprio 0
	s_barrier
	s_cmp_ge_u32 s26, s67
	s_mov_b32 s30, s26
	s_cbranch_scc0 .LBB0_1288
	s_cmpk_lt_u32 s61, 0x100
	s_cbranch_scc0 .LBB0_1291
	s_barrier

.LBB0_1302:
	ds_read_b128 v[150:153], v145
	ds_read_b128 v[154:157], v145 offset:1024
	ds_read_b128 v[158:161], v145 offset:2048
	ds_read_b128 v[162:165], v145 offset:3072
	ds_read_b128 v[166:169], v146
	ds_read_b128 v[170:173], v146 offset:1024
	ds_read_b128 v[174:177], v146 offset:2048
	ds_read_b128 v[178:181], v146 offset:3072
	s_add_u32 s30, s28, 0x100
	s_addc_u32 s31, s29, 0
	s_cmp_lg_u32 s52, 6
	s_cselect_b32 s40, s30, 0
	s_cselect_b32 s41, s31, 0
	s_add_u32 s42, s24, s40
	s_addc_u32 s43, s25, s41
	s_add_u32 s40, s22, s40
	s_addc_u32 s41, s23, s41
	s_mov_b32 m0, s53
	v_lshl_add_u64 v[216:217], v[136:137], 0, s[28:29]
	ds_read_b128 v[182:185], v147
	ds_read_b128 v[186:189], v147 offset:1024
	ds_read_b128 v[190:193], v147 offset:2048
	ds_read_b128 v[194:197], v147 offset:3072
	ds_read_b128 v[198:201], v147 offset:4096
	ds_read_b128 v[202:205], v147 offset:5120
	ds_read_b128 v[206:209], v147 offset:6144
	ds_read_b128 v[210:213], v147 offset:7168
	global_load_lds_dwordx4 v[216:217], off
	v_lshl_add_u64 v[216:217], v[138:139], 0, s[28:29]
	s_mov_b32 m0, s61
	s_nop 0
	global_load_lds_dwordx4 v[216:217], off
	s_waitcnt vmcnt(8)
	s_waitcnt lgkmcnt(0)
	s_barrier
	s_setprio 1
	s_waitcnt lgkmcnt(0)
	v_mfma_f32_16x16x32_bf16 v[124:127], v[150:153], v[182:185], v[124:127]
	v_mfma_f32_16x16x32_bf16 v[120:123], v[158:161], v[182:185], v[120:123]
	v_mfma_f32_16x16x32_bf16 v[108:111], v[150:153], v[190:193], v[108:111]
	v_mfma_f32_16x16x32_bf16 v[104:107], v[158:161], v[190:193], v[104:107]
	v_mfma_f32_16x16x32_bf16 v[92:95], v[150:153], v[198:201], v[92:95]
	v_mfma_f32_16x16x32_bf16 v[88:91], v[158:161], v[198:201], v[88:91]
	v_mfma_f32_16x16x32_bf16 v[76:79], v[150:153], v[206:209], v[76:79]
	v_mfma_f32_16x16x32_bf16 v[72:75], v[158:161], v[206:209], v[72:75]
	v_mfma_f32_16x16x32_bf16 v[124:127], v[154:157], v[186:189], v[124:127]
	v_mfma_f32_16x16x32_bf16 v[120:123], v[162:165], v[186:189], v[120:123]
	v_mfma_f32_16x16x32_bf16 v[108:111], v[154:157], v[194:197], v[108:111]
	v_mfma_f32_16x16x32_bf16 v[104:107], v[162:165], v[194:197], v[104:107]
	v_mfma_f32_16x16x32_bf16 v[92:95], v[154:157], v[202:205], v[92:95]
	v_mfma_f32_16x16x32_bf16 v[88:91], v[162:165], v[202:205], v[88:91]
	v_mfma_f32_16x16x32_bf16 v[76:79], v[154:157], v[210:213], v[76:79]
	v_mfma_f32_16x16x32_bf16 v[72:75], v[162:165], v[210:213], v[72:75]
	s_setprio 0
	s_setprio 1
	v_mfma_f32_16x16x32_bf16 v[116:119], v[166:169], v[182:185], v[116:119]
	v_mfma_f32_16x16x32_bf16 v[112:115], v[174:177], v[182:185], v[112:115]
	v_mfma_f32_16x16x32_bf16 v[100:103], v[166:169], v[190:193], v[100:103]
	v_mfma_f32_16x16x32_bf16 v[96:99], v[174:177], v[190:193], v[96:99]
	v_mfma_f32_16x16x32_bf16 v[84:87], v[166:169], v[198:201], v[84:87]
	v_mfma_f32_16x16x32_bf16 v[80:83], v[174:177], v[198:201], v[80:83]
	v_mfma_f32_16x16x32_bf16 v[68:71], v[166:169], v[206:209], v[68:71]
	v_mfma_f32_16x16x32_bf16 v[64:67], v[174:177], v[206:209], v[64:67]
	v_mfma_f32_16x16x32_bf16 v[116:119], v[170:173], v[186:189], v[116:119]
	v_mfma_f32_16x16x32_bf16 v[112:115], v[178:181], v[186:189], v[112:115]
	v_mfma_f32_16x16x32_bf16 v[100:103], v[170:173], v[194:197], v[100:103]
	v_mfma_f32_16x16x32_bf16 v[96:99], v[178:181], v[194:197], v[96:99]
	v_mfma_f32_16x16x32_bf16 v[84:87], v[170:173], v[202:205], v[84:87]
	v_mfma_f32_16x16x32_bf16 v[80:83], v[178:181], v[202:205], v[80:83]
	v_mfma_f32_16x16x32_bf16 v[68:71], v[170:173], v[210:213], v[68:71]
	v_mfma_f32_16x16x32_bf16 v[64:67], v[178:181], v[210:213], v[64:67]
	s_setprio 0
	s_barrier
	s_mov_b32 m0, s62
	v_lshl_add_u64 v[216:217], s[40:41], 0, v[130:131]
	s_add_u32 s28, s40, 0xb0000
	ds_read_b128 v[182:185], v147 offset:16384
	ds_read_b128 v[186:189], v147 offset:17408
	ds_read_b128 v[190:193], v147 offset:18432
	ds_read_b128 v[194:197], v147 offset:19456
	ds_read_b128 v[198:201], v147 offset:20480
	ds_read_b128 v[202:205], v147 offset:21504
	ds_read_b128 v[206:209], v147 offset:22528
	ds_read_b128 v[210:213], v147 offset:23552
	global_load_lds_dwordx4 v[216:217], off
	v_lshl_add_u64 v[218:219], s[40:41], 0, v[134:135]
	s_mov_b32 m0, s63
	s_addc_u32 s29, s41, 0
	global_load_lds_dwordx4 v[218:219], off
	v_lshl_add_u64 v[220:221], s[28:29], 0, v[130:131]
	s_mov_b32 m0, s64
	v_lshl_add_u64 v[222:223], s[42:43], 0, v[132:133]
	global_load_lds_dwordx4 v[220:221], off
	v_lshl_add_u64 v[220:221], s[28:29], 0, v[134:135]
	s_mov_b32 m0, s65
	s_nop 0
	global_load_lds_dwordx4 v[220:221], off
	v_lshl_add_u64 v[220:221], s[42:43], 0, v[128:129]
	s_mov_b32 m0, s57
	s_nop 0
	global_load_lds_dwordx4 v[220:221], off
	s_mov_b32 m0, s54
	s_nop 0
	global_load_lds_dwordx4 v[222:223], off
	s_waitcnt vmcnt(8)
	s_waitcnt lgkmcnt(0)
	s_barrier
	s_setprio 1
	s_waitcnt lgkmcnt(0)
	v_mfma_f32_16x16x32_bf16 v[60:63], v[150:153], v[182:185], v[60:63]
	v_mfma_f32_16x16x32_bf16 v[56:59], v[158:161], v[182:185], v[56:59]
	v_mfma_f32_16x16x32_bf16 v[44:47], v[150:153], v[190:193], v[44:47]
	v_mfma_f32_16x16x32_bf16 v[40:43], v[158:161], v[190:193], v[40:43]
	v_mfma_f32_16x16x32_bf16 v[36:39], v[150:153], v[198:201], v[36:39]
	v_mfma_f32_16x16x32_bf16 v[24:27], v[158:161], v[198:201], v[24:27]
	v_mfma_f32_16x16x32_bf16 v[16:19], v[150:153], v[206:209], v[16:19]
	v_mfma_f32_16x16x32_bf16 v[8:11], v[158:161], v[206:209], v[8:11]
	v_mfma_f32_16x16x32_bf16 v[60:63], v[154:157], v[186:189], v[60:63]
	v_mfma_f32_16x16x32_bf16 v[56:59], v[162:165], v[186:189], v[56:59]
	v_mfma_f32_16x16x32_bf16 v[44:47], v[154:157], v[194:197], v[44:47]
	v_mfma_f32_16x16x32_bf16 v[40:43], v[162:165], v[194:197], v[40:43]
	v_mfma_f32_16x16x32_bf16 v[36:39], v[154:157], v[202:205], v[36:39]
	v_mfma_f32_16x16x32_bf16 v[24:27], v[162:165], v[202:205], v[24:27]
	v_mfma_f32_16x16x32_bf16 v[16:19], v[154:157], v[210:213], v[16:19]
	v_mfma_f32_16x16x32_bf16 v[8:11], v[162:165], v[210:213], v[8:11]
	s_setprio 0
	s_setprio 1
	v_mfma_f32_16x16x32_bf16 v[52:55], v[166:169], v[182:185], v[52:55]
	v_mfma_f32_16x16x32_bf16 v[48:51], v[174:177], v[182:185], v[48:51]
	v_mfma_f32_16x16x32_bf16 v[32:35], v[166:169], v[190:193], v[32:35]
	v_mfma_f32_16x16x32_bf16 v[28:31], v[174:177], v[190:193], v[28:31]
	v_mfma_f32_16x16x32_bf16 v[20:23], v[166:169], v[198:201], v[20:23]
	v_mfma_f32_16x16x32_bf16 v[12:15], v[174:177], v[198:201], v[12:15]
	v_mfma_f32_16x16x32_bf16 v[4:7], v[166:169], v[206:209], v[4:7]
	v_mfma_f32_16x16x32_bf16 v[0:3], v[174:177], v[206:209], v[0:3]
	v_mfma_f32_16x16x32_bf16 v[52:55], v[170:173], v[186:189], v[52:55]
	v_mfma_f32_16x16x32_bf16 v[48:51], v[178:181], v[186:189], v[48:51]
	v_mfma_f32_16x16x32_bf16 v[32:35], v[170:173], v[194:197], v[32:35]
	v_mfma_f32_16x16x32_bf16 v[28:31], v[178:181], v[194:197], v[28:31]
	v_mfma_f32_16x16x32_bf16 v[20:23], v[170:173], v[202:205], v[20:23]
	v_mfma_f32_16x16x32_bf16 v[12:15], v[178:181], v[202:205], v[12:15]
	v_mfma_f32_16x16x32_bf16 v[4:7], v[170:173], v[210:213], v[4:7]
	v_mfma_f32_16x16x32_bf16 v[0:3], v[178:181], v[210:213], v[0:3]
	s_setprio 0
	s_barrier
	ds_read_b128 v[150:153], v148
	ds_read_b128 v[154:157], v148 offset:1024
	ds_read_b128 v[158:161], v148 offset:2048
	ds_read_b128 v[162:165], v148 offset:3072
	ds_read_b128 v[166:169], v149
	ds_read_b128 v[170:173], v149 offset:1024
	ds_read_b128 v[174:177], v149 offset:2048
	ds_read_b128 v[178:181], v149 offset:3072
	s_add_u32 s28, s42, 0xb0000
	s_addc_u32 s29, s43, 0
	s_mov_b32 m0, s55
	v_lshl_add_u64 v[224:225], s[28:29], 0, v[128:129]
	ds_read_b128 v[182:185], v147 offset:32768
	ds_read_b128 v[186:189], v147 offset:33792
	ds_read_b128 v[190:193], v147 offset:34816
	ds_read_b128 v[194:197], v147 offset:35840
	ds_read_b128 v[198:201], v147 offset:36864
	ds_read_b128 v[202:205], v147 offset:37888
	ds_read_b128 v[206:209], v147 offset:38912
	ds_read_b128 v[210:213], v147 offset:39936
	global_load_lds_dwordx4 v[224:225], off
	v_lshl_add_u64 v[224:225], s[28:29], 0, v[132:133]
	s_mov_b32 m0, s56
	s_nop 0
	global_load_lds_dwordx4 v[224:225], off
	s_waitcnt vmcnt(8)
	s_waitcnt lgkmcnt(0)
	s_barrier
	s_setprio 1
	s_waitcnt lgkmcnt(0)
	v_mfma_f32_16x16x32_bf16 v[124:127], v[150:153], v[182:185], v[124:127]
	v_mfma_f32_16x16x32_bf16 v[120:123], v[158:161], v[182:185], v[120:123]
	v_mfma_f32_16x16x32_bf16 v[108:111], v[150:153], v[190:193], v[108:111]
	v_mfma_f32_16x16x32_bf16 v[104:107], v[158:161], v[190:193], v[104:107]
	v_mfma_f32_16x16x32_bf16 v[92:95], v[150:153], v[198:201], v[92:95]
	v_mfma_f32_16x16x32_bf16 v[88:91], v[158:161], v[198:201], v[88:91]
	v_mfma_f32_16x16x32_bf16 v[76:79], v[150:153], v[206:209], v[76:79]
	v_mfma_f32_16x16x32_bf16 v[72:75], v[158:161], v[206:209], v[72:75]
	v_mfma_f32_16x16x32_bf16 v[124:127], v[154:157], v[186:189], v[124:127]
	v_mfma_f32_16x16x32_bf16 v[120:123], v[162:165], v[186:189], v[120:123]
	v_mfma_f32_16x16x32_bf16 v[108:111], v[154:157], v[194:197], v[108:111]
	v_mfma_f32_16x16x32_bf16 v[104:107], v[162:165], v[194:197], v[104:107]
	v_mfma_f32_16x16x32_bf16 v[92:95], v[154:157], v[202:205], v[92:95]
	v_mfma_f32_16x16x32_bf16 v[88:91], v[162:165], v[202:205], v[88:91]
	v_mfma_f32_16x16x32_bf16 v[76:79], v[154:157], v[210:213], v[76:79]
	v_mfma_f32_16x16x32_bf16 v[72:75], v[162:165], v[210:213], v[72:75]
	s_setprio 0
	s_setprio 1
	v_mfma_f32_16x16x32_bf16 v[116:119], v[166:169], v[182:185], v[116:119]
	v_mfma_f32_16x16x32_bf16 v[112:115], v[174:177], v[182:185], v[112:115]
	v_mfma_f32_16x16x32_bf16 v[100:103], v[166:169], v[190:193], v[100:103]
	v_mfma_f32_16x16x32_bf16 v[96:99], v[174:177], v[190:193], v[96:99]
	v_mfma_f32_16x16x32_bf16 v[84:87], v[166:169], v[198:201], v[84:87]
	v_mfma_f32_16x16x32_bf16 v[80:83], v[174:177], v[198:201], v[80:83]
	v_mfma_f32_16x16x32_bf16 v[68:71], v[166:169], v[206:209], v[68:71]
	v_mfma_f32_16x16x32_bf16 v[64:67], v[174:177], v[206:209], v[64:67]
	v_mfma_f32_16x16x32_bf16 v[116:119], v[170:173], v[186:189], v[116:119]
	v_mfma_f32_16x16x32_bf16 v[112:115], v[178:181], v[186:189], v[112:115]
	v_mfma_f32_16x16x32_bf16 v[100:103], v[170:173], v[194:197], v[100:103]
	v_mfma_f32_16x16x32_bf16 v[96:99], v[178:181], v[194:197], v[96:99]
	v_mfma_f32_16x16x32_bf16 v[84:87], v[170:173], v[202:205], v[84:87]
	v_mfma_f32_16x16x32_bf16 v[80:83], v[178:181], v[202:205], v[80:83]
	v_mfma_f32_16x16x32_bf16 v[68:71], v[170:173], v[210:213], v[68:71]
	v_mfma_f32_16x16x32_bf16 v[64:67], v[178:181], v[210:213], v[64:67]
	s_setprio 0
	s_barrier
	s_mov_b32 m0, s66
	v_lshl_add_u64 v[216:217], v[216:217], 0, s[26:27]
	s_add_u32 s28, s40, 0xb0080
	ds_read_b128 v[182:185], v147 offset:49152
	ds_read_b128 v[186:189], v147 offset:50176
	ds_read_b128 v[190:193], v147 offset:51200
	ds_read_b128 v[194:197], v147 offset:52224
	ds_read_b128 v[198:201], v147 offset:53248
	ds_read_b128 v[202:205], v147 offset:54272
	ds_read_b128 v[206:209], v147 offset:55296
	ds_read_b128 v[210:213], v147 offset:56320
	global_load_lds_dwordx4 v[216:217], off
	v_lshl_add_u64 v[216:217], v[218:219], 0, s[26:27]
	s_mov_b32 m0, s67
	s_addc_u32 s29, s41, 0
	global_load_lds_dwordx4 v[216:217], off
	v_lshl_add_u64 v[216:217], s[28:29], 0, v[130:131]
	s_mov_b32 m0, s68
	s_nop 0
	global_load_lds_dwordx4 v[216:217], off
	v_lshl_add_u64 v[216:217], s[28:29], 0, v[134:135]
	s_mov_b32 m0, s69
	s_nop 0
	global_load_lds_dwordx4 v[216:217], off
	v_lshl_add_u64 v[216:217], v[220:221], 0, s[26:27]
	s_mov_b32 m0, s58
	s_nop 0
	global_load_lds_dwordx4 v[216:217], off
	v_lshl_add_u64 v[216:217], v[222:223], 0, s[26:27]
	s_mov_b32 m0, s59
	s_nop 0
	global_load_lds_dwordx4 v[216:217], off
	s_waitcnt vmcnt(8)
	s_waitcnt lgkmcnt(0)
	s_barrier
	s_setprio 1
	s_waitcnt lgkmcnt(0)
	v_mfma_f32_16x16x32_bf16 v[60:63], v[150:153], v[182:185], v[60:63]
	v_mfma_f32_16x16x32_bf16 v[56:59], v[158:161], v[182:185], v[56:59]
	v_mfma_f32_16x16x32_bf16 v[44:47], v[150:153], v[190:193], v[44:47]
	v_mfma_f32_16x16x32_bf16 v[40:43], v[158:161], v[190:193], v[40:43]
	v_mfma_f32_16x16x32_bf16 v[36:39], v[150:153], v[198:201], v[36:39]
	v_mfma_f32_16x16x32_bf16 v[24:27], v[158:161], v[198:201], v[24:27]
	v_mfma_f32_16x16x32_bf16 v[16:19], v[150:153], v[206:209], v[16:19]
	v_mfma_f32_16x16x32_bf16 v[8:11], v[158:161], v[206:209], v[8:11]
	v_mfma_f32_16x16x32_bf16 v[60:63], v[154:157], v[186:189], v[60:63]
	v_mfma_f32_16x16x32_bf16 v[56:59], v[162:165], v[186:189], v[56:59]
	v_mfma_f32_16x16x32_bf16 v[44:47], v[154:157], v[194:197], v[44:47]
	v_mfma_f32_16x16x32_bf16 v[40:43], v[162:165], v[194:197], v[40:43]
	v_mfma_f32_16x16x32_bf16 v[36:39], v[154:157], v[202:205], v[36:39]
	v_mfma_f32_16x16x32_bf16 v[24:27], v[162:165], v[202:205], v[24:27]
	v_mfma_f32_16x16x32_bf16 v[16:19], v[154:157], v[210:213], v[16:19]
	v_mfma_f32_16x16x32_bf16 v[8:11], v[162:165], v[210:213], v[8:11]
	s_setprio 0
	s_setprio 1
	v_mfma_f32_16x16x32_bf16 v[52:55], v[166:169], v[182:185], v[52:55]
	v_mfma_f32_16x16x32_bf16 v[48:51], v[174:177], v[182:185], v[48:51]
	v_mfma_f32_16x16x32_bf16 v[32:35], v[166:169], v[190:193], v[32:35]
	v_mfma_f32_16x16x32_bf16 v[28:31], v[174:177], v[190:193], v[28:31]
	v_mfma_f32_16x16x32_bf16 v[20:23], v[166:169], v[198:201], v[20:23]
	v_mfma_f32_16x16x32_bf16 v[12:15], v[174:177], v[198:201], v[12:15]
	v_mfma_f32_16x16x32_bf16 v[4:7], v[166:169], v[206:209], v[4:7]
	v_mfma_f32_16x16x32_bf16 v[0:3], v[174:177], v[206:209], v[0:3]
	v_mfma_f32_16x16x32_bf16 v[52:55], v[170:173], v[186:189], v[52:55]
	v_mfma_f32_16x16x32_bf16 v[48:51], v[178:181], v[186:189], v[48:51]
	v_mfma_f32_16x16x32_bf16 v[32:35], v[170:173], v[194:197], v[32:35]
	v_mfma_f32_16x16x32_bf16 v[28:31], v[178:181], v[194:197], v[28:31]
	v_mfma_f32_16x16x32_bf16 v[20:23], v[170:173], v[202:205], v[20:23]
	v_mfma_f32_16x16x32_bf16 v[12:15], v[178:181], v[202:205], v[12:15]
	v_mfma_f32_16x16x32_bf16 v[4:7], v[170:173], v[210:213], v[4:7]
	v_mfma_f32_16x16x32_bf16 v[0:3], v[178:181], v[210:213], v[0:3]
	s_setprio 0
	s_barrier
	s_add_i32 s52, s52, 2
	s_cmp_gt_u32 s52, 7
	s_mov_b64 s[28:29], s[30:31]
	s_cbranch_scc0 .LBB0_1302
	s_cmpk_lt_u32 s60, 0x100
	s_cbranch_scc0 .LBB0_1305
	s_barrier

.LBB0_1361:
	ds_read_b128 v[142:145], v157
	ds_read_b128 v[146:149], v157 offset:1024
	ds_read_b128 v[150:153], v157 offset:2048
	ds_read_b128 v[160:163], v157 offset:3072
	ds_read_b128 v[164:167], v158
	ds_read_b128 v[168:171], v158 offset:1024
	ds_read_b128 v[172:175], v158 offset:2048
	ds_read_b128 v[176:179], v158 offset:3072
	s_add_u32 s16, s14, 0x100
	s_addc_u32 s17, s15, 0
	s_cmp_eq_u32 s51, 40
	s_cselect_b32 s21, s3, s17
	s_cselect_b32 s20, s2, s16
	s_cselect_b32 s19, s13, s50
	s_cselect_b32 s18, s12, s45
	v_lshl_add_u64 v[212:213], s[14:15], 0, v[136:137]
	s_add_i32 m0, s29, 0xc000
	ds_read_b128 v[180:183], v159
	ds_read_b128 v[184:187], v159 offset:1024
	ds_read_b128 v[188:191], v159 offset:2048
	ds_read_b128 v[192:195], v159 offset:3072
	ds_read_b128 v[196:199], v159 offset:4096
	ds_read_b128 v[200:203], v159 offset:5120
	ds_read_b128 v[204:207], v159 offset:6144
	ds_read_b128 v[208:211], v159 offset:7168
	global_load_lds_dwordx4 v[212:213], off
	v_lshl_add_u64 v[212:213], s[14:15], 0, v[138:139]
	s_add_i32 m0, s29, 0xe000
	s_nop 0
	global_load_lds_dwordx4 v[212:213], off
	s_waitcnt vmcnt(8)
	s_waitcnt lgkmcnt(0)
	s_barrier
	s_setprio 1
	s_waitcnt lgkmcnt(0)
	v_mfma_f32_16x16x32_bf16 v[124:127], v[142:145], v[180:183], v[124:127]
	v_mfma_f32_16x16x32_bf16 v[120:123], v[150:153], v[180:183], v[120:123]
	v_mfma_f32_16x16x32_bf16 v[108:111], v[142:145], v[188:191], v[108:111]
	v_mfma_f32_16x16x32_bf16 v[104:107], v[150:153], v[188:191], v[104:107]
	v_mfma_f32_16x16x32_bf16 v[92:95], v[142:145], v[196:199], v[92:95]
	v_mfma_f32_16x16x32_bf16 v[88:91], v[150:153], v[196:199], v[88:91]
	v_mfma_f32_16x16x32_bf16 v[80:83], v[142:145], v[204:207], v[80:83]
	v_mfma_f32_16x16x32_bf16 v[72:75], v[150:153], v[204:207], v[72:75]
	v_mfma_f32_16x16x32_bf16 v[124:127], v[146:149], v[184:187], v[124:127]
	v_mfma_f32_16x16x32_bf16 v[120:123], v[160:163], v[184:187], v[120:123]
	v_mfma_f32_16x16x32_bf16 v[108:111], v[146:149], v[192:195], v[108:111]
	v_mfma_f32_16x16x32_bf16 v[104:107], v[160:163], v[192:195], v[104:107]
	v_mfma_f32_16x16x32_bf16 v[92:95], v[146:149], v[200:203], v[92:95]
	v_mfma_f32_16x16x32_bf16 v[88:91], v[160:163], v[200:203], v[88:91]
	v_mfma_f32_16x16x32_bf16 v[80:83], v[146:149], v[208:211], v[80:83]
	v_mfma_f32_16x16x32_bf16 v[72:75], v[160:163], v[208:211], v[72:75]
	s_setprio 0
	s_setprio 1
	v_mfma_f32_16x16x32_bf16 v[116:119], v[164:167], v[180:183], v[116:119]
	v_mfma_f32_16x16x32_bf16 v[112:115], v[172:175], v[180:183], v[112:115]
	v_mfma_f32_16x16x32_bf16 v[100:103], v[164:167], v[188:191], v[100:103]
	v_mfma_f32_16x16x32_bf16 v[96:99], v[172:175], v[188:191], v[96:99]
	v_mfma_f32_16x16x32_bf16 v[84:87], v[164:167], v[196:199], v[84:87]
	v_mfma_f32_16x16x32_bf16 v[76:79], v[172:175], v[196:199], v[76:79]
	v_mfma_f32_16x16x32_bf16 v[68:71], v[164:167], v[204:207], v[68:71]
	v_mfma_f32_16x16x32_bf16 v[64:67], v[172:175], v[204:207], v[64:67]
	v_mfma_f32_16x16x32_bf16 v[116:119], v[168:171], v[184:187], v[116:119]
	v_mfma_f32_16x16x32_bf16 v[112:115], v[176:179], v[184:187], v[112:115]
	v_mfma_f32_16x16x32_bf16 v[100:103], v[168:171], v[192:195], v[100:103]
	v_mfma_f32_16x16x32_bf16 v[96:99], v[176:179], v[192:195], v[96:99]
	v_mfma_f32_16x16x32_bf16 v[84:87], v[168:171], v[200:203], v[84:87]
	v_mfma_f32_16x16x32_bf16 v[76:79], v[176:179], v[200:203], v[76:79]
	v_mfma_f32_16x16x32_bf16 v[68:71], v[168:171], v[208:211], v[68:71]
	v_mfma_f32_16x16x32_bf16 v[64:67], v[176:179], v[208:211], v[64:67]
	s_setprio 0
	s_barrier
	s_add_i32 s14, s4, s27
	v_lshl_add_u64 v[212:213], s[18:19], 0, v[132:133]
	s_mov_b32 m0, s14
	ds_read_b128 v[180:183], v159 offset:16384
	ds_read_b128 v[184:187], v159 offset:17408
	ds_read_b128 v[188:191], v159 offset:18432
	ds_read_b128 v[192:195], v159 offset:19456
	ds_read_b128 v[196:199], v159 offset:20480
	ds_read_b128 v[200:203], v159 offset:21504
	ds_read_b128 v[204:207], v159 offset:22528
	ds_read_b128 v[208:211], v159 offset:23552
	global_load_lds_dwordx4 v[212:213], off
	s_add_i32 m0, s14, 0x2000
	s_add_u32 s14, s18, 0xb0000
	v_lshl_add_u64 v[214:215], s[18:19], 0, v[128:129]
	s_addc_u32 s15, s19, 0
	s_add_i32 s52, s40, s27
	global_load_lds_dwordx4 v[214:215], off
	v_lshl_add_u64 v[216:217], s[14:15], 0, v[132:133]
	s_mov_b32 m0, s52
	v_lshl_add_u64 v[218:219], s[20:21], 0, v[130:131]
	global_load_lds_dwordx4 v[216:217], off
	v_lshl_add_u64 v[216:217], s[14:15], 0, v[128:129]
	s_add_i32 m0, s52, 0x2000
	s_nop 0
	global_load_lds_dwordx4 v[216:217], off
	v_lshl_add_u64 v[216:217], s[20:21], 0, v[134:135]
	s_mov_b32 m0, s29
	s_nop 0
	global_load_lds_dwordx4 v[216:217], off
	s_mov_b32 m0, s30
	s_nop 0
	global_load_lds_dwordx4 v[218:219], off
	s_waitcnt vmcnt(8)
	s_waitcnt lgkmcnt(0)
	s_barrier
	s_setprio 1
	s_waitcnt lgkmcnt(0)
	v_mfma_f32_16x16x32_bf16 v[60:63], v[142:145], v[180:183], v[60:63]
	v_mfma_f32_16x16x32_bf16 v[56:59], v[150:153], v[180:183], v[56:59]
	v_mfma_f32_16x16x32_bf16 v[44:47], v[142:145], v[188:191], v[44:47]
	v_mfma_f32_16x16x32_bf16 v[40:43], v[150:153], v[188:191], v[40:43]
	v_mfma_f32_16x16x32_bf16 v[36:39], v[142:145], v[196:199], v[36:39]
	v_mfma_f32_16x16x32_bf16 v[24:27], v[150:153], v[196:199], v[24:27]
	v_mfma_f32_16x16x32_bf16 v[16:19], v[142:145], v[204:207], v[16:19]
	v_mfma_f32_16x16x32_bf16 v[8:11], v[150:153], v[204:207], v[8:11]
	v_mfma_f32_16x16x32_bf16 v[60:63], v[146:149], v[184:187], v[60:63]
	v_mfma_f32_16x16x32_bf16 v[56:59], v[160:163], v[184:187], v[56:59]
	v_mfma_f32_16x16x32_bf16 v[44:47], v[146:149], v[192:195], v[44:47]
	v_mfma_f32_16x16x32_bf16 v[40:43], v[160:163], v[192:195], v[40:43]
	v_mfma_f32_16x16x32_bf16 v[36:39], v[146:149], v[200:203], v[36:39]
	v_mfma_f32_16x16x32_bf16 v[24:27], v[160:163], v[200:203], v[24:27]
	v_mfma_f32_16x16x32_bf16 v[16:19], v[146:149], v[208:211], v[16:19]
	v_mfma_f32_16x16x32_bf16 v[8:11], v[160:163], v[208:211], v[8:11]
	s_setprio 0
	s_setprio 1
	v_mfma_f32_16x16x32_bf16 v[52:55], v[164:167], v[180:183], v[52:55]
	v_mfma_f32_16x16x32_bf16 v[48:51], v[172:175], v[180:183], v[48:51]
	v_mfma_f32_16x16x32_bf16 v[32:35], v[164:167], v[188:191], v[32:35]
	v_mfma_f32_16x16x32_bf16 v[28:31], v[172:175], v[188:191], v[28:31]
	v_mfma_f32_16x16x32_bf16 v[20:23], v[164:167], v[196:199], v[20:23]
	v_mfma_f32_16x16x32_bf16 v[12:15], v[172:175], v[196:199], v[12:15]
	v_mfma_f32_16x16x32_bf16 v[4:7], v[164:167], v[204:207], v[4:7]
	v_mfma_f32_16x16x32_bf16 v[0:3], v[172:175], v[204:207], v[0:3]
	v_mfma_f32_16x16x32_bf16 v[52:55], v[168:171], v[184:187], v[52:55]
	v_mfma_f32_16x16x32_bf16 v[48:51], v[176:179], v[184:187], v[48:51]
	v_mfma_f32_16x16x32_bf16 v[32:35], v[168:171], v[192:195], v[32:35]
	v_mfma_f32_16x16x32_bf16 v[28:31], v[176:179], v[192:195], v[28:31]
	v_mfma_f32_16x16x32_bf16 v[20:23], v[168:171], v[200:203], v[20:23]
	v_mfma_f32_16x16x32_bf16 v[12:15], v[176:179], v[200:203], v[12:15]
	v_mfma_f32_16x16x32_bf16 v[4:7], v[168:171], v[208:211], v[4:7]
	v_mfma_f32_16x16x32_bf16 v[0:3], v[176:179], v[208:211], v[0:3]
	s_setprio 0
	s_barrier
	s_add_i32 s52, 0, 0x18000
	s_add_i32 s53, 0, 0x1c000
	v_add_u32_e32 v160, s52, v155
	v_add_u32_e32 v176, s53, v155
	ds_read_b128 v[142:145], v160
	ds_read_b128 v[146:149], v160 offset:1024
	ds_read_b128 v[150:153], v160 offset:2048
	ds_read_b128 v[160:163], v160 offset:3072
	ds_read_b128 v[164:167], v176
	ds_read_b128 v[168:171], v176 offset:1024
	ds_read_b128 v[172:175], v176 offset:2048
	ds_read_b128 v[176:179], v176 offset:3072
	s_add_u32 s14, s20, 0xb0000
	s_addc_u32 s15, s21, 0
	s_mov_b32 m0, s31
	v_lshl_add_u64 v[220:221], s[14:15], 0, v[134:135]
	ds_read_b128 v[180:183], v159 offset:32768
	ds_read_b128 v[184:187], v159 offset:33792
	ds_read_b128 v[188:191], v159 offset:34816
	ds_read_b128 v[192:195], v159 offset:35840
	ds_read_b128 v[196:199], v159 offset:36864
	ds_read_b128 v[200:203], v159 offset:37888
	ds_read_b128 v[204:207], v159 offset:38912
	ds_read_b128 v[208:211], v159 offset:39936
	global_load_lds_dwordx4 v[220:221], off
	v_lshl_add_u64 v[220:221], s[14:15], 0, v[130:131]
	s_mov_b32 m0, s34
	s_nop 0
	global_load_lds_dwordx4 v[220:221], off
	s_waitcnt vmcnt(8)
	s_waitcnt lgkmcnt(0)
	s_barrier
	s_setprio 1
	s_waitcnt lgkmcnt(0)
	v_mfma_f32_16x16x32_bf16 v[124:127], v[142:145], v[180:183], v[124:127]
	v_mfma_f32_16x16x32_bf16 v[120:123], v[150:153], v[180:183], v[120:123]
	v_mfma_f32_16x16x32_bf16 v[108:111], v[142:145], v[188:191], v[108:111]
	v_mfma_f32_16x16x32_bf16 v[104:107], v[150:153], v[188:191], v[104:107]
	v_mfma_f32_16x16x32_bf16 v[92:95], v[142:145], v[196:199], v[92:95]
	v_mfma_f32_16x16x32_bf16 v[88:91], v[150:153], v[196:199], v[88:91]
	v_mfma_f32_16x16x32_bf16 v[80:83], v[142:145], v[204:207], v[80:83]
	v_mfma_f32_16x16x32_bf16 v[72:75], v[150:153], v[204:207], v[72:75]
	v_mfma_f32_16x16x32_bf16 v[124:127], v[146:149], v[184:187], v[124:127]
	v_mfma_f32_16x16x32_bf16 v[120:123], v[160:163], v[184:187], v[120:123]
	v_mfma_f32_16x16x32_bf16 v[108:111], v[146:149], v[192:195], v[108:111]
	v_mfma_f32_16x16x32_bf16 v[104:107], v[160:163], v[192:195], v[104:107]
	v_mfma_f32_16x16x32_bf16 v[92:95], v[146:149], v[200:203], v[92:95]
	v_mfma_f32_16x16x32_bf16 v[88:91], v[160:163], v[200:203], v[88:91]
	v_mfma_f32_16x16x32_bf16 v[80:83], v[146:149], v[208:211], v[80:83]
	v_mfma_f32_16x16x32_bf16 v[72:75], v[160:163], v[208:211], v[72:75]
	s_setprio 0
	s_setprio 1
	v_mfma_f32_16x16x32_bf16 v[116:119], v[164:167], v[180:183], v[116:119]
	v_mfma_f32_16x16x32_bf16 v[112:115], v[172:175], v[180:183], v[112:115]
	v_mfma_f32_16x16x32_bf16 v[100:103], v[164:167], v[188:191], v[100:103]
	v_mfma_f32_16x16x32_bf16 v[96:99], v[172:175], v[188:191], v[96:99]
	v_mfma_f32_16x16x32_bf16 v[84:87], v[164:167], v[196:199], v[84:87]
	v_mfma_f32_16x16x32_bf16 v[76:79], v[172:175], v[196:199], v[76:79]
	v_mfma_f32_16x16x32_bf16 v[68:71], v[164:167], v[204:207], v[68:71]
	v_mfma_f32_16x16x32_bf16 v[64:67], v[172:175], v[204:207], v[64:67]
	v_mfma_f32_16x16x32_bf16 v[116:119], v[168:171], v[184:187], v[116:119]
	v_mfma_f32_16x16x32_bf16 v[112:115], v[176:179], v[184:187], v[112:115]
	v_mfma_f32_16x16x32_bf16 v[100:103], v[168:171], v[192:195], v[100:103]
	v_mfma_f32_16x16x32_bf16 v[96:99], v[176:179], v[192:195], v[96:99]
	v_mfma_f32_16x16x32_bf16 v[84:87], v[168:171], v[200:203], v[84:87]
	v_mfma_f32_16x16x32_bf16 v[76:79], v[176:179], v[200:203], v[76:79]
	v_mfma_f32_16x16x32_bf16 v[68:71], v[168:171], v[208:211], v[68:71]
	v_mfma_f32_16x16x32_bf16 v[64:67], v[176:179], v[208:211], v[64:67]
	s_setprio 0
	s_barrier
	s_add_i32 s14, s52, s27
	v_lshl_add_u64 v[212:213], v[212:213], 0, s[8:9]
	s_mov_b32 m0, s14
	ds_read_b128 v[180:183], v159 offset:49152
	ds_read_b128 v[184:187], v159 offset:50176
	ds_read_b128 v[188:191], v159 offset:51200
	ds_read_b128 v[192:195], v159 offset:52224
	ds_read_b128 v[196:199], v159 offset:53248
	ds_read_b128 v[200:203], v159 offset:54272
	ds_read_b128 v[204:207], v159 offset:55296
	ds_read_b128 v[208:211], v159 offset:56320
	global_load_lds_dwordx4 v[212:213], off
	s_add_i32 m0, s14, 0x2000
	s_add_u32 s14, s18, 0xb0080
	v_lshl_add_u64 v[212:213], v[214:215], 0, s[8:9]
	s_addc_u32 s15, s19, 0
	s_add_i32 s18, s53, s27
	global_load_lds_dwordx4 v[212:213], off
	v_lshl_add_u64 v[212:213], s[14:15], 0, v[132:133]
	s_mov_b32 m0, s18
	s_nop 0
	global_load_lds_dwordx4 v[212:213], off
	v_lshl_add_u64 v[212:213], s[14:15], 0, v[128:129]
	s_add_i32 m0, s18, 0x2000
	s_nop 0
	global_load_lds_dwordx4 v[212:213], off
	v_lshl_add_u64 v[212:213], v[216:217], 0, s[8:9]
	s_mov_b32 m0, s38
	s_nop 0
	global_load_lds_dwordx4 v[212:213], off
	v_lshl_add_u64 v[212:213], v[218:219], 0, s[8:9]
	s_mov_b32 m0, s39
	s_nop 0
	global_load_lds_dwordx4 v[212:213], off
	s_waitcnt vmcnt(8)
	s_waitcnt lgkmcnt(0)
	s_barrier
	s_setprio 1
	s_waitcnt lgkmcnt(0)
	v_mfma_f32_16x16x32_bf16 v[60:63], v[142:145], v[180:183], v[60:63]
	v_mfma_f32_16x16x32_bf16 v[56:59], v[150:153], v[180:183], v[56:59]
	v_mfma_f32_16x16x32_bf16 v[44:47], v[142:145], v[188:191], v[44:47]
	v_mfma_f32_16x16x32_bf16 v[40:43], v[150:153], v[188:191], v[40:43]
	v_mfma_f32_16x16x32_bf16 v[36:39], v[142:145], v[196:199], v[36:39]
	v_mfma_f32_16x16x32_bf16 v[24:27], v[150:153], v[196:199], v[24:27]
	v_mfma_f32_16x16x32_bf16 v[16:19], v[142:145], v[204:207], v[16:19]
	v_mfma_f32_16x16x32_bf16 v[8:11], v[150:153], v[204:207], v[8:11]
	v_mfma_f32_16x16x32_bf16 v[60:63], v[146:149], v[184:187], v[60:63]
	v_mfma_f32_16x16x32_bf16 v[56:59], v[160:163], v[184:187], v[56:59]
	v_mfma_f32_16x16x32_bf16 v[44:47], v[146:149], v[192:195], v[44:47]
	v_mfma_f32_16x16x32_bf16 v[40:43], v[160:163], v[192:195], v[40:43]
	v_mfma_f32_16x16x32_bf16 v[36:39], v[146:149], v[200:203], v[36:39]
	v_mfma_f32_16x16x32_bf16 v[24:27], v[160:163], v[200:203], v[24:27]
	v_mfma_f32_16x16x32_bf16 v[16:19], v[146:149], v[208:211], v[16:19]
	v_mfma_f32_16x16x32_bf16 v[8:11], v[160:163], v[208:211], v[8:11]
	s_setprio 0
	s_setprio 1
	v_mfma_f32_16x16x32_bf16 v[52:55], v[164:167], v[180:183], v[52:55]
	v_mfma_f32_16x16x32_bf16 v[48:51], v[172:175], v[180:183], v[48:51]
	v_mfma_f32_16x16x32_bf16 v[32:35], v[164:167], v[188:191], v[32:35]
	v_mfma_f32_16x16x32_bf16 v[28:31], v[172:175], v[188:191], v[28:31]
	v_mfma_f32_16x16x32_bf16 v[20:23], v[164:167], v[196:199], v[20:23]
	v_mfma_f32_16x16x32_bf16 v[12:15], v[172:175], v[196:199], v[12:15]
	v_mfma_f32_16x16x32_bf16 v[4:7], v[164:167], v[204:207], v[4:7]
	v_mfma_f32_16x16x32_bf16 v[0:3], v[172:175], v[204:207], v[0:3]
	v_mfma_f32_16x16x32_bf16 v[52:55], v[168:171], v[184:187], v[52:55]
	v_mfma_f32_16x16x32_bf16 v[48:51], v[176:179], v[184:187], v[48:51]
	v_mfma_f32_16x16x32_bf16 v[32:35], v[168:171], v[192:195], v[32:35]
	v_mfma_f32_16x16x32_bf16 v[28:31], v[176:179], v[192:195], v[28:31]
	v_mfma_f32_16x16x32_bf16 v[20:23], v[168:171], v[200:203], v[20:23]
	v_mfma_f32_16x16x32_bf16 v[12:15], v[176:179], v[200:203], v[12:15]
	v_mfma_f32_16x16x32_bf16 v[4:7], v[168:171], v[208:211], v[4:7]
	v_mfma_f32_16x16x32_bf16 v[0:3], v[176:179], v[208:211], v[0:3]
	s_setprio 0
	s_barrier
	s_add_i32 s51, s51, 2
	s_add_u32 s45, s45, 0x100
	s_addc_u32 s50, s50, 0
	s_cmp_gt_u32 s51, 41
	s_mov_b64 s[14:15], s[16:17]
	s_cbranch_scc0 .LBB0_1361
	s_and_b64 vcc, exec, s[10:11]
	s_cbranch_vccz .LBB0_1364
	s_barrier
